# GEMM k-loops: back edge rotated (guide 7.11): next iteration's first fragment ds_reads issued right after the barrier, before the last MFMA pair (22 of 25 loops)
# speedup vs baseline: 1.0138x; 1.0021x over previous
; DEV int tid_l() { int t = threadIdx.x; asm volatile("" : "+v"(t)); return t; }
; DEV int stage_next(int s) { return (s == 2 * GS_STAGE) ? 0 : s + GS_STAGE; }
; template <int WAIT0>
; DEV void gk_main(f32x16 (&acc)[2][2], const GTile& t, int s0) {
;   const int tid = tid_l(), lane = tid & 63, wid = __builtin_amdgcn_readfirstlane(tid >> 6), wm = wid & 1, wn = wid >> 1, l32 = lane & 31, hi = lane >> 5;
;   GK_SRC(t)
;   const int sw = (l32 >> 1) & 7;
;   int xk[4], wk[4];
; #pragma unroll
;   for (int ks = 0; ks < 4; ++ks) { const int ko = ((2 * ks + hi) ^ sw) << 4; xk[ks] = GS_A + (64 * wm + l32) * 128 + ko; wk[ks] = GS_B + (64 * wn + l32) * 128 + ko; }
;   const int nk = t.K >> 6;
;     ...
;   vm_wait_bar<WAIT0>();
;   int stc = s0, std_ = stage_next(stage_next(s0));
; #pragma nounroll
;   for (int kt = 0; kt < nk - 2; ++kt) {
;     GK_DMA(std_, kt + 2);
;     GK_COMPUTE(stc);
;     vm_wait_bar<6>();
;     stc = stage_next(stc); std_ = stage_next(std_);
;   }
.LBB0_72:
	s_cmp_lg_u32 s17, 0
	s_cbranch_scc0 .LBB0_85
	s_bitcmp0_b32 s17, 0
	s_mov_b64 s[6:7], -1
	s_cbranch_scc1 .LBB0_77
	v_mov_b32_e32 v1, v176
	s_waitcnt vmcnt(14) lgkmcnt(0)
	s_barrier
	v_readfirstlane_b32 s6, v1
	s_ashr_i32 s7, s6, 6
	v_and_b32_e32 v2, 31, v1
	v_bfe_u32 v0, v1, 3, 3
	v_lshl_or_b32 v0, s7, 3, v0
	v_and_or_b32 v5, s6, 64, v2
	s_lshr_b32 s6, s6, 1
	v_lshrrev_b32_e32 v3, 1, v0
	s_and_b32 s6, s6, 0x1ffffc0
	v_xor_b32_e32 v3, v3, v1
	v_or_b32_e32 v2, s6, v2
	s_lshl_b32 s6, s7, 10
	v_lshlrev_b32_e32 v3, 4, v3
	s_add_i32 s19, s6, 0
	s_add_i32 s6, s16, 0xc000
	v_and_b32_e32 v6, 0x70, v3
	v_bfe_u32 v3, v1, 5, 1
	v_lshrrev_b32_e32 v4, 1, v1
	v_bfe_u32 v1, v1, 1, 3
	s_cmp_lg_u32 s16, 0x18000
	v_bitop3_b32 v7, v3, v1, 2 bitop3:0x36
	v_bitop3_b32 v8, v3, v1, 4 bitop3:0x36
	v_bitop3_b32 v1, v3, v1, 6 bitop3:0x36
	s_cselect_b32 s9, s6, 0
	v_lshlrev_b32_e32 v5, 7, v5
	v_lshlrev_b32_e32 v2, 7, v2
	v_bitop3_b32 v4, v3, v4, 7 bitop3:0x78
	v_lshlrev_b32_e32 v1, 4, v1
	s_add_i32 s6, s9, 0xc000
	v_lshlrev_b32_e32 v4, 4, v4
	v_lshlrev_b32_e32 v7, 4, v7
	v_lshlrev_b32_e32 v8, 4, v8
	v_or_b32_e32 v76, v1, v5
	s_cmp_lg_u32 s9, 0x18000
	v_or_b32_e32 v77, v2, v1
	v_ashrrev_i32_e32 v1, 31, v0
	s_cselect_b32 s20, s6, 0
	v_or_b32_e32 v83, v2, v4
	v_or_b32_e32 v81, v2, v7
	v_or_b32_e32 v79, v2, v8
	v_lshlrev_b64 v[2:3], 11, v[0:1]
	s_add_u32 s6, s14, 0x100
	v_or_b32_e32 v2, v2, v6
	s_addc_u32 s7, s15, 0
	v_or_b32_e32 v82, v4, v5
	v_lshl_add_u64 v[64:65], s[12:13], 0, v[2:3]
	v_add_u32_e32 v4, 64, v0
	v_lshl_add_u64 v[68:69], s[6:7], 0, v[2:3]
	v_add_u32_e32 v2, 0x80, v0
	v_add_u32_e32 v0, 0xc0, v0
	v_ashrrev_i32_e32 v1, 31, v0
	v_or_b32_e32 v80, v7, v5
	v_or_b32_e32 v78, v8, v5
	v_ashrrev_i32_e32 v5, 31, v4
	v_ashrrev_i32_e32 v3, 31, v2
	v_lshlrev_b64 v[0:1], 11, v[0:1]
	v_lshlrev_b64 v[4:5], 11, v[4:5]
	v_lshlrev_b64 v[2:3], 11, v[2:3]
	v_or_b32_e32 v0, v0, v6
	v_or_b32_e32 v4, v4, v6
	v_or_b32_e32 v2, v2, v6
	v_lshl_add_u64 v[74:75], s[6:7], 0, v[0:1]
	v_mov_b32_e32 v0, 0
	v_lshl_add_u64 v[66:67], s[12:13], 0, v[4:5]
	v_lshl_add_u64 v[70:71], s[6:7], 0, v[4:5]
	v_lshl_add_u64 v[72:73], s[6:7], 0, v[2:3]
	s_mov_b64 s[6:7], 0
	s_mov_b32 s18, s16
	v_mov_b32_e32 v1, v0
	v_mov_b32_e32 v2, v0
	v_mov_b32_e32 v3, v0
	v_mov_b32_e32 v4, v0
	v_mov_b32_e32 v5, v0
	v_mov_b32_e32 v6, v0
	v_mov_b32_e32 v7, v0
	v_mov_b32_e32 v8, v0
	v_mov_b32_e32 v9, v0
	v_mov_b32_e32 v10, v0
	v_mov_b32_e32 v11, v0
	v_mov_b32_e32 v12, v0
	v_mov_b32_e32 v13, v0
	v_mov_b32_e32 v14, v0
	v_mov_b32_e32 v15, v0
	v_mov_b32_e32 v32, v0
	v_mov_b32_e32 v33, v0
	v_mov_b32_e32 v34, v0
	v_mov_b32_e32 v35, v0
	v_mov_b32_e32 v36, v0
	v_mov_b32_e32 v37, v0
	v_mov_b32_e32 v38, v0
	v_mov_b32_e32 v39, v0
	v_mov_b32_e32 v40, v0
	v_mov_b32_e32 v41, v0
	v_mov_b32_e32 v42, v0
	v_mov_b32_e32 v43, v0
	v_mov_b32_e32 v44, v0
	v_mov_b32_e32 v45, v0
	v_mov_b32_e32 v46, v0
	v_mov_b32_e32 v47, v0
	v_mov_b32_e32 v16, v0
	v_mov_b32_e32 v17, v0
	v_mov_b32_e32 v18, v0
	v_mov_b32_e32 v19, v0
	v_mov_b32_e32 v20, v0
	v_mov_b32_e32 v21, v0
	v_mov_b32_e32 v22, v0
	v_mov_b32_e32 v23, v0
	v_mov_b32_e32 v24, v0
	v_mov_b32_e32 v25, v0
	v_mov_b32_e32 v26, v0
	v_mov_b32_e32 v27, v0
	v_mov_b32_e32 v28, v0
	v_mov_b32_e32 v29, v0
	v_mov_b32_e32 v30, v0
	v_mov_b32_e32 v31, v0
	v_mov_b32_e32 v48, v0
	v_mov_b32_e32 v49, v0
	v_mov_b32_e32 v50, v0
	v_mov_b32_e32 v51, v0
	v_mov_b32_e32 v52, v0
	v_mov_b32_e32 v53, v0
	v_mov_b32_e32 v54, v0
	v_mov_b32_e32 v55, v0
	v_mov_b32_e32 v56, v0
	v_mov_b32_e32 v57, v0
	v_mov_b32_e32 v58, v0
	v_mov_b32_e32 v59, v0
	v_mov_b32_e32 v60, v0
	v_mov_b32_e32 v61, v0
	v_mov_b32_e32 v62, v0
	v_mov_b32_e32 v63, v0
	s_add_i32 s99, s18, 0
	v_add_u32_e32 v100, s99, v82
	v_add_u32_e32 v101, s99, v83
	ds_read_b128 v[84:87], v101 offset:16384
	ds_read_b128 v[88:91], v100
	ds_read_b128 v[92:95], v100 offset:4096
.LBB0_75:
	s_add_i32 s21, s19, s20
	s_mov_b32 s98, s21
	s_mov_b64 s[100:101], s[6:7]
	s_waitcnt lgkmcnt(0)
	v_add_u32_e32 v100, s99, v80
	s_add_i32 s21, s18, 0xc000
	s_cmp_lg_u32 s18, 0x18000
	s_cselect_b32 s18, s21, 0
	s_add_i32 s21, s20, 0xc000
	s_cmp_lg_u32 s20, 0x18000
	s_cselect_b32 s20, s21, 0
	ds_read_b128 v[236:239], v101 offset:20480
	v_mfma_f32_32x32x16_bf16 v[48:63], v[84:87], v[88:91], v[48:63]
	v_mfma_f32_32x32x16_bf16 v[16:31], v[84:87], v[92:95], v[16:31]
	s_mov_b32 m0, s98
	v_lshl_add_u64 v[254:255], v[64:65], 0, s[100:101]
	global_load_lds_dwordx4 v[254:255], off
	v_add_u32_e32 v101, s99, v81
	s_add_u32 s6, s6, 0x80
	s_addc_u32 s7, s7, 0
	s_waitcnt lgkmcnt(0)
	ds_read_b128 v[84:87], v101 offset:16384
	ds_read_b128 v[240:243], v100
	ds_read_b128 v[244:247], v100 offset:4096
	v_mfma_f32_32x32x16_bf16 v[32:47], v[236:239], v[88:91], v[32:47]
	v_mfma_f32_32x32x16_bf16 v[0:15], v[236:239], v[92:95], v[0:15]
	s_add_i32 m0, s98, 0x2000
	v_lshl_add_u64 v[254:255], v[66:67], 0, s[100:101]
	global_load_lds_dwordx4 v[254:255], off
	v_add_u32_e32 v100, s99, v78
	s_waitcnt lgkmcnt(0)
	ds_read_b128 v[236:239], v101 offset:20480
	v_mfma_f32_32x32x16_bf16 v[48:63], v[84:87], v[240:243], v[48:63]
	v_mfma_f32_32x32x16_bf16 v[16:31], v[84:87], v[244:247], v[16:31]
	s_add_i32 m0, s98, 0x4000
	v_lshl_add_u64 v[254:255], v[68:69], 0, s[100:101]
	global_load_lds_dwordx4 v[254:255], off
	v_add_u32_e32 v101, s99, v79
	s_waitcnt lgkmcnt(0)
	ds_read_b128 v[84:87], v101 offset:16384
	ds_read_b128 v[88:91], v100
	ds_read_b128 v[92:95], v100 offset:4096
	v_mfma_f32_32x32x16_bf16 v[32:47], v[236:239], v[240:243], v[32:47]
	v_mfma_f32_32x32x16_bf16 v[0:15], v[236:239], v[244:247], v[0:15]
	s_add_i32 m0, s98, 0x6000
	v_lshl_add_u64 v[254:255], v[70:71], 0, s[100:101]
	global_load_lds_dwordx4 v[254:255], off
	v_add_u32_e32 v100, s99, v76
	s_waitcnt lgkmcnt(0)
	ds_read_b128 v[236:239], v101 offset:20480
	v_mfma_f32_32x32x16_bf16 v[48:63], v[84:87], v[88:91], v[48:63]
	v_mfma_f32_32x32x16_bf16 v[16:31], v[84:87], v[92:95], v[16:31]
	s_add_i32 m0, s98, 0x8000
	v_lshl_add_u64 v[254:255], v[72:73], 0, s[100:101]
	global_load_lds_dwordx4 v[254:255], off
	v_add_u32_e32 v101, s99, v77
	s_waitcnt lgkmcnt(0)
	ds_read_b128 v[84:87], v101 offset:16384
	ds_read_b128 v[240:243], v100
	ds_read_b128 v[244:247], v100 offset:4096
	v_mfma_f32_32x32x16_bf16 v[32:47], v[236:239], v[88:91], v[32:47]
	v_mfma_f32_32x32x16_bf16 v[0:15], v[236:239], v[92:95], v[0:15]
	s_add_i32 m0, s98, 0xa000
	v_lshl_add_u64 v[254:255], v[74:75], 0, s[100:101]
	global_load_lds_dwordx4 v[254:255], off
	s_waitcnt lgkmcnt(0)
	ds_read_b128 v[236:239], v101 offset:20480
	v_mfma_f32_32x32x16_bf16 v[48:63], v[84:87], v[240:243], v[48:63]
	v_mfma_f32_32x32x16_bf16 v[16:31], v[84:87], v[244:247], v[16:31]
	s_waitcnt vmcnt(6) lgkmcnt(0)
	s_barrier
; DEV int stage_next(int s) { return (s == 2 * GS_STAGE) ? 0 : s + GS_STAGE; }
; template <int WAIT0>
; DEV void gk_main(f32x16 (&acc)[2][2], const GTile& t, int s0) {
;     ...
;   for (int kt = 0; kt < nk - 2; ++kt) {
;     GK_DMA(std_, kt + 2);
;     GK_COMPUTE(stc);
;     vm_wait_bar<6>();
;     stc = stage_next(stc); std_ = stage_next(std_);
;   }
;   GK_COMPUTE(stc);
;   vm_wait_bar<0>();
;   stc = stage_next(stc);
;   GK_COMPUTE(stc);
;   vm_wait_bar<0>();
	s_waitcnt lgkmcnt(0)
	s_add_i32 s99, s18, 0
	v_add_u32_e32 v100, s99, v82
	v_add_u32_e32 v101, s99, v83
	ds_read_b128 v[84:87], v101 offset:16384
	ds_read_b128 v[88:91], v100
	ds_read_b128 v[92:95], v100 offset:4096
	v_mfma_f32_32x32x16_bf16 v[32:47], v[236:239], v[240:243], v[32:47]
	v_mfma_f32_32x32x16_bf16 v[0:15], v[236:239], v[244:247], v[0:15]
	s_cmpk_lg_i32 s6, 0x700
	s_cbranch_scc1 .LBB0_75
	s_waitcnt lgkmcnt(0)
	s_add_i32 s6, s18, 0
	v_add_u32_e32 v84, s6, v83
	ds_read_b128 v[64:67], v84 offset:16384
	v_add_u32_e32 v72, s6, v82
	ds_read_b128 v[68:71], v72
	ds_read_b128 v[72:75], v72 offset:4096
	s_waitcnt lgkmcnt(0)
	v_mfma_f32_32x32x16_bf16 v[48:63], v[64:67], v[68:71], v[48:63]
	v_mfma_f32_32x32x16_bf16 v[16:31], v[64:67], v[72:75], v[16:31]
	ds_read_b128 v[64:67], v84 offset:20480
	v_add_u32_e32 v84, s6, v81
	s_waitcnt lgkmcnt(0)
	v_mfma_f32_32x32x16_bf16 v[32:47], v[64:67], v[68:71], v[32:47]
	v_mfma_f32_32x32x16_bf16 v[0:15], v[64:67], v[72:75], v[0:15]
	ds_read_b128 v[64:67], v84 offset:16384
	v_add_u32_e32 v72, s6, v80
	ds_read_b128 v[68:71], v72
	ds_read_b128 v[72:75], v72 offset:4096
	s_waitcnt lgkmcnt(0)
	v_mfma_f32_32x32x16_bf16 v[48:63], v[64:67], v[68:71], v[48:63]
	v_mfma_f32_32x32x16_bf16 v[16:31], v[64:67], v[72:75], v[16:31]
	ds_read_b128 v[64:67], v84 offset:20480
	v_add_u32_e32 v84, s6, v79
	s_waitcnt lgkmcnt(0)
	v_mfma_f32_32x32x16_bf16 v[32:47], v[64:67], v[68:71], v[32:47]
	v_mfma_f32_32x32x16_bf16 v[0:15], v[64:67], v[72:75], v[0:15]
	ds_read_b128 v[64:67], v84 offset:16384
	v_add_u32_e32 v72, s6, v78
	ds_read_b128 v[68:71], v72
	ds_read_b128 v[72:75], v72 offset:4096
	s_waitcnt lgkmcnt(0)
	v_mfma_f32_32x32x16_bf16 v[48:63], v[64:67], v[68:71], v[48:63]
	v_mfma_f32_32x32x16_bf16 v[16:31], v[64:67], v[72:75], v[16:31]
	ds_read_b128 v[64:67], v84 offset:20480
	v_add_u32_e32 v84, s6, v77
	s_waitcnt lgkmcnt(0)
	v_mfma_f32_32x32x16_bf16 v[32:47], v[64:67], v[68:71], v[32:47]
	v_mfma_f32_32x32x16_bf16 v[0:15], v[64:67], v[72:75], v[0:15]
	ds_read_b128 v[64:67], v84 offset:16384
	v_add_u32_e32 v72, s6, v76
	ds_read_b128 v[68:71], v72
	ds_read_b128 v[72:75], v72 offset:4096
	s_add_i32 s6, s18, 0xc000
	s_cmp_lg_u32 s18, 0x18000
	s_cselect_b32 s6, s6, 0
	s_waitcnt lgkmcnt(0)
	v_mfma_f32_32x32x16_bf16 v[48:63], v[64:67], v[68:71], v[48:63]
	s_add_i32 s6, s6, 0
	v_add_u32_e32 v83, s6, v83
	v_add_u32_e32 v81, s6, v81
	v_add_u32_e32 v79, s6, v79
	v_add_u32_e32 v77, s6, v77
	v_mfma_f32_32x32x16_bf16 v[16:31], v[64:67], v[72:75], v[16:31]
	ds_read_b128 v[64:67], v84 offset:20480
	s_waitcnt vmcnt(0) lgkmcnt(0)
	s_barrier
	s_waitcnt lgkmcnt(0)
	v_mfma_f32_32x32x16_bf16 v[32:47], v[64:67], v[68:71], v[32:47]
	v_mfma_f32_32x32x16_bf16 v[0:15], v[64:67], v[72:75], v[0:15]
	ds_read_b128 v[64:67], v83 offset:16384
	v_add_u32_e32 v72, s6, v82
	ds_read_b128 v[68:71], v72
	ds_read_b128 v[72:75], v72 offset:4096
	s_waitcnt lgkmcnt(0)
	v_mfma_f32_32x32x16_bf16 v[48:63], v[64:67], v[68:71], v[48:63]
	v_mfma_f32_32x32x16_bf16 v[16:31], v[64:67], v[72:75], v[16:31]
	ds_read_b128 v[64:67], v83 offset:20480
	s_waitcnt lgkmcnt(0)
	v_mfma_f32_32x32x16_bf16 v[32:47], v[64:67], v[68:71], v[32:47]
	v_mfma_f32_32x32x16_bf16 v[0:15], v[64:67], v[72:75], v[0:15]
	ds_read_b128 v[64:67], v81 offset:16384
	v_add_u32_e32 v72, s6, v80
	ds_read_b128 v[68:71], v72
	ds_read_b128 v[72:75], v72 offset:4096
	s_waitcnt lgkmcnt(0)
	v_mfma_f32_32x32x16_bf16 v[48:63], v[64:67], v[68:71], v[48:63]
	v_mfma_f32_32x32x16_bf16 v[16:31], v[64:67], v[72:75], v[16:31]
	ds_read_b128 v[64:67], v81 offset:20480
	s_waitcnt lgkmcnt(0)
	v_mfma_f32_32x32x16_bf16 v[32:47], v[64:67], v[68:71], v[32:47]
	v_mfma_f32_32x32x16_bf16 v[0:15], v[64:67], v[72:75], v[0:15]
	ds_read_b128 v[64:67], v79 offset:16384
	v_add_u32_e32 v72, s6, v78
	ds_read_b128 v[68:71], v72
	ds_read_b128 v[72:75], v72 offset:4096
	s_waitcnt lgkmcnt(0)
	v_mfma_f32_32x32x16_bf16 v[48:63], v[64:67], v[68:71], v[48:63]
	v_mfma_f32_32x32x16_bf16 v[16:31], v[64:67], v[72:75], v[16:31]
	ds_read_b128 v[64:67], v79 offset:20480
	s_waitcnt lgkmcnt(0)
	v_mfma_f32_32x32x16_bf16 v[32:47], v[64:67], v[68:71], v[32:47]
	v_mfma_f32_32x32x16_bf16 v[0:15], v[64:67], v[72:75], v[0:15]
	ds_read_b128 v[64:67], v77 offset:16384
	v_add_u32_e32 v72, s6, v76
	ds_read_b128 v[68:71], v72
	ds_read_b128 v[72:75], v72 offset:4096
	s_mov_b64 s[6:7], 0
	s_waitcnt lgkmcnt(0)
	v_mfma_f32_32x32x16_bf16 v[48:63], v[64:67], v[68:71], v[48:63]
	v_mfma_f32_32x32x16_bf16 v[16:31], v[64:67], v[72:75], v[16:31]
	ds_read_b128 v[64:67], v77 offset:20480
	s_waitcnt vmcnt(0) lgkmcnt(0)
	s_barrier
	s_waitcnt lgkmcnt(0)
	v_mfma_f32_32x32x16_bf16 v[32:47], v[64:67], v[68:71], v[32:47]
	v_mfma_f32_32x32x16_bf16 v[0:15], v[64:67], v[72:75], v[0:15]
; DEV int tid_l() { int t = threadIdx.x; asm volatile("" : "+v"(t)); return t; }
; DEV int stage_next(int s) { return (s == 2 * GS_STAGE) ? 0 : s + GS_STAGE; }
; template <int WAIT0>
; DEV void gk_main(f32x16 (&acc)[2][2], const GTile& t, int s0) {
;   const int tid = tid_l(), lane = tid & 63, wid = __builtin_amdgcn_readfirstlane(tid >> 6), wm = wid & 1, wn = wid >> 1, l32 = lane & 31, hi = lane >> 5;
;   GK_SRC(t)
;   const int sw = (l32 >> 1) & 7;
;   int xk[4], wk[4];
; #pragma unroll
;   for (int ks = 0; ks < 4; ++ks) { const int ko = ((2 * ks + hi) ^ sw) << 4; xk[ks] = GS_A + (64 * wm + l32) * 128 + ko; wk[ks] = GS_B + (64 * wn + l32) * 128 + ko; }
;   const int nk = t.K >> 6;
;     ...
;   vm_wait_bar<WAIT0>();
;   int stc = s0, std_ = stage_next(stage_next(s0));
; #pragma nounroll
;   for (int kt = 0; kt < nk - 2; ++kt) {
;     GK_DMA(std_, kt + 2);
;     GK_COMPUTE(stc);
;     vm_wait_bar<6>();
;     stc = stage_next(stc); std_ = stage_next(std_);
;   }
.LBB0_77:
	s_and_b64 vcc, exec, s[6:7]
	s_cbranch_vccz .LBB0_81
	s_nop 9
	v_mov_b32_e32 v1, v176
	s_waitcnt vmcnt(14) lgkmcnt(0)
	s_barrier
	v_readfirstlane_b32 s6, v1
	s_ashr_i32 s7, s6, 6
	v_and_b32_e32 v2, 31, v1
	v_bfe_u32 v0, v1, 3, 3
	v_lshl_or_b32 v0, s7, 3, v0
	v_and_or_b32 v5, s6, 64, v2
	s_lshr_b32 s6, s6, 1
	v_lshrrev_b32_e32 v3, 1, v0
	s_and_b32 s6, s6, 0x1ffffc0
	v_xor_b32_e32 v3, v3, v1
	v_or_b32_e32 v2, s6, v2
	s_lshl_b32 s6, s7, 10
	v_lshlrev_b32_e32 v3, 4, v3
	s_add_i32 s19, s6, 0
	s_add_i32 s6, s16, 0xc000
	v_and_b32_e32 v6, 0x70, v3
	v_bfe_u32 v3, v1, 5, 1
	v_lshrrev_b32_e32 v4, 1, v1
	v_bfe_u32 v1, v1, 1, 3
	s_cmp_lg_u32 s16, 0x18000
	v_bitop3_b32 v7, v3, v1, 2 bitop3:0x36
	v_bitop3_b32 v8, v3, v1, 4 bitop3:0x36
	v_bitop3_b32 v1, v3, v1, 6 bitop3:0x36
	s_cselect_b32 s9, s6, 0
	v_lshlrev_b32_e32 v5, 7, v5
	v_lshlrev_b32_e32 v2, 7, v2
	v_bitop3_b32 v4, v3, v4, 7 bitop3:0x78
	v_lshlrev_b32_e32 v1, 4, v1
	s_add_i32 s6, s9, 0xc000
	v_lshlrev_b32_e32 v4, 4, v4
	v_lshlrev_b32_e32 v7, 4, v7
	v_lshlrev_b32_e32 v8, 4, v8
	v_or_b32_e32 v76, v1, v5
	s_cmp_lg_u32 s9, 0x18000
	v_or_b32_e32 v77, v2, v1
	v_ashrrev_i32_e32 v1, 31, v0
	s_cselect_b32 s20, s6, 0
	v_or_b32_e32 v83, v2, v4
	v_or_b32_e32 v81, v2, v7
	v_or_b32_e32 v79, v2, v8
	v_lshlrev_b64 v[2:3], 11, v[0:1]
	s_add_u32 s6, s14, 0x100
	v_or_b32_e32 v2, v2, v6
	s_addc_u32 s7, s15, 0
	v_or_b32_e32 v82, v4, v5
	v_lshl_add_u64 v[64:65], s[12:13], 0, v[2:3]
	v_add_u32_e32 v4, 64, v0
	v_lshl_add_u64 v[68:69], s[6:7], 0, v[2:3]
	v_add_u32_e32 v2, 0x80, v0
	v_add_u32_e32 v0, 0xc0, v0
	v_ashrrev_i32_e32 v1, 31, v0
	v_or_b32_e32 v80, v7, v5
	v_or_b32_e32 v78, v8, v5
	v_ashrrev_i32_e32 v5, 31, v4
	v_ashrrev_i32_e32 v3, 31, v2
	v_lshlrev_b64 v[0:1], 11, v[0:1]
	v_lshlrev_b64 v[4:5], 11, v[4:5]
	v_lshlrev_b64 v[2:3], 11, v[2:3]
	v_or_b32_e32 v0, v0, v6
	v_or_b32_e32 v4, v4, v6
	v_or_b32_e32 v2, v2, v6
	v_lshl_add_u64 v[74:75], s[6:7], 0, v[0:1]
	v_mov_b32_e32 v0, 0
	v_lshl_add_u64 v[66:67], s[12:13], 0, v[4:5]
	v_lshl_add_u64 v[70:71], s[6:7], 0, v[4:5]
	v_lshl_add_u64 v[72:73], s[6:7], 0, v[2:3]
	s_mov_b64 s[6:7], 0
	s_mov_b32 s18, s16
	v_mov_b32_e32 v1, v0
	v_mov_b32_e32 v2, v0
	v_mov_b32_e32 v3, v0
	v_mov_b32_e32 v4, v0
	v_mov_b32_e32 v5, v0
	v_mov_b32_e32 v6, v0
	v_mov_b32_e32 v7, v0
	v_mov_b32_e32 v8, v0
	v_mov_b32_e32 v9, v0
	v_mov_b32_e32 v10, v0
	v_mov_b32_e32 v11, v0
	v_mov_b32_e32 v12, v0
	v_mov_b32_e32 v13, v0
	v_mov_b32_e32 v14, v0
	v_mov_b32_e32 v15, v0
	v_mov_b32_e32 v32, v0
	v_mov_b32_e32 v33, v0
	v_mov_b32_e32 v34, v0
	v_mov_b32_e32 v35, v0
	v_mov_b32_e32 v36, v0
	v_mov_b32_e32 v37, v0
	v_mov_b32_e32 v38, v0
	v_mov_b32_e32 v39, v0
	v_mov_b32_e32 v40, v0
	v_mov_b32_e32 v41, v0
	v_mov_b32_e32 v42, v0
	v_mov_b32_e32 v43, v0
	v_mov_b32_e32 v44, v0
	v_mov_b32_e32 v45, v0
	v_mov_b32_e32 v46, v0
	v_mov_b32_e32 v47, v0
	v_mov_b32_e32 v16, v0
	v_mov_b32_e32 v17, v0
	v_mov_b32_e32 v18, v0
	v_mov_b32_e32 v19, v0
	v_mov_b32_e32 v20, v0
	v_mov_b32_e32 v21, v0
	v_mov_b32_e32 v22, v0
	v_mov_b32_e32 v23, v0
	v_mov_b32_e32 v24, v0
	v_mov_b32_e32 v25, v0
	v_mov_b32_e32 v26, v0
	v_mov_b32_e32 v27, v0
	v_mov_b32_e32 v28, v0
	v_mov_b32_e32 v29, v0
	v_mov_b32_e32 v30, v0
	v_mov_b32_e32 v31, v0
	v_mov_b32_e32 v48, v0
	v_mov_b32_e32 v49, v0
	v_mov_b32_e32 v50, v0
	v_mov_b32_e32 v51, v0
	v_mov_b32_e32 v52, v0
	v_mov_b32_e32 v53, v0
	v_mov_b32_e32 v54, v0
	v_mov_b32_e32 v55, v0
	v_mov_b32_e32 v56, v0
	v_mov_b32_e32 v57, v0
	v_mov_b32_e32 v58, v0
	v_mov_b32_e32 v59, v0
	v_mov_b32_e32 v60, v0
	v_mov_b32_e32 v61, v0
	v_mov_b32_e32 v62, v0
	v_mov_b32_e32 v63, v0
	s_add_i32 s99, s18, 0
	v_add_u32_e32 v100, s99, v82
	v_add_u32_e32 v101, s99, v83
	ds_read_b128 v[84:87], v101 offset:16384
	ds_read_b128 v[88:91], v100
	ds_read_b128 v[92:95], v100 offset:4096
.LBB0_79:
	s_add_i32 s21, s19, s20
	s_mov_b32 s98, s21
	s_mov_b64 s[100:101], s[6:7]
	s_waitcnt lgkmcnt(0)
	v_add_u32_e32 v100, s99, v80
	s_add_i32 s21, s18, 0xc000
	s_cmp_lg_u32 s18, 0x18000
	s_cselect_b32 s18, s21, 0
	s_add_i32 s21, s20, 0xc000
	s_cmp_lg_u32 s20, 0x18000
	s_cselect_b32 s20, s21, 0
	ds_read_b128 v[236:239], v101 offset:20480
	v_mfma_f32_32x32x16_bf16 v[48:63], v[84:87], v[88:91], v[48:63]
	v_mfma_f32_32x32x16_bf16 v[16:31], v[84:87], v[92:95], v[16:31]
	s_mov_b32 m0, s98
	v_lshl_add_u64 v[254:255], v[64:65], 0, s[100:101]
	global_load_lds_dwordx4 v[254:255], off
	v_add_u32_e32 v101, s99, v81
	s_add_u32 s6, s6, 0x80
	s_addc_u32 s7, s7, 0
	s_waitcnt lgkmcnt(0)
	ds_read_b128 v[84:87], v101 offset:16384
	ds_read_b128 v[240:243], v100
	ds_read_b128 v[244:247], v100 offset:4096
	v_mfma_f32_32x32x16_bf16 v[32:47], v[236:239], v[88:91], v[32:47]
	v_mfma_f32_32x32x16_bf16 v[0:15], v[236:239], v[92:95], v[0:15]
	s_add_i32 m0, s98, 0x2000
	v_lshl_add_u64 v[254:255], v[66:67], 0, s[100:101]
	global_load_lds_dwordx4 v[254:255], off
	v_add_u32_e32 v100, s99, v78
	s_waitcnt lgkmcnt(0)
	ds_read_b128 v[236:239], v101 offset:20480
	v_mfma_f32_32x32x16_bf16 v[48:63], v[84:87], v[240:243], v[48:63]
	v_mfma_f32_32x32x16_bf16 v[16:31], v[84:87], v[244:247], v[16:31]
	s_add_i32 m0, s98, 0x4000
	v_lshl_add_u64 v[254:255], v[68:69], 0, s[100:101]
	global_load_lds_dwordx4 v[254:255], off
	v_add_u32_e32 v101, s99, v79
	s_waitcnt lgkmcnt(0)
	ds_read_b128 v[84:87], v101 offset:16384
	ds_read_b128 v[88:91], v100
	ds_read_b128 v[92:95], v100 offset:4096
	v_mfma_f32_32x32x16_bf16 v[32:47], v[236:239], v[240:243], v[32:47]
	v_mfma_f32_32x32x16_bf16 v[0:15], v[236:239], v[244:247], v[0:15]
	s_add_i32 m0, s98, 0x6000
	v_lshl_add_u64 v[254:255], v[70:71], 0, s[100:101]
	global_load_lds_dwordx4 v[254:255], off
	v_add_u32_e32 v100, s99, v76
	s_waitcnt lgkmcnt(0)
	ds_read_b128 v[236:239], v101 offset:20480
	v_mfma_f32_32x32x16_bf16 v[48:63], v[84:87], v[88:91], v[48:63]
	v_mfma_f32_32x32x16_bf16 v[16:31], v[84:87], v[92:95], v[16:31]
	s_add_i32 m0, s98, 0x8000
	v_lshl_add_u64 v[254:255], v[72:73], 0, s[100:101]
	global_load_lds_dwordx4 v[254:255], off
	v_add_u32_e32 v101, s99, v77
	s_waitcnt lgkmcnt(0)
	ds_read_b128 v[84:87], v101 offset:16384
	ds_read_b128 v[240:243], v100
	ds_read_b128 v[244:247], v100 offset:4096
	v_mfma_f32_32x32x16_bf16 v[32:47], v[236:239], v[88:91], v[32:47]
	v_mfma_f32_32x32x16_bf16 v[0:15], v[236:239], v[92:95], v[0:15]
	s_add_i32 m0, s98, 0xa000
	v_lshl_add_u64 v[254:255], v[74:75], 0, s[100:101]
	global_load_lds_dwordx4 v[254:255], off
	s_waitcnt lgkmcnt(0)
	ds_read_b128 v[236:239], v101 offset:20480
	v_mfma_f32_32x32x16_bf16 v[48:63], v[84:87], v[240:243], v[48:63]
	v_mfma_f32_32x32x16_bf16 v[16:31], v[84:87], v[244:247], v[16:31]
	s_waitcnt vmcnt(6) lgkmcnt(0)
	s_barrier
; DEV int stage_next(int s) { return (s == 2 * GS_STAGE) ? 0 : s + GS_STAGE; }
; template <int WAIT0>
; DEV void gk_main(f32x16 (&acc)[2][2], const GTile& t, int s0) {
;     ...
;   for (int kt = 0; kt < nk - 2; ++kt) {
;     GK_DMA(std_, kt + 2);
;     GK_COMPUTE(stc);
;     vm_wait_bar<6>();
;     stc = stage_next(stc); std_ = stage_next(std_);
;   }
;   GK_COMPUTE(stc);
;   vm_wait_bar<0>();
;   stc = stage_next(stc);
;   GK_COMPUTE(stc);
;   vm_wait_bar<0>();
	s_waitcnt lgkmcnt(0)
	s_add_i32 s99, s18, 0
	v_add_u32_e32 v100, s99, v82
	v_add_u32_e32 v101, s99, v83
	ds_read_b128 v[84:87], v101 offset:16384
	ds_read_b128 v[88:91], v100
	ds_read_b128 v[92:95], v100 offset:4096
	v_mfma_f32_32x32x16_bf16 v[32:47], v[236:239], v[240:243], v[32:47]
	v_mfma_f32_32x32x16_bf16 v[0:15], v[236:239], v[244:247], v[0:15]
	s_cmpk_lg_i32 s6, 0x700
	s_cbranch_scc1 .LBB0_79
	s_waitcnt lgkmcnt(0)
	s_add_i32 s6, s18, 0
	v_add_u32_e32 v84, s6, v83
	ds_read_b128 v[64:67], v84 offset:16384
	v_add_u32_e32 v72, s6, v82
	ds_read_b128 v[68:71], v72
	ds_read_b128 v[72:75], v72 offset:4096
	s_waitcnt lgkmcnt(0)
	v_mfma_f32_32x32x16_bf16 v[48:63], v[64:67], v[68:71], v[48:63]
	v_mfma_f32_32x32x16_bf16 v[16:31], v[64:67], v[72:75], v[16:31]
	ds_read_b128 v[64:67], v84 offset:20480
	v_add_u32_e32 v84, s6, v81
	s_waitcnt lgkmcnt(0)
	v_mfma_f32_32x32x16_bf16 v[32:47], v[64:67], v[68:71], v[32:47]
	v_mfma_f32_32x32x16_bf16 v[0:15], v[64:67], v[72:75], v[0:15]
	ds_read_b128 v[64:67], v84 offset:16384
	v_add_u32_e32 v72, s6, v80
	ds_read_b128 v[68:71], v72
	ds_read_b128 v[72:75], v72 offset:4096
	s_waitcnt lgkmcnt(0)
	v_mfma_f32_32x32x16_bf16 v[48:63], v[64:67], v[68:71], v[48:63]
	v_mfma_f32_32x32x16_bf16 v[16:31], v[64:67], v[72:75], v[16:31]
	ds_read_b128 v[64:67], v84 offset:20480
	v_add_u32_e32 v84, s6, v79
	s_waitcnt lgkmcnt(0)
	v_mfma_f32_32x32x16_bf16 v[32:47], v[64:67], v[68:71], v[32:47]
	v_mfma_f32_32x32x16_bf16 v[0:15], v[64:67], v[72:75], v[0:15]
	ds_read_b128 v[64:67], v84 offset:16384
	v_add_u32_e32 v72, s6, v78
	ds_read_b128 v[68:71], v72
	ds_read_b128 v[72:75], v72 offset:4096
	s_waitcnt lgkmcnt(0)
	v_mfma_f32_32x32x16_bf16 v[48:63], v[64:67], v[68:71], v[48:63]
	v_mfma_f32_32x32x16_bf16 v[16:31], v[64:67], v[72:75], v[16:31]
	ds_read_b128 v[64:67], v84 offset:20480
	v_add_u32_e32 v84, s6, v77
	s_waitcnt lgkmcnt(0)
	v_mfma_f32_32x32x16_bf16 v[32:47], v[64:67], v[68:71], v[32:47]
	v_mfma_f32_32x32x16_bf16 v[0:15], v[64:67], v[72:75], v[0:15]
	ds_read_b128 v[64:67], v84 offset:16384
	v_add_u32_e32 v72, s6, v76
	ds_read_b128 v[68:71], v72
	ds_read_b128 v[72:75], v72 offset:4096
	s_add_i32 s6, s18, 0xc000
	s_cmp_lg_u32 s18, 0x18000
	s_cselect_b32 s6, s6, 0
	s_waitcnt lgkmcnt(0)
	v_mfma_f32_32x32x16_bf16 v[48:63], v[64:67], v[68:71], v[48:63]
	s_add_i32 s6, s6, 0
	v_add_u32_e32 v83, s6, v83
	v_add_u32_e32 v81, s6, v81
	v_add_u32_e32 v79, s6, v79
	v_add_u32_e32 v77, s6, v77
	v_mfma_f32_32x32x16_bf16 v[16:31], v[64:67], v[72:75], v[16:31]
	ds_read_b128 v[64:67], v84 offset:20480
	s_waitcnt vmcnt(0) lgkmcnt(0)
	s_barrier
	s_waitcnt lgkmcnt(0)
	v_mfma_f32_32x32x16_bf16 v[32:47], v[64:67], v[68:71], v[32:47]
	v_mfma_f32_32x32x16_bf16 v[0:15], v[64:67], v[72:75], v[0:15]
	ds_read_b128 v[64:67], v83 offset:16384
	v_add_u32_e32 v72, s6, v82
	ds_read_b128 v[68:71], v72
	ds_read_b128 v[72:75], v72 offset:4096
	s_waitcnt lgkmcnt(0)
	v_mfma_f32_32x32x16_bf16 v[48:63], v[64:67], v[68:71], v[48:63]
	v_mfma_f32_32x32x16_bf16 v[16:31], v[64:67], v[72:75], v[16:31]
	ds_read_b128 v[64:67], v83 offset:20480
	s_waitcnt lgkmcnt(0)
	v_mfma_f32_32x32x16_bf16 v[32:47], v[64:67], v[68:71], v[32:47]
	v_mfma_f32_32x32x16_bf16 v[0:15], v[64:67], v[72:75], v[0:15]
	ds_read_b128 v[64:67], v81 offset:16384
	v_add_u32_e32 v72, s6, v80
	ds_read_b128 v[68:71], v72
	ds_read_b128 v[72:75], v72 offset:4096
	s_waitcnt lgkmcnt(0)
	v_mfma_f32_32x32x16_bf16 v[48:63], v[64:67], v[68:71], v[48:63]
	v_mfma_f32_32x32x16_bf16 v[16:31], v[64:67], v[72:75], v[16:31]
	ds_read_b128 v[64:67], v81 offset:20480
	s_waitcnt lgkmcnt(0)
	v_mfma_f32_32x32x16_bf16 v[32:47], v[64:67], v[68:71], v[32:47]
	v_mfma_f32_32x32x16_bf16 v[0:15], v[64:67], v[72:75], v[0:15]
	ds_read_b128 v[64:67], v79 offset:16384
	v_add_u32_e32 v72, s6, v78
	ds_read_b128 v[68:71], v72
	ds_read_b128 v[72:75], v72 offset:4096
	s_waitcnt lgkmcnt(0)
	v_mfma_f32_32x32x16_bf16 v[48:63], v[64:67], v[68:71], v[48:63]
	v_mfma_f32_32x32x16_bf16 v[16:31], v[64:67], v[72:75], v[16:31]
	ds_read_b128 v[64:67], v79 offset:20480
	s_waitcnt lgkmcnt(0)
	v_mfma_f32_32x32x16_bf16 v[32:47], v[64:67], v[68:71], v[32:47]
	v_mfma_f32_32x32x16_bf16 v[0:15], v[64:67], v[72:75], v[0:15]
	ds_read_b128 v[64:67], v77 offset:16384
	v_add_u32_e32 v72, s6, v76
	ds_read_b128 v[68:71], v72
	ds_read_b128 v[72:75], v72 offset:4096
	s_waitcnt lgkmcnt(0)
	v_mfma_f32_32x32x16_bf16 v[48:63], v[64:67], v[68:71], v[48:63]
	v_mfma_f32_32x32x16_bf16 v[16:31], v[64:67], v[72:75], v[16:31]
	ds_read_b128 v[64:67], v77 offset:20480
	s_waitcnt vmcnt(0) lgkmcnt(0)
	s_barrier
	s_waitcnt lgkmcnt(0)
	v_mfma_f32_32x32x16_bf16 v[32:47], v[64:67], v[68:71], v[32:47]
	v_mfma_f32_32x32x16_bf16 v[0:15], v[64:67], v[72:75], v[0:15]

; DEV int tid_l() { int t = threadIdx.x; asm volatile("" : "+v"(t)); return t; }
; DEV int stage_next(int s) { return (s == 2 * GS_STAGE) ? 0 : s + GS_STAGE; }
; template <int WAIT0>
; DEV void gk_main(f32x16 (&acc)[2][2], const GTile& t, int s0) {
;   const int tid = tid_l(), lane = tid & 63, wid = __builtin_amdgcn_readfirstlane(tid >> 6), wm = wid & 1, wn = wid >> 1, l32 = lane & 31, hi = lane >> 5;
;   GK_SRC(t)
;   const int sw = (l32 >> 1) & 7;
;   int xk[4], wk[4];
; #pragma unroll
;   for (int ks = 0; ks < 4; ++ks) { const int ko = ((2 * ks + hi) ^ sw) << 4; xk[ks] = GS_A + (64 * wm + l32) * 128 + ko; wk[ks] = GS_B + (64 * wn + l32) * 128 + ko; }
;   const int nk = t.K >> 6;
;     ...
;   vm_wait_bar<WAIT0>();
;   int stc = s0, std_ = stage_next(stage_next(s0));
; #pragma nounroll
;   for (int kt = 0; kt < nk - 2; ++kt) {
;     GK_DMA(std_, kt + 2);
;     GK_COMPUTE(stc);
;     vm_wait_bar<6>();
;     stc = stage_next(stc); std_ = stage_next(std_);
;   }
.LBB0_85:
.LBB0_86:
	s_nop 5
	v_mov_b32_e32 v1, v176
	s_waitcnt vmcnt(6) lgkmcnt(0)
	s_barrier
	s_nop 2
	v_readfirstlane_b32 s6, v1
	s_ashr_i32 s7, s6, 6
	v_and_b32_e32 v2, 31, v1
	v_bfe_u32 v0, v1, 3, 3
	v_lshl_or_b32 v0, s7, 3, v0
	v_and_or_b32 v5, s6, 64, v2
	s_lshr_b32 s6, s6, 1
	v_lshrrev_b32_e32 v3, 1, v0
	s_and_b32 s6, s6, 0x1ffffc0
	v_xor_b32_e32 v3, v3, v1
	v_or_b32_e32 v2, s6, v2
	s_lshl_b32 s6, s7, 10
	v_lshlrev_b32_e32 v3, 4, v3
	s_add_i32 s19, s6, 0
	s_add_i32 s6, s16, 0xc000
	v_and_b32_e32 v6, 0x70, v3
	v_bfe_u32 v3, v1, 5, 1
	v_lshrrev_b32_e32 v4, 1, v1
	v_bfe_u32 v1, v1, 1, 3
	s_cmp_lg_u32 s16, 0x18000
	v_bitop3_b32 v7, v3, v1, 2 bitop3:0x36
	v_bitop3_b32 v8, v3, v1, 4 bitop3:0x36
	v_bitop3_b32 v1, v3, v1, 6 bitop3:0x36
	s_cselect_b32 s9, s6, 0
	v_lshlrev_b32_e32 v5, 7, v5
	v_lshlrev_b32_e32 v2, 7, v2
	v_bitop3_b32 v4, v3, v4, 7 bitop3:0x78
	v_lshlrev_b32_e32 v1, 4, v1
	s_add_i32 s6, s9, 0xc000
	v_lshlrev_b32_e32 v4, 4, v4
	v_lshlrev_b32_e32 v7, 4, v7
	v_lshlrev_b32_e32 v8, 4, v8
	v_or_b32_e32 v76, v1, v5
	s_cmp_lg_u32 s9, 0x18000
	v_or_b32_e32 v77, v2, v1
	v_ashrrev_i32_e32 v1, 31, v0
	s_cselect_b32 s20, s6, 0
	v_or_b32_e32 v83, v2, v4
	v_or_b32_e32 v81, v2, v7
	v_or_b32_e32 v79, v2, v8
	v_lshlrev_b64 v[2:3], 11, v[0:1]
	s_add_u32 s6, s14, 0x100
	v_or_b32_e32 v2, v2, v6
	s_addc_u32 s7, s15, 0
	v_or_b32_e32 v82, v4, v5
	v_lshl_add_u64 v[64:65], s[12:13], 0, v[2:3]
	v_add_u32_e32 v4, 64, v0
	v_lshl_add_u64 v[68:69], s[6:7], 0, v[2:3]
	v_add_u32_e32 v2, 0x80, v0
	v_add_u32_e32 v0, 0xc0, v0
	v_ashrrev_i32_e32 v1, 31, v0
	v_or_b32_e32 v80, v7, v5
	v_or_b32_e32 v78, v8, v5
	v_ashrrev_i32_e32 v5, 31, v4
	v_ashrrev_i32_e32 v3, 31, v2
	v_lshlrev_b64 v[0:1], 11, v[0:1]
	v_lshlrev_b64 v[4:5], 11, v[4:5]
	v_lshlrev_b64 v[2:3], 11, v[2:3]
	v_or_b32_e32 v0, v0, v6
	v_or_b32_e32 v4, v4, v6
	v_or_b32_e32 v2, v2, v6
	v_lshl_add_u64 v[74:75], s[6:7], 0, v[0:1]
	v_mov_b32_e32 v0, 0
	v_lshl_add_u64 v[66:67], s[12:13], 0, v[4:5]
	v_lshl_add_u64 v[70:71], s[6:7], 0, v[4:5]
	v_lshl_add_u64 v[72:73], s[6:7], 0, v[2:3]
	s_mov_b64 s[6:7], 0
	s_mov_b32 s18, s16
	v_mov_b32_e32 v1, v0
	v_mov_b32_e32 v2, v0
	v_mov_b32_e32 v3, v0
	v_mov_b32_e32 v4, v0
	v_mov_b32_e32 v5, v0
	v_mov_b32_e32 v6, v0
	v_mov_b32_e32 v7, v0
	v_mov_b32_e32 v8, v0
	v_mov_b32_e32 v9, v0
	v_mov_b32_e32 v10, v0
	v_mov_b32_e32 v11, v0
	v_mov_b32_e32 v12, v0
	v_mov_b32_e32 v13, v0
	v_mov_b32_e32 v14, v0
	v_mov_b32_e32 v15, v0
	v_mov_b32_e32 v32, v0
	v_mov_b32_e32 v33, v0
	v_mov_b32_e32 v34, v0
	v_mov_b32_e32 v35, v0
	v_mov_b32_e32 v36, v0
	v_mov_b32_e32 v37, v0
	v_mov_b32_e32 v38, v0
	v_mov_b32_e32 v39, v0
	v_mov_b32_e32 v40, v0
	v_mov_b32_e32 v41, v0
	v_mov_b32_e32 v42, v0
	v_mov_b32_e32 v43, v0
	v_mov_b32_e32 v44, v0
	v_mov_b32_e32 v45, v0
	v_mov_b32_e32 v46, v0
	v_mov_b32_e32 v47, v0
	v_mov_b32_e32 v16, v0
	v_mov_b32_e32 v17, v0
	v_mov_b32_e32 v18, v0
	v_mov_b32_e32 v19, v0
	v_mov_b32_e32 v20, v0
	v_mov_b32_e32 v21, v0
	v_mov_b32_e32 v22, v0
	v_mov_b32_e32 v23, v0
	v_mov_b32_e32 v24, v0
	v_mov_b32_e32 v25, v0
	v_mov_b32_e32 v26, v0
	v_mov_b32_e32 v27, v0
	v_mov_b32_e32 v28, v0
	v_mov_b32_e32 v29, v0
	v_mov_b32_e32 v30, v0
	v_mov_b32_e32 v31, v0
	v_mov_b32_e32 v48, v0
	v_mov_b32_e32 v49, v0
	v_mov_b32_e32 v50, v0
	v_mov_b32_e32 v51, v0
	v_mov_b32_e32 v52, v0
	v_mov_b32_e32 v53, v0
	v_mov_b32_e32 v54, v0
	v_mov_b32_e32 v55, v0
	v_mov_b32_e32 v56, v0
	v_mov_b32_e32 v57, v0
	v_mov_b32_e32 v58, v0
	v_mov_b32_e32 v59, v0
	v_mov_b32_e32 v60, v0
	v_mov_b32_e32 v61, v0
	v_mov_b32_e32 v62, v0
	v_mov_b32_e32 v63, v0
	s_add_i32 s99, s18, 0
	v_add_u32_e32 v100, s99, v82
	v_add_u32_e32 v101, s99, v83
	ds_read_b128 v[84:87], v101 offset:16384
	ds_read_b128 v[88:91], v100
	ds_read_b128 v[92:95], v100 offset:4096
.LBB0_87:
	s_add_i32 s21, s19, s20
	s_mov_b32 s98, s21
	s_mov_b64 s[100:101], s[6:7]
	s_waitcnt lgkmcnt(0)
	v_add_u32_e32 v100, s99, v80
	s_add_i32 s21, s18, 0xc000
	s_cmp_lg_u32 s18, 0x18000
	s_cselect_b32 s18, s21, 0
	s_add_i32 s21, s20, 0xc000
	s_cmp_lg_u32 s20, 0x18000
	s_cselect_b32 s20, s21, 0
	ds_read_b128 v[236:239], v101 offset:20480
	v_mfma_f32_32x32x16_bf16 v[48:63], v[84:87], v[88:91], v[48:63]
	v_mfma_f32_32x32x16_bf16 v[16:31], v[84:87], v[92:95], v[16:31]
	s_mov_b32 m0, s98
	v_lshl_add_u64 v[254:255], v[64:65], 0, s[100:101]
	global_load_lds_dwordx4 v[254:255], off
	v_add_u32_e32 v101, s99, v81
	s_add_u32 s6, s6, 0x80
	s_addc_u32 s7, s7, 0
	s_waitcnt lgkmcnt(0)
	ds_read_b128 v[84:87], v101 offset:16384
	ds_read_b128 v[240:243], v100
	ds_read_b128 v[244:247], v100 offset:4096
	v_mfma_f32_32x32x16_bf16 v[32:47], v[236:239], v[88:91], v[32:47]
	v_mfma_f32_32x32x16_bf16 v[0:15], v[236:239], v[92:95], v[0:15]
	s_add_i32 m0, s98, 0x2000
	v_lshl_add_u64 v[254:255], v[66:67], 0, s[100:101]
	global_load_lds_dwordx4 v[254:255], off
	v_add_u32_e32 v100, s99, v78
	s_waitcnt lgkmcnt(0)
	ds_read_b128 v[236:239], v101 offset:20480
	v_mfma_f32_32x32x16_bf16 v[48:63], v[84:87], v[240:243], v[48:63]
	v_mfma_f32_32x32x16_bf16 v[16:31], v[84:87], v[244:247], v[16:31]
	s_add_i32 m0, s98, 0x4000
	v_lshl_add_u64 v[254:255], v[68:69], 0, s[100:101]
	global_load_lds_dwordx4 v[254:255], off
	v_add_u32_e32 v101, s99, v79
	s_waitcnt lgkmcnt(0)
	ds_read_b128 v[84:87], v101 offset:16384
	ds_read_b128 v[88:91], v100
	ds_read_b128 v[92:95], v100 offset:4096
	v_mfma_f32_32x32x16_bf16 v[32:47], v[236:239], v[240:243], v[32:47]
	v_mfma_f32_32x32x16_bf16 v[0:15], v[236:239], v[244:247], v[0:15]
	s_add_i32 m0, s98, 0x6000
	v_lshl_add_u64 v[254:255], v[70:71], 0, s[100:101]
	global_load_lds_dwordx4 v[254:255], off
	v_add_u32_e32 v100, s99, v76
	s_waitcnt lgkmcnt(0)
	ds_read_b128 v[236:239], v101 offset:20480
	v_mfma_f32_32x32x16_bf16 v[48:63], v[84:87], v[88:91], v[48:63]
	v_mfma_f32_32x32x16_bf16 v[16:31], v[84:87], v[92:95], v[16:31]
	s_add_i32 m0, s98, 0x8000
	v_lshl_add_u64 v[254:255], v[72:73], 0, s[100:101]
	global_load_lds_dwordx4 v[254:255], off
	v_add_u32_e32 v101, s99, v77
	s_waitcnt lgkmcnt(0)
	ds_read_b128 v[84:87], v101 offset:16384
	ds_read_b128 v[240:243], v100
	ds_read_b128 v[244:247], v100 offset:4096
	v_mfma_f32_32x32x16_bf16 v[32:47], v[236:239], v[88:91], v[32:47]
	v_mfma_f32_32x32x16_bf16 v[0:15], v[236:239], v[92:95], v[0:15]
	s_add_i32 m0, s98, 0xa000
	v_lshl_add_u64 v[254:255], v[74:75], 0, s[100:101]
	global_load_lds_dwordx4 v[254:255], off
	s_waitcnt lgkmcnt(0)
	ds_read_b128 v[236:239], v101 offset:20480
	v_mfma_f32_32x32x16_bf16 v[48:63], v[84:87], v[240:243], v[48:63]
	v_mfma_f32_32x32x16_bf16 v[16:31], v[84:87], v[244:247], v[16:31]
	s_waitcnt vmcnt(6) lgkmcnt(0)
	s_barrier
; DEV int stage_next(int s) { return (s == 2 * GS_STAGE) ? 0 : s + GS_STAGE; }
; template <int WAIT0>
; DEV void gk_main(f32x16 (&acc)[2][2], const GTile& t, int s0) {
;     ...
;   for (int kt = 0; kt < nk - 2; ++kt) {
;     GK_DMA(std_, kt + 2);
;     GK_COMPUTE(stc);
;     vm_wait_bar<6>();
;     stc = stage_next(stc); std_ = stage_next(std_);
;   }
;   GK_COMPUTE(stc);
;   vm_wait_bar<0>();
;   stc = stage_next(stc);
;   GK_COMPUTE(stc);
;   vm_wait_bar<0>();
; template <int WAIT_E, int WAIT_O, class TileFn, class EpiFn>
; DEV void gemm_seq(int ntiles, TileFn tf, EpiFn epi) {
;     ...
;   for (int i = 0; i < ntiles; ++i) {
;     f32x16 acc[2][2]; acc_zero(acc);
;     if (i == 0) gk_main<6>(acc, cur, s0);
;     else if (i & 1) gk_main<WAIT_O>(acc, cur, s0);
;     else gk_main<WAIT_E>(acc, cur, s0);
;     const int sn = stage_next(s0);
;     if (i + 1 < ntiles) { cur = tf(i + 1); gk_issue2(cur, sn); }
;     epi(i, acc, s0);
;     s0 = sn;
;   }
	s_waitcnt lgkmcnt(0)
	s_add_i32 s99, s18, 0
	v_add_u32_e32 v100, s99, v82
	v_add_u32_e32 v101, s99, v83
	ds_read_b128 v[84:87], v101 offset:16384
	ds_read_b128 v[88:91], v100
	ds_read_b128 v[92:95], v100 offset:4096
	v_mfma_f32_32x32x16_bf16 v[32:47], v[236:239], v[240:243], v[32:47]
	v_mfma_f32_32x32x16_bf16 v[0:15], v[236:239], v[244:247], v[0:15]
	s_cmpk_lg_i32 s6, 0x700
	s_cbranch_scc1 .LBB0_87
	s_waitcnt lgkmcnt(0)
	s_add_i32 s6, s18, 0
	v_add_u32_e32 v84, s6, v83
	ds_read_b128 v[64:67], v84 offset:16384
	v_add_u32_e32 v72, s6, v82
	ds_read_b128 v[68:71], v72
	ds_read_b128 v[72:75], v72 offset:4096
	s_waitcnt lgkmcnt(0)
	v_mfma_f32_32x32x16_bf16 v[48:63], v[64:67], v[68:71], v[48:63]
	v_mfma_f32_32x32x16_bf16 v[16:31], v[64:67], v[72:75], v[16:31]
	ds_read_b128 v[64:67], v84 offset:20480
	v_add_u32_e32 v84, s6, v81
	s_waitcnt lgkmcnt(0)
	v_mfma_f32_32x32x16_bf16 v[32:47], v[64:67], v[68:71], v[32:47]
	v_mfma_f32_32x32x16_bf16 v[0:15], v[64:67], v[72:75], v[0:15]
	ds_read_b128 v[64:67], v84 offset:16384
	v_add_u32_e32 v72, s6, v80
	ds_read_b128 v[68:71], v72
	ds_read_b128 v[72:75], v72 offset:4096
	s_waitcnt lgkmcnt(0)
	v_mfma_f32_32x32x16_bf16 v[48:63], v[64:67], v[68:71], v[48:63]
	v_mfma_f32_32x32x16_bf16 v[16:31], v[64:67], v[72:75], v[16:31]
	ds_read_b128 v[64:67], v84 offset:20480
	v_add_u32_e32 v84, s6, v79
	s_waitcnt lgkmcnt(0)
	v_mfma_f32_32x32x16_bf16 v[32:47], v[64:67], v[68:71], v[32:47]
	v_mfma_f32_32x32x16_bf16 v[0:15], v[64:67], v[72:75], v[0:15]
	ds_read_b128 v[64:67], v84 offset:16384
	v_add_u32_e32 v72, s6, v78
	ds_read_b128 v[68:71], v72
	ds_read_b128 v[72:75], v72 offset:4096
	s_waitcnt lgkmcnt(0)
	v_mfma_f32_32x32x16_bf16 v[48:63], v[64:67], v[68:71], v[48:63]
	v_mfma_f32_32x32x16_bf16 v[16:31], v[64:67], v[72:75], v[16:31]
	ds_read_b128 v[64:67], v84 offset:20480
	v_add_u32_e32 v84, s6, v77
	s_waitcnt lgkmcnt(0)
	v_mfma_f32_32x32x16_bf16 v[32:47], v[64:67], v[68:71], v[32:47]
	v_mfma_f32_32x32x16_bf16 v[0:15], v[64:67], v[72:75], v[0:15]
	ds_read_b128 v[64:67], v84 offset:16384
	v_add_u32_e32 v72, s6, v76
	ds_read_b128 v[68:71], v72
	ds_read_b128 v[72:75], v72 offset:4096
	s_add_i32 s6, s18, 0xc000
	s_cmp_lg_u32 s18, 0x18000
	s_cselect_b32 s6, s6, 0
	s_waitcnt lgkmcnt(0)
	v_mfma_f32_32x32x16_bf16 v[48:63], v[64:67], v[68:71], v[48:63]
	s_add_i32 s6, s6, 0
	v_add_u32_e32 v83, s6, v83
	v_add_u32_e32 v81, s6, v81
	v_add_u32_e32 v79, s6, v79
	v_add_u32_e32 v77, s6, v77
	v_mfma_f32_32x32x16_bf16 v[16:31], v[64:67], v[72:75], v[16:31]
	ds_read_b128 v[64:67], v84 offset:20480
	s_waitcnt vmcnt(0) lgkmcnt(0)
	s_barrier
	s_waitcnt lgkmcnt(0)
	v_mfma_f32_32x32x16_bf16 v[32:47], v[64:67], v[68:71], v[32:47]
	v_mfma_f32_32x32x16_bf16 v[0:15], v[64:67], v[72:75], v[0:15]
	ds_read_b128 v[64:67], v83 offset:16384
	v_add_u32_e32 v72, s6, v82
	ds_read_b128 v[68:71], v72
	ds_read_b128 v[72:75], v72 offset:4096
	s_waitcnt lgkmcnt(0)
	v_mfma_f32_32x32x16_bf16 v[48:63], v[64:67], v[68:71], v[48:63]
	v_mfma_f32_32x32x16_bf16 v[16:31], v[64:67], v[72:75], v[16:31]
	ds_read_b128 v[64:67], v83 offset:20480
	s_waitcnt lgkmcnt(0)
	v_mfma_f32_32x32x16_bf16 v[32:47], v[64:67], v[68:71], v[32:47]
	v_mfma_f32_32x32x16_bf16 v[0:15], v[64:67], v[72:75], v[0:15]
	ds_read_b128 v[64:67], v81 offset:16384
	v_add_u32_e32 v72, s6, v80
	ds_read_b128 v[68:71], v72
	ds_read_b128 v[72:75], v72 offset:4096
	s_waitcnt lgkmcnt(0)
	v_mfma_f32_32x32x16_bf16 v[48:63], v[64:67], v[68:71], v[48:63]
	v_mfma_f32_32x32x16_bf16 v[16:31], v[64:67], v[72:75], v[16:31]
	ds_read_b128 v[64:67], v81 offset:20480
	s_waitcnt lgkmcnt(0)
	v_mfma_f32_32x32x16_bf16 v[32:47], v[64:67], v[68:71], v[32:47]
	v_mfma_f32_32x32x16_bf16 v[0:15], v[64:67], v[72:75], v[0:15]
	ds_read_b128 v[64:67], v79 offset:16384
	v_add_u32_e32 v72, s6, v78
	ds_read_b128 v[68:71], v72
	ds_read_b128 v[72:75], v72 offset:4096
	s_waitcnt lgkmcnt(0)
	v_mfma_f32_32x32x16_bf16 v[48:63], v[64:67], v[68:71], v[48:63]
	v_mfma_f32_32x32x16_bf16 v[16:31], v[64:67], v[72:75], v[16:31]
	ds_read_b128 v[64:67], v79 offset:20480
	s_waitcnt lgkmcnt(0)
	v_mfma_f32_32x32x16_bf16 v[32:47], v[64:67], v[68:71], v[32:47]
	v_mfma_f32_32x32x16_bf16 v[0:15], v[64:67], v[72:75], v[0:15]
	ds_read_b128 v[64:67], v77 offset:16384
	v_add_u32_e32 v72, s6, v76
	ds_read_b128 v[68:71], v72
	ds_read_b128 v[72:75], v72 offset:4096
	s_waitcnt lgkmcnt(0)
	v_mfma_f32_32x32x16_bf16 v[48:63], v[64:67], v[68:71], v[48:63]
	v_mfma_f32_32x32x16_bf16 v[16:31], v[64:67], v[72:75], v[16:31]
	ds_read_b128 v[64:67], v77 offset:20480
	s_waitcnt vmcnt(0) lgkmcnt(0)
	s_barrier
	s_waitcnt lgkmcnt(0)
	v_mfma_f32_32x32x16_bf16 v[32:47], v[64:67], v[68:71], v[32:47]
	v_mfma_f32_32x32x16_bf16 v[0:15], v[64:67], v[72:75], v[0:15]
	s_add_i32 s18, s17, 1
	s_cmp_eq_u32 s17, 11
	s_cbranch_scc1 .LBB0_83

; DEV int tid_l() { int t = threadIdx.x; asm volatile("" : "+v"(t)); return t; }
; DEV int stage_next(int s) { return (s == 2 * GS_STAGE) ? 0 : s + GS_STAGE; }
; DEV void gk_issue2(const GTile& t, int s0) {
;   const int tid = tid_l(), lane = tid & 63, wid = __builtin_amdgcn_readfirstlane(tid >> 6);
;   GK_SRC(t)
;   asm volatile("" ::: "memory");
;   GK_DMA(s0, 0);
;   GK_DMA(stage_next(s0), 1);
;   asm volatile("" ::: "memory");
; }
; template <int WAIT0>
; DEV void gk_main(f32x16 (&acc)[2][2], const GTile& t, int s0) {
;   const int tid = tid_l(), lane = tid & 63, wid = __builtin_amdgcn_readfirstlane(tid >> 6), wm = wid & 1, wn = wid >> 1, l32 = lane & 31, hi = lane >> 5;
;   GK_SRC(t)
;   const int sw = (l32 >> 1) & 7;
;   int xk[4], wk[4];
; #pragma unroll
;   for (int ks = 0; ks < 4; ++ks) { const int ko = ((2 * ks + hi) ^ sw) << 4; xk[ks] = GS_A + (64 * wm + l32) * 128 + ko; wk[ks] = GS_B + (64 * wn + l32) * 128 + ko; }
;   const int nk = t.K >> 6;
;     ...
;   vm_wait_bar<WAIT0>();
;   int stc = s0, std_ = stage_next(stage_next(s0));
; DEV void fold_unit(const Params& P, int u) {
;   GEO
;   const int l = u >> 6, jt = (u >> 3) & 7, hh = u & 7;
;   const bf16_t* A = (const bf16_t*)(P.ws + W_QB) + (size_t)l * 1024 * 2048 + (size_t)(jt * 128) * 2048 + hh * 256;
;   const bf16_t* Bt = (const bf16_t*)(P.ws + W_SK) + (size_t)l * 65536;
;   bf16_t* wpt = (bf16_t*)(P.ws + W_PT);
;   gemm_seq<6, 6>(1, [&](int) { return GTile{A, 2048, Bt, 256, 256}; }, [&](int, f32x16 (&acc)[2][2], int) {
.LBB0_95:
	s_lshl_b32 s8, s30, 12
	s_ashr_i32 s20, s36, 6
	s_and_b32 s42, s8, 0x380000
	s_lshl_b32 s8, s33, 1
	s_ashr_i32 s21, s20, 31
	s_and_b32 s43, s8, 0xe00
	s_lshl_b64 s[24:25], s[20:21], 22
	s_add_u32 s8, s28, s24
	s_addc_u32 s22, s29, s25
	s_lshl_b32 s23, s36, 4
	s_and_b32 s37, s23, 0x380
	s_lshl_b32 s23, s37, 12
	s_add_u32 s23, s8, s23
	s_addc_u32 s22, s22, 0
	s_lshl_b32 s8, s36, 8
	s_and_b32 s8, s8, 0x700
	s_lshl_b32 s38, s8, 1
	s_add_u32 s38, s23, s38
	v_mov_b32_e32 v82, v176
	s_addc_u32 s39, s22, 0
	s_lshl_b64 s[22:23], s[20:21], 17
	v_mov_b32_e32 v2, v176
	s_add_u32 s40, s26, s22
	s_waitcnt vmcnt(0) lgkmcnt(0)
	s_barrier
	s_addc_u32 s41, s27, s23
	v_readfirstlane_b32 s44, v2
	s_ashr_i32 s44, s44, 6
	v_bfe_u32 v0, v2, 3, 3
	v_lshl_or_b32 v0, s44, 3, v0
	v_lshrrev_b32_e32 v3, 1, v0
	v_xor_b32_e32 v2, v3, v2
	v_add_u32_e32 v4, 64, v0
	v_ashrrev_i32_e32 v1, 31, v0
	v_lshlrev_b32_e32 v2, 4, v2
	v_ashrrev_i32_e32 v5, 31, v4
	v_and_b32_e32 v80, 0x70, v2
	v_lshlrev_b64 v[2:3], 12, v[0:1]
	v_lshlrev_b64 v[6:7], 12, v[4:5]
	v_lshl_add_u64 v[2:3], s[38:39], 0, v[2:3]
	v_lshl_add_u64 v[6:7], s[38:39], 0, v[6:7]
	s_lshl_b32 s38, s44, 10
	s_add_i32 s38, s38, 0
	v_lshl_add_u64 v[2:3], v[2:3], 0, v[80:81]
	v_lshlrev_b64 v[0:1], 9, v[0:1]
	s_mov_b32 m0, s38
	v_lshl_add_u64 v[6:7], v[6:7], 0, v[80:81]
	v_lshl_add_u64 v[0:1], s[40:41], 0, v[0:1]
	v_lshlrev_b64 v[4:5], 9, v[4:5]
	global_load_lds_dwordx4 v[2:3], off
	s_add_i32 m0, s38, 0x2000
	v_lshl_add_u64 v[0:1], v[0:1], 0, v[80:81]
	v_lshl_add_u64 v[4:5], s[40:41], 0, v[4:5]
	global_load_lds_dwordx4 v[6:7], off
	s_add_i32 m0, s38, 0x4000
	v_lshl_add_u64 v[4:5], v[4:5], 0, v[80:81]
	global_load_lds_dwordx4 v[0:1], off
	s_add_i32 m0, s38, 0x6000
	v_lshl_add_u64 v[8:9], v[0:1], 0, s[10:11]
	global_load_lds_dwordx4 v[4:5], off
	s_add_i32 m0, s38, 0x8000
	v_lshl_add_u64 v[10:11], v[0:1], 0, s[12:13]
	global_load_lds_dwordx4 v[8:9], off
	s_add_i32 m0, s38, 0xa000
	v_lshl_add_u64 v[2:3], v[2:3], 0, s[14:15]
	global_load_lds_dwordx4 v[10:11], off
	s_add_i32 m0, s38, 0xc000
	s_or_b32 s24, s24, s42
	global_load_lds_dwordx4 v[2:3], off
	v_lshl_add_u64 v[2:3], v[6:7], 0, s[14:15]
	s_add_i32 m0, s38, 0xe000
	v_mov_b32_e32 v7, v81
	global_load_lds_dwordx4 v[2:3], off
	s_add_i32 m0, s38, 0x10000
	v_lshl_add_u64 v[2:3], v[0:1], 0, s[14:15]
	global_load_lds_dwordx4 v[2:3], off
	v_lshl_add_u64 v[2:3], v[4:5], 0, s[14:15]
	s_add_i32 m0, s38, 0x12000
	v_mov_b32_e32 v8, v81
	global_load_lds_dwordx4 v[2:3], off
	v_lshl_add_u64 v[2:3], v[0:1], 0, s[16:17]
	s_add_i32 m0, s38, 0x14000
	v_lshl_add_u64 v[0:1], v[0:1], 0, s[18:19]
	global_load_lds_dwordx4 v[2:3], off
	s_add_i32 m0, s38, 0x16000
	v_mov_b32_e32 v9, v81
	global_load_lds_dwordx4 v[0:1], off
	v_mov_b32_e32 v1, v176
	s_waitcnt vmcnt(6) lgkmcnt(0)
	s_barrier
	v_readfirstlane_b32 s38, v1
	s_ashr_i32 s39, s38, 6
	v_bfe_u32 v0, v1, 3, 3
	v_lshl_or_b32 v0, s39, 3, v0
	v_and_b32_e32 v2, 31, v1
	v_lshrrev_b32_e32 v3, 1, v0
	v_xor_b32_e32 v3, v3, v1
	v_and_or_b32 v5, s38, 64, v2
	s_lshr_b32 s38, s38, 1
	v_lshlrev_b32_e32 v3, 4, v3
	s_and_b32 s38, s38, 0x1ffffc0
	v_and_b32_e32 v6, 0x70, v3
	v_bfe_u32 v3, v1, 5, 1
	v_lshrrev_b32_e32 v4, 1, v1
	v_or_b32_e32 v2, s38, v2
	v_bfe_u32 v1, v1, 1, 3
	v_lshlrev_b32_e32 v79, 7, v2
	v_bitop3_b32 v2, v3, v4, 7 bitop3:0x78
	v_lshlrev_b32_e32 v90, 4, v2
	v_bitop3_b32 v2, v3, v1, 2 bitop3:0x36
	v_lshlrev_b32_e32 v76, 4, v2
	v_bitop3_b32 v2, v3, v1, 4 bitop3:0x36
	v_bitop3_b32 v1, v3, v1, 6 bitop3:0x36
	v_lshlrev_b32_e32 v78, 4, v1
	v_ashrrev_i32_e32 v1, 31, v0
	v_lshlrev_b32_e32 v77, 4, v2
	v_lshlrev_b64 v[2:3], 12, v[0:1]
	v_lshl_add_u64 v[2:3], s[24:25], 0, v[2:3]
	v_or3_b32 v2, v2, s43, v6
	v_lshl_add_u64 v[64:65], s[4:5], 0, v[2:3]
	v_add_u32_e32 v2, 64, v0
	v_lshlrev_b32_e32 v5, 7, v5
	v_ashrrev_i32_e32 v3, 31, v2
	v_or_b32_e32 v88, v90, v5
	v_or_b32_e32 v86, v76, v5
	v_or_b32_e32 v84, v77, v5
	v_or_b32_e32 v80, v78, v5
	v_lshlrev_b64 v[4:5], 12, v[2:3]
	v_lshlrev_b64 v[2:3], 9, v[2:3]
	v_lshl_add_u64 v[4:5], s[24:25], 0, v[4:5]
	v_lshl_add_u64 v[2:3], s[22:23], 0, v[2:3]
	v_or3_b32 v4, v4, s43, v6
	v_or_b32_e32 v2, v2, v6
	v_lshl_add_u64 v[66:67], s[4:5], 0, v[4:5]
	v_lshlrev_b64 v[4:5], 9, v[0:1]
	v_lshl_add_u64 v[70:71], s[6:7], 0, v[2:3]
	v_add_u32_e32 v2, 0x80, v0
	v_add_u32_e32 v0, 0xc0, v0
	v_ashrrev_i32_e32 v3, 31, v2
	v_ashrrev_i32_e32 v1, 31, v0
	v_lshlrev_b64 v[2:3], 9, v[2:3]
	v_lshlrev_b64 v[0:1], 9, v[0:1]
	v_lshl_add_u64 v[4:5], s[22:23], 0, v[4:5]
	v_lshl_add_u64 v[2:3], s[22:23], 0, v[2:3]
	v_lshl_add_u64 v[0:1], s[22:23], 0, v[0:1]
	s_lshl_b32 s38, s39, 10
	v_or_b32_e32 v4, v4, v6
	v_or_b32_e32 v2, v2, v6
	v_or_b32_e32 v0, v0, v6
	s_add_i32 s38, s38, 0
	v_or_b32_e32 v89, v79, v90
	v_or_b32_e32 v87, v79, v76
	v_or_b32_e32 v85, v79, v77
	v_or_b32_e32 v83, v79, v78
	v_lshl_add_u64 v[68:69], s[6:7], 0, v[4:5]
	v_lshl_add_u64 v[72:73], s[6:7], 0, v[2:3]
	v_lshl_add_u64 v[74:75], s[6:7], 0, v[0:1]
	s_mov_b64 s[22:23], 0
	s_mov_b32 s24, 0x18000
	s_mov_b32 s25, s9
	v_mov_b32_e32 v0, 0
	v_mov_b32_e32 v1, v81
	v_mov_b32_e32 v2, v81
	v_mov_b32_e32 v3, v81
	v_mov_b32_e32 v4, v81
	v_mov_b32_e32 v5, v81
	v_mov_b32_e32 v6, v81
	v_mov_b32_e32 v10, v81
	v_mov_b32_e32 v11, v81
	v_mov_b32_e32 v12, v81
	v_mov_b32_e32 v13, v81
	v_mov_b32_e32 v14, v81
	v_mov_b32_e32 v15, v81
	v_mov_b32_e32 v16, 0
	v_mov_b32_e32 v17, v81
	v_mov_b32_e32 v18, v81
	v_mov_b32_e32 v19, v81
	v_mov_b32_e32 v20, v81
	v_mov_b32_e32 v21, v81
	v_mov_b32_e32 v22, v81
	v_mov_b32_e32 v23, v81
	v_mov_b32_e32 v24, v81
	v_mov_b32_e32 v25, v81
	v_mov_b32_e32 v26, v81
	v_mov_b32_e32 v27, v81
	v_mov_b32_e32 v28, v81
	v_mov_b32_e32 v29, v81
	v_mov_b32_e32 v30, v81
	v_mov_b32_e32 v31, v81
	v_mov_b32_e32 v32, 0
	v_mov_b32_e32 v33, v81
	v_mov_b32_e32 v34, v81
	v_mov_b32_e32 v35, v81
	v_mov_b32_e32 v36, v81
	v_mov_b32_e32 v37, v81
	v_mov_b32_e32 v38, v81
	v_mov_b32_e32 v39, v81
	v_mov_b32_e32 v40, v81
	v_mov_b32_e32 v41, v81
	v_mov_b32_e32 v42, v81
	v_mov_b32_e32 v43, v81
	v_mov_b32_e32 v44, v81
	v_mov_b32_e32 v45, v81
	v_mov_b32_e32 v46, v81
	v_mov_b32_e32 v47, v81
	v_mov_b32_e32 v48, 0
	v_mov_b32_e32 v49, v81
	v_mov_b32_e32 v50, v81
	v_mov_b32_e32 v51, v81
	v_mov_b32_e32 v52, v81
	v_mov_b32_e32 v53, v81
	v_mov_b32_e32 v54, v81
	v_mov_b32_e32 v55, v81
	v_mov_b32_e32 v56, v81
	v_mov_b32_e32 v57, v81
	v_mov_b32_e32 v58, v81
	v_mov_b32_e32 v59, v81
	v_mov_b32_e32 v60, v81
	v_mov_b32_e32 v61, v81
	v_mov_b32_e32 v62, v81
	v_mov_b32_e32 v63, v81
	s_add_i32 s99, s25, 0
	v_add_u32_e32 v252, s99, v89
	v_add_u32_e32 v91, s99, v88
	ds_read_b128 v[92:95], v252 offset:16384
	ds_read_b128 v[96:99], v91
	ds_read_b128 v[100:103], v91 offset:4096
	ds_read_b128 v[104:107], v252 offset:20480
; DEV int stage_next(int s) { return (s == 2 * GS_STAGE) ? 0 : s + GS_STAGE; }
; template <int WAIT0>
; DEV void gk_main(f32x16 (&acc)[2][2], const GTile& t, int s0) {
;     ...
;   for (int kt = 0; kt < nk - 2; ++kt) {
;     GK_DMA(std_, kt + 2);
;     GK_COMPUTE(stc);
;     vm_wait_bar<6>();
;     stc = stage_next(stc); std_ = stage_next(std_);
;   }
;   GK_COMPUTE(stc);
;   vm_wait_bar<0>();
;   stc = stage_next(stc);
;   GK_COMPUTE(stc);
;   vm_wait_bar<0>();
.LBB0_96:
	s_add_i32 s39, s38, s24
	s_mov_b32 s98, s39
	s_mov_b64 s[100:101], s[22:23]
	s_waitcnt lgkmcnt(0)
	v_add_u32_e32 v108, s99, v87
	v_add_u32_e32 v91, s99, v86
	s_add_i32 s39, s25, 0xc000
	s_cmp_lg_u32 s25, 0x18000
	s_cselect_b32 s25, s39, 0
	s_add_i32 s39, s24, 0xc000
	s_cmp_lg_u32 s24, 0x18000
	s_cselect_b32 s24, s39, 0
	s_add_u32 s22, s22, 0x80
	s_addc_u32 s23, s23, 0
	ds_read_b128 v[236:239], v108 offset:16384
	ds_read_b128 v[240:243], v91
	ds_read_b128 v[244:247], v91 offset:4096
	ds_read_b128 v[248:251], v108 offset:20480
	v_mfma_f32_32x32x16_bf16 v[48:63], v[92:95], v[96:99], v[48:63]
	v_mfma_f32_32x32x16_bf16 v[32:47], v[92:95], v[100:103], v[32:47]
	s_mov_b32 m0, s98
	v_lshl_add_u64 v[254:255], v[64:65], 0, s[100:101]
	global_load_lds_dwordx4 v[254:255], off
	v_mfma_f32_32x32x16_bf16 v[16:31], v[104:107], v[96:99], v[16:31]
	v_mfma_f32_32x32x16_bf16 v[0:15], v[104:107], v[100:103], v[0:15]
	s_add_i32 m0, s98, 0x2000
	v_lshl_add_u64 v[254:255], v[66:67], 0, s[100:101]
	global_load_lds_dwordx4 v[254:255], off
	v_add_u32_e32 v108, s99, v85
	v_add_u32_e32 v91, s99, v84
	s_waitcnt lgkmcnt(0)
	ds_read_b128 v[92:95], v108 offset:16384
	ds_read_b128 v[96:99], v91
	ds_read_b128 v[100:103], v91 offset:4096
	ds_read_b128 v[104:107], v108 offset:20480
	v_mfma_f32_32x32x16_bf16 v[48:63], v[236:239], v[240:243], v[48:63]
	v_mfma_f32_32x32x16_bf16 v[32:47], v[236:239], v[244:247], v[32:47]
	s_add_i32 m0, s98, 0x4000
	v_lshl_add_u64 v[254:255], v[68:69], 0, s[100:101]
	global_load_lds_dwordx4 v[254:255], off
	v_mfma_f32_32x32x16_bf16 v[16:31], v[248:251], v[240:243], v[16:31]
	v_mfma_f32_32x32x16_bf16 v[0:15], v[248:251], v[244:247], v[0:15]
	s_add_i32 m0, s98, 0x6000
	v_lshl_add_u64 v[254:255], v[70:71], 0, s[100:101]
	global_load_lds_dwordx4 v[254:255], off
	v_add_u32_e32 v108, s99, v83
	v_add_u32_e32 v91, s99, v80
	s_waitcnt lgkmcnt(0)
	ds_read_b128 v[236:239], v108 offset:16384
	ds_read_b128 v[240:243], v91
	ds_read_b128 v[244:247], v91 offset:4096
	ds_read_b128 v[248:251], v108 offset:20480
	v_mfma_f32_32x32x16_bf16 v[48:63], v[92:95], v[96:99], v[48:63]
	v_mfma_f32_32x32x16_bf16 v[32:47], v[92:95], v[100:103], v[32:47]
	s_add_i32 m0, s98, 0x8000
	v_lshl_add_u64 v[254:255], v[72:73], 0, s[100:101]
	global_load_lds_dwordx4 v[254:255], off
	v_mfma_f32_32x32x16_bf16 v[16:31], v[104:107], v[96:99], v[16:31]
	v_mfma_f32_32x32x16_bf16 v[0:15], v[104:107], v[100:103], v[0:15]
	s_add_i32 m0, s98, 0xa000
	v_lshl_add_u64 v[254:255], v[74:75], 0, s[100:101]
	global_load_lds_dwordx4 v[254:255], off
	s_waitcnt vmcnt(6) lgkmcnt(0)
	s_barrier
	s_waitcnt lgkmcnt(0)
	s_add_i32 s99, s25, 0
	v_add_u32_e32 v252, s99, v89
	v_add_u32_e32 v91, s99, v88
	ds_read_b128 v[92:95], v252 offset:16384
	ds_read_b128 v[96:99], v91
	ds_read_b128 v[100:103], v91 offset:4096
	ds_read_b128 v[104:107], v252 offset:20480
	v_mfma_f32_32x32x16_bf16 v[48:63], v[236:239], v[240:243], v[48:63]
	v_mfma_f32_32x32x16_bf16 v[32:47], v[236:239], v[244:247], v[32:47]
	v_mfma_f32_32x32x16_bf16 v[16:31], v[248:251], v[240:243], v[16:31]
	v_mfma_f32_32x32x16_bf16 v[0:15], v[248:251], v[244:247], v[0:15]
	s_cmpk_lg_i32 s22, 0x100
	s_cbranch_scc1 .LBB0_96
	s_waitcnt lgkmcnt(0)
	v_add_u32_e32 v72, 0x4000, v79
	v_or_b32_e32 v64, v72, v90
	v_add_u32_e32 v73, s35, v64
	ds_read_b128 v[64:67], v73
	v_add_u32_e32 v74, s35, v88
	ds_read_b128 v[68:71], v74
	ds_read_b128 v[90:93], v74 offset:4096
	ds_read_b128 v[94:97], v73 offset:4096
	v_or_b32_e32 v73, v72, v76
	v_or_b32_e32 v74, v72, v77
	s_waitcnt lgkmcnt(0)
	v_mfma_f32_32x32x16_bf16 v[16:31], v[94:97], v[68:71], v[16:31]
	v_or_b32_e32 v76, v72, v78
	v_add_u32_e32 v72, s35, v80
	v_add_u32_e32 v76, s35, v76
	v_add_u32_e32 v88, 0, v88
	v_add_u32_e32 v154, 0, v87
	v_add_u32_e32 v80, 0, v80
	s_lshl_b64 s[20:21], s[20:21], 11
	v_mfma_f32_32x32x16_bf16 v[48:63], v[64:67], v[68:71], v[48:63]
	v_add_u32_e32 v68, s35, v74
	s_or_b64 s[20:21], s[20:21], s[8:9]
	s_add_i32 s36, s36, s86
	s_add_i32 s30, s30, s31
	s_add_i32 s33, s33, s34
	s_cmpk_gt_i32 s36, 0x7f
	v_mfma_f32_32x32x16_bf16 v[32:47], v[64:67], v[90:93], v[32:47]
	v_add_u32_e32 v64, s35, v86
	ds_read_b128 v[98:101], v64
	ds_read_b128 v[102:105], v64 offset:4096
	v_add_u32_e32 v64, s35, v73
	ds_read_b128 v[106:109], v64
	ds_read_b128 v[110:113], v64 offset:4096
	v_add_u32_e32 v64, s35, v84
	ds_read_b128 v[114:117], v64
	ds_read_b128 v[64:67], v64 offset:4096
	ds_read_b128 v[118:121], v68
	ds_read_b128 v[68:71], v68 offset:4096
	s_waitcnt lgkmcnt(0)
	v_mfma_f32_32x32x16_bf16 v[48:63], v[106:109], v[98:101], v[48:63]
	ds_read_b128 v[122:125], v72
	ds_read_b128 v[72:75], v72 offset:4096
	ds_read_b128 v[126:129], v76
	ds_read_b128 v[76:79], v76 offset:4096
	s_waitcnt vmcnt(0) lgkmcnt(0)
	s_barrier
	ds_read_b128 v[130:133], v88
	ds_read_b128 v[134:137], v88 offset:4096
	v_add_u32_e32 v88, 0, v89
	v_mfma_f32_32x32x16_bf16 v[48:63], v[118:121], v[114:117], v[48:63]
	ds_read_b128 v[138:141], v88 offset:16384
	ds_read_b128 v[142:145], v88 offset:20480
	v_add_u32_e32 v86, 0, v86
	ds_read_b128 v[146:149], v86
	ds_read_b128 v[150:153], v86 offset:4096
	ds_read_b128 v[86:89], v154 offset:16384
	ds_read_b128 v[154:157], v154 offset:20480
	v_add_u32_e32 v84, 0, v84
	ds_read_b128 v[158:161], v84
	ds_read_b128 v[162:165], v84 offset:4096
	v_add_u32_e32 v84, 0, v85
	s_waitcnt lgkmcnt(0)
	v_mfma_f32_32x32x16_bf16 v[48:63], v[126:129], v[122:125], v[48:63]
	ds_read_b128 v[166:169], v84 offset:16384
	ds_read_b128 v[170:173], v84 offset:20480
	ds_read_b128 v[182:185], v80
	ds_read_b128 v[186:189], v80 offset:4096
	v_add_u32_e32 v80, 0, v83
	ds_read_b128 v[190:193], v80 offset:16384
	ds_read_b128 v[194:197], v80 offset:20480
	v_ashrrev_i32_e32 v83, 1, v82
	v_and_b32_e32 v80, 0x5f, v82
	v_and_b32_e32 v83, 0xffffffc0, v83
	v_mfma_f32_32x32x16_bf16 v[48:63], v[138:141], v[130:133], v[48:63]
	v_lshrrev_b32_e32 v82, 3, v82
	v_and_or_b32 v84, v82, 4, v83
	v_or_b32_e32 v80, s37, v80
	v_ashrrev_i32_e32 v85, 31, v84
	v_lshlrev_b32_e32 v80, 1, v80
	v_lshl_add_u64 v[174:175], s[20:21], 0, v[84:85]
	v_lshl_add_u64 v[82:83], s[2:3], 0, v[80:81]
	v_mfma_f32_32x32x16_bf16 v[32:47], v[106:109], v[102:105], v[32:47]
	v_lshlrev_b64 v[174:175], 11, v[174:175]
	v_lshl_add_u64 v[198:199], v[82:83], 0, v[174:175]
	s_waitcnt vmcnt(0) lgkmcnt(0)
	s_barrier
; DEV bf16_t f2bf(float f) { return (bf16_t)(pk2(f, 0.f) & 0xffffu); }
; #define FOR_ACC _Pragma("unroll") for (int nb = 0; nb < 2; ++nb) _Pragma("unroll") for (int mb = 0; mb < 2; ++mb) _Pragma("unroll") for (int rq = 0; rq < 4; ++rq)
; DEV void fold_unit(const Params& P, int u) {
;     ...
;   gemm_seq<6, 6>(1, [&](int) { return GTile{A, 2048, Bt, 256, 256}; }, [&](int, f32x16 (&acc)[2][2], int) {
;     FOR_ACC {
;       const int j = jt * 128 + 64 * wm + 32 * mb + l32, n = 64 * wn + 32 * nb + 8 * rq + 4 * hi;
; #pragma unroll
;       for (int e = 0; e < 4; ++e) wpt[((size_t)l * 2048 + hh * 256 + n + e) * 1024 + j] = f2bf(acc[nb][mb][4 * rq + e]);
;     }
;   });
	v_mfma_f32_32x32x16_bf16 v[48:63], v[86:89], v[146:149], v[48:63]
	v_mfma_f32_32x32x16_bf16 v[32:47], v[118:121], v[64:67], v[32:47]
	s_waitcnt lgkmcnt(0)
	v_mfma_f32_32x32x16_bf16 v[48:63], v[166:169], v[158:161], v[48:63]
	v_mfma_f32_32x32x16_bf16 v[32:47], v[126:129], v[72:75], v[32:47]
	v_mfma_f32_32x32x16_bf16 v[48:63], v[190:193], v[182:185], v[48:63]
	v_mfma_f32_32x32x16_bf16 v[16:31], v[110:113], v[98:101], v[16:31]
	s_nop 10
	v_cvt_pk_bf16_f32 v48, v48, s0
	global_store_short v[198:199], v48, off
	v_cvt_pk_bf16_f32 v48, v49, s0
	global_store_short v[198:199], v48, off offset:2048
	v_or_b32_e32 v48, 0x1000, v174
	v_mov_b32_e32 v49, v175
	v_cvt_pk_bf16_f32 v50, v50, s0
	v_mfma_f32_32x32x16_bf16 v[32:47], v[138:141], v[134:137], v[32:47]
	v_or_b32_e32 v174, 0x1800, v174
	v_cvt_pk_bf16_f32 v80, v51, s0
	v_cvt_pk_bf16_f32 v52, v52, s0
	v_cvt_pk_bf16_f32 v54, v54, s0
	v_cvt_pk_bf16_f32 v56, v56, s0
	v_cvt_pk_bf16_f32 v58, v58, s0
	v_cvt_pk_bf16_f32 v60, v60, s0
	v_mfma_f32_32x32x16_bf16 v[16:31], v[68:71], v[114:117], v[16:31]
	v_cvt_pk_bf16_f32 v62, v62, s0
	v_mfma_f32_32x32x16_bf16 v[0:15], v[94:97], v[90:93], v[0:15]
	v_lshl_add_u64 v[90:91], v[82:83], 0, v[48:49]
	global_store_short v[90:91], v50, off
	v_lshl_add_u64 v[50:51], v[82:83], 0, v[174:175]
	global_store_short v[50:51], v80, off
	v_or_b32_e32 v50, 8, v84
	v_ashrrev_i32_e32 v51, 31, v50
	v_lshl_add_u64 v[50:51], s[20:21], 0, v[50:51]
	v_mfma_f32_32x32x16_bf16 v[32:47], v[86:89], v[150:153], v[32:47]
	v_lshlrev_b64 v[50:51], 11, v[50:51]
	v_lshl_add_u64 v[90:91], v[82:83], 0, v[50:51]
	global_store_short v[90:91], v52, off
	v_cvt_pk_bf16_f32 v80, v53, s0
	v_or_b32_e32 v52, 0x800, v50
	v_mov_b32_e32 v53, v51
	v_or_b32_e32 v92, 0x1000, v50
	v_mfma_f32_32x32x16_bf16 v[16:31], v[76:79], v[122:125], v[16:31]
	v_mov_b32_e32 v93, v51
	v_lshl_add_u64 v[52:53], v[82:83], 0, v[52:53]
	v_lshl_add_u64 v[92:93], v[82:83], 0, v[92:93]
	v_or_b32_e32 v50, 0x1800, v50
	global_store_short v[52:53], v80, off
	global_store_short v[92:93], v54, off
	v_cvt_pk_bf16_f32 v54, v55, s0
	v_lshl_add_u64 v[50:51], v[82:83], 0, v[50:51]
	v_mfma_f32_32x32x16_bf16 v[32:47], v[166:169], v[162:165], v[32:47]
	global_store_short v[50:51], v54, off
	v_or_b32_e32 v54, 16, v84
	v_ashrrev_i32_e32 v55, 31, v54
	v_lshl_add_u64 v[54:55], s[20:21], 0, v[54:55]
	v_lshlrev_b64 v[54:55], 11, v[54:55]
	v_lshl_add_u64 v[94:95], v[82:83], 0, v[54:55]
	global_store_short v[94:95], v56, off
	v_mfma_f32_32x32x16_bf16 v[16:31], v[142:145], v[130:133], v[16:31]
	v_cvt_pk_bf16_f32 v80, v57, s0
	v_or_b32_e32 v56, 0x800, v54
	v_mov_b32_e32 v57, v55
	v_or_b32_e32 v96, 0x1000, v54
	v_mov_b32_e32 v97, v55
	v_lshl_add_u64 v[56:57], v[82:83], 0, v[56:57]
	v_lshl_add_u64 v[96:97], v[82:83], 0, v[96:97]
	v_or_b32_e32 v54, 0x1800, v54
	global_store_short v[56:57], v80, off
	global_store_short v[96:97], v58, off
	v_cvt_pk_bf16_f32 v58, v59, s0
	v_lshl_add_u64 v[54:55], v[82:83], 0, v[54:55]
	v_mfma_f32_32x32x16_bf16 v[32:47], v[190:193], v[186:189], v[32:47]
	global_store_short v[54:55], v58, off
	v_or_b32_e32 v58, 24, v84
	v_ashrrev_i32_e32 v59, 31, v58
	v_lshl_add_u64 v[58:59], s[20:21], 0, v[58:59]
	v_lshlrev_b64 v[58:59], 11, v[58:59]
	v_lshl_add_u64 v[86:87], v[82:83], 0, v[58:59]
	global_store_short v[86:87], v60, off
	v_mfma_f32_32x32x16_bf16 v[0:15], v[110:113], v[102:105], v[0:15]
	v_cvt_pk_bf16_f32 v80, v61, s0
	v_or_b32_e32 v60, 0x800, v58
	v_mov_b32_e32 v61, v59
	v_or_b32_e32 v88, 0x1000, v58
	v_mov_b32_e32 v89, v59
	v_lshl_add_u64 v[60:61], v[82:83], 0, v[60:61]
	v_lshl_add_u64 v[88:89], v[82:83], 0, v[88:89]
	v_mfma_f32_32x32x16_bf16 v[16:31], v[154:157], v[146:149], v[16:31]
	v_or_b32_e32 v58, 0x1800, v58
	global_store_short v[60:61], v80, off
	global_store_short v[88:89], v62, off
	v_cvt_pk_bf16_f32 v62, v63, s0
	v_lshl_add_u64 v[58:59], v[82:83], 0, v[58:59]
	v_cvt_pk_bf16_f32 v32, v32, s0
	global_store_short v[58:59], v62, off
	v_lshl_add_u64 v[62:63], v[82:83], 0, 64
	global_store_short v[198:199], v32, off offset:64
	v_cvt_pk_bf16_f32 v32, v33, s0
	global_store_short v[198:199], v32, off offset:2112
	v_cvt_pk_bf16_f32 v34, v34, s0
	v_lshl_add_u64 v[32:33], v[62:63], 0, v[48:49]
	global_store_short v[32:33], v34, off
	v_cvt_pk_bf16_f32 v34, v35, s0
	v_lshl_add_u64 v[32:33], v[62:63], 0, v[174:175]
	global_store_short v[32:33], v34, off
	v_cvt_pk_bf16_f32 v32, v36, s0
	v_mfma_f32_32x32x16_bf16 v[16:31], v[170:173], v[158:161], v[16:31]
	global_store_short v[90:91], v32, off offset:64
	v_cvt_pk_bf16_f32 v32, v37, s0
	global_store_short v[52:53], v32, off offset:64
	v_cvt_pk_bf16_f32 v32, v38, s0
	global_store_short v[92:93], v32, off offset:64
	v_cvt_pk_bf16_f32 v32, v39, s0
	global_store_short v[50:51], v32, off offset:64
	v_mfma_f32_32x32x16_bf16 v[0:15], v[68:71], v[64:67], v[0:15]
	v_cvt_pk_bf16_f32 v32, v40, s0
	global_store_short v[94:95], v32, off offset:64
	v_cvt_pk_bf16_f32 v32, v41, s0
	global_store_short v[56:57], v32, off offset:64
	v_cvt_pk_bf16_f32 v32, v42, s0
	global_store_short v[96:97], v32, off offset:64
	v_cvt_pk_bf16_f32 v32, v43, s0
	global_store_short v[54:55], v32, off offset:64
; DEV bf16_t f2bf(float f) { return (bf16_t)(pk2(f, 0.f) & 0xffffu); }
; #define FOR_ACC _Pragma("unroll") for (int nb = 0; nb < 2; ++nb) _Pragma("unroll") for (int mb = 0; mb < 2; ++mb) _Pragma("unroll") for (int rq = 0; rq < 4; ++rq)
; DEV void fold_unit(const Params& P, int u) {
;     ...
;   gemm_seq<6, 6>(1, [&](int) { return GTile{A, 2048, Bt, 256, 256}; }, [&](int, f32x16 (&acc)[2][2], int) {
;     FOR_ACC {
;       const int j = jt * 128 + 64 * wm + 32 * mb + l32, n = 64 * wn + 32 * nb + 8 * rq + 4 * hi;
; #pragma unroll
;       for (int e = 0; e < 4; ++e) wpt[((size_t)l * 2048 + hh * 256 + n + e) * 1024 + j] = f2bf(acc[nb][mb][4 * rq + e]);
;     }
;   });
	v_cvt_pk_bf16_f32 v32, v44, s0
	v_mfma_f32_32x32x16_bf16 v[16:31], v[194:197], v[182:185], v[16:31]
	global_store_short v[86:87], v32, off offset:64
	v_cvt_pk_bf16_f32 v32, v45, s0
	global_store_short v[60:61], v32, off offset:64
	v_cvt_pk_bf16_f32 v32, v46, s0
	global_store_short v[88:89], v32, off offset:64
	v_cvt_pk_bf16_f32 v32, v47, s0
	global_store_short v[58:59], v32, off offset:64
	v_mfma_f32_32x32x16_bf16 v[0:15], v[76:79], v[72:75], v[0:15]
	v_or_b32_e32 v32, 32, v84
	v_ashrrev_i32_e32 v33, 31, v32
	v_lshl_add_u64 v[32:33], s[20:21], 0, v[32:33]
	v_lshlrev_b64 v[32:33], 11, v[32:33]
	v_cvt_pk_bf16_f32 v16, v16, s0
	v_lshl_add_u64 v[34:35], v[82:83], 0, v[32:33]
	global_store_short v[34:35], v16, off
	v_mfma_f32_32x32x16_bf16 v[0:15], v[142:145], v[134:137], v[0:15]
	v_cvt_pk_bf16_f32 v36, v17, s0
	v_or_b32_e32 v16, 0x800, v32
	v_mov_b32_e32 v17, v33
	v_lshl_add_u64 v[16:17], v[82:83], 0, v[16:17]
	global_store_short v[16:17], v36, off
	v_or_b32_e32 v36, 0x1000, v32
	v_mov_b32_e32 v37, v33
	v_cvt_pk_bf16_f32 v18, v18, s0
	v_lshl_add_u64 v[36:37], v[82:83], 0, v[36:37]
	v_or_b32_e32 v32, 0x1800, v32
	global_store_short v[36:37], v18, off
	v_cvt_pk_bf16_f32 v38, v19, s0
	v_lshl_add_u64 v[18:19], v[82:83], 0, v[32:33]
	v_or_b32_e32 v32, 40, v84
	v_ashrrev_i32_e32 v33, 31, v32
	v_lshl_add_u64 v[32:33], s[20:21], 0, v[32:33]
	v_mfma_f32_32x32x16_bf16 v[0:15], v[154:157], v[150:153], v[0:15]
	v_lshlrev_b64 v[32:33], 11, v[32:33]
	global_store_short v[18:19], v38, off
	v_cvt_pk_bf16_f32 v20, v20, s0
	v_lshl_add_u64 v[38:39], v[82:83], 0, v[32:33]
	global_store_short v[38:39], v20, off
	v_cvt_pk_bf16_f32 v40, v21, s0
	v_or_b32_e32 v20, 0x800, v32
	v_mov_b32_e32 v21, v33
	v_lshl_add_u64 v[20:21], v[82:83], 0, v[20:21]
	global_store_short v[20:21], v40, off
	v_or_b32_e32 v40, 0x1000, v32
	v_mov_b32_e32 v41, v33
	v_cvt_pk_bf16_f32 v22, v22, s0
	v_lshl_add_u64 v[40:41], v[82:83], 0, v[40:41]
	v_or_b32_e32 v32, 0x1800, v32
	global_store_short v[40:41], v22, off
	v_cvt_pk_bf16_f32 v42, v23, s0
	v_lshl_add_u64 v[22:23], v[82:83], 0, v[32:33]
	v_or_b32_e32 v32, 48, v84
	v_ashrrev_i32_e32 v33, 31, v32
	v_mfma_f32_32x32x16_bf16 v[0:15], v[170:173], v[162:165], v[0:15]
	v_lshl_add_u64 v[32:33], s[20:21], 0, v[32:33]
	v_lshlrev_b64 v[32:33], 11, v[32:33]
	global_store_short v[22:23], v42, off
	v_cvt_pk_bf16_f32 v24, v24, s0
	v_lshl_add_u64 v[42:43], v[82:83], 0, v[32:33]
	global_store_short v[42:43], v24, off
	v_cvt_pk_bf16_f32 v44, v25, s0
	v_or_b32_e32 v24, 0x800, v32
	v_mov_b32_e32 v25, v33
	v_lshl_add_u64 v[24:25], v[82:83], 0, v[24:25]
	global_store_short v[24:25], v44, off
	v_or_b32_e32 v44, 0x1000, v32
	v_mov_b32_e32 v45, v33
	v_cvt_pk_bf16_f32 v26, v26, s0
	v_lshl_add_u64 v[44:45], v[82:83], 0, v[44:45]
	v_or_b32_e32 v32, 0x1800, v32
	global_store_short v[44:45], v26, off
	v_cvt_pk_bf16_f32 v46, v27, s0
	v_lshl_add_u64 v[26:27], v[82:83], 0, v[32:33]
	v_or_b32_e32 v32, 56, v84
	v_mfma_f32_32x32x16_bf16 v[0:15], v[194:197], v[186:189], v[0:15]
	v_ashrrev_i32_e32 v33, 31, v32
	v_lshl_add_u64 v[32:33], s[20:21], 0, v[32:33]
	v_lshlrev_b64 v[32:33], 11, v[32:33]
	global_store_short v[26:27], v46, off
	v_cvt_pk_bf16_f32 v28, v28, s0
	v_lshl_add_u64 v[46:47], v[82:83], 0, v[32:33]
	global_store_short v[46:47], v28, off
	v_cvt_pk_bf16_f32 v48, v29, s0
	v_or_b32_e32 v28, 0x800, v32
	v_mov_b32_e32 v29, v33
	v_lshl_add_u64 v[28:29], v[82:83], 0, v[28:29]
	global_store_short v[28:29], v48, off
	v_or_b32_e32 v48, 0x1000, v32
	v_mov_b32_e32 v49, v33
	v_cvt_pk_bf16_f32 v30, v30, s0
	v_lshl_add_u64 v[48:49], v[82:83], 0, v[48:49]
	v_or_b32_e32 v32, 0x1800, v32
	global_store_short v[48:49], v30, off
	v_cvt_pk_bf16_f32 v50, v31, s0
	v_lshl_add_u64 v[30:31], v[82:83], 0, v[32:33]
	v_cvt_pk_bf16_f32 v0, v0, s0
	global_store_short v[30:31], v50, off
	global_store_short v[34:35], v0, off offset:64
	v_cvt_pk_bf16_f32 v0, v1, s0
	global_store_short v[16:17], v0, off offset:64
	v_cvt_pk_bf16_f32 v0, v2, s0
	global_store_short v[36:37], v0, off offset:64
	v_cvt_pk_bf16_f32 v0, v3, s0
	global_store_short v[18:19], v0, off offset:64
	v_cvt_pk_bf16_f32 v0, v4, s0
	global_store_short v[38:39], v0, off offset:64
	v_cvt_pk_bf16_f32 v0, v5, s0
	global_store_short v[20:21], v0, off offset:64
	v_cvt_pk_bf16_f32 v0, v6, s0
	global_store_short v[40:41], v0, off offset:64
	v_cvt_pk_bf16_f32 v0, v7, s0
	global_store_short v[22:23], v0, off offset:64
	v_cvt_pk_bf16_f32 v0, v8, s0
	global_store_short v[42:43], v0, off offset:64
	v_cvt_pk_bf16_f32 v0, v9, s0
	global_store_short v[24:25], v0, off offset:64
	v_cvt_pk_bf16_f32 v0, v10, s0
	global_store_short v[44:45], v0, off offset:64
	v_cvt_pk_bf16_f32 v0, v11, s0
	global_store_short v[26:27], v0, off offset:64
	v_cvt_pk_bf16_f32 v0, v12, s0
	global_store_short v[46:47], v0, off offset:64
	v_cvt_pk_bf16_f32 v0, v13, s0
	global_store_short v[28:29], v0, off offset:64
	v_cvt_pk_bf16_f32 v0, v14, s0
	global_store_short v[48:49], v0, off offset:64
	v_cvt_pk_bf16_f32 v0, v15, s0
	global_store_short v[30:31], v0, off offset:64
	s_waitcnt vmcnt(0)
	s_cbranch_scc0 .LBB0_95

; DEV int tid_l() { int t = threadIdx.x; asm volatile("" : "+v"(t)); return t; }
; DEV int stage_next(int s) { return (s == 2 * GS_STAGE) ? 0 : s + GS_STAGE; }
; template <int WAIT0>
; DEV void gk_main(f32x16 (&acc)[2][2], const GTile& t, int s0) {
;   const int tid = tid_l(), lane = tid & 63, wid = __builtin_amdgcn_readfirstlane(tid >> 6), wm = wid & 1, wn = wid >> 1, l32 = lane & 31, hi = lane >> 5;
;   GK_SRC(t)
;   const int sw = (l32 >> 1) & 7;
;   int xk[4], wk[4];
; #pragma unroll
;   for (int ks = 0; ks < 4; ++ks) { const int ko = ((2 * ks + hi) ^ sw) << 4; xk[ks] = GS_A + (64 * wm + l32) * 128 + ko; wk[ks] = GS_B + (64 * wn + l32) * 128 + ko; }
;   const int nk = t.K >> 6;
;     ...
;   vm_wait_bar<WAIT0>();
;   int stc = s0, std_ = stage_next(stage_next(s0));
; #pragma nounroll
;   for (int kt = 0; kt < nk - 2; ++kt) {
;     GK_DMA(std_, kt + 2);
;     GK_COMPUTE(stc);
;     vm_wait_bar<6>();
;     stc = stage_next(stc); std_ = stage_next(std_);
;   }
.LBB0_273:
	s_cmp_lg_u32 s2, 0
	s_cbranch_scc0 .LBB0_284
	s_bitcmp0_b32 s2, 0
	s_mov_b64 s[6:7], -1
	s_cbranch_scc1 .LBB0_278
	v_mov_b32_e32 v1, v176
	s_waitcnt vmcnt(22) lgkmcnt(0)
	s_barrier
	v_readfirstlane_b32 s3, v1
	s_ashr_i32 s6, s3, 6
	v_bfe_u32 v0, v1, 3, 3
	v_and_b32_e32 v2, 31, v1
	v_lshl_or_b32 v0, s6, 3, v0
	v_lshrrev_b32_e32 v3, 1, v0
	v_and_or_b32 v6, s3, 64, v2
	s_lshr_b32 s3, s3, 1
	v_xor_b32_e32 v3, v3, v1
	s_and_b32 s3, s3, 0x1ffffc0
	v_lshlrev_b32_e32 v3, 4, v3
	v_or_b32_e32 v2, s3, v2
	s_lshl_b32 s3, s6, 10
	v_and_b32_e32 v4, 0x70, v3
	v_bfe_u32 v3, v1, 5, 1
	v_lshrrev_b32_e32 v5, 1, v1
	v_bfe_u32 v1, v1, 1, 3
	s_add_i32 s10, s3, 0
	s_add_i32 s3, s9, 0xc000
	v_bitop3_b32 v5, v3, v5, 7 bitop3:0x78
	v_bitop3_b32 v7, v3, v1, 2 bitop3:0x36
	v_bitop3_b32 v8, v3, v1, 4 bitop3:0x36
	v_bitop3_b32 v1, v3, v1, 6 bitop3:0x36
	s_cmp_lg_u32 s9, 0x18000
	v_lshlrev_b32_e32 v2, 7, v2
	v_lshlrev_b32_e32 v5, 4, v5
	v_lshlrev_b32_e32 v7, 4, v7
	v_lshlrev_b32_e32 v8, 4, v8
	v_lshlrev_b32_e32 v1, 4, v1
	s_cselect_b32 s8, s3, 0
	s_add_i32 s3, s8, 0xc000
	s_waitcnt vmcnt(0)
	v_or_b32_e32 v83, v2, v5
	v_or_b32_e32 v81, v2, v7
	v_or_b32_e32 v79, v2, v8
	v_or_b32_e32 v77, v2, v1
	v_add_u32_e32 v2, 0xc0, v0
	s_cmp_lg_u32 s8, 0x18000
	v_ashrrev_i32_e32 v3, 31, v2
	s_cselect_b32 s11, s3, 0
	s_add_u32 s6, s4, 0x100
	v_lshlrev_b64 v[2:3], 11, v[2:3]
	s_addc_u32 s7, s5, 0
	v_or_b32_e32 v2, v2, v4
	v_lshl_add_u64 v[64:65], s[6:7], 0, v[2:3]
	v_add_u32_e32 v2, 0x80, v0
	v_ashrrev_i32_e32 v3, 31, v2
	v_lshlrev_b64 v[2:3], 11, v[2:3]
	v_or_b32_e32 v2, v2, v4
	v_lshlrev_b32_e32 v6, 7, v6
	v_lshl_add_u64 v[66:67], s[6:7], 0, v[2:3]
	v_add_u32_e32 v2, 64, v0
	v_or_b32_e32 v76, v1, v6
	v_ashrrev_i32_e32 v3, 31, v2
	v_ashrrev_i32_e32 v1, 31, v0
	v_lshlrev_b64 v[2:3], 11, v[2:3]
	v_lshlrev_b64 v[0:1], 11, v[0:1]
	v_or_b32_e32 v2, v2, v4
	v_or_b32_e32 v0, v0, v4
	v_lshl_add_u64 v[68:69], s[6:7], 0, v[2:3]
	v_lshl_add_u64 v[70:71], s[6:7], 0, v[0:1]
	v_readlane_b32 s6, v231, 15
	v_readlane_b32 s7, v231, 16
	v_or_b32_e32 v82, v5, v6
	v_or_b32_e32 v80, v7, v6
	v_lshl_add_u64 v[74:75], s[6:7], 0, v[0:1]
	v_mov_b32_e32 v0, 0
	v_or_b32_e32 v78, v8, v6
	v_lshl_add_u64 v[72:73], s[6:7], 0, v[2:3]
	s_mov_b64 s[6:7], 0
	s_mov_b32 s3, s9
	v_mov_b32_e32 v1, v0
	v_mov_b32_e32 v2, v0
	v_mov_b32_e32 v3, v0
	v_mov_b32_e32 v4, v0
	v_mov_b32_e32 v5, v0
	v_mov_b32_e32 v6, v0
	v_mov_b32_e32 v7, v0
	v_mov_b32_e32 v8, v0
	v_mov_b32_e32 v9, v0
	v_mov_b32_e32 v10, v0
	v_mov_b32_e32 v11, v0
	v_mov_b32_e32 v12, v0
	v_mov_b32_e32 v13, v0
	v_mov_b32_e32 v14, v0
	v_mov_b32_e32 v15, v0
	v_mov_b32_e32 v32, v0
	v_mov_b32_e32 v33, v0
	v_mov_b32_e32 v34, v0
	v_mov_b32_e32 v35, v0
	v_mov_b32_e32 v36, v0
	v_mov_b32_e32 v37, v0
	v_mov_b32_e32 v38, v0
	v_mov_b32_e32 v39, v0
	v_mov_b32_e32 v40, v0
	v_mov_b32_e32 v41, v0
	v_mov_b32_e32 v42, v0
	v_mov_b32_e32 v43, v0
	v_mov_b32_e32 v44, v0
	v_mov_b32_e32 v45, v0
	v_mov_b32_e32 v46, v0
	v_mov_b32_e32 v47, v0
	v_mov_b32_e32 v16, v0
	v_mov_b32_e32 v17, v0
	v_mov_b32_e32 v18, v0
	v_mov_b32_e32 v19, v0
	v_mov_b32_e32 v20, v0
	v_mov_b32_e32 v21, v0
	v_mov_b32_e32 v22, v0
	v_mov_b32_e32 v23, v0
	v_mov_b32_e32 v24, v0
	v_mov_b32_e32 v25, v0
	v_mov_b32_e32 v26, v0
	v_mov_b32_e32 v27, v0
	v_mov_b32_e32 v28, v0
	v_mov_b32_e32 v29, v0
	v_mov_b32_e32 v30, v0
	v_mov_b32_e32 v31, v0
	v_mov_b32_e32 v48, v0
	v_mov_b32_e32 v49, v0
	v_mov_b32_e32 v50, v0
	v_mov_b32_e32 v51, v0
	v_mov_b32_e32 v52, v0
	v_mov_b32_e32 v53, v0
	v_mov_b32_e32 v54, v0
	v_mov_b32_e32 v55, v0
	v_mov_b32_e32 v56, v0
	v_mov_b32_e32 v57, v0
	v_mov_b32_e32 v58, v0
	v_mov_b32_e32 v59, v0
	v_mov_b32_e32 v60, v0
	v_mov_b32_e32 v61, v0
	v_mov_b32_e32 v62, v0
	v_mov_b32_e32 v63, v0
	s_add_i32 s99, s3, 0
	v_add_u32_e32 v252, s99, v82
	v_add_u32_e32 v253, s99, v83
	ds_read_b128 v[84:87], v252
	ds_read_b128 v[88:91], v252 offset:4096
	ds_read_b128 v[92:95], v253 offset:16384
	ds_read_b128 v[96:99], v253 offset:20480
.LBB0_276:
	s_add_i32 s12, s10, s11
	s_mov_b32 s98, s12
	s_mov_b64 s[100:101], s[6:7]
	s_waitcnt lgkmcnt(0)
	v_add_u32_e32 v252, s99, v80
	v_add_u32_e32 v253, s99, v81
	ds_read_b128 v[236:239], v252
	ds_read_b128 v[240:243], v252 offset:4096
	ds_read_b128 v[244:247], v253 offset:16384
	ds_read_b128 v[248:251], v253 offset:20480
	v_mfma_f32_32x32x16_bf16 v[48:63], v[92:95], v[84:87], v[48:63]
	v_mfma_f32_32x32x16_bf16 v[16:31], v[92:95], v[88:91], v[16:31]
	s_mov_b32 m0, s98
	v_lshl_add_u64 v[254:255], v[74:75], 0, s[100:101]
	global_load_lds_dwordx4 v[254:255], off
	v_mfma_f32_32x32x16_bf16 v[32:47], v[96:99], v[84:87], v[32:47]
	v_mfma_f32_32x32x16_bf16 v[0:15], v[96:99], v[88:91], v[0:15]
	s_add_i32 m0, s98, 0x2000
	v_lshl_add_u64 v[254:255], v[72:73], 0, s[100:101]
	global_load_lds_dwordx4 v[254:255], off
	s_waitcnt lgkmcnt(0)
	v_add_u32_e32 v252, s99, v78
	v_add_u32_e32 v253, s99, v79
	ds_read_b128 v[84:87], v252
	ds_read_b128 v[88:91], v252 offset:4096
	ds_read_b128 v[92:95], v253 offset:16384
	ds_read_b128 v[96:99], v253 offset:20480
	v_mfma_f32_32x32x16_bf16 v[48:63], v[244:247], v[236:239], v[48:63]
	v_mfma_f32_32x32x16_bf16 v[16:31], v[244:247], v[240:243], v[16:31]
	s_add_i32 m0, s98, 0x4000
	v_lshl_add_u64 v[254:255], v[70:71], 0, s[100:101]
	global_load_lds_dwordx4 v[254:255], off
	v_mfma_f32_32x32x16_bf16 v[32:47], v[248:251], v[236:239], v[32:47]
	v_mfma_f32_32x32x16_bf16 v[0:15], v[248:251], v[240:243], v[0:15]
	s_add_i32 m0, s98, 0x6000
	v_lshl_add_u64 v[254:255], v[68:69], 0, s[100:101]
	global_load_lds_dwordx4 v[254:255], off
	s_waitcnt lgkmcnt(0)
	v_add_u32_e32 v252, s99, v76
	v_add_u32_e32 v253, s99, v77
	ds_read_b128 v[236:239], v252
	ds_read_b128 v[240:243], v252 offset:4096
	ds_read_b128 v[244:247], v253 offset:16384
	ds_read_b128 v[248:251], v253 offset:20480
	v_mfma_f32_32x32x16_bf16 v[48:63], v[92:95], v[84:87], v[48:63]
	v_mfma_f32_32x32x16_bf16 v[16:31], v[92:95], v[88:91], v[16:31]
	s_add_i32 m0, s98, 0x8000
	v_lshl_add_u64 v[254:255], v[66:67], 0, s[100:101]
	global_load_lds_dwordx4 v[254:255], off
	v_mfma_f32_32x32x16_bf16 v[32:47], v[96:99], v[84:87], v[32:47]
	v_mfma_f32_32x32x16_bf16 v[0:15], v[96:99], v[88:91], v[0:15]
	s_add_i32 m0, s98, 0xa000
	v_lshl_add_u64 v[254:255], v[64:65], 0, s[100:101]
	global_load_lds_dwordx4 v[254:255], off
	s_add_i32 s12, s3, 0xc000
	s_cmp_lg_u32 s3, 0x18000
	s_cselect_b32 s3, s12, 0
	s_waitcnt lgkmcnt(0)
	v_mfma_f32_32x32x16_bf16 v[48:63], v[244:247], v[236:239], v[48:63]
	s_add_i32 s12, s11, 0xc000
	s_cmp_lg_u32 s11, 0x18000
	s_waitcnt vmcnt(6) lgkmcnt(0)
	s_barrier
; DEV int stage_next(int s) { return (s == 2 * GS_STAGE) ? 0 : s + GS_STAGE; }
; template <int WAIT0>
; DEV void gk_main(f32x16 (&acc)[2][2], const GTile& t, int s0) {
;     ...
;   for (int kt = 0; kt < nk - 2; ++kt) {
;     GK_DMA(std_, kt + 2);
;     GK_COMPUTE(stc);
;     vm_wait_bar<6>();
;     stc = stage_next(stc); std_ = stage_next(std_);
;   }
;   GK_COMPUTE(stc);
;   vm_wait_bar<0>();
;   stc = stage_next(stc);
;   GK_COMPUTE(stc);
;   vm_wait_bar<0>();
	s_cselect_b32 s11, s12, 0
	s_add_u32 s6, s6, 0x80
	s_add_i32 s99, s3, 0
	v_add_u32_e32 v252, s99, v82
	v_add_u32_e32 v253, s99, v83
	ds_read_b128 v[84:87], v252
	ds_read_b128 v[88:91], v252 offset:4096
	ds_read_b128 v[92:95], v253 offset:16384
	ds_read_b128 v[96:99], v253 offset:20480
	v_mfma_f32_32x32x16_bf16 v[16:31], v[244:247], v[240:243], v[16:31]
	s_addc_u32 s7, s7, 0
	s_cmpk_lg_i32 s6, 0x700
	v_mfma_f32_32x32x16_bf16 v[32:47], v[248:251], v[236:239], v[32:47]
	v_mfma_f32_32x32x16_bf16 v[0:15], v[248:251], v[240:243], v[0:15]
	s_cbranch_scc1 .LBB0_276
	s_waitcnt lgkmcnt(0)
	s_add_i32 s6, s3, 0
	v_add_u32_e32 v84, s6, v83
	ds_read_b128 v[64:67], v84 offset:16384
	v_add_u32_e32 v72, s6, v82
	ds_read_b128 v[68:71], v72
	ds_read_b128 v[72:75], v72 offset:4096
	s_waitcnt lgkmcnt(0)
	v_mfma_f32_32x32x16_bf16 v[48:63], v[64:67], v[68:71], v[48:63]
	v_mfma_f32_32x32x16_bf16 v[16:31], v[64:67], v[72:75], v[16:31]
	ds_read_b128 v[64:67], v84 offset:20480
	v_add_u32_e32 v84, s6, v81
	s_waitcnt lgkmcnt(0)
	v_mfma_f32_32x32x16_bf16 v[32:47], v[64:67], v[68:71], v[32:47]
	v_mfma_f32_32x32x16_bf16 v[0:15], v[64:67], v[72:75], v[0:15]
	ds_read_b128 v[64:67], v84 offset:16384
	v_add_u32_e32 v72, s6, v80
	ds_read_b128 v[68:71], v72
	ds_read_b128 v[72:75], v72 offset:4096
	s_waitcnt lgkmcnt(0)
	v_mfma_f32_32x32x16_bf16 v[48:63], v[64:67], v[68:71], v[48:63]
	v_mfma_f32_32x32x16_bf16 v[16:31], v[64:67], v[72:75], v[16:31]
	ds_read_b128 v[64:67], v84 offset:20480
	v_add_u32_e32 v84, s6, v79
	s_waitcnt lgkmcnt(0)
	v_mfma_f32_32x32x16_bf16 v[32:47], v[64:67], v[68:71], v[32:47]
	v_mfma_f32_32x32x16_bf16 v[0:15], v[64:67], v[72:75], v[0:15]
	ds_read_b128 v[64:67], v84 offset:16384
	v_add_u32_e32 v72, s6, v78
	ds_read_b128 v[68:71], v72
	ds_read_b128 v[72:75], v72 offset:4096
	s_waitcnt lgkmcnt(0)
	v_mfma_f32_32x32x16_bf16 v[48:63], v[64:67], v[68:71], v[48:63]
	v_mfma_f32_32x32x16_bf16 v[16:31], v[64:67], v[72:75], v[16:31]
	ds_read_b128 v[64:67], v84 offset:20480
	v_add_u32_e32 v84, s6, v77
	s_waitcnt lgkmcnt(0)
	v_mfma_f32_32x32x16_bf16 v[32:47], v[64:67], v[68:71], v[32:47]
	v_mfma_f32_32x32x16_bf16 v[0:15], v[64:67], v[72:75], v[0:15]
	ds_read_b128 v[64:67], v84 offset:16384
	v_add_u32_e32 v72, s6, v76
	ds_read_b128 v[68:71], v72
	ds_read_b128 v[72:75], v72 offset:4096
	s_add_i32 s6, s3, 0xc000
	s_cmp_lg_u32 s3, 0x18000
	s_cselect_b32 s3, s6, 0
	s_waitcnt lgkmcnt(0)
	v_mfma_f32_32x32x16_bf16 v[48:63], v[64:67], v[68:71], v[48:63]
	s_add_i32 s3, s3, 0
	v_add_u32_e32 v83, s3, v83
	v_add_u32_e32 v81, s3, v81
	v_add_u32_e32 v79, s3, v79
	v_add_u32_e32 v77, s3, v77
	s_mov_b64 s[6:7], 0
	v_mfma_f32_32x32x16_bf16 v[16:31], v[64:67], v[72:75], v[16:31]
	ds_read_b128 v[64:67], v84 offset:20480
	s_waitcnt vmcnt(0) lgkmcnt(0)
	s_barrier
	s_waitcnt lgkmcnt(0)
	v_mfma_f32_32x32x16_bf16 v[32:47], v[64:67], v[68:71], v[32:47]
	v_mfma_f32_32x32x16_bf16 v[0:15], v[64:67], v[72:75], v[0:15]
	ds_read_b128 v[64:67], v83 offset:16384
	v_add_u32_e32 v72, s3, v82
	ds_read_b128 v[68:71], v72
	ds_read_b128 v[72:75], v72 offset:4096
	s_waitcnt lgkmcnt(0)
	v_mfma_f32_32x32x16_bf16 v[48:63], v[64:67], v[68:71], v[48:63]
	v_mfma_f32_32x32x16_bf16 v[16:31], v[64:67], v[72:75], v[16:31]
	ds_read_b128 v[64:67], v83 offset:20480
	s_waitcnt lgkmcnt(0)
	v_mfma_f32_32x32x16_bf16 v[32:47], v[64:67], v[68:71], v[32:47]
	v_mfma_f32_32x32x16_bf16 v[0:15], v[64:67], v[72:75], v[0:15]
	ds_read_b128 v[64:67], v81 offset:16384
	v_add_u32_e32 v72, s3, v80
	ds_read_b128 v[68:71], v72
	ds_read_b128 v[72:75], v72 offset:4096
	s_waitcnt lgkmcnt(0)
	v_mfma_f32_32x32x16_bf16 v[48:63], v[64:67], v[68:71], v[48:63]
	v_mfma_f32_32x32x16_bf16 v[16:31], v[64:67], v[72:75], v[16:31]
	ds_read_b128 v[64:67], v81 offset:20480
	s_waitcnt lgkmcnt(0)
	v_mfma_f32_32x32x16_bf16 v[32:47], v[64:67], v[68:71], v[32:47]
	v_mfma_f32_32x32x16_bf16 v[0:15], v[64:67], v[72:75], v[0:15]
	ds_read_b128 v[64:67], v79 offset:16384
	v_add_u32_e32 v72, s3, v78
	ds_read_b128 v[68:71], v72
	ds_read_b128 v[72:75], v72 offset:4096
	s_waitcnt lgkmcnt(0)
	v_mfma_f32_32x32x16_bf16 v[48:63], v[64:67], v[68:71], v[48:63]
	v_mfma_f32_32x32x16_bf16 v[16:31], v[64:67], v[72:75], v[16:31]
	ds_read_b128 v[64:67], v79 offset:20480
	s_waitcnt lgkmcnt(0)
	v_mfma_f32_32x32x16_bf16 v[32:47], v[64:67], v[68:71], v[32:47]
	v_mfma_f32_32x32x16_bf16 v[0:15], v[64:67], v[72:75], v[0:15]
	ds_read_b128 v[64:67], v77 offset:16384
	v_add_u32_e32 v72, s3, v76
	ds_read_b128 v[68:71], v72
	ds_read_b128 v[72:75], v72 offset:4096
	s_waitcnt lgkmcnt(0)
	v_mfma_f32_32x32x16_bf16 v[48:63], v[64:67], v[68:71], v[48:63]
	v_mfma_f32_32x32x16_bf16 v[16:31], v[64:67], v[72:75], v[16:31]
	ds_read_b128 v[64:67], v77 offset:20480
	s_waitcnt vmcnt(0) lgkmcnt(0)
	s_barrier
	s_waitcnt lgkmcnt(0)
	v_mfma_f32_32x32x16_bf16 v[32:47], v[64:67], v[68:71], v[32:47]
	v_mfma_f32_32x32x16_bf16 v[0:15], v[64:67], v[72:75], v[0:15]
; DEV int tid_l() { int t = threadIdx.x; asm volatile("" : "+v"(t)); return t; }
; DEV int stage_next(int s) { return (s == 2 * GS_STAGE) ? 0 : s + GS_STAGE; }
; template <int WAIT0>
; DEV void gk_main(f32x16 (&acc)[2][2], const GTile& t, int s0) {
;   const int tid = tid_l(), lane = tid & 63, wid = __builtin_amdgcn_readfirstlane(tid >> 6), wm = wid & 1, wn = wid >> 1, l32 = lane & 31, hi = lane >> 5;
;   GK_SRC(t)
;   const int sw = (l32 >> 1) & 7;
;   int xk[4], wk[4];
; #pragma unroll
;   for (int ks = 0; ks < 4; ++ks) { const int ko = ((2 * ks + hi) ^ sw) << 4; xk[ks] = GS_A + (64 * wm + l32) * 128 + ko; wk[ks] = GS_B + (64 * wn + l32) * 128 + ko; }
;   const int nk = t.K >> 6;
;     ...
;   vm_wait_bar<WAIT0>();
;   int stc = s0, std_ = stage_next(stage_next(s0));
; #pragma nounroll
;   for (int kt = 0; kt < nk - 2; ++kt) {
;     GK_DMA(std_, kt + 2);
;     GK_COMPUTE(stc);
;     vm_wait_bar<6>();
;     stc = stage_next(stc); std_ = stage_next(std_);
;   }
.LBB0_278:
	s_and_b64 vcc, exec, s[6:7]
	s_cbranch_vccz .LBB0_282
	s_nop 9
	v_mov_b32_e32 v1, v176
	s_waitcnt vmcnt(22) lgkmcnt(0)
	s_barrier
	v_readfirstlane_b32 s3, v1
	s_ashr_i32 s6, s3, 6
	v_bfe_u32 v0, v1, 3, 3
	v_and_b32_e32 v2, 31, v1
	v_lshl_or_b32 v0, s6, 3, v0
	v_lshrrev_b32_e32 v3, 1, v0
	v_and_or_b32 v6, s3, 64, v2
	s_lshr_b32 s3, s3, 1
	v_xor_b32_e32 v3, v3, v1
	s_and_b32 s3, s3, 0x1ffffc0
	v_lshlrev_b32_e32 v3, 4, v3
	v_or_b32_e32 v2, s3, v2
	s_lshl_b32 s3, s6, 10
	v_and_b32_e32 v4, 0x70, v3
	v_bfe_u32 v3, v1, 5, 1
	v_lshrrev_b32_e32 v5, 1, v1
	v_bfe_u32 v1, v1, 1, 3
	s_add_i32 s10, s3, 0
	s_add_i32 s3, s9, 0xc000
	v_bitop3_b32 v5, v3, v5, 7 bitop3:0x78
	v_bitop3_b32 v7, v3, v1, 2 bitop3:0x36
	v_bitop3_b32 v8, v3, v1, 4 bitop3:0x36
	v_bitop3_b32 v1, v3, v1, 6 bitop3:0x36
	s_cmp_lg_u32 s9, 0x18000
	v_lshlrev_b32_e32 v2, 7, v2
	v_lshlrev_b32_e32 v5, 4, v5
	v_lshlrev_b32_e32 v7, 4, v7
	v_lshlrev_b32_e32 v8, 4, v8
	v_lshlrev_b32_e32 v1, 4, v1
	s_cselect_b32 s8, s3, 0
	s_add_i32 s3, s8, 0xc000
	s_waitcnt vmcnt(0)
	v_or_b32_e32 v83, v2, v5
	v_or_b32_e32 v81, v2, v7
	v_or_b32_e32 v79, v2, v8
	v_or_b32_e32 v77, v2, v1
	v_add_u32_e32 v2, 0xc0, v0
	s_cmp_lg_u32 s8, 0x18000
	v_ashrrev_i32_e32 v3, 31, v2
	s_cselect_b32 s11, s3, 0
	s_add_u32 s6, s4, 0x100
	v_lshlrev_b64 v[2:3], 11, v[2:3]
	s_addc_u32 s7, s5, 0
	v_or_b32_e32 v2, v2, v4
	v_lshl_add_u64 v[64:65], s[6:7], 0, v[2:3]
	v_add_u32_e32 v2, 0x80, v0
	v_ashrrev_i32_e32 v3, 31, v2
	v_lshlrev_b64 v[2:3], 11, v[2:3]
	v_or_b32_e32 v2, v2, v4
	v_lshlrev_b32_e32 v6, 7, v6
	v_lshl_add_u64 v[66:67], s[6:7], 0, v[2:3]
	v_add_u32_e32 v2, 64, v0
	v_or_b32_e32 v76, v1, v6
	v_ashrrev_i32_e32 v3, 31, v2
	v_ashrrev_i32_e32 v1, 31, v0
	v_lshlrev_b64 v[2:3], 11, v[2:3]
	v_lshlrev_b64 v[0:1], 11, v[0:1]
	v_or_b32_e32 v2, v2, v4
	v_or_b32_e32 v0, v0, v4
	v_lshl_add_u64 v[68:69], s[6:7], 0, v[2:3]
	v_lshl_add_u64 v[70:71], s[6:7], 0, v[0:1]
	v_readlane_b32 s6, v231, 15
	v_readlane_b32 s7, v231, 16
	v_or_b32_e32 v82, v5, v6
	v_or_b32_e32 v80, v7, v6
	v_lshl_add_u64 v[74:75], s[6:7], 0, v[0:1]
	v_mov_b32_e32 v0, 0
	v_or_b32_e32 v78, v8, v6
	v_lshl_add_u64 v[72:73], s[6:7], 0, v[2:3]
	s_mov_b64 s[6:7], 0
	s_mov_b32 s3, s9
	v_mov_b32_e32 v1, v0
	v_mov_b32_e32 v2, v0
	v_mov_b32_e32 v3, v0
	v_mov_b32_e32 v4, v0
	v_mov_b32_e32 v5, v0
	v_mov_b32_e32 v6, v0
	v_mov_b32_e32 v7, v0
	v_mov_b32_e32 v8, v0
	v_mov_b32_e32 v9, v0
	v_mov_b32_e32 v10, v0
	v_mov_b32_e32 v11, v0
	v_mov_b32_e32 v12, v0
	v_mov_b32_e32 v13, v0
	v_mov_b32_e32 v14, v0
	v_mov_b32_e32 v15, v0
	v_mov_b32_e32 v32, v0
	v_mov_b32_e32 v33, v0
	v_mov_b32_e32 v34, v0
	v_mov_b32_e32 v35, v0
	v_mov_b32_e32 v36, v0
	v_mov_b32_e32 v37, v0
	v_mov_b32_e32 v38, v0
	v_mov_b32_e32 v39, v0
	v_mov_b32_e32 v40, v0
	v_mov_b32_e32 v41, v0
	v_mov_b32_e32 v42, v0
	v_mov_b32_e32 v43, v0
	v_mov_b32_e32 v44, v0
	v_mov_b32_e32 v45, v0
	v_mov_b32_e32 v46, v0
	v_mov_b32_e32 v47, v0
	v_mov_b32_e32 v16, v0
	v_mov_b32_e32 v17, v0
	v_mov_b32_e32 v18, v0
	v_mov_b32_e32 v19, v0
	v_mov_b32_e32 v20, v0
	v_mov_b32_e32 v21, v0
	v_mov_b32_e32 v22, v0
	v_mov_b32_e32 v23, v0
	v_mov_b32_e32 v24, v0
	v_mov_b32_e32 v25, v0
	v_mov_b32_e32 v26, v0
	v_mov_b32_e32 v27, v0
	v_mov_b32_e32 v28, v0
	v_mov_b32_e32 v29, v0
	v_mov_b32_e32 v30, v0
	v_mov_b32_e32 v31, v0
	v_mov_b32_e32 v48, v0
	v_mov_b32_e32 v49, v0
	v_mov_b32_e32 v50, v0
	v_mov_b32_e32 v51, v0
	v_mov_b32_e32 v52, v0
	v_mov_b32_e32 v53, v0
	v_mov_b32_e32 v54, v0
	v_mov_b32_e32 v55, v0
	v_mov_b32_e32 v56, v0
	v_mov_b32_e32 v57, v0
	v_mov_b32_e32 v58, v0
	v_mov_b32_e32 v59, v0
	v_mov_b32_e32 v60, v0
	v_mov_b32_e32 v61, v0
	v_mov_b32_e32 v62, v0
	v_mov_b32_e32 v63, v0
	s_add_i32 s99, s3, 0
	v_add_u32_e32 v252, s99, v82
	v_add_u32_e32 v253, s99, v83
	ds_read_b128 v[84:87], v252
	ds_read_b128 v[88:91], v252 offset:4096
	ds_read_b128 v[92:95], v253 offset:16384
	ds_read_b128 v[96:99], v253 offset:20480
.LBB0_280:
	s_add_i32 s12, s10, s11
	s_mov_b32 s98, s12
	s_mov_b64 s[100:101], s[6:7]
	s_waitcnt lgkmcnt(0)
	v_add_u32_e32 v252, s99, v80
	v_add_u32_e32 v253, s99, v81
	ds_read_b128 v[236:239], v252
	ds_read_b128 v[240:243], v252 offset:4096
	ds_read_b128 v[244:247], v253 offset:16384
	ds_read_b128 v[248:251], v253 offset:20480
	v_mfma_f32_32x32x16_bf16 v[48:63], v[92:95], v[84:87], v[48:63]
	v_mfma_f32_32x32x16_bf16 v[16:31], v[92:95], v[88:91], v[16:31]
	s_mov_b32 m0, s98
	v_lshl_add_u64 v[254:255], v[74:75], 0, s[100:101]
	global_load_lds_dwordx4 v[254:255], off
	v_mfma_f32_32x32x16_bf16 v[32:47], v[96:99], v[84:87], v[32:47]
	v_mfma_f32_32x32x16_bf16 v[0:15], v[96:99], v[88:91], v[0:15]
	s_add_i32 m0, s98, 0x2000
	v_lshl_add_u64 v[254:255], v[72:73], 0, s[100:101]
	global_load_lds_dwordx4 v[254:255], off
	s_waitcnt lgkmcnt(0)
	v_add_u32_e32 v252, s99, v78
	v_add_u32_e32 v253, s99, v79
	ds_read_b128 v[84:87], v252
	ds_read_b128 v[88:91], v252 offset:4096
	ds_read_b128 v[92:95], v253 offset:16384
	ds_read_b128 v[96:99], v253 offset:20480
	v_mfma_f32_32x32x16_bf16 v[48:63], v[244:247], v[236:239], v[48:63]
	v_mfma_f32_32x32x16_bf16 v[16:31], v[244:247], v[240:243], v[16:31]
	s_add_i32 m0, s98, 0x4000
	v_lshl_add_u64 v[254:255], v[70:71], 0, s[100:101]
	global_load_lds_dwordx4 v[254:255], off
	v_mfma_f32_32x32x16_bf16 v[32:47], v[248:251], v[236:239], v[32:47]
	v_mfma_f32_32x32x16_bf16 v[0:15], v[248:251], v[240:243], v[0:15]
	s_add_i32 m0, s98, 0x6000
	v_lshl_add_u64 v[254:255], v[68:69], 0, s[100:101]
	global_load_lds_dwordx4 v[254:255], off
	s_waitcnt lgkmcnt(0)
	v_add_u32_e32 v252, s99, v76
	v_add_u32_e32 v253, s99, v77
	ds_read_b128 v[236:239], v252
	ds_read_b128 v[240:243], v252 offset:4096
	ds_read_b128 v[244:247], v253 offset:16384
	ds_read_b128 v[248:251], v253 offset:20480
	v_mfma_f32_32x32x16_bf16 v[48:63], v[92:95], v[84:87], v[48:63]
	v_mfma_f32_32x32x16_bf16 v[16:31], v[92:95], v[88:91], v[16:31]
	s_add_i32 m0, s98, 0x8000
	v_lshl_add_u64 v[254:255], v[66:67], 0, s[100:101]
	global_load_lds_dwordx4 v[254:255], off
	v_mfma_f32_32x32x16_bf16 v[32:47], v[96:99], v[84:87], v[32:47]
	v_mfma_f32_32x32x16_bf16 v[0:15], v[96:99], v[88:91], v[0:15]
	s_add_i32 m0, s98, 0xa000
	v_lshl_add_u64 v[254:255], v[64:65], 0, s[100:101]
	global_load_lds_dwordx4 v[254:255], off
	s_add_i32 s12, s3, 0xc000
	s_cmp_lg_u32 s3, 0x18000
	s_cselect_b32 s3, s12, 0
	s_waitcnt lgkmcnt(0)
	v_mfma_f32_32x32x16_bf16 v[48:63], v[244:247], v[236:239], v[48:63]
	s_add_i32 s12, s11, 0xc000
	s_cmp_lg_u32 s11, 0x18000
	s_waitcnt vmcnt(6) lgkmcnt(0)
	s_barrier
; DEV int stage_next(int s) { return (s == 2 * GS_STAGE) ? 0 : s + GS_STAGE; }
; template <int WAIT0>
; DEV void gk_main(f32x16 (&acc)[2][2], const GTile& t, int s0) {
;     ...
;   for (int kt = 0; kt < nk - 2; ++kt) {
;     GK_DMA(std_, kt + 2);
;     GK_COMPUTE(stc);
;     vm_wait_bar<6>();
;     stc = stage_next(stc); std_ = stage_next(std_);
;   }
;   GK_COMPUTE(stc);
;   vm_wait_bar<0>();
;   stc = stage_next(stc);
;   GK_COMPUTE(stc);
;   vm_wait_bar<0>();
	s_cselect_b32 s11, s12, 0
	s_add_u32 s6, s6, 0x80
	s_add_i32 s99, s3, 0
	v_add_u32_e32 v252, s99, v82
	v_add_u32_e32 v253, s99, v83
	ds_read_b128 v[84:87], v252
	ds_read_b128 v[88:91], v252 offset:4096
	ds_read_b128 v[92:95], v253 offset:16384
	ds_read_b128 v[96:99], v253 offset:20480
	v_mfma_f32_32x32x16_bf16 v[16:31], v[244:247], v[240:243], v[16:31]
	s_addc_u32 s7, s7, 0
	s_cmpk_lg_i32 s6, 0x700
	v_mfma_f32_32x32x16_bf16 v[32:47], v[248:251], v[236:239], v[32:47]
	v_mfma_f32_32x32x16_bf16 v[0:15], v[248:251], v[240:243], v[0:15]
	s_cbranch_scc1 .LBB0_280
	s_waitcnt lgkmcnt(0)
	s_add_i32 s6, s3, 0
	v_add_u32_e32 v84, s6, v83
	ds_read_b128 v[64:67], v84 offset:16384
	v_add_u32_e32 v72, s6, v82
	ds_read_b128 v[68:71], v72
	ds_read_b128 v[72:75], v72 offset:4096
	s_waitcnt lgkmcnt(0)
	v_mfma_f32_32x32x16_bf16 v[48:63], v[64:67], v[68:71], v[48:63]
	v_mfma_f32_32x32x16_bf16 v[16:31], v[64:67], v[72:75], v[16:31]
	ds_read_b128 v[64:67], v84 offset:20480
	v_add_u32_e32 v84, s6, v81
	s_waitcnt lgkmcnt(0)
	v_mfma_f32_32x32x16_bf16 v[32:47], v[64:67], v[68:71], v[32:47]
	v_mfma_f32_32x32x16_bf16 v[0:15], v[64:67], v[72:75], v[0:15]
	ds_read_b128 v[64:67], v84 offset:16384
	v_add_u32_e32 v72, s6, v80
	ds_read_b128 v[68:71], v72
	ds_read_b128 v[72:75], v72 offset:4096
	s_waitcnt lgkmcnt(0)
	v_mfma_f32_32x32x16_bf16 v[48:63], v[64:67], v[68:71], v[48:63]
	v_mfma_f32_32x32x16_bf16 v[16:31], v[64:67], v[72:75], v[16:31]
	ds_read_b128 v[64:67], v84 offset:20480
	v_add_u32_e32 v84, s6, v79
	s_waitcnt lgkmcnt(0)
	v_mfma_f32_32x32x16_bf16 v[32:47], v[64:67], v[68:71], v[32:47]
	v_mfma_f32_32x32x16_bf16 v[0:15], v[64:67], v[72:75], v[0:15]
	ds_read_b128 v[64:67], v84 offset:16384
	v_add_u32_e32 v72, s6, v78
	ds_read_b128 v[68:71], v72
	ds_read_b128 v[72:75], v72 offset:4096
	s_waitcnt lgkmcnt(0)
	v_mfma_f32_32x32x16_bf16 v[48:63], v[64:67], v[68:71], v[48:63]
	v_mfma_f32_32x32x16_bf16 v[16:31], v[64:67], v[72:75], v[16:31]
	ds_read_b128 v[64:67], v84 offset:20480
	v_add_u32_e32 v84, s6, v77
	s_waitcnt lgkmcnt(0)
	v_mfma_f32_32x32x16_bf16 v[32:47], v[64:67], v[68:71], v[32:47]
	v_mfma_f32_32x32x16_bf16 v[0:15], v[64:67], v[72:75], v[0:15]
	ds_read_b128 v[64:67], v84 offset:16384
	v_add_u32_e32 v72, s6, v76
	ds_read_b128 v[68:71], v72
	ds_read_b128 v[72:75], v72 offset:4096
	s_add_i32 s6, s3, 0xc000
	s_cmp_lg_u32 s3, 0x18000
	s_cselect_b32 s3, s6, 0
	s_waitcnt lgkmcnt(0)
	v_mfma_f32_32x32x16_bf16 v[48:63], v[64:67], v[68:71], v[48:63]
	s_add_i32 s3, s3, 0
	v_add_u32_e32 v83, s3, v83
	v_add_u32_e32 v81, s3, v81
	v_add_u32_e32 v79, s3, v79
	v_add_u32_e32 v77, s3, v77
	v_mfma_f32_32x32x16_bf16 v[16:31], v[64:67], v[72:75], v[16:31]
	ds_read_b128 v[64:67], v84 offset:20480
	s_waitcnt vmcnt(0) lgkmcnt(0)
	s_barrier
	s_waitcnt lgkmcnt(0)
	v_mfma_f32_32x32x16_bf16 v[32:47], v[64:67], v[68:71], v[32:47]
	v_mfma_f32_32x32x16_bf16 v[0:15], v[64:67], v[72:75], v[0:15]
	ds_read_b128 v[64:67], v83 offset:16384
	v_add_u32_e32 v72, s3, v82
	ds_read_b128 v[68:71], v72
	ds_read_b128 v[72:75], v72 offset:4096
	s_waitcnt lgkmcnt(0)
	v_mfma_f32_32x32x16_bf16 v[48:63], v[64:67], v[68:71], v[48:63]
	v_mfma_f32_32x32x16_bf16 v[16:31], v[64:67], v[72:75], v[16:31]
	ds_read_b128 v[64:67], v83 offset:20480
	s_waitcnt lgkmcnt(0)
	v_mfma_f32_32x32x16_bf16 v[32:47], v[64:67], v[68:71], v[32:47]
	v_mfma_f32_32x32x16_bf16 v[0:15], v[64:67], v[72:75], v[0:15]
	ds_read_b128 v[64:67], v81 offset:16384
	v_add_u32_e32 v72, s3, v80
	ds_read_b128 v[68:71], v72
	ds_read_b128 v[72:75], v72 offset:4096
	s_waitcnt lgkmcnt(0)
	v_mfma_f32_32x32x16_bf16 v[48:63], v[64:67], v[68:71], v[48:63]
	v_mfma_f32_32x32x16_bf16 v[16:31], v[64:67], v[72:75], v[16:31]
	ds_read_b128 v[64:67], v81 offset:20480
	s_waitcnt lgkmcnt(0)
	v_mfma_f32_32x32x16_bf16 v[32:47], v[64:67], v[68:71], v[32:47]
	v_mfma_f32_32x32x16_bf16 v[0:15], v[64:67], v[72:75], v[0:15]
	ds_read_b128 v[64:67], v79 offset:16384
	v_add_u32_e32 v72, s3, v78
	ds_read_b128 v[68:71], v72
	ds_read_b128 v[72:75], v72 offset:4096
	s_waitcnt lgkmcnt(0)
	v_mfma_f32_32x32x16_bf16 v[48:63], v[64:67], v[68:71], v[48:63]
	v_mfma_f32_32x32x16_bf16 v[16:31], v[64:67], v[72:75], v[16:31]
	ds_read_b128 v[64:67], v79 offset:20480
	s_waitcnt lgkmcnt(0)
	v_mfma_f32_32x32x16_bf16 v[32:47], v[64:67], v[68:71], v[32:47]
	v_mfma_f32_32x32x16_bf16 v[0:15], v[64:67], v[72:75], v[0:15]
	ds_read_b128 v[64:67], v77 offset:16384
	v_add_u32_e32 v72, s3, v76
	ds_read_b128 v[68:71], v72
	ds_read_b128 v[72:75], v72 offset:4096
	s_waitcnt lgkmcnt(0)
	v_mfma_f32_32x32x16_bf16 v[48:63], v[64:67], v[68:71], v[48:63]
	v_mfma_f32_32x32x16_bf16 v[16:31], v[64:67], v[72:75], v[16:31]
	ds_read_b128 v[64:67], v77 offset:20480
	s_waitcnt vmcnt(0) lgkmcnt(0)
	s_barrier
	s_waitcnt lgkmcnt(0)
	v_mfma_f32_32x32x16_bf16 v[32:47], v[64:67], v[68:71], v[32:47]
	v_mfma_f32_32x32x16_bf16 v[0:15], v[64:67], v[72:75], v[0:15]

; DEV int tid_l() { int t = threadIdx.x; asm volatile("" : "+v"(t)); return t; }
; DEV int stage_next(int s) { return (s == 2 * GS_STAGE) ? 0 : s + GS_STAGE; }
; template <int WAIT0>
; DEV void gk_main(f32x16 (&acc)[2][2], const GTile& t, int s0) {
;   const int tid = tid_l(), lane = tid & 63, wid = __builtin_amdgcn_readfirstlane(tid >> 6), wm = wid & 1, wn = wid >> 1, l32 = lane & 31, hi = lane >> 5;
;   GK_SRC(t)
;   const int sw = (l32 >> 1) & 7;
;   int xk[4], wk[4];
; #pragma unroll
;   for (int ks = 0; ks < 4; ++ks) { const int ko = ((2 * ks + hi) ^ sw) << 4; xk[ks] = GS_A + (64 * wm + l32) * 128 + ko; wk[ks] = GS_B + (64 * wn + l32) * 128 + ko; }
;   const int nk = t.K >> 6;
;     ...
;   vm_wait_bar<WAIT0>();
;   int stc = s0, std_ = stage_next(stage_next(s0));
; #pragma nounroll
;   for (int kt = 0; kt < nk - 2; ++kt) {
;     GK_DMA(std_, kt + 2);
;     GK_COMPUTE(stc);
;     vm_wait_bar<6>();
;     stc = stage_next(stc); std_ = stage_next(std_);
;   }
.LBB0_284:
.LBB0_285:
	s_nop 10
	v_mov_b32_e32 v1, v176
	s_waitcnt vmcnt(6) lgkmcnt(0)
	s_barrier
	v_readfirstlane_b32 s3, v1
	s_ashr_i32 s6, s3, 6
	v_bfe_u32 v0, v1, 3, 3
	v_and_b32_e32 v2, 31, v1
	v_lshl_or_b32 v0, s6, 3, v0
	v_lshrrev_b32_e32 v3, 1, v0
	v_and_or_b32 v6, s3, 64, v2
	s_lshr_b32 s3, s3, 1
	v_xor_b32_e32 v3, v3, v1
	s_and_b32 s3, s3, 0x1ffffc0
	v_lshlrev_b32_e32 v3, 4, v3
	v_or_b32_e32 v2, s3, v2
	s_lshl_b32 s3, s6, 10
	v_and_b32_e32 v4, 0x70, v3
	v_bfe_u32 v3, v1, 5, 1
	v_lshrrev_b32_e32 v5, 1, v1
	v_bfe_u32 v1, v1, 1, 3
	s_add_i32 s10, s3, 0
	s_add_i32 s3, s9, 0xc000
	v_bitop3_b32 v5, v3, v5, 7 bitop3:0x78
	v_bitop3_b32 v7, v3, v1, 2 bitop3:0x36
	v_bitop3_b32 v8, v3, v1, 4 bitop3:0x36
	v_bitop3_b32 v1, v3, v1, 6 bitop3:0x36
	s_cmp_lg_u32 s9, 0x18000
	v_lshlrev_b32_e32 v2, 7, v2
	v_lshlrev_b32_e32 v5, 4, v5
	v_lshlrev_b32_e32 v7, 4, v7
	v_lshlrev_b32_e32 v8, 4, v8
	v_lshlrev_b32_e32 v1, 4, v1
	s_cselect_b32 s8, s3, 0
	s_add_i32 s3, s8, 0xc000
	s_waitcnt vmcnt(0)
	v_or_b32_e32 v83, v2, v5
	v_or_b32_e32 v81, v2, v7
	v_or_b32_e32 v79, v2, v8
	v_or_b32_e32 v77, v2, v1
	v_add_u32_e32 v2, 0xc0, v0
	s_cmp_lg_u32 s8, 0x18000
	v_ashrrev_i32_e32 v3, 31, v2
	s_cselect_b32 s11, s3, 0
	s_add_u32 s6, s4, 0x100
	v_lshlrev_b64 v[2:3], 11, v[2:3]
	s_addc_u32 s7, s5, 0
	v_or_b32_e32 v2, v2, v4
	v_lshl_add_u64 v[64:65], s[6:7], 0, v[2:3]
	v_add_u32_e32 v2, 0x80, v0
	v_ashrrev_i32_e32 v3, 31, v2
	v_lshlrev_b64 v[2:3], 11, v[2:3]
	v_or_b32_e32 v2, v2, v4
	v_lshlrev_b32_e32 v6, 7, v6
	v_lshl_add_u64 v[66:67], s[6:7], 0, v[2:3]
	v_add_u32_e32 v2, 64, v0
	v_or_b32_e32 v76, v1, v6
	v_ashrrev_i32_e32 v3, 31, v2
	v_ashrrev_i32_e32 v1, 31, v0
	v_lshlrev_b64 v[2:3], 11, v[2:3]
	v_lshlrev_b64 v[0:1], 11, v[0:1]
	v_or_b32_e32 v2, v2, v4
	v_or_b32_e32 v0, v0, v4
	v_lshl_add_u64 v[68:69], s[6:7], 0, v[2:3]
	v_lshl_add_u64 v[70:71], s[6:7], 0, v[0:1]
	v_readlane_b32 s6, v231, 15
	v_readlane_b32 s7, v231, 16
	v_or_b32_e32 v82, v5, v6
	v_or_b32_e32 v80, v7, v6
	v_lshl_add_u64 v[74:75], s[6:7], 0, v[0:1]
	v_mov_b32_e32 v0, 0
	v_or_b32_e32 v78, v8, v6
	v_lshl_add_u64 v[72:73], s[6:7], 0, v[2:3]
	s_mov_b64 s[6:7], 0
	s_mov_b32 s3, s9
	v_mov_b32_e32 v1, v0
	v_mov_b32_e32 v2, v0
	v_mov_b32_e32 v3, v0
	v_mov_b32_e32 v4, v0
	v_mov_b32_e32 v5, v0
	v_mov_b32_e32 v6, v0
	v_mov_b32_e32 v7, v0
	v_mov_b32_e32 v8, v0
	v_mov_b32_e32 v9, v0
	v_mov_b32_e32 v10, v0
	v_mov_b32_e32 v11, v0
	v_mov_b32_e32 v12, v0
	v_mov_b32_e32 v13, v0
	v_mov_b32_e32 v14, v0
	v_mov_b32_e32 v15, v0
	v_mov_b32_e32 v32, v0
	v_mov_b32_e32 v33, v0
	v_mov_b32_e32 v34, v0
	v_mov_b32_e32 v35, v0
	v_mov_b32_e32 v36, v0
	v_mov_b32_e32 v37, v0
	v_mov_b32_e32 v38, v0
	v_mov_b32_e32 v39, v0
	v_mov_b32_e32 v40, v0
	v_mov_b32_e32 v41, v0
	v_mov_b32_e32 v42, v0
	v_mov_b32_e32 v43, v0
	v_mov_b32_e32 v44, v0
	v_mov_b32_e32 v45, v0
	v_mov_b32_e32 v46, v0
	v_mov_b32_e32 v47, v0
	v_mov_b32_e32 v16, v0
	v_mov_b32_e32 v17, v0
	v_mov_b32_e32 v18, v0
	v_mov_b32_e32 v19, v0
	v_mov_b32_e32 v20, v0
	v_mov_b32_e32 v21, v0
	v_mov_b32_e32 v22, v0
	v_mov_b32_e32 v23, v0
	v_mov_b32_e32 v24, v0
	v_mov_b32_e32 v25, v0
	v_mov_b32_e32 v26, v0
	v_mov_b32_e32 v27, v0
	v_mov_b32_e32 v28, v0
	v_mov_b32_e32 v29, v0
	v_mov_b32_e32 v30, v0
	v_mov_b32_e32 v31, v0
	v_mov_b32_e32 v48, v0
	v_mov_b32_e32 v49, v0
	v_mov_b32_e32 v50, v0
	v_mov_b32_e32 v51, v0
	v_mov_b32_e32 v52, v0
	v_mov_b32_e32 v53, v0
	v_mov_b32_e32 v54, v0
	v_mov_b32_e32 v55, v0
	v_mov_b32_e32 v56, v0
	v_mov_b32_e32 v57, v0
	v_mov_b32_e32 v58, v0
	v_mov_b32_e32 v59, v0
	v_mov_b32_e32 v60, v0
	v_mov_b32_e32 v61, v0
	v_mov_b32_e32 v62, v0
	v_mov_b32_e32 v63, v0
	s_add_i32 s99, s3, 0
	v_add_u32_e32 v252, s99, v82
	v_add_u32_e32 v253, s99, v83
	ds_read_b128 v[84:87], v252
	ds_read_b128 v[88:91], v252 offset:4096
	ds_read_b128 v[92:95], v253 offset:16384
	ds_read_b128 v[96:99], v253 offset:20480
.LBB0_286:
	s_add_i32 s12, s10, s11
	s_mov_b32 s98, s12
	s_mov_b64 s[100:101], s[6:7]
	s_waitcnt lgkmcnt(0)
	v_add_u32_e32 v252, s99, v80
	v_add_u32_e32 v253, s99, v81
	ds_read_b128 v[236:239], v252
	ds_read_b128 v[240:243], v252 offset:4096
	ds_read_b128 v[244:247], v253 offset:16384
	ds_read_b128 v[248:251], v253 offset:20480
	v_mfma_f32_32x32x16_bf16 v[48:63], v[92:95], v[84:87], v[48:63]
	v_mfma_f32_32x32x16_bf16 v[16:31], v[92:95], v[88:91], v[16:31]
	s_mov_b32 m0, s98
	v_lshl_add_u64 v[254:255], v[74:75], 0, s[100:101]
	global_load_lds_dwordx4 v[254:255], off
	v_mfma_f32_32x32x16_bf16 v[32:47], v[96:99], v[84:87], v[32:47]
	v_mfma_f32_32x32x16_bf16 v[0:15], v[96:99], v[88:91], v[0:15]
	s_add_i32 m0, s98, 0x2000
	v_lshl_add_u64 v[254:255], v[72:73], 0, s[100:101]
	global_load_lds_dwordx4 v[254:255], off
	s_waitcnt lgkmcnt(0)
	v_add_u32_e32 v252, s99, v78
	v_add_u32_e32 v253, s99, v79
	ds_read_b128 v[84:87], v252
	ds_read_b128 v[88:91], v252 offset:4096
	ds_read_b128 v[92:95], v253 offset:16384
	ds_read_b128 v[96:99], v253 offset:20480
	v_mfma_f32_32x32x16_bf16 v[48:63], v[244:247], v[236:239], v[48:63]
	v_mfma_f32_32x32x16_bf16 v[16:31], v[244:247], v[240:243], v[16:31]
	s_add_i32 m0, s98, 0x4000
	v_lshl_add_u64 v[254:255], v[70:71], 0, s[100:101]
	global_load_lds_dwordx4 v[254:255], off
	v_mfma_f32_32x32x16_bf16 v[32:47], v[248:251], v[236:239], v[32:47]
	v_mfma_f32_32x32x16_bf16 v[0:15], v[248:251], v[240:243], v[0:15]
	s_add_i32 m0, s98, 0x6000
	v_lshl_add_u64 v[254:255], v[68:69], 0, s[100:101]
	global_load_lds_dwordx4 v[254:255], off
	s_waitcnt lgkmcnt(0)
	v_add_u32_e32 v252, s99, v76
	v_add_u32_e32 v253, s99, v77
	ds_read_b128 v[236:239], v252
	ds_read_b128 v[240:243], v252 offset:4096
	ds_read_b128 v[244:247], v253 offset:16384
	ds_read_b128 v[248:251], v253 offset:20480
	v_mfma_f32_32x32x16_bf16 v[48:63], v[92:95], v[84:87], v[48:63]
	v_mfma_f32_32x32x16_bf16 v[16:31], v[92:95], v[88:91], v[16:31]
	s_add_i32 m0, s98, 0x8000
	v_lshl_add_u64 v[254:255], v[66:67], 0, s[100:101]
	global_load_lds_dwordx4 v[254:255], off
	v_mfma_f32_32x32x16_bf16 v[32:47], v[96:99], v[84:87], v[32:47]
	v_mfma_f32_32x32x16_bf16 v[0:15], v[96:99], v[88:91], v[0:15]
	s_add_i32 m0, s98, 0xa000
	v_lshl_add_u64 v[254:255], v[64:65], 0, s[100:101]
	global_load_lds_dwordx4 v[254:255], off
	s_add_i32 s12, s3, 0xc000
	s_cmp_lg_u32 s3, 0x18000
	s_cselect_b32 s3, s12, 0
	s_waitcnt lgkmcnt(0)
	v_mfma_f32_32x32x16_bf16 v[48:63], v[244:247], v[236:239], v[48:63]
	s_add_i32 s12, s11, 0xc000
	s_cmp_lg_u32 s11, 0x18000
	s_waitcnt vmcnt(6) lgkmcnt(0)
	s_barrier
; DEV int stage_next(int s) { return (s == 2 * GS_STAGE) ? 0 : s + GS_STAGE; }
; template <int WAIT0>
; DEV void gk_main(f32x16 (&acc)[2][2], const GTile& t, int s0) {
;     ...
;   for (int kt = 0; kt < nk - 2; ++kt) {
;     GK_DMA(std_, kt + 2);
;     GK_COMPUTE(stc);
;     vm_wait_bar<6>();
;     stc = stage_next(stc); std_ = stage_next(std_);
;   }
;   GK_COMPUTE(stc);
;   vm_wait_bar<0>();
;   stc = stage_next(stc);
;   GK_COMPUTE(stc);
;   vm_wait_bar<0>();
; template <int WAIT_E, int WAIT_O, class TileFn, class EpiFn>
; DEV void gemm_seq(int ntiles, TileFn tf, EpiFn epi) {
;     ...
;   for (int i = 0; i < ntiles; ++i) {
;     f32x16 acc[2][2]; acc_zero(acc);
;     if (i == 0) gk_main<6>(acc, cur, s0);
;     else if (i & 1) gk_main<WAIT_O>(acc, cur, s0);
;     else gk_main<WAIT_E>(acc, cur, s0);
;     const int sn = stage_next(s0);
;     if (i + 1 < ntiles) { cur = tf(i + 1); gk_issue2(cur, sn); }
;     epi(i, acc, s0);
;     s0 = sn;
;   }
	s_cselect_b32 s11, s12, 0
	s_add_u32 s6, s6, 0x80
	s_add_i32 s99, s3, 0
	v_add_u32_e32 v252, s99, v82
	v_add_u32_e32 v253, s99, v83
	ds_read_b128 v[84:87], v252
	ds_read_b128 v[88:91], v252 offset:4096
	ds_read_b128 v[92:95], v253 offset:16384
	ds_read_b128 v[96:99], v253 offset:20480
	v_mfma_f32_32x32x16_bf16 v[16:31], v[244:247], v[240:243], v[16:31]
	s_addc_u32 s7, s7, 0
	s_cmpk_lg_i32 s6, 0x700
	v_mfma_f32_32x32x16_bf16 v[32:47], v[248:251], v[236:239], v[32:47]
	v_mfma_f32_32x32x16_bf16 v[0:15], v[248:251], v[240:243], v[0:15]
	s_cbranch_scc1 .LBB0_286
	s_waitcnt lgkmcnt(0)
	s_add_i32 s6, s3, 0
	v_add_u32_e32 v84, s6, v83
	ds_read_b128 v[64:67], v84 offset:16384
	v_add_u32_e32 v72, s6, v82
	ds_read_b128 v[68:71], v72
	ds_read_b128 v[72:75], v72 offset:4096
	s_waitcnt lgkmcnt(0)
	v_mfma_f32_32x32x16_bf16 v[48:63], v[64:67], v[68:71], v[48:63]
	v_mfma_f32_32x32x16_bf16 v[16:31], v[64:67], v[72:75], v[16:31]
	ds_read_b128 v[64:67], v84 offset:20480
	v_add_u32_e32 v84, s6, v81
	s_waitcnt lgkmcnt(0)
	v_mfma_f32_32x32x16_bf16 v[32:47], v[64:67], v[68:71], v[32:47]
	v_mfma_f32_32x32x16_bf16 v[0:15], v[64:67], v[72:75], v[0:15]
	ds_read_b128 v[64:67], v84 offset:16384
	v_add_u32_e32 v72, s6, v80
	ds_read_b128 v[68:71], v72
	ds_read_b128 v[72:75], v72 offset:4096
	s_waitcnt lgkmcnt(0)
	v_mfma_f32_32x32x16_bf16 v[48:63], v[64:67], v[68:71], v[48:63]
	v_mfma_f32_32x32x16_bf16 v[16:31], v[64:67], v[72:75], v[16:31]
	ds_read_b128 v[64:67], v84 offset:20480
	v_add_u32_e32 v84, s6, v79
	s_waitcnt lgkmcnt(0)
	v_mfma_f32_32x32x16_bf16 v[32:47], v[64:67], v[68:71], v[32:47]
	v_mfma_f32_32x32x16_bf16 v[0:15], v[64:67], v[72:75], v[0:15]
	ds_read_b128 v[64:67], v84 offset:16384
	v_add_u32_e32 v72, s6, v78
	ds_read_b128 v[68:71], v72
	ds_read_b128 v[72:75], v72 offset:4096
	s_waitcnt lgkmcnt(0)
	v_mfma_f32_32x32x16_bf16 v[48:63], v[64:67], v[68:71], v[48:63]
	v_mfma_f32_32x32x16_bf16 v[16:31], v[64:67], v[72:75], v[16:31]
	ds_read_b128 v[64:67], v84 offset:20480
	v_add_u32_e32 v84, s6, v77
	s_waitcnt lgkmcnt(0)
	v_mfma_f32_32x32x16_bf16 v[32:47], v[64:67], v[68:71], v[32:47]
	v_mfma_f32_32x32x16_bf16 v[0:15], v[64:67], v[72:75], v[0:15]
	ds_read_b128 v[64:67], v84 offset:16384
	v_add_u32_e32 v72, s6, v76
	ds_read_b128 v[68:71], v72
	ds_read_b128 v[72:75], v72 offset:4096
	s_add_i32 s6, s3, 0xc000
	s_cmp_lg_u32 s3, 0x18000
	s_cselect_b32 s3, s6, 0
	s_waitcnt lgkmcnt(0)
	v_mfma_f32_32x32x16_bf16 v[48:63], v[64:67], v[68:71], v[48:63]
	s_add_i32 s3, s3, 0
	v_add_u32_e32 v83, s3, v83
	v_add_u32_e32 v81, s3, v81
	v_add_u32_e32 v79, s3, v79
	v_add_u32_e32 v77, s3, v77
	v_mfma_f32_32x32x16_bf16 v[16:31], v[64:67], v[72:75], v[16:31]
	ds_read_b128 v[64:67], v84 offset:20480
	s_waitcnt vmcnt(0) lgkmcnt(0)
	s_barrier
	s_waitcnt lgkmcnt(0)
	v_mfma_f32_32x32x16_bf16 v[32:47], v[64:67], v[68:71], v[32:47]
	v_mfma_f32_32x32x16_bf16 v[0:15], v[64:67], v[72:75], v[0:15]
	ds_read_b128 v[64:67], v83 offset:16384
	v_add_u32_e32 v72, s3, v82
	ds_read_b128 v[68:71], v72
	ds_read_b128 v[72:75], v72 offset:4096
	s_waitcnt lgkmcnt(0)
	v_mfma_f32_32x32x16_bf16 v[48:63], v[64:67], v[68:71], v[48:63]
	v_mfma_f32_32x32x16_bf16 v[16:31], v[64:67], v[72:75], v[16:31]
	ds_read_b128 v[64:67], v83 offset:20480
	s_waitcnt lgkmcnt(0)
	v_mfma_f32_32x32x16_bf16 v[32:47], v[64:67], v[68:71], v[32:47]
	v_mfma_f32_32x32x16_bf16 v[0:15], v[64:67], v[72:75], v[0:15]
	ds_read_b128 v[64:67], v81 offset:16384
	v_add_u32_e32 v72, s3, v80
	ds_read_b128 v[68:71], v72
	ds_read_b128 v[72:75], v72 offset:4096
	s_waitcnt lgkmcnt(0)
	v_mfma_f32_32x32x16_bf16 v[48:63], v[64:67], v[68:71], v[48:63]
	v_mfma_f32_32x32x16_bf16 v[16:31], v[64:67], v[72:75], v[16:31]
	ds_read_b128 v[64:67], v81 offset:20480
	s_waitcnt lgkmcnt(0)
	v_mfma_f32_32x32x16_bf16 v[32:47], v[64:67], v[68:71], v[32:47]
	v_mfma_f32_32x32x16_bf16 v[0:15], v[64:67], v[72:75], v[0:15]
	ds_read_b128 v[64:67], v79 offset:16384
	v_add_u32_e32 v72, s3, v78
	ds_read_b128 v[68:71], v72
	ds_read_b128 v[72:75], v72 offset:4096
	s_waitcnt lgkmcnt(0)
	v_mfma_f32_32x32x16_bf16 v[48:63], v[64:67], v[68:71], v[48:63]
	v_mfma_f32_32x32x16_bf16 v[16:31], v[64:67], v[72:75], v[16:31]
	ds_read_b128 v[64:67], v79 offset:20480
	s_waitcnt lgkmcnt(0)
	v_mfma_f32_32x32x16_bf16 v[32:47], v[64:67], v[68:71], v[32:47]
	v_mfma_f32_32x32x16_bf16 v[0:15], v[64:67], v[72:75], v[0:15]
	ds_read_b128 v[64:67], v77 offset:16384
	v_add_u32_e32 v72, s3, v76
	ds_read_b128 v[68:71], v72
	ds_read_b128 v[72:75], v72 offset:4096
	s_waitcnt lgkmcnt(0)
	v_mfma_f32_32x32x16_bf16 v[48:63], v[64:67], v[68:71], v[48:63]
	v_mfma_f32_32x32x16_bf16 v[16:31], v[64:67], v[72:75], v[16:31]
	ds_read_b128 v[64:67], v77 offset:20480
	s_waitcnt vmcnt(0) lgkmcnt(0)
	s_barrier
	s_waitcnt lgkmcnt(0)
	v_mfma_f32_32x32x16_bf16 v[32:47], v[64:67], v[68:71], v[32:47]
	v_mfma_f32_32x32x16_bf16 v[0:15], v[64:67], v[72:75], v[0:15]
	s_add_i32 s3, s2, 1
	s_cmp_eq_u32 s2, 3
	s_cbranch_scc1 .LBB0_272

; DEV int tid_l() { int t = threadIdx.x; asm volatile("" : "+v"(t)); return t; }
; DEV int stage_next(int s) { return (s == 2 * GS_STAGE) ? 0 : s + GS_STAGE; }
; template <int WAIT0>
; DEV void gk_main(f32x16 (&acc)[2][2], const GTile& t, int s0) {
;   const int tid = tid_l(), lane = tid & 63, wid = __builtin_amdgcn_readfirstlane(tid >> 6), wm = wid & 1, wn = wid >> 1, l32 = lane & 31, hi = lane >> 5;
;   GK_SRC(t)
;   const int sw = (l32 >> 1) & 7;
;   int xk[4], wk[4];
; #pragma unroll
;   for (int ks = 0; ks < 4; ++ks) { const int ko = ((2 * ks + hi) ^ sw) << 4; xk[ks] = GS_A + (64 * wm + l32) * 128 + ko; wk[ks] = GS_B + (64 * wn + l32) * 128 + ko; }
;   const int nk = t.K >> 6;
;     ...
;   vm_wait_bar<WAIT0>();
;   int stc = s0, std_ = stage_next(stage_next(s0));
.LBB0_400:
	s_cmp_lg_u32 s19, 0
	s_cbranch_scc0 .LBB0_413
	s_bitcmp0_b32 s19, 0
	s_mov_b64 s[8:9], -1
	s_cbranch_scc1 .LBB0_405
	v_mov_b32_e32 v0, v176
	s_add_i32 s8, s18, 0xc000
	v_readfirstlane_b32 s2, v0
	v_and_b32_e32 v1, 31, v0
	s_ashr_i32 s3, s2, 6
	v_and_or_b32 v7, s2, 64, v1
	s_lshr_b32 s2, s2, 1
	s_and_b32 s2, s2, 0x1ffffc0
	v_bfe_u32 v2, v0, 3, 3
	v_or_b32_e32 v1, s2, v1
	s_lshl_b32 s2, s3, 10
	v_lshl_or_b32 v4, s3, 3, v2
	s_add_i32 s3, s2, 0
	s_lshr_b32 s2, s16, 6
	s_cmp_lg_u32 s18, 0x18000
	s_cselect_b32 s17, s8, 0
	s_add_i32 s8, s17, 0xc000
	v_lshrrev_b32_e32 v2, 1, v4
	v_bfe_u32 v3, v0, 5, 1
	v_lshrrev_b32_e32 v5, 1, v0
	v_bfe_u32 v6, v0, 1, 3
	s_cmp_lg_u32 s17, 0x18000
	v_bitop3_b32 v5, v3, v5, 7 bitop3:0x78
	v_bitop3_b32 v8, v3, v6, 2 bitop3:0x36
	v_bitop3_b32 v9, v3, v6, 4 bitop3:0x36
	v_bitop3_b32 v3, v3, v6, 6 bitop3:0x36
	s_cselect_b32 s8, s8, 0
	s_add_i32 s9, s2, -2
	v_bitop3_b32 v0, v2, 7, v0 bitop3:0x48
	v_lshlrev_b32_e32 v1, 7, v1
	v_lshlrev_b32_e32 v5, 4, v5
	v_lshlrev_b32_e32 v8, 4, v8
	v_lshlrev_b32_e32 v9, 4, v9
	v_lshlrev_b32_e32 v3, 4, v3
	v_lshlrev_b32_e32 v120, 4, v0
	s_add_u32 s10, s6, 0x100
	v_add_u32_e32 v0, 0xc0, v4
	v_lshlrev_b32_e32 v7, 7, v7
	v_or_b32_e32 v83, v1, v5
	v_or_b32_e32 v81, v1, v8
	v_or_b32_e32 v79, v1, v9
	v_or_b32_e32 v77, v1, v3
	s_addc_u32 s11, s7, 0
	v_ashrrev_i32_e32 v1, 31, v0
	v_or_b32_e32 v76, v3, v7
	v_alignbit_b32 v3, v1, v0, 31
	v_lshlrev_b32_e32 v2, 1, v0
	v_mov_b64_e32 v[0:1], s[10:11]
	v_mad_u64_u32 v[64:65], s[10:11], v2, s16, v[0:1]
	v_mov_b32_e32 v2, v65
	v_mad_u64_u32 v[2:3], s[10:11], v3, s16, v[2:3]
	v_mov_b32_e32 v65, v2
	v_add_u32_e32 v2, 0x80, v4
	v_ashrrev_i32_e32 v3, 31, v2
	v_alignbit_b32 v3, v3, v2, 31
	v_lshlrev_b32_e32 v2, 1, v2
	v_mad_u64_u32 v[66:67], s[10:11], v2, s16, v[0:1]
	v_mov_b32_e32 v2, v67
	v_mad_u64_u32 v[2:3], s[10:11], v3, s16, v[2:3]
	v_add_u32_e32 v3, 64, v4
	v_lshlrev_b32_e32 v6, 1, v3
	v_or_b32_e32 v82, v5, v7
	v_ashrrev_i32_e32 v5, 31, v3
	v_mad_u64_u32 v[68:69], s[10:11], v6, s16, v[0:1]
	v_mov_b32_e32 v67, v2
	v_mov_b32_e32 v2, v69
	v_alignbit_b32 v5, v5, v3, 31
	v_or_b32_e32 v80, v8, v7
	v_or_b32_e32 v78, v9, v7
	v_mad_u64_u32 v[2:3], s[10:11], v5, s16, v[2:3]
	v_lshlrev_b32_e32 v7, 1, v4
	v_mov_b32_e32 v69, v2
	v_ashrrev_i32_e32 v2, 31, v4
	v_mad_u64_u32 v[70:71], s[10:11], v7, s16, v[0:1]
	v_mov_b32_e32 v0, v71
	v_alignbit_b32 v4, v2, v4, 31
	v_mad_u64_u32 v[0:1], s[10:11], v4, s16, v[0:1]
	s_add_u32 s10, s4, 0x100
	s_addc_u32 s11, s5, 0
	v_mov_b32_e32 v71, v0
	v_mov_b64_e32 v[0:1], s[10:11]
	v_mad_u64_u32 v[74:75], s[10:11], v7, s16, v[0:1]
	v_mad_u64_u32 v[72:73], s[10:11], v6, s16, v[0:1]
	v_mov_b32_e32 v0, v75
	s_waitcnt vmcnt(6) lgkmcnt(0)
	s_barrier
	v_mov_b32_e32 v2, v73
	v_mad_u64_u32 v[0:1], s[10:11], v4, s16, v[0:1]
	v_mad_u64_u32 v[2:3], s[10:11], v5, s16, v[2:3]
	v_mov_b32_e32 v75, v0
	v_mov_b32_e32 v0, 0
	v_mov_b32_e32 v73, v2
	s_mov_b32 s2, s18
	v_mov_b32_e32 v1, v0
	v_mov_b32_e32 v2, v0
	v_mov_b32_e32 v3, v0
	v_mov_b32_e32 v4, v0
	v_mov_b32_e32 v5, v0
	v_mov_b32_e32 v6, v0
	v_mov_b32_e32 v7, v0
	v_mov_b32_e32 v8, v0
	v_mov_b32_e32 v9, v0
	v_mov_b32_e32 v10, v0
	v_mov_b32_e32 v11, v0
	v_mov_b32_e32 v12, v0
	v_mov_b32_e32 v13, v0
	v_mov_b32_e32 v14, v0
	v_mov_b32_e32 v15, v0
	v_mov_b32_e32 v16, v0
	v_mov_b32_e32 v17, v0
	v_mov_b32_e32 v18, v0
	v_mov_b32_e32 v19, v0
	v_mov_b32_e32 v20, v0
	v_mov_b32_e32 v21, v0
	v_mov_b32_e32 v22, v0
	v_mov_b32_e32 v23, v0
	v_mov_b32_e32 v24, v0
	v_mov_b32_e32 v25, v0
	v_mov_b32_e32 v26, v0
	v_mov_b32_e32 v27, v0
	v_mov_b32_e32 v28, v0
	v_mov_b32_e32 v29, v0
	v_mov_b32_e32 v30, v0
	v_mov_b32_e32 v31, v0
	v_mov_b32_e32 v32, v0
	v_mov_b32_e32 v33, v0
	v_mov_b32_e32 v34, v0
	v_mov_b32_e32 v35, v0
	v_mov_b32_e32 v36, v0
	v_mov_b32_e32 v37, v0
	v_mov_b32_e32 v38, v0
	v_mov_b32_e32 v39, v0
	v_mov_b32_e32 v40, v0
	v_mov_b32_e32 v41, v0
	v_mov_b32_e32 v42, v0
	v_mov_b32_e32 v43, v0
	v_mov_b32_e32 v44, v0
	v_mov_b32_e32 v45, v0
	v_mov_b32_e32 v46, v0
	v_mov_b32_e32 v47, v0
	v_mov_b32_e32 v48, v0
	v_mov_b32_e32 v49, v0
	v_mov_b32_e32 v50, v0
	v_mov_b32_e32 v51, v0
	v_mov_b32_e32 v52, v0
	v_mov_b32_e32 v53, v0
	v_mov_b32_e32 v54, v0
	v_mov_b32_e32 v55, v0
	v_mov_b32_e32 v56, v0
	v_mov_b32_e32 v57, v0
	v_mov_b32_e32 v58, v0
	v_mov_b32_e32 v59, v0
	v_mov_b32_e32 v60, v0
	v_mov_b32_e32 v61, v0
	v_mov_b32_e32 v62, v0
	v_mov_b32_e32 v63, v0
	s_add_i32 s99, s2, 0
	v_add_u32_e32 v252, s99, v82
	v_add_u32_e32 v253, s99, v83
	ds_read_b128 v[84:87], v252
	ds_read_b128 v[88:91], v252 offset:4096
	ds_read_b128 v[92:95], v253 offset:16384
	ds_read_b128 v[96:99], v253 offset:20480
; DEV int stage_next(int s) { return (s == 2 * GS_STAGE) ? 0 : s + GS_STAGE; }
; template <int WAIT0>
; DEV void gk_main(f32x16 (&acc)[2][2], const GTile& t, int s0) {
;     ...
;   for (int kt = 0; kt < nk - 2; ++kt) {
;     GK_DMA(std_, kt + 2);
;     GK_COMPUTE(stc);
;     vm_wait_bar<6>();
;     stc = stage_next(stc); std_ = stage_next(std_);
;   }
;   GK_COMPUTE(stc);
;   vm_wait_bar<0>();
;   stc = stage_next(stc);
;   GK_COMPUTE(stc);
;   vm_wait_bar<0>();
.LBB0_403:
	s_add_i32 s10, s3, s8
	s_mov_b32 s98, s10
	s_waitcnt lgkmcnt(0)
	v_add_u32_e32 v252, s99, v80
	v_add_u32_e32 v253, s99, v81
	ds_read_b128 v[236:239], v252
	ds_read_b128 v[240:243], v252 offset:4096
	ds_read_b128 v[244:247], v253 offset:16384
	ds_read_b128 v[248:251], v253 offset:20480
	v_mfma_f32_32x32x16_bf16 v[48:63], v[92:95], v[84:87], v[48:63]
	v_mfma_f32_32x32x16_bf16 v[32:47], v[92:95], v[88:91], v[32:47]
	s_mov_b32 m0, s98
	v_lshl_add_u64 v[254:255], v[74:75], 0, v[120:121]
	global_load_lds_dwordx4 v[254:255], off
	v_lshl_add_u64 v[74:75], v[74:75], 0, s[96:97]
	v_mfma_f32_32x32x16_bf16 v[16:31], v[96:99], v[84:87], v[16:31]
	v_mfma_f32_32x32x16_bf16 v[0:15], v[96:99], v[88:91], v[0:15]
	s_add_i32 m0, s98, 0x2000
	v_lshl_add_u64 v[254:255], v[72:73], 0, v[120:121]
	global_load_lds_dwordx4 v[254:255], off
	v_lshl_add_u64 v[72:73], v[72:73], 0, s[96:97]
	s_waitcnt lgkmcnt(0)
	v_add_u32_e32 v252, s99, v78
	v_add_u32_e32 v253, s99, v79
	ds_read_b128 v[84:87], v252
	ds_read_b128 v[88:91], v252 offset:4096
	ds_read_b128 v[92:95], v253 offset:16384
	ds_read_b128 v[96:99], v253 offset:20480
	v_mfma_f32_32x32x16_bf16 v[48:63], v[244:247], v[236:239], v[48:63]
	v_mfma_f32_32x32x16_bf16 v[32:47], v[244:247], v[240:243], v[32:47]
	s_add_i32 m0, s98, 0x4000
	v_lshl_add_u64 v[254:255], v[70:71], 0, v[120:121]
	global_load_lds_dwordx4 v[254:255], off
	v_lshl_add_u64 v[70:71], v[70:71], 0, s[96:97]
	v_mfma_f32_32x32x16_bf16 v[16:31], v[248:251], v[236:239], v[16:31]
	v_mfma_f32_32x32x16_bf16 v[0:15], v[248:251], v[240:243], v[0:15]
	s_add_i32 m0, s98, 0x6000
	v_lshl_add_u64 v[254:255], v[68:69], 0, v[120:121]
	global_load_lds_dwordx4 v[254:255], off
	v_lshl_add_u64 v[68:69], v[68:69], 0, s[96:97]
	s_waitcnt lgkmcnt(0)
	v_add_u32_e32 v252, s99, v76
	v_add_u32_e32 v253, s99, v77
	ds_read_b128 v[236:239], v252
	ds_read_b128 v[240:243], v252 offset:4096
	ds_read_b128 v[244:247], v253 offset:16384
	ds_read_b128 v[248:251], v253 offset:20480
	v_mfma_f32_32x32x16_bf16 v[48:63], v[92:95], v[84:87], v[48:63]
	v_mfma_f32_32x32x16_bf16 v[32:47], v[92:95], v[88:91], v[32:47]
	s_add_i32 m0, s98, 0x8000
	v_lshl_add_u64 v[254:255], v[66:67], 0, v[120:121]
	global_load_lds_dwordx4 v[254:255], off
	v_lshl_add_u64 v[66:67], v[66:67], 0, s[96:97]
	v_mfma_f32_32x32x16_bf16 v[16:31], v[96:99], v[84:87], v[16:31]
	v_mfma_f32_32x32x16_bf16 v[0:15], v[96:99], v[88:91], v[0:15]
	s_add_i32 m0, s98, 0xa000
	v_lshl_add_u64 v[254:255], v[64:65], 0, v[120:121]
	global_load_lds_dwordx4 v[254:255], off
	v_lshl_add_u64 v[64:65], v[64:65], 0, s[96:97]
	s_add_i32 s10, s2, 0xc000
	s_cmp_lg_u32 s2, 0x18000
	s_cselect_b32 s2, s10, 0
	s_waitcnt lgkmcnt(0)
	v_mfma_f32_32x32x16_bf16 v[48:63], v[244:247], v[236:239], v[48:63]
	s_add_i32 s10, s8, 0xc000
	s_waitcnt vmcnt(6) lgkmcnt(0)
	s_barrier
	s_cmp_lg_u32 s8, 0x18000
	s_cselect_b32 s8, s10, 0
	s_add_i32 s9, s9, -1
	s_add_i32 s99, s2, 0
	v_add_u32_e32 v252, s99, v82
	v_add_u32_e32 v253, s99, v83
	ds_read_b128 v[84:87], v252
	ds_read_b128 v[88:91], v252 offset:4096
	ds_read_b128 v[92:95], v253 offset:16384
	ds_read_b128 v[96:99], v253 offset:20480
	v_mfma_f32_32x32x16_bf16 v[32:47], v[244:247], v[240:243], v[32:47]
	s_cmp_lg_u32 s9, 0
	v_mfma_f32_32x32x16_bf16 v[16:31], v[248:251], v[236:239], v[16:31]
	v_mfma_f32_32x32x16_bf16 v[0:15], v[248:251], v[240:243], v[0:15]
	s_cbranch_scc1 .LBB0_403
	s_waitcnt lgkmcnt(0)
	s_add_i32 s3, s2, 0
	v_add_u32_e32 v84, s3, v83
	ds_read_b128 v[64:67], v84 offset:16384
	v_add_u32_e32 v72, s3, v82
	ds_read_b128 v[68:71], v72
	ds_read_b128 v[72:75], v72 offset:4096
	s_mov_b64 s[8:9], 0
	s_waitcnt lgkmcnt(0)
	v_mfma_f32_32x32x16_bf16 v[48:63], v[64:67], v[68:71], v[48:63]
	v_mfma_f32_32x32x16_bf16 v[32:47], v[64:67], v[72:75], v[32:47]
	ds_read_b128 v[64:67], v84 offset:20480
	v_add_u32_e32 v84, s3, v81
	s_waitcnt lgkmcnt(0)
	v_mfma_f32_32x32x16_bf16 v[16:31], v[64:67], v[68:71], v[16:31]
	v_mfma_f32_32x32x16_bf16 v[0:15], v[64:67], v[72:75], v[0:15]
	ds_read_b128 v[64:67], v84 offset:16384
	v_add_u32_e32 v72, s3, v80
	ds_read_b128 v[68:71], v72
	ds_read_b128 v[72:75], v72 offset:4096
	s_waitcnt lgkmcnt(0)
	v_mfma_f32_32x32x16_bf16 v[48:63], v[64:67], v[68:71], v[48:63]
	v_mfma_f32_32x32x16_bf16 v[32:47], v[64:67], v[72:75], v[32:47]
	ds_read_b128 v[64:67], v84 offset:20480
	v_add_u32_e32 v84, s3, v79
	s_waitcnt lgkmcnt(0)
	v_mfma_f32_32x32x16_bf16 v[16:31], v[64:67], v[68:71], v[16:31]
	v_mfma_f32_32x32x16_bf16 v[0:15], v[64:67], v[72:75], v[0:15]
	ds_read_b128 v[64:67], v84 offset:16384
	v_add_u32_e32 v72, s3, v78
	ds_read_b128 v[68:71], v72
	ds_read_b128 v[72:75], v72 offset:4096
	s_waitcnt lgkmcnt(0)
	v_mfma_f32_32x32x16_bf16 v[48:63], v[64:67], v[68:71], v[48:63]
	v_mfma_f32_32x32x16_bf16 v[32:47], v[64:67], v[72:75], v[32:47]
	ds_read_b128 v[64:67], v84 offset:20480
	v_add_u32_e32 v84, s3, v77
	s_waitcnt lgkmcnt(0)
	v_mfma_f32_32x32x16_bf16 v[16:31], v[64:67], v[68:71], v[16:31]
	v_mfma_f32_32x32x16_bf16 v[0:15], v[64:67], v[72:75], v[0:15]
	ds_read_b128 v[64:67], v84 offset:16384
	v_add_u32_e32 v72, s3, v76
	ds_read_b128 v[68:71], v72
	ds_read_b128 v[72:75], v72 offset:4096
	s_add_i32 s3, s2, 0xc000
	s_cmp_lg_u32 s2, 0x18000
	s_cselect_b32 s2, s3, 0
	s_waitcnt lgkmcnt(0)
	v_mfma_f32_32x32x16_bf16 v[48:63], v[64:67], v[68:71], v[48:63]
	s_add_i32 s2, s2, 0
	v_add_u32_e32 v83, s2, v83
	v_add_u32_e32 v81, s2, v81
	v_add_u32_e32 v79, s2, v79
	v_add_u32_e32 v77, s2, v77
	v_mfma_f32_32x32x16_bf16 v[32:47], v[64:67], v[72:75], v[32:47]
	ds_read_b128 v[64:67], v84 offset:20480
	s_waitcnt vmcnt(0) lgkmcnt(0)
	s_barrier
; DEV int tid_l() { int t = threadIdx.x; asm volatile("" : "+v"(t)); return t; }
; DEV int stage_next(int s) { return (s == 2 * GS_STAGE) ? 0 : s + GS_STAGE; }
; DEV void gk_issue2(const GTile& t, int s0) {
;   const int tid = tid_l(), lane = tid & 63, wid = __builtin_amdgcn_readfirstlane(tid >> 6);
;   GK_SRC(t)
;   asm volatile("" ::: "memory");
;   GK_DMA(s0, 0);
;   GK_DMA(stage_next(s0), 1);
;   asm volatile("" ::: "memory");
; }
; template <int WAIT0>
; DEV void gk_main(f32x16 (&acc)[2][2], const GTile& t, int s0) {
;   const int tid = tid_l(), lane = tid & 63, wid = __builtin_amdgcn_readfirstlane(tid >> 6), wm = wid & 1, wn = wid >> 1, l32 = lane & 31, hi = lane >> 5;
;   GK_SRC(t)
;   const int sw = (l32 >> 1) & 7;
;   int xk[4], wk[4];
; #pragma unroll
;   for (int ks = 0; ks < 4; ++ks) { const int ko = ((2 * ks + hi) ^ sw) << 4; xk[ks] = GS_A + (64 * wm + l32) * 128 + ko; wk[ks] = GS_B + (64 * wn + l32) * 128 + ko; }
;   const int nk = t.K >> 6;
;     ...
;   vm_wait_bar<WAIT0>();
;   int stc = s0, std_ = stage_next(stage_next(s0));
;     ...
;   GK_COMPUTE(stc);
;   vm_wait_bar<0>();
;   stc = stage_next(stc);
;   GK_COMPUTE(stc);
;   vm_wait_bar<0>();
	s_waitcnt lgkmcnt(0)
	v_mfma_f32_32x32x16_bf16 v[16:31], v[64:67], v[68:71], v[16:31]
	v_mfma_f32_32x32x16_bf16 v[0:15], v[64:67], v[72:75], v[0:15]
	ds_read_b128 v[64:67], v83 offset:16384
	v_add_u32_e32 v72, s2, v82
	ds_read_b128 v[68:71], v72
	ds_read_b128 v[72:75], v72 offset:4096
	s_waitcnt lgkmcnt(0)
	v_mfma_f32_32x32x16_bf16 v[48:63], v[64:67], v[68:71], v[48:63]
	v_mfma_f32_32x32x16_bf16 v[32:47], v[64:67], v[72:75], v[32:47]
	ds_read_b128 v[64:67], v83 offset:20480
	s_waitcnt lgkmcnt(0)
	v_mfma_f32_32x32x16_bf16 v[16:31], v[64:67], v[68:71], v[16:31]
	v_mfma_f32_32x32x16_bf16 v[0:15], v[64:67], v[72:75], v[0:15]
	ds_read_b128 v[64:67], v81 offset:16384
	v_add_u32_e32 v72, s2, v80
	ds_read_b128 v[68:71], v72
	ds_read_b128 v[72:75], v72 offset:4096
	s_waitcnt lgkmcnt(0)
	v_mfma_f32_32x32x16_bf16 v[48:63], v[64:67], v[68:71], v[48:63]
	v_mfma_f32_32x32x16_bf16 v[32:47], v[64:67], v[72:75], v[32:47]
	ds_read_b128 v[64:67], v81 offset:20480
	s_waitcnt lgkmcnt(0)
	v_mfma_f32_32x32x16_bf16 v[16:31], v[64:67], v[68:71], v[16:31]
	v_mfma_f32_32x32x16_bf16 v[0:15], v[64:67], v[72:75], v[0:15]
	ds_read_b128 v[64:67], v79 offset:16384
	v_add_u32_e32 v72, s2, v78
	ds_read_b128 v[68:71], v72
	ds_read_b128 v[72:75], v72 offset:4096
	s_waitcnt lgkmcnt(0)
	v_mfma_f32_32x32x16_bf16 v[48:63], v[64:67], v[68:71], v[48:63]
	v_mfma_f32_32x32x16_bf16 v[32:47], v[64:67], v[72:75], v[32:47]
	ds_read_b128 v[64:67], v79 offset:20480
	s_waitcnt lgkmcnt(0)
	v_mfma_f32_32x32x16_bf16 v[16:31], v[64:67], v[68:71], v[16:31]
	v_mfma_f32_32x32x16_bf16 v[0:15], v[64:67], v[72:75], v[0:15]
	ds_read_b128 v[64:67], v77 offset:16384
	v_add_u32_e32 v72, s2, v76
	ds_read_b128 v[68:71], v72
	ds_read_b128 v[72:75], v72 offset:4096
	s_waitcnt lgkmcnt(0)
	v_mfma_f32_32x32x16_bf16 v[48:63], v[64:67], v[68:71], v[48:63]
	v_mfma_f32_32x32x16_bf16 v[32:47], v[64:67], v[72:75], v[32:47]
	ds_read_b128 v[64:67], v77 offset:20480
	s_waitcnt vmcnt(0) lgkmcnt(0)
	s_barrier
	s_waitcnt lgkmcnt(0)
	v_mfma_f32_32x32x16_bf16 v[16:31], v[64:67], v[68:71], v[16:31]
	v_mfma_f32_32x32x16_bf16 v[0:15], v[64:67], v[72:75], v[0:15]
.LBB0_405:
	s_and_b64 vcc, exec, s[8:9]
	s_cbranch_vccz .LBB0_409
	s_nop 9
	v_mov_b32_e32 v0, v176
	s_add_i32 s8, s18, 0xc000
	v_readfirstlane_b32 s2, v0
	v_and_b32_e32 v1, 31, v0
	s_ashr_i32 s3, s2, 6
	v_and_or_b32 v7, s2, 64, v1
	s_lshr_b32 s2, s2, 1
	s_and_b32 s2, s2, 0x1ffffc0
	v_bfe_u32 v2, v0, 3, 3
	v_or_b32_e32 v1, s2, v1
	s_lshl_b32 s2, s3, 10
	v_lshl_or_b32 v4, s3, 3, v2
	s_add_i32 s3, s2, 0
	s_lshr_b32 s2, s16, 6
	s_cmp_lg_u32 s18, 0x18000
	s_cselect_b32 s17, s8, 0
	s_add_i32 s8, s17, 0xc000
	v_lshrrev_b32_e32 v2, 1, v4
	v_bfe_u32 v3, v0, 5, 1
	v_lshrrev_b32_e32 v5, 1, v0
	v_bfe_u32 v6, v0, 1, 3
	s_cmp_lg_u32 s17, 0x18000
	v_bitop3_b32 v5, v3, v5, 7 bitop3:0x78
	v_bitop3_b32 v8, v3, v6, 2 bitop3:0x36
	v_bitop3_b32 v9, v3, v6, 4 bitop3:0x36
	v_bitop3_b32 v3, v3, v6, 6 bitop3:0x36
	s_cselect_b32 s8, s8, 0
	s_add_i32 s9, s2, -2
	v_bitop3_b32 v0, v2, 7, v0 bitop3:0x48
	v_lshlrev_b32_e32 v1, 7, v1
	v_lshlrev_b32_e32 v5, 4, v5
	v_lshlrev_b32_e32 v8, 4, v8
	v_lshlrev_b32_e32 v9, 4, v9
	v_lshlrev_b32_e32 v3, 4, v3
	v_lshlrev_b32_e32 v120, 4, v0
	s_add_u32 s10, s6, 0x100
	v_add_u32_e32 v0, 0xc0, v4
	v_lshlrev_b32_e32 v7, 7, v7
	v_or_b32_e32 v83, v1, v5
	v_or_b32_e32 v81, v1, v8
	v_or_b32_e32 v79, v1, v9
	v_or_b32_e32 v77, v1, v3
	s_addc_u32 s11, s7, 0
	v_ashrrev_i32_e32 v1, 31, v0
	v_or_b32_e32 v76, v3, v7
	v_alignbit_b32 v3, v1, v0, 31
	v_lshlrev_b32_e32 v2, 1, v0
	v_mov_b64_e32 v[0:1], s[10:11]
	v_mad_u64_u32 v[64:65], s[10:11], v2, s16, v[0:1]
	v_mov_b32_e32 v2, v65
	v_mad_u64_u32 v[2:3], s[10:11], v3, s16, v[2:3]
	v_mov_b32_e32 v65, v2
	v_add_u32_e32 v2, 0x80, v4
	v_ashrrev_i32_e32 v3, 31, v2
	v_alignbit_b32 v3, v3, v2, 31
	v_lshlrev_b32_e32 v2, 1, v2
	v_mad_u64_u32 v[66:67], s[10:11], v2, s16, v[0:1]
	v_mov_b32_e32 v2, v67
	v_mad_u64_u32 v[2:3], s[10:11], v3, s16, v[2:3]
	v_add_u32_e32 v3, 64, v4
	v_lshlrev_b32_e32 v6, 1, v3
	v_or_b32_e32 v82, v5, v7
	v_ashrrev_i32_e32 v5, 31, v3
	v_mad_u64_u32 v[68:69], s[10:11], v6, s16, v[0:1]
	v_mov_b32_e32 v67, v2
	v_mov_b32_e32 v2, v69
	v_alignbit_b32 v5, v5, v3, 31
	v_or_b32_e32 v80, v8, v7
	v_or_b32_e32 v78, v9, v7
	v_mad_u64_u32 v[2:3], s[10:11], v5, s16, v[2:3]
	v_lshlrev_b32_e32 v7, 1, v4
	v_mov_b32_e32 v69, v2
	v_ashrrev_i32_e32 v2, 31, v4
	v_mad_u64_u32 v[70:71], s[10:11], v7, s16, v[0:1]
	v_mov_b32_e32 v0, v71
	v_alignbit_b32 v4, v2, v4, 31
	v_mad_u64_u32 v[0:1], s[10:11], v4, s16, v[0:1]
	s_add_u32 s10, s4, 0x100
	s_addc_u32 s11, s5, 0
	v_mov_b32_e32 v71, v0
	v_mov_b64_e32 v[0:1], s[10:11]
	v_mad_u64_u32 v[74:75], s[10:11], v7, s16, v[0:1]
	v_mad_u64_u32 v[72:73], s[10:11], v6, s16, v[0:1]
	v_mov_b32_e32 v0, v75
	s_waitcnt vmcnt(22) lgkmcnt(0)
	s_barrier
	v_mov_b32_e32 v2, v73
	v_mad_u64_u32 v[0:1], s[10:11], v4, s16, v[0:1]
	v_mad_u64_u32 v[2:3], s[10:11], v5, s16, v[2:3]
	v_mov_b32_e32 v75, v0
	v_mov_b32_e32 v0, 0
	v_mov_b32_e32 v73, v2
	s_mov_b32 s2, s18
	v_mov_b32_e32 v1, v0
	v_mov_b32_e32 v2, v0
	v_mov_b32_e32 v3, v0
	v_mov_b32_e32 v4, v0
	v_mov_b32_e32 v5, v0
	v_mov_b32_e32 v6, v0
	v_mov_b32_e32 v7, v0
	v_mov_b32_e32 v8, v0
	v_mov_b32_e32 v9, v0
	v_mov_b32_e32 v10, v0
	v_mov_b32_e32 v11, v0
	v_mov_b32_e32 v12, v0
	v_mov_b32_e32 v13, v0
	v_mov_b32_e32 v14, v0
	v_mov_b32_e32 v15, v0
	v_mov_b32_e32 v16, v0
	v_mov_b32_e32 v17, v0
	v_mov_b32_e32 v18, v0
	v_mov_b32_e32 v19, v0
	v_mov_b32_e32 v20, v0
	v_mov_b32_e32 v21, v0
	v_mov_b32_e32 v22, v0
	v_mov_b32_e32 v23, v0
	v_mov_b32_e32 v24, v0
	v_mov_b32_e32 v25, v0
	v_mov_b32_e32 v26, v0
	v_mov_b32_e32 v27, v0
	v_mov_b32_e32 v28, v0
	v_mov_b32_e32 v29, v0
	v_mov_b32_e32 v30, v0
	v_mov_b32_e32 v31, v0
	v_mov_b32_e32 v32, v0
	v_mov_b32_e32 v33, v0
	v_mov_b32_e32 v34, v0
	v_mov_b32_e32 v35, v0
	v_mov_b32_e32 v36, v0
	v_mov_b32_e32 v37, v0
	v_mov_b32_e32 v38, v0
	v_mov_b32_e32 v39, v0
	v_mov_b32_e32 v40, v0
	v_mov_b32_e32 v41, v0
	v_mov_b32_e32 v42, v0
	v_mov_b32_e32 v43, v0
	v_mov_b32_e32 v44, v0
	v_mov_b32_e32 v45, v0
	v_mov_b32_e32 v46, v0
	v_mov_b32_e32 v47, v0
	v_mov_b32_e32 v48, v0
	v_mov_b32_e32 v49, v0
	v_mov_b32_e32 v50, v0
	v_mov_b32_e32 v51, v0
	v_mov_b32_e32 v52, v0
	v_mov_b32_e32 v53, v0
	v_mov_b32_e32 v54, v0
	v_mov_b32_e32 v55, v0
	v_mov_b32_e32 v56, v0
	v_mov_b32_e32 v57, v0
	v_mov_b32_e32 v58, v0
	v_mov_b32_e32 v59, v0
	v_mov_b32_e32 v60, v0
	v_mov_b32_e32 v61, v0
	v_mov_b32_e32 v62, v0
	v_mov_b32_e32 v63, v0
	s_add_i32 s99, s2, 0
	v_add_u32_e32 v252, s99, v82
	v_add_u32_e32 v253, s99, v83
	ds_read_b128 v[84:87], v252
	ds_read_b128 v[88:91], v252 offset:4096
	ds_read_b128 v[92:95], v253 offset:16384
	ds_read_b128 v[96:99], v253 offset:20480
; DEV int tid_l() { int t = threadIdx.x; asm volatile("" : "+v"(t)); return t; }
; DEV int stage_next(int s) { return (s == 2 * GS_STAGE) ? 0 : s + GS_STAGE; }
; DEV void gk_issue2(const GTile& t, int s0) {
;   const int tid = tid_l(), lane = tid & 63, wid = __builtin_amdgcn_readfirstlane(tid >> 6);
;   GK_SRC(t)
;   asm volatile("" ::: "memory");
;   GK_DMA(s0, 0);
;   GK_DMA(stage_next(s0), 1);
;   asm volatile("" ::: "memory");
; }
; template <int WAIT0>
; DEV void gk_main(f32x16 (&acc)[2][2], const GTile& t, int s0) {
;   const int tid = tid_l(), lane = tid & 63, wid = __builtin_amdgcn_readfirstlane(tid >> 6), wm = wid & 1, wn = wid >> 1, l32 = lane & 31, hi = lane >> 5;
;   GK_SRC(t)
;   const int sw = (l32 >> 1) & 7;
;   int xk[4], wk[4];
; #pragma unroll
;   for (int ks = 0; ks < 4; ++ks) { const int ko = ((2 * ks + hi) ^ sw) << 4; xk[ks] = GS_A + (64 * wm + l32) * 128 + ko; wk[ks] = GS_B + (64 * wn + l32) * 128 + ko; }
;   const int nk = t.K >> 6;
;     ...
;   vm_wait_bar<WAIT0>();
;   int stc = s0, std_ = stage_next(stage_next(s0));
; #pragma nounroll
;   for (int kt = 0; kt < nk - 2; ++kt) {
;     GK_DMA(std_, kt + 2);
;     GK_COMPUTE(stc);
;     vm_wait_bar<6>();
;     stc = stage_next(stc); std_ = stage_next(std_);
;   }
.LBB0_407:
	s_add_i32 s10, s3, s8
	s_mov_b32 s98, s10
	s_waitcnt lgkmcnt(0)
	v_add_u32_e32 v252, s99, v80
	v_add_u32_e32 v253, s99, v81
	ds_read_b128 v[236:239], v252
	ds_read_b128 v[240:243], v252 offset:4096
	ds_read_b128 v[244:247], v253 offset:16384
	ds_read_b128 v[248:251], v253 offset:20480
	v_mfma_f32_32x32x16_bf16 v[48:63], v[92:95], v[84:87], v[48:63]
	v_mfma_f32_32x32x16_bf16 v[32:47], v[92:95], v[88:91], v[32:47]
	s_mov_b32 m0, s98
	v_lshl_add_u64 v[254:255], v[74:75], 0, v[120:121]
	global_load_lds_dwordx4 v[254:255], off
	v_lshl_add_u64 v[74:75], v[74:75], 0, s[96:97]
	v_mfma_f32_32x32x16_bf16 v[16:31], v[96:99], v[84:87], v[16:31]
	v_mfma_f32_32x32x16_bf16 v[0:15], v[96:99], v[88:91], v[0:15]
	s_add_i32 m0, s98, 0x2000
	v_lshl_add_u64 v[254:255], v[72:73], 0, v[120:121]
	global_load_lds_dwordx4 v[254:255], off
	v_lshl_add_u64 v[72:73], v[72:73], 0, s[96:97]
	s_waitcnt lgkmcnt(0)
	v_add_u32_e32 v252, s99, v78
	v_add_u32_e32 v253, s99, v79
	ds_read_b128 v[84:87], v252
	ds_read_b128 v[88:91], v252 offset:4096
	ds_read_b128 v[92:95], v253 offset:16384
	ds_read_b128 v[96:99], v253 offset:20480
	v_mfma_f32_32x32x16_bf16 v[48:63], v[244:247], v[236:239], v[48:63]
	v_mfma_f32_32x32x16_bf16 v[32:47], v[244:247], v[240:243], v[32:47]
	s_add_i32 m0, s98, 0x4000
	v_lshl_add_u64 v[254:255], v[70:71], 0, v[120:121]
	global_load_lds_dwordx4 v[254:255], off
	v_lshl_add_u64 v[70:71], v[70:71], 0, s[96:97]
	v_mfma_f32_32x32x16_bf16 v[16:31], v[248:251], v[236:239], v[16:31]
	v_mfma_f32_32x32x16_bf16 v[0:15], v[248:251], v[240:243], v[0:15]
	s_add_i32 m0, s98, 0x6000
	v_lshl_add_u64 v[254:255], v[68:69], 0, v[120:121]
	global_load_lds_dwordx4 v[254:255], off
	v_lshl_add_u64 v[68:69], v[68:69], 0, s[96:97]
	s_waitcnt lgkmcnt(0)
	v_add_u32_e32 v252, s99, v76
	v_add_u32_e32 v253, s99, v77
	ds_read_b128 v[236:239], v252
	ds_read_b128 v[240:243], v252 offset:4096
	ds_read_b128 v[244:247], v253 offset:16384
	ds_read_b128 v[248:251], v253 offset:20480
	v_mfma_f32_32x32x16_bf16 v[48:63], v[92:95], v[84:87], v[48:63]
	v_mfma_f32_32x32x16_bf16 v[32:47], v[92:95], v[88:91], v[32:47]
	s_add_i32 m0, s98, 0x8000
	v_lshl_add_u64 v[254:255], v[66:67], 0, v[120:121]
	global_load_lds_dwordx4 v[254:255], off
	v_lshl_add_u64 v[66:67], v[66:67], 0, s[96:97]
	v_mfma_f32_32x32x16_bf16 v[16:31], v[96:99], v[84:87], v[16:31]
	v_mfma_f32_32x32x16_bf16 v[0:15], v[96:99], v[88:91], v[0:15]
	s_add_i32 m0, s98, 0xa000
	v_lshl_add_u64 v[254:255], v[64:65], 0, v[120:121]
	global_load_lds_dwordx4 v[254:255], off
	v_lshl_add_u64 v[64:65], v[64:65], 0, s[96:97]
	s_add_i32 s10, s2, 0xc000
	s_cmp_lg_u32 s2, 0x18000
	s_cselect_b32 s2, s10, 0
	s_waitcnt lgkmcnt(0)
	v_mfma_f32_32x32x16_bf16 v[48:63], v[244:247], v[236:239], v[48:63]
	s_add_i32 s10, s8, 0xc000
	s_waitcnt vmcnt(6) lgkmcnt(0)
	s_barrier
	s_cmp_lg_u32 s8, 0x18000
	s_cselect_b32 s8, s10, 0
	s_add_i32 s9, s9, -1
	s_add_i32 s99, s2, 0
	v_add_u32_e32 v252, s99, v82
	v_add_u32_e32 v253, s99, v83
	ds_read_b128 v[84:87], v252
	ds_read_b128 v[88:91], v252 offset:4096
	ds_read_b128 v[92:95], v253 offset:16384
	ds_read_b128 v[96:99], v253 offset:20480
	v_mfma_f32_32x32x16_bf16 v[32:47], v[244:247], v[240:243], v[32:47]
	s_cmp_lg_u32 s9, 0
	v_mfma_f32_32x32x16_bf16 v[16:31], v[248:251], v[236:239], v[16:31]
	v_mfma_f32_32x32x16_bf16 v[0:15], v[248:251], v[240:243], v[0:15]
	s_cbranch_scc1 .LBB0_407
; DEV int stage_next(int s) { return (s == 2 * GS_STAGE) ? 0 : s + GS_STAGE; }
; template <int WAIT0>
; DEV void gk_main(f32x16 (&acc)[2][2], const GTile& t, int s0) {
;     ...
;   vm_wait_bar<WAIT0>();
;   int stc = s0, std_ = stage_next(stage_next(s0));
; #pragma nounroll
;   for (int kt = 0; kt < nk - 2; ++kt) {
;     GK_DMA(std_, kt + 2);
;     GK_COMPUTE(stc);
;     vm_wait_bar<6>();
;     stc = stage_next(stc); std_ = stage_next(std_);
;   }
;   GK_COMPUTE(stc);
;   vm_wait_bar<0>();
;   stc = stage_next(stc);
;   GK_COMPUTE(stc);
;   vm_wait_bar<0>();
	s_waitcnt lgkmcnt(0)
	s_add_i32 s3, s2, 0
	v_add_u32_e32 v84, s3, v83
	ds_read_b128 v[64:67], v84 offset:16384
	v_add_u32_e32 v72, s3, v82
	ds_read_b128 v[68:71], v72
	ds_read_b128 v[72:75], v72 offset:4096
	s_waitcnt lgkmcnt(0)
	v_mfma_f32_32x32x16_bf16 v[48:63], v[64:67], v[68:71], v[48:63]
	v_mfma_f32_32x32x16_bf16 v[32:47], v[64:67], v[72:75], v[32:47]
	ds_read_b128 v[64:67], v84 offset:20480
	v_add_u32_e32 v84, s3, v81
	s_waitcnt lgkmcnt(0)
	v_mfma_f32_32x32x16_bf16 v[16:31], v[64:67], v[68:71], v[16:31]
	v_mfma_f32_32x32x16_bf16 v[0:15], v[64:67], v[72:75], v[0:15]
	ds_read_b128 v[64:67], v84 offset:16384
	v_add_u32_e32 v72, s3, v80
	ds_read_b128 v[68:71], v72
	ds_read_b128 v[72:75], v72 offset:4096
	s_waitcnt lgkmcnt(0)
	v_mfma_f32_32x32x16_bf16 v[48:63], v[64:67], v[68:71], v[48:63]
	v_mfma_f32_32x32x16_bf16 v[32:47], v[64:67], v[72:75], v[32:47]
	ds_read_b128 v[64:67], v84 offset:20480
	v_add_u32_e32 v84, s3, v79
	s_waitcnt lgkmcnt(0)
	v_mfma_f32_32x32x16_bf16 v[16:31], v[64:67], v[68:71], v[16:31]
	v_mfma_f32_32x32x16_bf16 v[0:15], v[64:67], v[72:75], v[0:15]
	ds_read_b128 v[64:67], v84 offset:16384
	v_add_u32_e32 v72, s3, v78
	ds_read_b128 v[68:71], v72
	ds_read_b128 v[72:75], v72 offset:4096
	s_waitcnt lgkmcnt(0)
	v_mfma_f32_32x32x16_bf16 v[48:63], v[64:67], v[68:71], v[48:63]
	v_mfma_f32_32x32x16_bf16 v[32:47], v[64:67], v[72:75], v[32:47]
	ds_read_b128 v[64:67], v84 offset:20480
	v_add_u32_e32 v84, s3, v77
	s_waitcnt lgkmcnt(0)
	v_mfma_f32_32x32x16_bf16 v[16:31], v[64:67], v[68:71], v[16:31]
	v_mfma_f32_32x32x16_bf16 v[0:15], v[64:67], v[72:75], v[0:15]
	ds_read_b128 v[64:67], v84 offset:16384
	v_add_u32_e32 v72, s3, v76
	ds_read_b128 v[68:71], v72
	ds_read_b128 v[72:75], v72 offset:4096
	s_add_i32 s3, s2, 0xc000
	s_cmp_lg_u32 s2, 0x18000
	s_cselect_b32 s2, s3, 0
	s_waitcnt lgkmcnt(0)
	v_mfma_f32_32x32x16_bf16 v[48:63], v[64:67], v[68:71], v[48:63]
	s_add_i32 s2, s2, 0
	v_add_u32_e32 v83, s2, v83
	v_add_u32_e32 v81, s2, v81
	v_add_u32_e32 v79, s2, v79
	v_add_u32_e32 v77, s2, v77
	v_mfma_f32_32x32x16_bf16 v[32:47], v[64:67], v[72:75], v[32:47]
	ds_read_b128 v[64:67], v84 offset:20480
	s_waitcnt vmcnt(0) lgkmcnt(0)
	s_barrier
	s_waitcnt lgkmcnt(0)
	v_mfma_f32_32x32x16_bf16 v[16:31], v[64:67], v[68:71], v[16:31]
	v_mfma_f32_32x32x16_bf16 v[0:15], v[64:67], v[72:75], v[0:15]
	ds_read_b128 v[64:67], v83 offset:16384
	v_add_u32_e32 v72, s2, v82
	ds_read_b128 v[68:71], v72
	ds_read_b128 v[72:75], v72 offset:4096
	s_waitcnt lgkmcnt(0)
	v_mfma_f32_32x32x16_bf16 v[48:63], v[64:67], v[68:71], v[48:63]
	v_mfma_f32_32x32x16_bf16 v[32:47], v[64:67], v[72:75], v[32:47]
	ds_read_b128 v[64:67], v83 offset:20480
	s_waitcnt lgkmcnt(0)
	v_mfma_f32_32x32x16_bf16 v[16:31], v[64:67], v[68:71], v[16:31]
	v_mfma_f32_32x32x16_bf16 v[0:15], v[64:67], v[72:75], v[0:15]
	ds_read_b128 v[64:67], v81 offset:16384
	v_add_u32_e32 v72, s2, v80
	ds_read_b128 v[68:71], v72
	ds_read_b128 v[72:75], v72 offset:4096
	s_waitcnt lgkmcnt(0)
	v_mfma_f32_32x32x16_bf16 v[48:63], v[64:67], v[68:71], v[48:63]
	v_mfma_f32_32x32x16_bf16 v[32:47], v[64:67], v[72:75], v[32:47]
	ds_read_b128 v[64:67], v81 offset:20480
	s_waitcnt lgkmcnt(0)
	v_mfma_f32_32x32x16_bf16 v[16:31], v[64:67], v[68:71], v[16:31]
	v_mfma_f32_32x32x16_bf16 v[0:15], v[64:67], v[72:75], v[0:15]
	ds_read_b128 v[64:67], v79 offset:16384
	v_add_u32_e32 v72, s2, v78
	ds_read_b128 v[68:71], v72
	ds_read_b128 v[72:75], v72 offset:4096
	s_waitcnt lgkmcnt(0)
	v_mfma_f32_32x32x16_bf16 v[48:63], v[64:67], v[68:71], v[48:63]
	v_mfma_f32_32x32x16_bf16 v[32:47], v[64:67], v[72:75], v[32:47]
	ds_read_b128 v[64:67], v79 offset:20480
	s_waitcnt lgkmcnt(0)
	v_mfma_f32_32x32x16_bf16 v[16:31], v[64:67], v[68:71], v[16:31]
	v_mfma_f32_32x32x16_bf16 v[0:15], v[64:67], v[72:75], v[0:15]
	ds_read_b128 v[64:67], v77 offset:16384
	v_add_u32_e32 v72, s2, v76
	ds_read_b128 v[68:71], v72
	ds_read_b128 v[72:75], v72 offset:4096
	s_waitcnt lgkmcnt(0)
	v_mfma_f32_32x32x16_bf16 v[48:63], v[64:67], v[68:71], v[48:63]
	v_mfma_f32_32x32x16_bf16 v[32:47], v[64:67], v[72:75], v[32:47]
	ds_read_b128 v[64:67], v77 offset:20480
	s_waitcnt vmcnt(0) lgkmcnt(0)
	s_barrier
	s_waitcnt lgkmcnt(0)
	v_mfma_f32_32x32x16_bf16 v[16:31], v[64:67], v[68:71], v[16:31]
	v_mfma_f32_32x32x16_bf16 v[0:15], v[64:67], v[72:75], v[0:15]

; DEV int tid_l() { int t = threadIdx.x; asm volatile("" : "+v"(t)); return t; }
; DEV int stage_next(int s) { return (s == 2 * GS_STAGE) ? 0 : s + GS_STAGE; }
; DEV void gk_issue2(const GTile& t, int s0) {
;   const int tid = tid_l(), lane = tid & 63, wid = __builtin_amdgcn_readfirstlane(tid >> 6);
;   GK_SRC(t)
;   asm volatile("" ::: "memory");
;   GK_DMA(s0, 0);
;   GK_DMA(stage_next(s0), 1);
;   asm volatile("" ::: "memory");
; }
; template <int WAIT0>
; DEV void gk_main(f32x16 (&acc)[2][2], const GTile& t, int s0) {
;   const int tid = tid_l(), lane = tid & 63, wid = __builtin_amdgcn_readfirstlane(tid >> 6), wm = wid & 1, wn = wid >> 1, l32 = lane & 31, hi = lane >> 5;
;   GK_SRC(t)
;   const int sw = (l32 >> 1) & 7;
;   int xk[4], wk[4];
; #pragma unroll
;   for (int ks = 0; ks < 4; ++ks) { const int ko = ((2 * ks + hi) ^ sw) << 4; xk[ks] = GS_A + (64 * wm + l32) * 128 + ko; wk[ks] = GS_B + (64 * wn + l32) * 128 + ko; }
;   const int nk = t.K >> 6;
;     ...
;   vm_wait_bar<WAIT0>();
;   int stc = s0, std_ = stage_next(stage_next(s0));
.LBB0_413:
.LBB0_414:
	s_nop 5
	v_mov_b32_e32 v0, v176
	s_add_i32 s8, s18, 0xc000
	s_nop 2
	v_readfirstlane_b32 s2, v0
	v_and_b32_e32 v1, 31, v0
	s_ashr_i32 s3, s2, 6
	v_and_or_b32 v7, s2, 64, v1
	s_lshr_b32 s2, s2, 1
	s_and_b32 s2, s2, 0x1ffffc0
	v_bfe_u32 v2, v0, 3, 3
	v_or_b32_e32 v1, s2, v1
	s_lshl_b32 s2, s3, 10
	v_lshl_or_b32 v4, s3, 3, v2
	s_add_i32 s3, s2, 0
	s_lshr_b32 s2, s16, 6
	s_cmp_lg_u32 s18, 0x18000
	s_cselect_b32 s17, s8, 0
	s_add_i32 s8, s17, 0xc000
	v_lshrrev_b32_e32 v2, 1, v4
	v_bfe_u32 v3, v0, 5, 1
	v_lshrrev_b32_e32 v5, 1, v0
	v_bfe_u32 v6, v0, 1, 3
	s_cmp_lg_u32 s17, 0x18000
	v_bitop3_b32 v5, v3, v5, 7 bitop3:0x78
	v_bitop3_b32 v8, v3, v6, 2 bitop3:0x36
	v_bitop3_b32 v9, v3, v6, 4 bitop3:0x36
	v_bitop3_b32 v3, v3, v6, 6 bitop3:0x36
	s_cselect_b32 s8, s8, 0
	s_add_i32 s9, s2, -2
	v_bitop3_b32 v0, v2, 7, v0 bitop3:0x48
	v_lshlrev_b32_e32 v1, 7, v1
	v_lshlrev_b32_e32 v5, 4, v5
	v_lshlrev_b32_e32 v8, 4, v8
	v_lshlrev_b32_e32 v9, 4, v9
	v_lshlrev_b32_e32 v3, 4, v3
	v_lshlrev_b32_e32 v120, 4, v0
	s_add_u32 s10, s6, 0x100
	v_add_u32_e32 v0, 0xc0, v4
	v_lshlrev_b32_e32 v7, 7, v7
	v_or_b32_e32 v83, v1, v5
	v_or_b32_e32 v81, v1, v8
	v_or_b32_e32 v79, v1, v9
	v_or_b32_e32 v77, v1, v3
	s_addc_u32 s11, s7, 0
	v_ashrrev_i32_e32 v1, 31, v0
	v_or_b32_e32 v76, v3, v7
	v_alignbit_b32 v3, v1, v0, 31
	v_lshlrev_b32_e32 v2, 1, v0
	v_mov_b64_e32 v[0:1], s[10:11]
	v_mad_u64_u32 v[64:65], s[10:11], v2, s16, v[0:1]
	v_mov_b32_e32 v2, v65
	v_mad_u64_u32 v[2:3], s[10:11], v3, s16, v[2:3]
	v_mov_b32_e32 v65, v2
	v_add_u32_e32 v2, 0x80, v4
	v_ashrrev_i32_e32 v3, 31, v2
	v_alignbit_b32 v3, v3, v2, 31
	v_lshlrev_b32_e32 v2, 1, v2
	v_mad_u64_u32 v[66:67], s[10:11], v2, s16, v[0:1]
	v_mov_b32_e32 v2, v67
	v_mad_u64_u32 v[2:3], s[10:11], v3, s16, v[2:3]
	v_add_u32_e32 v3, 64, v4
	v_lshlrev_b32_e32 v6, 1, v3
	v_or_b32_e32 v82, v5, v7
	v_ashrrev_i32_e32 v5, 31, v3
	v_mad_u64_u32 v[68:69], s[10:11], v6, s16, v[0:1]
	v_mov_b32_e32 v67, v2
	v_mov_b32_e32 v2, v69
	v_alignbit_b32 v5, v5, v3, 31
	v_or_b32_e32 v80, v8, v7
	v_or_b32_e32 v78, v9, v7
	v_mad_u64_u32 v[2:3], s[10:11], v5, s16, v[2:3]
	v_lshlrev_b32_e32 v7, 1, v4
	v_mov_b32_e32 v69, v2
	v_ashrrev_i32_e32 v2, 31, v4
	v_mad_u64_u32 v[70:71], s[10:11], v7, s16, v[0:1]
	v_mov_b32_e32 v0, v71
	v_alignbit_b32 v4, v2, v4, 31
	v_mad_u64_u32 v[0:1], s[10:11], v4, s16, v[0:1]
	s_add_u32 s10, s4, 0x100
	s_addc_u32 s11, s5, 0
	v_mov_b32_e32 v71, v0
	v_mov_b64_e32 v[0:1], s[10:11]
	v_mad_u64_u32 v[74:75], s[10:11], v7, s16, v[0:1]
	v_mad_u64_u32 v[72:73], s[10:11], v6, s16, v[0:1]
	v_mov_b32_e32 v0, v75
	s_waitcnt vmcnt(6) lgkmcnt(0)
	s_barrier
	v_mov_b32_e32 v2, v73
	v_mad_u64_u32 v[0:1], s[10:11], v4, s16, v[0:1]
	v_mad_u64_u32 v[2:3], s[10:11], v5, s16, v[2:3]
	v_mov_b32_e32 v75, v0
	v_mov_b32_e32 v0, 0
	v_mov_b32_e32 v73, v2
	s_mov_b32 s2, s18
	v_mov_b32_e32 v1, v0
	v_mov_b32_e32 v2, v0
	v_mov_b32_e32 v3, v0
	v_mov_b32_e32 v4, v0
	v_mov_b32_e32 v5, v0
	v_mov_b32_e32 v6, v0
	v_mov_b32_e32 v7, v0
	v_mov_b32_e32 v8, v0
	v_mov_b32_e32 v9, v0
	v_mov_b32_e32 v10, v0
	v_mov_b32_e32 v11, v0
	v_mov_b32_e32 v12, v0
	v_mov_b32_e32 v13, v0
	v_mov_b32_e32 v14, v0
	v_mov_b32_e32 v15, v0
	v_mov_b32_e32 v16, v0
	v_mov_b32_e32 v17, v0
	v_mov_b32_e32 v18, v0
	v_mov_b32_e32 v19, v0
	v_mov_b32_e32 v20, v0
	v_mov_b32_e32 v21, v0
	v_mov_b32_e32 v22, v0
	v_mov_b32_e32 v23, v0
	v_mov_b32_e32 v24, v0
	v_mov_b32_e32 v25, v0
	v_mov_b32_e32 v26, v0
	v_mov_b32_e32 v27, v0
	v_mov_b32_e32 v28, v0
	v_mov_b32_e32 v29, v0
	v_mov_b32_e32 v30, v0
	v_mov_b32_e32 v31, v0
	v_mov_b32_e32 v32, v0
	v_mov_b32_e32 v33, v0
	v_mov_b32_e32 v34, v0
	v_mov_b32_e32 v35, v0
	v_mov_b32_e32 v36, v0
	v_mov_b32_e32 v37, v0
	v_mov_b32_e32 v38, v0
	v_mov_b32_e32 v39, v0
	v_mov_b32_e32 v40, v0
	v_mov_b32_e32 v41, v0
	v_mov_b32_e32 v42, v0
	v_mov_b32_e32 v43, v0
	v_mov_b32_e32 v44, v0
	v_mov_b32_e32 v45, v0
	v_mov_b32_e32 v46, v0
	v_mov_b32_e32 v47, v0
	v_mov_b32_e32 v48, v0
	v_mov_b32_e32 v49, v0
	v_mov_b32_e32 v50, v0
	v_mov_b32_e32 v51, v0
	v_mov_b32_e32 v52, v0
	v_mov_b32_e32 v53, v0
	v_mov_b32_e32 v54, v0
	v_mov_b32_e32 v55, v0
	v_mov_b32_e32 v56, v0
	v_mov_b32_e32 v57, v0
	v_mov_b32_e32 v58, v0
	v_mov_b32_e32 v59, v0
	v_mov_b32_e32 v60, v0
	v_mov_b32_e32 v61, v0
	v_mov_b32_e32 v62, v0
	v_mov_b32_e32 v63, v0
	s_add_i32 s99, s2, 0
	v_add_u32_e32 v252, s99, v82
	v_add_u32_e32 v253, s99, v83
	ds_read_b128 v[84:87], v252
	ds_read_b128 v[88:91], v252 offset:4096
	ds_read_b128 v[92:95], v253 offset:16384
	ds_read_b128 v[96:99], v253 offset:20480
; DEV int tid_l() { int t = threadIdx.x; asm volatile("" : "+v"(t)); return t; }
; DEV int stage_next(int s) { return (s == 2 * GS_STAGE) ? 0 : s + GS_STAGE; }
; DEV void gk_issue2(const GTile& t, int s0) {
;   const int tid = tid_l(), lane = tid & 63, wid = __builtin_amdgcn_readfirstlane(tid >> 6);
;   GK_SRC(t)
;   asm volatile("" ::: "memory");
;   GK_DMA(s0, 0);
;   GK_DMA(stage_next(s0), 1);
;   asm volatile("" ::: "memory");
; }
; template <int WAIT0>
; DEV void gk_main(f32x16 (&acc)[2][2], const GTile& t, int s0) {
;   const int tid = tid_l(), lane = tid & 63, wid = __builtin_amdgcn_readfirstlane(tid >> 6), wm = wid & 1, wn = wid >> 1, l32 = lane & 31, hi = lane >> 5;
;   GK_SRC(t)
;   const int sw = (l32 >> 1) & 7;
;   int xk[4], wk[4];
; #pragma unroll
;   for (int ks = 0; ks < 4; ++ks) { const int ko = ((2 * ks + hi) ^ sw) << 4; xk[ks] = GS_A + (64 * wm + l32) * 128 + ko; wk[ks] = GS_B + (64 * wn + l32) * 128 + ko; }
;   const int nk = t.K >> 6;
;     ...
;   vm_wait_bar<WAIT0>();
;   int stc = s0, std_ = stage_next(stage_next(s0));
; #pragma nounroll
;   for (int kt = 0; kt < nk - 2; ++kt) {
;     GK_DMA(std_, kt + 2);
;     GK_COMPUTE(stc);
;     vm_wait_bar<6>();
;     stc = stage_next(stc); std_ = stage_next(std_);
;   }
.LBB0_415:
	s_add_i32 s10, s3, s8
	s_mov_b32 s98, s10
	s_waitcnt lgkmcnt(0)
	v_add_u32_e32 v252, s99, v80
	v_add_u32_e32 v253, s99, v81
	ds_read_b128 v[236:239], v252
	ds_read_b128 v[240:243], v252 offset:4096
	ds_read_b128 v[244:247], v253 offset:16384
	ds_read_b128 v[248:251], v253 offset:20480
	v_mfma_f32_32x32x16_bf16 v[48:63], v[92:95], v[84:87], v[48:63]
	v_mfma_f32_32x32x16_bf16 v[32:47], v[92:95], v[88:91], v[32:47]
	s_mov_b32 m0, s98
	v_lshl_add_u64 v[254:255], v[74:75], 0, v[120:121]
	global_load_lds_dwordx4 v[254:255], off
	v_lshl_add_u64 v[74:75], v[74:75], 0, s[96:97]
	v_mfma_f32_32x32x16_bf16 v[16:31], v[96:99], v[84:87], v[16:31]
	v_mfma_f32_32x32x16_bf16 v[0:15], v[96:99], v[88:91], v[0:15]
	s_add_i32 m0, s98, 0x2000
	v_lshl_add_u64 v[254:255], v[72:73], 0, v[120:121]
	global_load_lds_dwordx4 v[254:255], off
	v_lshl_add_u64 v[72:73], v[72:73], 0, s[96:97]
	s_waitcnt lgkmcnt(0)
	v_add_u32_e32 v252, s99, v78
	v_add_u32_e32 v253, s99, v79
	ds_read_b128 v[84:87], v252
	ds_read_b128 v[88:91], v252 offset:4096
	ds_read_b128 v[92:95], v253 offset:16384
	ds_read_b128 v[96:99], v253 offset:20480
	v_mfma_f32_32x32x16_bf16 v[48:63], v[244:247], v[236:239], v[48:63]
	v_mfma_f32_32x32x16_bf16 v[32:47], v[244:247], v[240:243], v[32:47]
	s_add_i32 m0, s98, 0x4000
	v_lshl_add_u64 v[254:255], v[70:71], 0, v[120:121]
	global_load_lds_dwordx4 v[254:255], off
	v_lshl_add_u64 v[70:71], v[70:71], 0, s[96:97]
	v_mfma_f32_32x32x16_bf16 v[16:31], v[248:251], v[236:239], v[16:31]
	v_mfma_f32_32x32x16_bf16 v[0:15], v[248:251], v[240:243], v[0:15]
	s_add_i32 m0, s98, 0x6000
	v_lshl_add_u64 v[254:255], v[68:69], 0, v[120:121]
	global_load_lds_dwordx4 v[254:255], off
	v_lshl_add_u64 v[68:69], v[68:69], 0, s[96:97]
	s_waitcnt lgkmcnt(0)
	v_add_u32_e32 v252, s99, v76
	v_add_u32_e32 v253, s99, v77
	ds_read_b128 v[236:239], v252
	ds_read_b128 v[240:243], v252 offset:4096
	ds_read_b128 v[244:247], v253 offset:16384
	ds_read_b128 v[248:251], v253 offset:20480
	v_mfma_f32_32x32x16_bf16 v[48:63], v[92:95], v[84:87], v[48:63]
	v_mfma_f32_32x32x16_bf16 v[32:47], v[92:95], v[88:91], v[32:47]
	s_add_i32 m0, s98, 0x8000
	v_lshl_add_u64 v[254:255], v[66:67], 0, v[120:121]
	global_load_lds_dwordx4 v[254:255], off
	v_lshl_add_u64 v[66:67], v[66:67], 0, s[96:97]
	v_mfma_f32_32x32x16_bf16 v[16:31], v[96:99], v[84:87], v[16:31]
	v_mfma_f32_32x32x16_bf16 v[0:15], v[96:99], v[88:91], v[0:15]
	s_add_i32 m0, s98, 0xa000
	v_lshl_add_u64 v[254:255], v[64:65], 0, v[120:121]
	global_load_lds_dwordx4 v[254:255], off
	v_lshl_add_u64 v[64:65], v[64:65], 0, s[96:97]
	s_add_i32 s10, s2, 0xc000
	s_cmp_lg_u32 s2, 0x18000
	s_cselect_b32 s2, s10, 0
	s_waitcnt lgkmcnt(0)
	v_mfma_f32_32x32x16_bf16 v[48:63], v[244:247], v[236:239], v[48:63]
	s_add_i32 s10, s8, 0xc000
	s_waitcnt vmcnt(6) lgkmcnt(0)
	s_barrier
	s_cmp_lg_u32 s8, 0x18000
	s_cselect_b32 s8, s10, 0
	s_add_i32 s9, s9, -1
	s_add_i32 s99, s2, 0
	v_add_u32_e32 v252, s99, v82
	v_add_u32_e32 v253, s99, v83
	ds_read_b128 v[84:87], v252
	ds_read_b128 v[88:91], v252 offset:4096
	ds_read_b128 v[92:95], v253 offset:16384
	ds_read_b128 v[96:99], v253 offset:20480
	v_mfma_f32_32x32x16_bf16 v[32:47], v[244:247], v[240:243], v[32:47]
	s_cmp_lg_u32 s9, 0
	v_mfma_f32_32x32x16_bf16 v[16:31], v[248:251], v[236:239], v[16:31]
	v_mfma_f32_32x32x16_bf16 v[0:15], v[248:251], v[240:243], v[0:15]
	s_cbranch_scc1 .LBB0_415
; DEV int stage_next(int s) { return (s == 2 * GS_STAGE) ? 0 : s + GS_STAGE; }
; template <int WAIT0>
; DEV void gk_main(f32x16 (&acc)[2][2], const GTile& t, int s0) {
;     ...
;   vm_wait_bar<WAIT0>();
;   int stc = s0, std_ = stage_next(stage_next(s0));
; #pragma nounroll
;   for (int kt = 0; kt < nk - 2; ++kt) {
;     GK_DMA(std_, kt + 2);
;     GK_COMPUTE(stc);
;     vm_wait_bar<6>();
;     stc = stage_next(stc); std_ = stage_next(std_);
;   }
;   GK_COMPUTE(stc);
;   vm_wait_bar<0>();
;   stc = stage_next(stc);
;   GK_COMPUTE(stc);
;   vm_wait_bar<0>();
	s_waitcnt lgkmcnt(0)
	s_add_i32 s3, s2, 0
	v_add_u32_e32 v84, s3, v83
	ds_read_b128 v[64:67], v84 offset:16384
	v_add_u32_e32 v72, s3, v82
	ds_read_b128 v[68:71], v72
	ds_read_b128 v[72:75], v72 offset:4096
	s_waitcnt lgkmcnt(0)
	v_mfma_f32_32x32x16_bf16 v[48:63], v[64:67], v[68:71], v[48:63]
	v_mfma_f32_32x32x16_bf16 v[32:47], v[64:67], v[72:75], v[32:47]
	ds_read_b128 v[64:67], v84 offset:20480
	v_add_u32_e32 v84, s3, v81
	s_waitcnt lgkmcnt(0)
	v_mfma_f32_32x32x16_bf16 v[16:31], v[64:67], v[68:71], v[16:31]
	v_mfma_f32_32x32x16_bf16 v[0:15], v[64:67], v[72:75], v[0:15]
	ds_read_b128 v[64:67], v84 offset:16384
	v_add_u32_e32 v72, s3, v80
	ds_read_b128 v[68:71], v72
	ds_read_b128 v[72:75], v72 offset:4096
	s_waitcnt lgkmcnt(0)
	v_mfma_f32_32x32x16_bf16 v[48:63], v[64:67], v[68:71], v[48:63]
	v_mfma_f32_32x32x16_bf16 v[32:47], v[64:67], v[72:75], v[32:47]
	ds_read_b128 v[64:67], v84 offset:20480
	v_add_u32_e32 v84, s3, v79
	s_waitcnt lgkmcnt(0)
	v_mfma_f32_32x32x16_bf16 v[16:31], v[64:67], v[68:71], v[16:31]
	v_mfma_f32_32x32x16_bf16 v[0:15], v[64:67], v[72:75], v[0:15]
	ds_read_b128 v[64:67], v84 offset:16384
	v_add_u32_e32 v72, s3, v78
	ds_read_b128 v[68:71], v72
	ds_read_b128 v[72:75], v72 offset:4096
	s_waitcnt lgkmcnt(0)
	v_mfma_f32_32x32x16_bf16 v[48:63], v[64:67], v[68:71], v[48:63]
	v_mfma_f32_32x32x16_bf16 v[32:47], v[64:67], v[72:75], v[32:47]
	ds_read_b128 v[64:67], v84 offset:20480
	v_add_u32_e32 v84, s3, v77
	s_waitcnt lgkmcnt(0)
	v_mfma_f32_32x32x16_bf16 v[16:31], v[64:67], v[68:71], v[16:31]
	v_mfma_f32_32x32x16_bf16 v[0:15], v[64:67], v[72:75], v[0:15]
	ds_read_b128 v[64:67], v84 offset:16384
	v_add_u32_e32 v72, s3, v76
	ds_read_b128 v[68:71], v72
	ds_read_b128 v[72:75], v72 offset:4096
	s_add_i32 s3, s2, 0xc000
	s_cmp_lg_u32 s2, 0x18000
	s_cselect_b32 s2, s3, 0
	s_waitcnt lgkmcnt(0)
	v_mfma_f32_32x32x16_bf16 v[48:63], v[64:67], v[68:71], v[48:63]
	s_add_i32 s2, s2, 0
	v_add_u32_e32 v83, s2, v83
	v_add_u32_e32 v81, s2, v81
	v_add_u32_e32 v79, s2, v79
	v_add_u32_e32 v77, s2, v77
	v_mfma_f32_32x32x16_bf16 v[32:47], v[64:67], v[72:75], v[32:47]
	ds_read_b128 v[64:67], v84 offset:20480
	s_waitcnt vmcnt(0) lgkmcnt(0)
	s_barrier
	s_waitcnt lgkmcnt(0)
	v_mfma_f32_32x32x16_bf16 v[16:31], v[64:67], v[68:71], v[16:31]
	v_mfma_f32_32x32x16_bf16 v[0:15], v[64:67], v[72:75], v[0:15]
	ds_read_b128 v[64:67], v83 offset:16384
	v_add_u32_e32 v72, s2, v82
	ds_read_b128 v[68:71], v72
	ds_read_b128 v[72:75], v72 offset:4096
	s_waitcnt lgkmcnt(0)
	v_mfma_f32_32x32x16_bf16 v[48:63], v[64:67], v[68:71], v[48:63]
	v_mfma_f32_32x32x16_bf16 v[32:47], v[64:67], v[72:75], v[32:47]
	ds_read_b128 v[64:67], v83 offset:20480
	s_waitcnt lgkmcnt(0)
	v_mfma_f32_32x32x16_bf16 v[16:31], v[64:67], v[68:71], v[16:31]
	v_mfma_f32_32x32x16_bf16 v[0:15], v[64:67], v[72:75], v[0:15]
	ds_read_b128 v[64:67], v81 offset:16384
	v_add_u32_e32 v72, s2, v80
	ds_read_b128 v[68:71], v72
	ds_read_b128 v[72:75], v72 offset:4096
	s_waitcnt lgkmcnt(0)
	v_mfma_f32_32x32x16_bf16 v[48:63], v[64:67], v[68:71], v[48:63]
	v_mfma_f32_32x32x16_bf16 v[32:47], v[64:67], v[72:75], v[32:47]
	ds_read_b128 v[64:67], v81 offset:20480
	s_waitcnt lgkmcnt(0)
	v_mfma_f32_32x32x16_bf16 v[16:31], v[64:67], v[68:71], v[16:31]
	v_mfma_f32_32x32x16_bf16 v[0:15], v[64:67], v[72:75], v[0:15]
	ds_read_b128 v[64:67], v79 offset:16384
	v_add_u32_e32 v72, s2, v78
	ds_read_b128 v[68:71], v72
	ds_read_b128 v[72:75], v72 offset:4096
	s_waitcnt lgkmcnt(0)
	v_mfma_f32_32x32x16_bf16 v[48:63], v[64:67], v[68:71], v[48:63]
	v_mfma_f32_32x32x16_bf16 v[32:47], v[64:67], v[72:75], v[32:47]
	ds_read_b128 v[64:67], v79 offset:20480
	s_waitcnt lgkmcnt(0)
	v_mfma_f32_32x32x16_bf16 v[16:31], v[64:67], v[68:71], v[16:31]
	v_mfma_f32_32x32x16_bf16 v[0:15], v[64:67], v[72:75], v[0:15]
	ds_read_b128 v[64:67], v77 offset:16384
	v_add_u32_e32 v72, s2, v76
	ds_read_b128 v[68:71], v72
	ds_read_b128 v[72:75], v72 offset:4096
	s_waitcnt lgkmcnt(0)
	v_mfma_f32_32x32x16_bf16 v[48:63], v[64:67], v[68:71], v[48:63]
	v_mfma_f32_32x32x16_bf16 v[32:47], v[64:67], v[72:75], v[32:47]
	ds_read_b128 v[64:67], v77 offset:20480
	s_waitcnt vmcnt(0) lgkmcnt(0)
	s_barrier
	s_waitcnt lgkmcnt(0)
	v_mfma_f32_32x32x16_bf16 v[16:31], v[64:67], v[68:71], v[16:31]
	v_mfma_f32_32x32x16_bf16 v[0:15], v[64:67], v[72:75], v[0:15]
	s_add_i32 s2, s19, 1
	s_cmp_eq_u32 s19, 7
	s_mov_b64 s[8:9], 0
	s_cbranch_scc1 .LBB0_411

; DEV int tid_l() { int t = threadIdx.x; asm volatile("" : "+v"(t)); return t; }
; DEV int stage_next(int s) { return (s == 2 * GS_STAGE) ? 0 : s + GS_STAGE; }
; DEV void gk_issue2(const GTile& t, int s0) {
;   const int tid = tid_l(), lane = tid & 63, wid = __builtin_amdgcn_readfirstlane(tid >> 6);
;   GK_SRC(t)
;   asm volatile("" ::: "memory");
;   GK_DMA(s0, 0);
;   GK_DMA(stage_next(s0), 1);
;   asm volatile("" ::: "memory");
; }
; template <int WAIT0>
; DEV void gk_main(f32x16 (&acc)[2][2], const GTile& t, int s0) {
;   const int tid = tid_l(), lane = tid & 63, wid = __builtin_amdgcn_readfirstlane(tid >> 6), wm = wid & 1, wn = wid >> 1, l32 = lane & 31, hi = lane >> 5;
;   GK_SRC(t)
;   const int sw = (l32 >> 1) & 7;
;   int xk[4], wk[4];
; #pragma unroll
;   for (int ks = 0; ks < 4; ++ks) { const int ko = ((2 * ks + hi) ^ sw) << 4; xk[ks] = GS_A + (64 * wm + l32) * 128 + ko; wk[ks] = GS_B + (64 * wn + l32) * 128 + ko; }
;   const int nk = t.K >> 6;
;     ...
;   vm_wait_bar<WAIT0>();
;   int stc = s0, std_ = stage_next(stage_next(s0));
.LBB0_424:
	s_cmp_lg_u32 s2, 0
	s_cbranch_scc0 .LBB0_435
	s_bitcmp0_b32 s2, 0
	s_mov_b64 s[6:7], -1
	s_cbranch_scc1 .LBB0_429
	v_mov_b32_e32 v1, v176
	s_waitcnt vmcnt(14) lgkmcnt(0)
	s_barrier
	v_readfirstlane_b32 s3, v1
	s_ashr_i32 s6, s3, 6
	v_bfe_u32 v0, v1, 3, 3
	v_and_b32_e32 v2, 31, v1
	v_lshl_or_b32 v0, s6, 3, v0
	v_lshrrev_b32_e32 v3, 1, v0
	v_and_or_b32 v6, s3, 64, v2
	s_lshr_b32 s3, s3, 1
	v_xor_b32_e32 v3, v3, v1
	s_and_b32 s3, s3, 0x1ffffc0
	v_lshlrev_b32_e32 v3, 4, v3
	v_or_b32_e32 v2, s3, v2
	s_lshl_b32 s3, s6, 10
	v_and_b32_e32 v4, 0x70, v3
	v_bfe_u32 v3, v1, 5, 1
	v_lshrrev_b32_e32 v5, 1, v1
	v_bfe_u32 v1, v1, 1, 3
	s_add_i32 s10, s3, 0
	s_add_i32 s3, s9, 0xc000
	v_bitop3_b32 v5, v3, v5, 7 bitop3:0x78
	v_bitop3_b32 v7, v3, v1, 2 bitop3:0x36
	v_bitop3_b32 v8, v3, v1, 4 bitop3:0x36
	v_bitop3_b32 v1, v3, v1, 6 bitop3:0x36
	s_cmp_lg_u32 s9, 0x18000
	v_lshlrev_b32_e32 v2, 7, v2
	v_lshlrev_b32_e32 v5, 4, v5
	v_lshlrev_b32_e32 v7, 4, v7
	v_lshlrev_b32_e32 v8, 4, v8
	v_lshlrev_b32_e32 v1, 4, v1
	s_cselect_b32 s8, s3, 0
	s_add_i32 s3, s8, 0xc000
	v_or_b32_e32 v83, v2, v5
	v_or_b32_e32 v81, v2, v7
	v_or_b32_e32 v79, v2, v8
	v_or_b32_e32 v77, v2, v1
	v_add_u32_e32 v2, 0xc0, v0
	s_cmp_lg_u32 s8, 0x18000
	v_ashrrev_i32_e32 v3, 31, v2
	s_cselect_b32 s11, s3, 0
	s_add_u32 s6, s4, 0x100
	v_lshlrev_b64 v[2:3], 11, v[2:3]
	s_addc_u32 s7, s5, 0
	v_or_b32_e32 v2, v2, v4
	v_lshl_add_u64 v[64:65], s[6:7], 0, v[2:3]
	v_add_u32_e32 v2, 0x80, v0
	v_ashrrev_i32_e32 v3, 31, v2
	v_lshlrev_b64 v[2:3], 11, v[2:3]
	v_or_b32_e32 v2, v2, v4
	v_lshlrev_b32_e32 v6, 7, v6
	v_lshl_add_u64 v[66:67], s[6:7], 0, v[2:3]
	v_add_u32_e32 v2, 64, v0
	v_or_b32_e32 v76, v1, v6
	v_ashrrev_i32_e32 v3, 31, v2
	v_ashrrev_i32_e32 v1, 31, v0
	v_lshlrev_b64 v[2:3], 11, v[2:3]
	v_lshlrev_b64 v[0:1], 11, v[0:1]
	v_or_b32_e32 v2, v2, v4
	v_or_b32_e32 v0, v0, v4
	v_lshl_add_u64 v[68:69], s[6:7], 0, v[2:3]
	v_lshl_add_u64 v[70:71], s[6:7], 0, v[0:1]
	v_readlane_b32 s6, v231, 15
	v_readlane_b32 s7, v231, 16
	v_or_b32_e32 v82, v5, v6
	v_or_b32_e32 v80, v7, v6
	v_lshl_add_u64 v[74:75], s[6:7], 0, v[0:1]
	v_mov_b32_e32 v0, 0
	v_or_b32_e32 v78, v8, v6
	v_lshl_add_u64 v[72:73], s[6:7], 0, v[2:3]
	s_mov_b64 s[6:7], 0
	s_mov_b32 s3, s9
	v_mov_b32_e32 v1, v0
	v_mov_b32_e32 v2, v0
	v_mov_b32_e32 v3, v0
	v_mov_b32_e32 v4, v0
	v_mov_b32_e32 v5, v0
	v_mov_b32_e32 v6, v0
	v_mov_b32_e32 v7, v0
	v_mov_b32_e32 v8, v0
	v_mov_b32_e32 v9, v0
	v_mov_b32_e32 v10, v0
	v_mov_b32_e32 v11, v0
	v_mov_b32_e32 v12, v0
	v_mov_b32_e32 v13, v0
	v_mov_b32_e32 v14, v0
	v_mov_b32_e32 v15, v0
	v_mov_b32_e32 v32, v0
	v_mov_b32_e32 v33, v0
	v_mov_b32_e32 v34, v0
	v_mov_b32_e32 v35, v0
	v_mov_b32_e32 v36, v0
	v_mov_b32_e32 v37, v0
	v_mov_b32_e32 v38, v0
	v_mov_b32_e32 v39, v0
	v_mov_b32_e32 v40, v0
	v_mov_b32_e32 v41, v0
	v_mov_b32_e32 v42, v0
	v_mov_b32_e32 v43, v0
	v_mov_b32_e32 v44, v0
	v_mov_b32_e32 v45, v0
	v_mov_b32_e32 v46, v0
	v_mov_b32_e32 v47, v0
	v_mov_b32_e32 v16, v0
	v_mov_b32_e32 v17, v0
	v_mov_b32_e32 v18, v0
	v_mov_b32_e32 v19, v0
	v_mov_b32_e32 v20, v0
	v_mov_b32_e32 v21, v0
	v_mov_b32_e32 v22, v0
	v_mov_b32_e32 v23, v0
	v_mov_b32_e32 v24, v0
	v_mov_b32_e32 v25, v0
	v_mov_b32_e32 v26, v0
	v_mov_b32_e32 v27, v0
	v_mov_b32_e32 v28, v0
	v_mov_b32_e32 v29, v0
	v_mov_b32_e32 v30, v0
	v_mov_b32_e32 v31, v0
	v_mov_b32_e32 v48, v0
	v_mov_b32_e32 v49, v0
	v_mov_b32_e32 v50, v0
	v_mov_b32_e32 v51, v0
	v_mov_b32_e32 v52, v0
	v_mov_b32_e32 v53, v0
	v_mov_b32_e32 v54, v0
	v_mov_b32_e32 v55, v0
	v_mov_b32_e32 v56, v0
	v_mov_b32_e32 v57, v0
	v_mov_b32_e32 v58, v0
	v_mov_b32_e32 v59, v0
	v_mov_b32_e32 v60, v0
	v_mov_b32_e32 v61, v0
	v_mov_b32_e32 v62, v0
	v_mov_b32_e32 v63, v0
	s_add_i32 s99, s3, 0
	v_add_u32_e32 v252, s99, v82
	v_add_u32_e32 v253, s99, v83
	ds_read_b128 v[84:87], v252
	ds_read_b128 v[88:91], v252 offset:4096
	ds_read_b128 v[92:95], v253 offset:16384
	ds_read_b128 v[96:99], v253 offset:20480

; DEV int tid_l() { int t = threadIdx.x; asm volatile("" : "+v"(t)); return t; }
; DEV int stage_next(int s) { return (s == 2 * GS_STAGE) ? 0 : s + GS_STAGE; }
; DEV void gk_issue2(const GTile& t, int s0) {
;   const int tid = tid_l(), lane = tid & 63, wid = __builtin_amdgcn_readfirstlane(tid >> 6);
;   GK_SRC(t)
;   asm volatile("" ::: "memory");
;   GK_DMA(s0, 0);
;   GK_DMA(stage_next(s0), 1);
;   asm volatile("" ::: "memory");
; }
; template <int WAIT0>
; DEV void gk_main(f32x16 (&acc)[2][2], const GTile& t, int s0) {
;   const int tid = tid_l(), lane = tid & 63, wid = __builtin_amdgcn_readfirstlane(tid >> 6), wm = wid & 1, wn = wid >> 1, l32 = lane & 31, hi = lane >> 5;
;   GK_SRC(t)
;   const int sw = (l32 >> 1) & 7;
;   int xk[4], wk[4];
; #pragma unroll
;   for (int ks = 0; ks < 4; ++ks) { const int ko = ((2 * ks + hi) ^ sw) << 4; xk[ks] = GS_A + (64 * wm + l32) * 128 + ko; wk[ks] = GS_B + (64 * wn + l32) * 128 + ko; }
;   const int nk = t.K >> 6;
;     ...
;   vm_wait_bar<WAIT0>();
;   int stc = s0, std_ = stage_next(stage_next(s0));
.LBB0_429:
	s_and_b64 vcc, exec, s[6:7]
	s_cbranch_vccz .LBB0_433
	s_nop 9
	v_mov_b32_e32 v1, v176
	s_waitcnt vmcnt(14) lgkmcnt(0)
	s_barrier
	v_readfirstlane_b32 s3, v1
	s_ashr_i32 s6, s3, 6
	v_bfe_u32 v0, v1, 3, 3
	v_and_b32_e32 v2, 31, v1
	v_lshl_or_b32 v0, s6, 3, v0
	v_lshrrev_b32_e32 v3, 1, v0
	v_and_or_b32 v6, s3, 64, v2
	s_lshr_b32 s3, s3, 1
	v_xor_b32_e32 v3, v3, v1
	s_and_b32 s3, s3, 0x1ffffc0
	v_lshlrev_b32_e32 v3, 4, v3
	v_or_b32_e32 v2, s3, v2
	s_lshl_b32 s3, s6, 10
	v_and_b32_e32 v4, 0x70, v3
	v_bfe_u32 v3, v1, 5, 1
	v_lshrrev_b32_e32 v5, 1, v1
	v_bfe_u32 v1, v1, 1, 3
	s_add_i32 s10, s3, 0
	s_add_i32 s3, s9, 0xc000
	v_bitop3_b32 v5, v3, v5, 7 bitop3:0x78
	v_bitop3_b32 v7, v3, v1, 2 bitop3:0x36
	v_bitop3_b32 v8, v3, v1, 4 bitop3:0x36
	v_bitop3_b32 v1, v3, v1, 6 bitop3:0x36
	s_cmp_lg_u32 s9, 0x18000
	v_lshlrev_b32_e32 v2, 7, v2
	v_lshlrev_b32_e32 v5, 4, v5
	v_lshlrev_b32_e32 v7, 4, v7
	v_lshlrev_b32_e32 v8, 4, v8
	v_lshlrev_b32_e32 v1, 4, v1
	s_cselect_b32 s8, s3, 0
	s_add_i32 s3, s8, 0xc000
	v_or_b32_e32 v83, v2, v5
	v_or_b32_e32 v81, v2, v7
	v_or_b32_e32 v79, v2, v8
	v_or_b32_e32 v77, v2, v1
	v_add_u32_e32 v2, 0xc0, v0
	s_cmp_lg_u32 s8, 0x18000
	v_ashrrev_i32_e32 v3, 31, v2
	s_cselect_b32 s11, s3, 0
	s_add_u32 s6, s4, 0x100
	v_lshlrev_b64 v[2:3], 11, v[2:3]
	s_addc_u32 s7, s5, 0
	v_or_b32_e32 v2, v2, v4
	v_lshl_add_u64 v[64:65], s[6:7], 0, v[2:3]
	v_add_u32_e32 v2, 0x80, v0
	v_ashrrev_i32_e32 v3, 31, v2
	v_lshlrev_b64 v[2:3], 11, v[2:3]
	v_or_b32_e32 v2, v2, v4
	v_lshlrev_b32_e32 v6, 7, v6
	v_lshl_add_u64 v[66:67], s[6:7], 0, v[2:3]
	v_add_u32_e32 v2, 64, v0
	v_or_b32_e32 v76, v1, v6
	v_ashrrev_i32_e32 v3, 31, v2
	v_ashrrev_i32_e32 v1, 31, v0
	v_lshlrev_b64 v[2:3], 11, v[2:3]
	v_lshlrev_b64 v[0:1], 11, v[0:1]
	v_or_b32_e32 v2, v2, v4
	v_or_b32_e32 v0, v0, v4
	v_lshl_add_u64 v[68:69], s[6:7], 0, v[2:3]
	v_lshl_add_u64 v[70:71], s[6:7], 0, v[0:1]
	v_readlane_b32 s6, v231, 15
	v_readlane_b32 s7, v231, 16
	v_or_b32_e32 v82, v5, v6
	v_or_b32_e32 v80, v7, v6
	v_lshl_add_u64 v[74:75], s[6:7], 0, v[0:1]
	v_mov_b32_e32 v0, 0
	v_or_b32_e32 v78, v8, v6
	v_lshl_add_u64 v[72:73], s[6:7], 0, v[2:3]
	s_mov_b64 s[6:7], 0
	s_mov_b32 s3, s9
	v_mov_b32_e32 v1, v0
	v_mov_b32_e32 v2, v0
	v_mov_b32_e32 v3, v0
	v_mov_b32_e32 v4, v0
	v_mov_b32_e32 v5, v0
	v_mov_b32_e32 v6, v0
	v_mov_b32_e32 v7, v0
	v_mov_b32_e32 v8, v0
	v_mov_b32_e32 v9, v0
	v_mov_b32_e32 v10, v0
	v_mov_b32_e32 v11, v0
	v_mov_b32_e32 v12, v0
	v_mov_b32_e32 v13, v0
	v_mov_b32_e32 v14, v0
	v_mov_b32_e32 v15, v0
	v_mov_b32_e32 v32, v0
	v_mov_b32_e32 v33, v0
	v_mov_b32_e32 v34, v0
	v_mov_b32_e32 v35, v0
	v_mov_b32_e32 v36, v0
	v_mov_b32_e32 v37, v0
	v_mov_b32_e32 v38, v0
	v_mov_b32_e32 v39, v0
	v_mov_b32_e32 v40, v0
	v_mov_b32_e32 v41, v0
	v_mov_b32_e32 v42, v0
	v_mov_b32_e32 v43, v0
	v_mov_b32_e32 v44, v0
	v_mov_b32_e32 v45, v0
	v_mov_b32_e32 v46, v0
	v_mov_b32_e32 v47, v0
	v_mov_b32_e32 v16, v0
	v_mov_b32_e32 v17, v0
	v_mov_b32_e32 v18, v0
	v_mov_b32_e32 v19, v0
	v_mov_b32_e32 v20, v0
	v_mov_b32_e32 v21, v0
	v_mov_b32_e32 v22, v0
	v_mov_b32_e32 v23, v0
	v_mov_b32_e32 v24, v0
	v_mov_b32_e32 v25, v0
	v_mov_b32_e32 v26, v0
	v_mov_b32_e32 v27, v0
	v_mov_b32_e32 v28, v0
	v_mov_b32_e32 v29, v0
	v_mov_b32_e32 v30, v0
	v_mov_b32_e32 v31, v0
	v_mov_b32_e32 v48, v0
	v_mov_b32_e32 v49, v0
	v_mov_b32_e32 v50, v0
	v_mov_b32_e32 v51, v0
	v_mov_b32_e32 v52, v0
	v_mov_b32_e32 v53, v0
	v_mov_b32_e32 v54, v0
	v_mov_b32_e32 v55, v0
	v_mov_b32_e32 v56, v0
	v_mov_b32_e32 v57, v0
	v_mov_b32_e32 v58, v0
	v_mov_b32_e32 v59, v0
	v_mov_b32_e32 v60, v0
	v_mov_b32_e32 v61, v0
	v_mov_b32_e32 v62, v0
	v_mov_b32_e32 v63, v0
	s_add_i32 s99, s3, 0
	v_add_u32_e32 v252, s99, v82
	v_add_u32_e32 v253, s99, v83
	ds_read_b128 v[84:87], v252
	ds_read_b128 v[88:91], v252 offset:4096
	ds_read_b128 v[92:95], v253 offset:16384
	ds_read_b128 v[96:99], v253 offset:20480

; DEV int tid_l() { int t = threadIdx.x; asm volatile("" : "+v"(t)); return t; }
; DEV int stage_next(int s) { return (s == 2 * GS_STAGE) ? 0 : s + GS_STAGE; }
; DEV void gk_issue2(const GTile& t, int s0) {
;   const int tid = tid_l(), lane = tid & 63, wid = __builtin_amdgcn_readfirstlane(tid >> 6);
;   GK_SRC(t)
;   asm volatile("" ::: "memory");
;   GK_DMA(s0, 0);
;   GK_DMA(stage_next(s0), 1);
;   asm volatile("" ::: "memory");
; }
; template <int WAIT0>
; DEV void gk_main(f32x16 (&acc)[2][2], const GTile& t, int s0) {
;   const int tid = tid_l(), lane = tid & 63, wid = __builtin_amdgcn_readfirstlane(tid >> 6), wm = wid & 1, wn = wid >> 1, l32 = lane & 31, hi = lane >> 5;
;   GK_SRC(t)
;   const int sw = (l32 >> 1) & 7;
;   int xk[4], wk[4];
; #pragma unroll
;   for (int ks = 0; ks < 4; ++ks) { const int ko = ((2 * ks + hi) ^ sw) << 4; xk[ks] = GS_A + (64 * wm + l32) * 128 + ko; wk[ks] = GS_B + (64 * wn + l32) * 128 + ko; }
;   const int nk = t.K >> 6;
;     ...
;   vm_wait_bar<WAIT0>();
;   int stc = s0, std_ = stage_next(stage_next(s0));
; #pragma nounroll
;   for (int kt = 0; kt < nk - 2; ++kt) {
;     GK_DMA(std_, kt + 2);
;     GK_COMPUTE(stc);
;     vm_wait_bar<6>();
.LBB0_435:
.LBB0_436:
	s_nop 10
	v_mov_b32_e32 v1, v176
	s_waitcnt vmcnt(6) lgkmcnt(0)
	s_barrier
	v_readfirstlane_b32 s3, v1
	s_ashr_i32 s6, s3, 6
	v_bfe_u32 v0, v1, 3, 3
	v_and_b32_e32 v2, 31, v1
	v_lshl_or_b32 v0, s6, 3, v0
	v_lshrrev_b32_e32 v3, 1, v0
	v_and_or_b32 v6, s3, 64, v2
	s_lshr_b32 s3, s3, 1
	v_xor_b32_e32 v3, v3, v1
	s_and_b32 s3, s3, 0x1ffffc0
	v_lshlrev_b32_e32 v3, 4, v3
	v_or_b32_e32 v2, s3, v2
	s_lshl_b32 s3, s6, 10
	v_and_b32_e32 v4, 0x70, v3
	v_bfe_u32 v3, v1, 5, 1
	v_lshrrev_b32_e32 v5, 1, v1
	v_bfe_u32 v1, v1, 1, 3
	s_add_i32 s10, s3, 0
	s_add_i32 s3, s9, 0xc000
	v_bitop3_b32 v5, v3, v5, 7 bitop3:0x78
	v_bitop3_b32 v7, v3, v1, 2 bitop3:0x36
	v_bitop3_b32 v8, v3, v1, 4 bitop3:0x36
	v_bitop3_b32 v1, v3, v1, 6 bitop3:0x36
	s_cmp_lg_u32 s9, 0x18000
	v_lshlrev_b32_e32 v2, 7, v2
	v_lshlrev_b32_e32 v5, 4, v5
	v_lshlrev_b32_e32 v7, 4, v7
	v_lshlrev_b32_e32 v8, 4, v8
	v_lshlrev_b32_e32 v1, 4, v1
	s_cselect_b32 s8, s3, 0
	s_add_i32 s3, s8, 0xc000
	v_or_b32_e32 v83, v2, v5
	v_or_b32_e32 v81, v2, v7
	v_or_b32_e32 v79, v2, v8
	v_or_b32_e32 v77, v2, v1
	v_add_u32_e32 v2, 0xc0, v0
	s_cmp_lg_u32 s8, 0x18000
	v_ashrrev_i32_e32 v3, 31, v2
	s_cselect_b32 s11, s3, 0
	s_add_u32 s6, s4, 0x100
	v_lshlrev_b64 v[2:3], 11, v[2:3]
	s_addc_u32 s7, s5, 0
	v_or_b32_e32 v2, v2, v4
	v_lshl_add_u64 v[64:65], s[6:7], 0, v[2:3]
	v_add_u32_e32 v2, 0x80, v0
	v_ashrrev_i32_e32 v3, 31, v2
	v_lshlrev_b64 v[2:3], 11, v[2:3]
	v_or_b32_e32 v2, v2, v4
	v_lshlrev_b32_e32 v6, 7, v6
	v_lshl_add_u64 v[66:67], s[6:7], 0, v[2:3]
	v_add_u32_e32 v2, 64, v0
	v_or_b32_e32 v76, v1, v6
	v_ashrrev_i32_e32 v3, 31, v2
	v_ashrrev_i32_e32 v1, 31, v0
	v_lshlrev_b64 v[2:3], 11, v[2:3]
	v_lshlrev_b64 v[0:1], 11, v[0:1]
	v_or_b32_e32 v2, v2, v4
	v_or_b32_e32 v0, v0, v4
	v_lshl_add_u64 v[68:69], s[6:7], 0, v[2:3]
	v_lshl_add_u64 v[70:71], s[6:7], 0, v[0:1]
	v_readlane_b32 s6, v231, 15
	v_readlane_b32 s7, v231, 16
	v_or_b32_e32 v82, v5, v6
	v_or_b32_e32 v80, v7, v6
	v_lshl_add_u64 v[74:75], s[6:7], 0, v[0:1]
	v_mov_b32_e32 v0, 0
	v_or_b32_e32 v78, v8, v6
	v_lshl_add_u64 v[72:73], s[6:7], 0, v[2:3]
	s_mov_b64 s[6:7], 0
	s_mov_b32 s3, s9
	v_mov_b32_e32 v1, v0
	v_mov_b32_e32 v2, v0
	v_mov_b32_e32 v3, v0
	v_mov_b32_e32 v4, v0
	v_mov_b32_e32 v5, v0
	v_mov_b32_e32 v6, v0
	v_mov_b32_e32 v7, v0
	v_mov_b32_e32 v8, v0
	v_mov_b32_e32 v9, v0
	v_mov_b32_e32 v10, v0
	v_mov_b32_e32 v11, v0
	v_mov_b32_e32 v12, v0
	v_mov_b32_e32 v13, v0
	v_mov_b32_e32 v14, v0
	v_mov_b32_e32 v15, v0
	v_mov_b32_e32 v32, v0
	v_mov_b32_e32 v33, v0
	v_mov_b32_e32 v34, v0
	v_mov_b32_e32 v35, v0
	v_mov_b32_e32 v36, v0
	v_mov_b32_e32 v37, v0
	v_mov_b32_e32 v38, v0
	v_mov_b32_e32 v39, v0
	v_mov_b32_e32 v40, v0
	v_mov_b32_e32 v41, v0
	v_mov_b32_e32 v42, v0
	v_mov_b32_e32 v43, v0
	v_mov_b32_e32 v44, v0
	v_mov_b32_e32 v45, v0
	v_mov_b32_e32 v46, v0
	v_mov_b32_e32 v47, v0
	v_mov_b32_e32 v16, v0
	v_mov_b32_e32 v17, v0
	v_mov_b32_e32 v18, v0
	v_mov_b32_e32 v19, v0
	v_mov_b32_e32 v20, v0
	v_mov_b32_e32 v21, v0
	v_mov_b32_e32 v22, v0
	v_mov_b32_e32 v23, v0
	v_mov_b32_e32 v24, v0
	v_mov_b32_e32 v25, v0
	v_mov_b32_e32 v26, v0
	v_mov_b32_e32 v27, v0
	v_mov_b32_e32 v28, v0
	v_mov_b32_e32 v29, v0
	v_mov_b32_e32 v30, v0
	v_mov_b32_e32 v31, v0
	v_mov_b32_e32 v48, v0
	v_mov_b32_e32 v49, v0
	v_mov_b32_e32 v50, v0
	v_mov_b32_e32 v51, v0
	v_mov_b32_e32 v52, v0
	v_mov_b32_e32 v53, v0
	v_mov_b32_e32 v54, v0
	v_mov_b32_e32 v55, v0
	v_mov_b32_e32 v56, v0
	v_mov_b32_e32 v57, v0
	v_mov_b32_e32 v58, v0
	v_mov_b32_e32 v59, v0
	v_mov_b32_e32 v60, v0
	v_mov_b32_e32 v61, v0
	v_mov_b32_e32 v62, v0
	v_mov_b32_e32 v63, v0
	s_add_i32 s99, s3, 0
	v_add_u32_e32 v252, s99, v82
	v_add_u32_e32 v253, s99, v83
	ds_read_b128 v[84:87], v252
	ds_read_b128 v[88:91], v252 offset:4096
	ds_read_b128 v[92:95], v253 offset:16384
	ds_read_b128 v[96:99], v253 offset:20480
.LBB0_437:
	s_add_i32 s12, s10, s11
	s_mov_b32 s98, s12
	s_mov_b64 s[100:101], s[6:7]
	s_waitcnt lgkmcnt(0)
	v_add_u32_e32 v252, s99, v80
	v_add_u32_e32 v253, s99, v81
	ds_read_b128 v[236:239], v252
	ds_read_b128 v[240:243], v252 offset:4096
	ds_read_b128 v[244:247], v253 offset:16384
	ds_read_b128 v[248:251], v253 offset:20480
	v_mfma_f32_32x32x16_bf16 v[48:63], v[92:95], v[84:87], v[48:63]
	v_mfma_f32_32x32x16_bf16 v[16:31], v[92:95], v[88:91], v[16:31]
	s_mov_b32 m0, s98
	v_lshl_add_u64 v[254:255], v[74:75], 0, s[100:101]
	global_load_lds_dwordx4 v[254:255], off
	v_mfma_f32_32x32x16_bf16 v[32:47], v[96:99], v[84:87], v[32:47]
	v_mfma_f32_32x32x16_bf16 v[0:15], v[96:99], v[88:91], v[0:15]
	s_add_i32 m0, s98, 0x2000
	v_lshl_add_u64 v[254:255], v[72:73], 0, s[100:101]
	global_load_lds_dwordx4 v[254:255], off
	s_waitcnt lgkmcnt(0)
	v_add_u32_e32 v252, s99, v78
	v_add_u32_e32 v253, s99, v79
	ds_read_b128 v[84:87], v252
	ds_read_b128 v[88:91], v252 offset:4096
	ds_read_b128 v[92:95], v253 offset:16384
	ds_read_b128 v[96:99], v253 offset:20480
	v_mfma_f32_32x32x16_bf16 v[48:63], v[244:247], v[236:239], v[48:63]
	v_mfma_f32_32x32x16_bf16 v[16:31], v[244:247], v[240:243], v[16:31]
	s_add_i32 m0, s98, 0x4000
	v_lshl_add_u64 v[254:255], v[70:71], 0, s[100:101]
	global_load_lds_dwordx4 v[254:255], off
	v_mfma_f32_32x32x16_bf16 v[32:47], v[248:251], v[236:239], v[32:47]
	v_mfma_f32_32x32x16_bf16 v[0:15], v[248:251], v[240:243], v[0:15]
	s_add_i32 m0, s98, 0x6000
	v_lshl_add_u64 v[254:255], v[68:69], 0, s[100:101]
	global_load_lds_dwordx4 v[254:255], off
	s_waitcnt lgkmcnt(0)
	v_add_u32_e32 v252, s99, v76
	v_add_u32_e32 v253, s99, v77
	ds_read_b128 v[236:239], v252
	ds_read_b128 v[240:243], v252 offset:4096
	ds_read_b128 v[244:247], v253 offset:16384
	ds_read_b128 v[248:251], v253 offset:20480
	v_mfma_f32_32x32x16_bf16 v[48:63], v[92:95], v[84:87], v[48:63]
	v_mfma_f32_32x32x16_bf16 v[16:31], v[92:95], v[88:91], v[16:31]
	s_add_i32 m0, s98, 0x8000
	v_lshl_add_u64 v[254:255], v[66:67], 0, s[100:101]
	global_load_lds_dwordx4 v[254:255], off
	v_mfma_f32_32x32x16_bf16 v[32:47], v[96:99], v[84:87], v[32:47]
	v_mfma_f32_32x32x16_bf16 v[0:15], v[96:99], v[88:91], v[0:15]
	s_add_i32 m0, s98, 0xa000
	v_lshl_add_u64 v[254:255], v[64:65], 0, s[100:101]
	global_load_lds_dwordx4 v[254:255], off
	s_add_i32 s12, s3, 0xc000
	s_cmp_lg_u32 s3, 0x18000
	s_cselect_b32 s3, s12, 0
	s_waitcnt lgkmcnt(0)
	v_mfma_f32_32x32x16_bf16 v[48:63], v[244:247], v[236:239], v[48:63]
	s_add_i32 s12, s11, 0xc000
	s_cmp_lg_u32 s11, 0x18000
	s_waitcnt vmcnt(6) lgkmcnt(0)
	s_barrier
; DEV int stage_next(int s) { return (s == 2 * GS_STAGE) ? 0 : s + GS_STAGE; }
; template <int WAIT0>
; DEV void gk_main(f32x16 (&acc)[2][2], const GTile& t, int s0) {
;     ...
;   vm_wait_bar<WAIT0>();
;   int stc = s0, std_ = stage_next(stage_next(s0));
; #pragma nounroll
;   for (int kt = 0; kt < nk - 2; ++kt) {
;     GK_DMA(std_, kt + 2);
;     GK_COMPUTE(stc);
;     vm_wait_bar<6>();
;     stc = stage_next(stc); std_ = stage_next(std_);
;   }
;   GK_COMPUTE(stc);
;   vm_wait_bar<0>();
;   stc = stage_next(stc);
;   GK_COMPUTE(stc);
;   vm_wait_bar<0>();
	s_cselect_b32 s11, s12, 0
	s_add_u32 s6, s6, 0x80
	s_add_i32 s99, s3, 0
	v_add_u32_e32 v252, s99, v82
	v_add_u32_e32 v253, s99, v83
	ds_read_b128 v[84:87], v252
	ds_read_b128 v[88:91], v252 offset:4096
	ds_read_b128 v[92:95], v253 offset:16384
	ds_read_b128 v[96:99], v253 offset:20480
	v_mfma_f32_32x32x16_bf16 v[16:31], v[244:247], v[240:243], v[16:31]
	s_addc_u32 s7, s7, 0
	s_cmpk_lg_i32 s6, 0x700
	v_mfma_f32_32x32x16_bf16 v[32:47], v[248:251], v[236:239], v[32:47]
	v_mfma_f32_32x32x16_bf16 v[0:15], v[248:251], v[240:243], v[0:15]
	s_cbranch_scc1 .LBB0_437
	s_waitcnt lgkmcnt(0)
	s_add_i32 s6, s3, 0
	v_add_u32_e32 v84, s6, v83
	ds_read_b128 v[64:67], v84 offset:16384
	v_add_u32_e32 v72, s6, v82
	ds_read_b128 v[68:71], v72
	ds_read_b128 v[72:75], v72 offset:4096
	s_waitcnt lgkmcnt(0)
	v_mfma_f32_32x32x16_bf16 v[48:63], v[64:67], v[68:71], v[48:63]
	v_mfma_f32_32x32x16_bf16 v[16:31], v[64:67], v[72:75], v[16:31]
	ds_read_b128 v[64:67], v84 offset:20480
	v_add_u32_e32 v84, s6, v81
	s_waitcnt lgkmcnt(0)
	v_mfma_f32_32x32x16_bf16 v[32:47], v[64:67], v[68:71], v[32:47]
	v_mfma_f32_32x32x16_bf16 v[0:15], v[64:67], v[72:75], v[0:15]
	ds_read_b128 v[64:67], v84 offset:16384
	v_add_u32_e32 v72, s6, v80
	ds_read_b128 v[68:71], v72
	ds_read_b128 v[72:75], v72 offset:4096
	s_waitcnt lgkmcnt(0)
	v_mfma_f32_32x32x16_bf16 v[48:63], v[64:67], v[68:71], v[48:63]
	v_mfma_f32_32x32x16_bf16 v[16:31], v[64:67], v[72:75], v[16:31]
	ds_read_b128 v[64:67], v84 offset:20480
	v_add_u32_e32 v84, s6, v79
	s_waitcnt lgkmcnt(0)
	v_mfma_f32_32x32x16_bf16 v[32:47], v[64:67], v[68:71], v[32:47]
	v_mfma_f32_32x32x16_bf16 v[0:15], v[64:67], v[72:75], v[0:15]
	ds_read_b128 v[64:67], v84 offset:16384
	v_add_u32_e32 v72, s6, v78
	ds_read_b128 v[68:71], v72
	ds_read_b128 v[72:75], v72 offset:4096
	s_waitcnt lgkmcnt(0)
	v_mfma_f32_32x32x16_bf16 v[48:63], v[64:67], v[68:71], v[48:63]
	v_mfma_f32_32x32x16_bf16 v[16:31], v[64:67], v[72:75], v[16:31]
	ds_read_b128 v[64:67], v84 offset:20480
	v_add_u32_e32 v84, s6, v77
	s_waitcnt lgkmcnt(0)
	v_mfma_f32_32x32x16_bf16 v[32:47], v[64:67], v[68:71], v[32:47]
	v_mfma_f32_32x32x16_bf16 v[0:15], v[64:67], v[72:75], v[0:15]
	ds_read_b128 v[64:67], v84 offset:16384
	v_add_u32_e32 v72, s6, v76
	ds_read_b128 v[68:71], v72
	ds_read_b128 v[72:75], v72 offset:4096
	s_add_i32 s6, s3, 0xc000
	s_cmp_lg_u32 s3, 0x18000
	s_cselect_b32 s3, s6, 0
	s_waitcnt lgkmcnt(0)
	v_mfma_f32_32x32x16_bf16 v[48:63], v[64:67], v[68:71], v[48:63]
	s_add_i32 s3, s3, 0
	v_add_u32_e32 v83, s3, v83
	v_add_u32_e32 v81, s3, v81
	v_add_u32_e32 v79, s3, v79
	v_add_u32_e32 v77, s3, v77
	v_mfma_f32_32x32x16_bf16 v[16:31], v[64:67], v[72:75], v[16:31]
	ds_read_b128 v[64:67], v84 offset:20480
	s_waitcnt vmcnt(0) lgkmcnt(0)
	s_barrier
	s_waitcnt lgkmcnt(0)
	v_mfma_f32_32x32x16_bf16 v[32:47], v[64:67], v[68:71], v[32:47]
	v_mfma_f32_32x32x16_bf16 v[0:15], v[64:67], v[72:75], v[0:15]
	ds_read_b128 v[64:67], v83 offset:16384
	v_add_u32_e32 v72, s3, v82
	ds_read_b128 v[68:71], v72
	ds_read_b128 v[72:75], v72 offset:4096
	s_waitcnt lgkmcnt(0)
	v_mfma_f32_32x32x16_bf16 v[48:63], v[64:67], v[68:71], v[48:63]
	v_mfma_f32_32x32x16_bf16 v[16:31], v[64:67], v[72:75], v[16:31]
	ds_read_b128 v[64:67], v83 offset:20480
	s_waitcnt lgkmcnt(0)
	v_mfma_f32_32x32x16_bf16 v[32:47], v[64:67], v[68:71], v[32:47]
	v_mfma_f32_32x32x16_bf16 v[0:15], v[64:67], v[72:75], v[0:15]
	ds_read_b128 v[64:67], v81 offset:16384
	v_add_u32_e32 v72, s3, v80
	ds_read_b128 v[68:71], v72
	ds_read_b128 v[72:75], v72 offset:4096
	s_waitcnt lgkmcnt(0)
	v_mfma_f32_32x32x16_bf16 v[48:63], v[64:67], v[68:71], v[48:63]
	v_mfma_f32_32x32x16_bf16 v[16:31], v[64:67], v[72:75], v[16:31]
	ds_read_b128 v[64:67], v81 offset:20480
	s_waitcnt lgkmcnt(0)
	v_mfma_f32_32x32x16_bf16 v[32:47], v[64:67], v[68:71], v[32:47]
	v_mfma_f32_32x32x16_bf16 v[0:15], v[64:67], v[72:75], v[0:15]
	ds_read_b128 v[64:67], v79 offset:16384
	v_add_u32_e32 v72, s3, v78
	ds_read_b128 v[68:71], v72
	ds_read_b128 v[72:75], v72 offset:4096
	s_waitcnt lgkmcnt(0)
	v_mfma_f32_32x32x16_bf16 v[48:63], v[64:67], v[68:71], v[48:63]
	v_mfma_f32_32x32x16_bf16 v[16:31], v[64:67], v[72:75], v[16:31]
	ds_read_b128 v[64:67], v79 offset:20480
	s_waitcnt lgkmcnt(0)
	v_mfma_f32_32x32x16_bf16 v[32:47], v[64:67], v[68:71], v[32:47]
	v_mfma_f32_32x32x16_bf16 v[0:15], v[64:67], v[72:75], v[0:15]
	ds_read_b128 v[64:67], v77 offset:16384
	v_add_u32_e32 v72, s3, v76
	ds_read_b128 v[68:71], v72
	ds_read_b128 v[72:75], v72 offset:4096
	s_waitcnt lgkmcnt(0)
	v_mfma_f32_32x32x16_bf16 v[48:63], v[64:67], v[68:71], v[48:63]
	v_mfma_f32_32x32x16_bf16 v[16:31], v[64:67], v[72:75], v[16:31]
	ds_read_b128 v[64:67], v77 offset:20480
	s_waitcnt vmcnt(0) lgkmcnt(0)
	s_barrier
	s_waitcnt lgkmcnt(0)
	v_mfma_f32_32x32x16_bf16 v[32:47], v[64:67], v[68:71], v[32:47]
	v_mfma_f32_32x32x16_bf16 v[0:15], v[64:67], v[72:75], v[0:15]
	s_add_i32 s3, s2, 1
	s_cmp_eq_u32 s2, 7
	s_cbranch_scc1 .LBB0_423

; DEV int tid_l() { int t = threadIdx.x; asm volatile("" : "+v"(t)); return t; }
; DEV int stage_next(int s) { return (s == 2 * GS_STAGE) ? 0 : s + GS_STAGE; }
; DEV void gk_issue2(const GTile& t, int s0) {
;   const int tid = tid_l(), lane = tid & 63, wid = __builtin_amdgcn_readfirstlane(tid >> 6);
;   GK_SRC(t)
;   asm volatile("" ::: "memory");
;   GK_DMA(s0, 0);
;   GK_DMA(stage_next(s0), 1);
;   asm volatile("" ::: "memory");
; }
; template <int WAIT0>
; DEV void gk_main(f32x16 (&acc)[2][2], const GTile& t, int s0) {
;   const int tid = tid_l(), lane = tid & 63, wid = __builtin_amdgcn_readfirstlane(tid >> 6), wm = wid & 1, wn = wid >> 1, l32 = lane & 31, hi = lane >> 5;
;   GK_SRC(t)
;   const int sw = (l32 >> 1) & 7;
;   int xk[4], wk[4];
; #pragma unroll
;   for (int ks = 0; ks < 4; ++ks) { const int ko = ((2 * ks + hi) ^ sw) << 4; xk[ks] = GS_A + (64 * wm + l32) * 128 + ko; wk[ks] = GS_B + (64 * wn + l32) * 128 + ko; }
;   const int nk = t.K >> 6;
;     ...
;   vm_wait_bar<WAIT0>();
;   int stc = s0, std_ = stage_next(stage_next(s0));
; #pragma nounroll
;   for (int kt = 0; kt < nk - 2; ++kt) {
;     GK_DMA(std_, kt + 2);
;     GK_COMPUTE(stc);
;     vm_wait_bar<6>();
.LBB0_712:
	s_cmp_lg_u32 s12, 0
	s_cbranch_scc0 .LBB0_723
	s_bitcmp0_b32 s12, 0
	s_mov_b64 s[6:7], -1
	s_cbranch_scc1 .LBB0_717
	v_mov_b32_e32 v1, v176
	s_waitcnt vmcnt(22) lgkmcnt(0)
	s_barrier
	v_readfirstlane_b32 s2, v1
	s_ashr_i32 s3, s2, 6
	v_bfe_u32 v0, v1, 3, 3
	v_and_b32_e32 v2, 31, v1
	v_lshl_or_b32 v0, s3, 3, v0
	v_lshrrev_b32_e32 v3, 1, v0
	v_and_or_b32 v6, s2, 64, v2
	s_lshr_b32 s2, s2, 1
	v_xor_b32_e32 v3, v3, v1
	s_and_b32 s2, s2, 0x1ffffc0
	v_lshlrev_b32_e32 v3, 4, v3
	v_or_b32_e32 v2, s2, v2
	s_lshl_b32 s2, s3, 10
	v_and_b32_e32 v4, 0x70, v3
	v_bfe_u32 v3, v1, 5, 1
	v_lshrrev_b32_e32 v5, 1, v1
	v_bfe_u32 v1, v1, 1, 3
	s_add_i32 s3, s2, 0
	s_add_i32 s2, s11, 0xc000
	v_bitop3_b32 v5, v3, v5, 7 bitop3:0x78
	v_bitop3_b32 v7, v3, v1, 2 bitop3:0x36
	v_bitop3_b32 v8, v3, v1, 4 bitop3:0x36
	v_bitop3_b32 v1, v3, v1, 6 bitop3:0x36
	s_cmp_lg_u32 s11, 0x18000
	v_lshlrev_b32_e32 v2, 7, v2
	v_lshlrev_b32_e32 v5, 4, v5
	v_lshlrev_b32_e32 v7, 4, v7
	v_lshlrev_b32_e32 v8, 4, v8
	v_lshlrev_b32_e32 v1, 4, v1
	s_cselect_b32 s10, s2, 0
	s_add_i32 s2, s10, 0xc000
	v_or_b32_e32 v83, v2, v5
	v_or_b32_e32 v82, v2, v7
	v_or_b32_e32 v80, v2, v8
	v_or_b32_e32 v78, v2, v1
	v_add_u32_e32 v2, 0xc0, v0
	s_cmp_lg_u32 s10, 0x18000
	v_ashrrev_i32_e32 v3, 31, v2
	s_cselect_b32 s13, s2, 0
	s_add_u32 s6, s4, 0x100
	v_lshlrev_b64 v[2:3], 11, v[2:3]
	s_addc_u32 s7, s5, 0
	v_or_b32_e32 v2, v2, v4
	v_lshl_add_u64 v[64:65], s[6:7], 0, v[2:3]
	v_add_u32_e32 v2, 0x80, v0
	v_ashrrev_i32_e32 v3, 31, v2
	v_lshlrev_b64 v[2:3], 11, v[2:3]
	v_lshlrev_b32_e32 v6, 7, v6
	v_or_b32_e32 v2, v2, v4
	v_or_b32_e32 v76, v1, v6
	v_lshl_add_u64 v[66:67], s[6:7], 0, v[2:3]
	v_add_u32_e32 v2, 64, v0
	v_ashrrev_i32_e32 v1, 31, v0
	v_ashrrev_i32_e32 v3, 31, v2
	v_lshlrev_b64 v[0:1], 11, v[0:1]
	v_lshlrev_b64 v[2:3], 11, v[2:3]
	v_or_b32_e32 v0, v0, v4
	v_or_b32_e32 v2, v2, v4
	v_lshl_add_u64 v[70:71], s[6:7], 0, v[0:1]
	v_lshl_add_u64 v[74:75], s[8:9], 0, v[0:1]
	v_mov_b32_e32 v0, 0
	v_or_b32_e32 v81, v5, v6
	v_or_b32_e32 v79, v7, v6
	v_or_b32_e32 v77, v8, v6
	v_lshl_add_u64 v[68:69], s[6:7], 0, v[2:3]
	v_lshl_add_u64 v[72:73], s[8:9], 0, v[2:3]
	s_mov_b64 s[6:7], 0
	s_mov_b32 s2, s11
	v_mov_b32_e32 v1, v0
	v_mov_b32_e32 v2, v0
	v_mov_b32_e32 v3, v0
	v_mov_b32_e32 v4, v0
	v_mov_b32_e32 v5, v0
	v_mov_b32_e32 v6, v0
	v_mov_b32_e32 v7, v0
	v_mov_b32_e32 v8, v0
	v_mov_b32_e32 v9, v0
	v_mov_b32_e32 v10, v0
	v_mov_b32_e32 v11, v0
	v_mov_b32_e32 v12, v0
	v_mov_b32_e32 v13, v0
	v_mov_b32_e32 v14, v0
	v_mov_b32_e32 v15, v0
	v_mov_b32_e32 v32, v0
	v_mov_b32_e32 v33, v0
	v_mov_b32_e32 v34, v0
	v_mov_b32_e32 v35, v0
	v_mov_b32_e32 v36, v0
	v_mov_b32_e32 v37, v0
	v_mov_b32_e32 v38, v0
	v_mov_b32_e32 v39, v0
	v_mov_b32_e32 v40, v0
	v_mov_b32_e32 v41, v0
	v_mov_b32_e32 v42, v0
	v_mov_b32_e32 v43, v0
	v_mov_b32_e32 v44, v0
	v_mov_b32_e32 v45, v0
	v_mov_b32_e32 v46, v0
	v_mov_b32_e32 v47, v0
	v_mov_b32_e32 v16, v0
	v_mov_b32_e32 v17, v0
	v_mov_b32_e32 v18, v0
	v_mov_b32_e32 v19, v0
	v_mov_b32_e32 v20, v0
	v_mov_b32_e32 v21, v0
	v_mov_b32_e32 v22, v0
	v_mov_b32_e32 v23, v0
	v_mov_b32_e32 v24, v0
	v_mov_b32_e32 v25, v0
	v_mov_b32_e32 v26, v0
	v_mov_b32_e32 v27, v0
	v_mov_b32_e32 v28, v0
	v_mov_b32_e32 v29, v0
	v_mov_b32_e32 v30, v0
	v_mov_b32_e32 v31, v0
	v_mov_b32_e32 v48, v0
	v_mov_b32_e32 v49, v0
	v_mov_b32_e32 v50, v0
	v_mov_b32_e32 v51, v0
	v_mov_b32_e32 v52, v0
	v_mov_b32_e32 v53, v0
	v_mov_b32_e32 v54, v0
	v_mov_b32_e32 v55, v0
	v_mov_b32_e32 v56, v0
	v_mov_b32_e32 v57, v0
	v_mov_b32_e32 v58, v0
	v_mov_b32_e32 v59, v0
	v_mov_b32_e32 v60, v0
	v_mov_b32_e32 v61, v0
	v_mov_b32_e32 v62, v0
	v_mov_b32_e32 v63, v0
	s_add_i32 s99, s2, 0
	v_add_u32_e32 v253, s99, v81
	v_add_u32_e32 v252, s99, v83
	ds_read_b128 v[84:87], v252 offset:16384
	ds_read_b128 v[88:91], v253
	ds_read_b128 v[92:95], v253 offset:4096
	ds_read_b128 v[96:99], v252 offset:20480
.LBB0_715:
	s_add_i32 s14, s3, s13
	s_mov_b32 s98, s14
	s_mov_b64 s[100:101], s[6:7]
	s_waitcnt lgkmcnt(0)
	v_add_u32_e32 v101, s99, v82
	v_add_u32_e32 v100, s99, v79
	s_add_i32 s14, s2, 0xc000
	s_cmp_lg_u32 s2, 0x18000
	s_cselect_b32 s2, s14, 0
	s_add_i32 s14, s13, 0xc000
	s_cmp_lg_u32 s13, 0x18000
	s_cselect_b32 s13, s14, 0
	s_add_u32 s6, s6, 0x80
	s_addc_u32 s7, s7, 0
	ds_read_b128 v[236:239], v101 offset:16384
	ds_read_b128 v[240:243], v100
	ds_read_b128 v[244:247], v100 offset:4096
	ds_read_b128 v[248:251], v101 offset:20480
	v_mfma_f32_32x32x16_bf16 v[48:63], v[84:87], v[88:91], v[48:63]
	v_mfma_f32_32x32x16_bf16 v[16:31], v[84:87], v[92:95], v[16:31]
	s_mov_b32 m0, s98
	v_lshl_add_u64 v[254:255], v[74:75], 0, s[100:101]
	global_load_lds_dwordx4 v[254:255], off
	v_mfma_f32_32x32x16_bf16 v[32:47], v[96:99], v[88:91], v[32:47]
	v_mfma_f32_32x32x16_bf16 v[0:15], v[96:99], v[92:95], v[0:15]
	s_add_i32 m0, s98, 0x2000
	v_lshl_add_u64 v[254:255], v[72:73], 0, s[100:101]
	global_load_lds_dwordx4 v[254:255], off
	v_add_u32_e32 v101, s99, v80
	v_add_u32_e32 v100, s99, v77
	s_waitcnt lgkmcnt(0)
	ds_read_b128 v[84:87], v101 offset:16384
	ds_read_b128 v[88:91], v100
	ds_read_b128 v[92:95], v100 offset:4096
	ds_read_b128 v[96:99], v101 offset:20480
	v_mfma_f32_32x32x16_bf16 v[48:63], v[236:239], v[240:243], v[48:63]
	v_mfma_f32_32x32x16_bf16 v[16:31], v[236:239], v[244:247], v[16:31]
	s_add_i32 m0, s98, 0x4000
	v_lshl_add_u64 v[254:255], v[70:71], 0, s[100:101]
	global_load_lds_dwordx4 v[254:255], off
	v_mfma_f32_32x32x16_bf16 v[32:47], v[248:251], v[240:243], v[32:47]
	v_mfma_f32_32x32x16_bf16 v[0:15], v[248:251], v[244:247], v[0:15]
	s_add_i32 m0, s98, 0x6000
	v_lshl_add_u64 v[254:255], v[68:69], 0, s[100:101]
	global_load_lds_dwordx4 v[254:255], off
	v_add_u32_e32 v101, s99, v78
	v_add_u32_e32 v100, s99, v76
	s_waitcnt lgkmcnt(0)
	ds_read_b128 v[236:239], v101 offset:16384
	ds_read_b128 v[240:243], v100
	ds_read_b128 v[244:247], v100 offset:4096
	ds_read_b128 v[248:251], v101 offset:20480
	v_mfma_f32_32x32x16_bf16 v[48:63], v[84:87], v[88:91], v[48:63]
	v_mfma_f32_32x32x16_bf16 v[16:31], v[84:87], v[92:95], v[16:31]
	s_add_i32 m0, s98, 0x8000
	v_lshl_add_u64 v[254:255], v[66:67], 0, s[100:101]
	global_load_lds_dwordx4 v[254:255], off
	v_mfma_f32_32x32x16_bf16 v[32:47], v[96:99], v[88:91], v[32:47]
	v_mfma_f32_32x32x16_bf16 v[0:15], v[96:99], v[92:95], v[0:15]
	s_add_i32 m0, s98, 0xa000
	v_lshl_add_u64 v[254:255], v[64:65], 0, s[100:101]
	global_load_lds_dwordx4 v[254:255], off
	s_waitcnt vmcnt(6) lgkmcnt(0)
	s_barrier
; DEV int stage_next(int s) { return (s == 2 * GS_STAGE) ? 0 : s + GS_STAGE; }
; template <int WAIT0>
; DEV void gk_main(f32x16 (&acc)[2][2], const GTile& t, int s0) {
;     ...
;   vm_wait_bar<WAIT0>();
;   int stc = s0, std_ = stage_next(stage_next(s0));
; #pragma nounroll
;   for (int kt = 0; kt < nk - 2; ++kt) {
;     GK_DMA(std_, kt + 2);
;     GK_COMPUTE(stc);
;     vm_wait_bar<6>();
;     stc = stage_next(stc); std_ = stage_next(std_);
;   }
;   GK_COMPUTE(stc);
;   vm_wait_bar<0>();
;   stc = stage_next(stc);
;   GK_COMPUTE(stc);
;   vm_wait_bar<0>();
	s_waitcnt lgkmcnt(0)
	s_add_i32 s99, s2, 0
	v_add_u32_e32 v253, s99, v81
	v_add_u32_e32 v252, s99, v83
	ds_read_b128 v[84:87], v252 offset:16384
	ds_read_b128 v[88:91], v253
	ds_read_b128 v[92:95], v253 offset:4096
	ds_read_b128 v[96:99], v252 offset:20480
	v_mfma_f32_32x32x16_bf16 v[48:63], v[236:239], v[240:243], v[48:63]
	v_mfma_f32_32x32x16_bf16 v[16:31], v[236:239], v[244:247], v[16:31]
	v_mfma_f32_32x32x16_bf16 v[32:47], v[248:251], v[240:243], v[32:47]
	v_mfma_f32_32x32x16_bf16 v[0:15], v[248:251], v[244:247], v[0:15]
	s_cmpk_lg_i32 s6, 0x700
	s_cbranch_scc1 .LBB0_715
	s_waitcnt lgkmcnt(0)
	s_add_i32 s3, s2, 0
	v_add_u32_e32 v84, s3, v83
	ds_read_b128 v[64:67], v84 offset:16384
	v_add_u32_e32 v72, s3, v81
	ds_read_b128 v[68:71], v72
	ds_read_b128 v[72:75], v72 offset:4096
	ds_read_b128 v[84:87], v84 offset:20480
	s_mov_b64 s[6:7], 0
	s_waitcnt lgkmcnt(0)
	v_mfma_f32_32x32x16_bf16 v[32:47], v[84:87], v[68:71], v[32:47]
	v_mfma_f32_32x32x16_bf16 v[0:15], v[84:87], v[72:75], v[0:15]
	v_add_u32_e32 v84, s3, v82
	v_mfma_f32_32x32x16_bf16 v[48:63], v[64:67], v[68:71], v[48:63]
	v_mfma_f32_32x32x16_bf16 v[16:31], v[64:67], v[72:75], v[16:31]
	ds_read_b128 v[64:67], v84 offset:16384
	v_add_u32_e32 v72, s3, v79
	ds_read_b128 v[68:71], v72
	ds_read_b128 v[72:75], v72 offset:4096
	ds_read_b128 v[84:87], v84 offset:20480
	s_waitcnt lgkmcnt(0)
	v_mfma_f32_32x32x16_bf16 v[32:47], v[84:87], v[68:71], v[32:47]
	v_mfma_f32_32x32x16_bf16 v[0:15], v[84:87], v[72:75], v[0:15]
	v_add_u32_e32 v84, s3, v80
	v_mfma_f32_32x32x16_bf16 v[48:63], v[64:67], v[68:71], v[48:63]
	v_mfma_f32_32x32x16_bf16 v[16:31], v[64:67], v[72:75], v[16:31]
	ds_read_b128 v[64:67], v84 offset:16384
	v_add_u32_e32 v72, s3, v77
	ds_read_b128 v[68:71], v72
	ds_read_b128 v[72:75], v72 offset:4096
	ds_read_b128 v[84:87], v84 offset:20480
	s_waitcnt lgkmcnt(0)
	v_mfma_f32_32x32x16_bf16 v[32:47], v[84:87], v[68:71], v[32:47]
	v_mfma_f32_32x32x16_bf16 v[0:15], v[84:87], v[72:75], v[0:15]
	v_add_u32_e32 v84, s3, v78
	v_mfma_f32_32x32x16_bf16 v[48:63], v[64:67], v[68:71], v[48:63]
	v_mfma_f32_32x32x16_bf16 v[16:31], v[64:67], v[72:75], v[16:31]
	ds_read_b128 v[64:67], v84 offset:16384
	v_add_u32_e32 v72, s3, v76
	s_add_i32 s3, s2, 0xc000
	ds_read_b128 v[68:71], v72
	ds_read_b128 v[72:75], v72 offset:4096
	ds_read_b128 v[84:87], v84 offset:20480
	s_cmp_lg_u32 s2, 0x18000
	s_cselect_b32 s2, s3, 0
	s_add_i32 s2, s2, 0
	s_waitcnt vmcnt(0) lgkmcnt(0)
	s_barrier
	v_add_u32_e32 v83, s2, v83
	s_waitcnt lgkmcnt(0)
	v_mfma_f32_32x32x16_bf16 v[48:63], v[64:67], v[68:71], v[48:63]
	v_mfma_f32_32x32x16_bf16 v[16:31], v[64:67], v[72:75], v[16:31]
	ds_read_b128 v[64:67], v83 offset:16384
	v_mfma_f32_32x32x16_bf16 v[32:47], v[84:87], v[68:71], v[32:47]
	v_mfma_f32_32x32x16_bf16 v[0:15], v[84:87], v[72:75], v[0:15]
	v_add_u32_e32 v72, s2, v81
	ds_read_b128 v[68:71], v72
	ds_read_b128 v[72:75], v72 offset:4096
	ds_read_b128 v[84:87], v83 offset:20480
	v_add_u32_e32 v81, s2, v82
	s_waitcnt lgkmcnt(0)
	v_mfma_f32_32x32x16_bf16 v[48:63], v[64:67], v[68:71], v[48:63]
	v_mfma_f32_32x32x16_bf16 v[16:31], v[64:67], v[72:75], v[16:31]
	ds_read_b128 v[64:67], v81 offset:16384
	v_mfma_f32_32x32x16_bf16 v[32:47], v[84:87], v[68:71], v[32:47]
	v_mfma_f32_32x32x16_bf16 v[0:15], v[84:87], v[72:75], v[0:15]
	v_add_u32_e32 v72, s2, v79
	ds_read_b128 v[68:71], v72
	ds_read_b128 v[72:75], v72 offset:4096
	ds_read_b128 v[82:85], v81 offset:20480
	v_add_u32_e32 v79, s2, v80
	s_waitcnt lgkmcnt(0)
	v_mfma_f32_32x32x16_bf16 v[48:63], v[64:67], v[68:71], v[48:63]
	v_mfma_f32_32x32x16_bf16 v[16:31], v[64:67], v[72:75], v[16:31]
	ds_read_b128 v[64:67], v79 offset:16384
	v_mfma_f32_32x32x16_bf16 v[32:47], v[82:85], v[68:71], v[32:47]
	v_mfma_f32_32x32x16_bf16 v[0:15], v[82:85], v[72:75], v[0:15]
	v_add_u32_e32 v72, s2, v77
	ds_read_b128 v[68:71], v72
	ds_read_b128 v[72:75], v72 offset:4096
	ds_read_b128 v[80:83], v79 offset:20480
	v_add_u32_e32 v77, s2, v78
	s_waitcnt lgkmcnt(0)
	v_mfma_f32_32x32x16_bf16 v[48:63], v[64:67], v[68:71], v[48:63]
	v_mfma_f32_32x32x16_bf16 v[16:31], v[64:67], v[72:75], v[16:31]
	ds_read_b128 v[64:67], v77 offset:16384
	v_mfma_f32_32x32x16_bf16 v[32:47], v[80:83], v[68:71], v[32:47]
	v_mfma_f32_32x32x16_bf16 v[0:15], v[80:83], v[72:75], v[0:15]
	v_add_u32_e32 v72, s2, v76
	ds_read_b128 v[68:71], v72
	ds_read_b128 v[72:75], v72 offset:4096
	ds_read_b128 v[76:79], v77 offset:20480
	s_waitcnt vmcnt(0) lgkmcnt(0)
	s_barrier
	s_waitcnt lgkmcnt(0)
	v_mfma_f32_32x32x16_bf16 v[48:63], v[64:67], v[68:71], v[48:63]
	v_mfma_f32_32x32x16_bf16 v[16:31], v[64:67], v[72:75], v[16:31]
	v_mfma_f32_32x32x16_bf16 v[32:47], v[76:79], v[68:71], v[32:47]
	v_mfma_f32_32x32x16_bf16 v[0:15], v[76:79], v[72:75], v[0:15]
; DEV int tid_l() { int t = threadIdx.x; asm volatile("" : "+v"(t)); return t; }
; DEV int stage_next(int s) { return (s == 2 * GS_STAGE) ? 0 : s + GS_STAGE; }
; DEV void gk_issue2(const GTile& t, int s0) {
;   const int tid = tid_l(), lane = tid & 63, wid = __builtin_amdgcn_readfirstlane(tid >> 6);
;   GK_SRC(t)
;   asm volatile("" ::: "memory");
;   GK_DMA(s0, 0);
;   GK_DMA(stage_next(s0), 1);
;   asm volatile("" ::: "memory");
; }
; template <int WAIT0>
; DEV void gk_main(f32x16 (&acc)[2][2], const GTile& t, int s0) {
;   const int tid = tid_l(), lane = tid & 63, wid = __builtin_amdgcn_readfirstlane(tid >> 6), wm = wid & 1, wn = wid >> 1, l32 = lane & 31, hi = lane >> 5;
;   GK_SRC(t)
;   const int sw = (l32 >> 1) & 7;
;   int xk[4], wk[4];
; #pragma unroll
;   for (int ks = 0; ks < 4; ++ks) { const int ko = ((2 * ks + hi) ^ sw) << 4; xk[ks] = GS_A + (64 * wm + l32) * 128 + ko; wk[ks] = GS_B + (64 * wn + l32) * 128 + ko; }
;   const int nk = t.K >> 6;
;     ...
;   vm_wait_bar<WAIT0>();
;   int stc = s0, std_ = stage_next(stage_next(s0));
; #pragma nounroll
;   for (int kt = 0; kt < nk - 2; ++kt) {
;     GK_DMA(std_, kt + 2);
;     GK_COMPUTE(stc);
;     vm_wait_bar<6>();
.LBB0_717:
	s_and_b64 vcc, exec, s[6:7]
	s_cbranch_vccz .LBB0_721
	s_nop 9
	v_mov_b32_e32 v1, v176
	s_waitcnt vmcnt(22) lgkmcnt(0)
	s_barrier
	v_readfirstlane_b32 s2, v1
	s_ashr_i32 s3, s2, 6
	v_bfe_u32 v0, v1, 3, 3
	v_and_b32_e32 v2, 31, v1
	v_lshl_or_b32 v0, s3, 3, v0
	v_lshrrev_b32_e32 v3, 1, v0
	v_and_or_b32 v6, s2, 64, v2
	s_lshr_b32 s2, s2, 1
	v_xor_b32_e32 v3, v3, v1
	s_and_b32 s2, s2, 0x1ffffc0
	v_lshlrev_b32_e32 v3, 4, v3
	v_or_b32_e32 v2, s2, v2
	s_lshl_b32 s2, s3, 10
	v_and_b32_e32 v4, 0x70, v3
	v_bfe_u32 v3, v1, 5, 1
	v_lshrrev_b32_e32 v5, 1, v1
	v_bfe_u32 v1, v1, 1, 3
	s_add_i32 s3, s2, 0
	s_add_i32 s2, s11, 0xc000
	v_bitop3_b32 v5, v3, v5, 7 bitop3:0x78
	v_bitop3_b32 v7, v3, v1, 2 bitop3:0x36
	v_bitop3_b32 v8, v3, v1, 4 bitop3:0x36
	v_bitop3_b32 v1, v3, v1, 6 bitop3:0x36
	s_cmp_lg_u32 s11, 0x18000
	v_lshlrev_b32_e32 v2, 7, v2
	v_lshlrev_b32_e32 v5, 4, v5
	v_lshlrev_b32_e32 v7, 4, v7
	v_lshlrev_b32_e32 v8, 4, v8
	v_lshlrev_b32_e32 v1, 4, v1
	s_cselect_b32 s10, s2, 0
	s_add_i32 s2, s10, 0xc000
	v_or_b32_e32 v83, v2, v5
	v_or_b32_e32 v82, v2, v7
	v_or_b32_e32 v80, v2, v8
	v_or_b32_e32 v78, v2, v1
	v_add_u32_e32 v2, 0xc0, v0
	s_cmp_lg_u32 s10, 0x18000
	v_ashrrev_i32_e32 v3, 31, v2
	s_cselect_b32 s13, s2, 0
	s_add_u32 s6, s4, 0x100
	v_lshlrev_b64 v[2:3], 11, v[2:3]
	s_addc_u32 s7, s5, 0
	v_or_b32_e32 v2, v2, v4
	v_lshl_add_u64 v[64:65], s[6:7], 0, v[2:3]
	v_add_u32_e32 v2, 0x80, v0
	v_ashrrev_i32_e32 v3, 31, v2
	v_lshlrev_b64 v[2:3], 11, v[2:3]
	v_lshlrev_b32_e32 v6, 7, v6
	v_or_b32_e32 v2, v2, v4
	v_or_b32_e32 v76, v1, v6
	v_lshl_add_u64 v[66:67], s[6:7], 0, v[2:3]
	v_add_u32_e32 v2, 64, v0
	v_ashrrev_i32_e32 v1, 31, v0
	v_ashrrev_i32_e32 v3, 31, v2
	v_lshlrev_b64 v[0:1], 11, v[0:1]
	v_lshlrev_b64 v[2:3], 11, v[2:3]
	v_or_b32_e32 v0, v0, v4
	v_or_b32_e32 v2, v2, v4
	v_lshl_add_u64 v[70:71], s[6:7], 0, v[0:1]
	v_lshl_add_u64 v[74:75], s[8:9], 0, v[0:1]
	v_mov_b32_e32 v0, 0
	v_or_b32_e32 v81, v5, v6
	v_or_b32_e32 v79, v7, v6
	v_or_b32_e32 v77, v8, v6
	v_lshl_add_u64 v[68:69], s[6:7], 0, v[2:3]
	v_lshl_add_u64 v[72:73], s[8:9], 0, v[2:3]
	s_mov_b64 s[6:7], 0
	s_mov_b32 s2, s11
	v_mov_b32_e32 v1, v0
	v_mov_b32_e32 v2, v0
	v_mov_b32_e32 v3, v0
	v_mov_b32_e32 v4, v0
	v_mov_b32_e32 v5, v0
	v_mov_b32_e32 v6, v0
	v_mov_b32_e32 v7, v0
	v_mov_b32_e32 v8, v0
	v_mov_b32_e32 v9, v0
	v_mov_b32_e32 v10, v0
	v_mov_b32_e32 v11, v0
	v_mov_b32_e32 v12, v0
	v_mov_b32_e32 v13, v0
	v_mov_b32_e32 v14, v0
	v_mov_b32_e32 v15, v0
	v_mov_b32_e32 v32, v0
	v_mov_b32_e32 v33, v0
	v_mov_b32_e32 v34, v0
	v_mov_b32_e32 v35, v0
	v_mov_b32_e32 v36, v0
	v_mov_b32_e32 v37, v0
	v_mov_b32_e32 v38, v0
	v_mov_b32_e32 v39, v0
	v_mov_b32_e32 v40, v0
	v_mov_b32_e32 v41, v0
	v_mov_b32_e32 v42, v0
	v_mov_b32_e32 v43, v0
	v_mov_b32_e32 v44, v0
	v_mov_b32_e32 v45, v0
	v_mov_b32_e32 v46, v0
	v_mov_b32_e32 v47, v0
	v_mov_b32_e32 v16, v0
	v_mov_b32_e32 v17, v0
	v_mov_b32_e32 v18, v0
	v_mov_b32_e32 v19, v0
	v_mov_b32_e32 v20, v0
	v_mov_b32_e32 v21, v0
	v_mov_b32_e32 v22, v0
	v_mov_b32_e32 v23, v0
	v_mov_b32_e32 v24, v0
	v_mov_b32_e32 v25, v0
	v_mov_b32_e32 v26, v0
	v_mov_b32_e32 v27, v0
	v_mov_b32_e32 v28, v0
	v_mov_b32_e32 v29, v0
	v_mov_b32_e32 v30, v0
	v_mov_b32_e32 v31, v0
	v_mov_b32_e32 v48, v0
	v_mov_b32_e32 v49, v0
	v_mov_b32_e32 v50, v0
	v_mov_b32_e32 v51, v0
	v_mov_b32_e32 v52, v0
	v_mov_b32_e32 v53, v0
	v_mov_b32_e32 v54, v0
	v_mov_b32_e32 v55, v0
	v_mov_b32_e32 v56, v0
	v_mov_b32_e32 v57, v0
	v_mov_b32_e32 v58, v0
	v_mov_b32_e32 v59, v0
	v_mov_b32_e32 v60, v0
	v_mov_b32_e32 v61, v0
	v_mov_b32_e32 v62, v0
	v_mov_b32_e32 v63, v0
	s_add_i32 s99, s2, 0
	v_add_u32_e32 v253, s99, v81
	v_add_u32_e32 v252, s99, v83
	ds_read_b128 v[84:87], v252 offset:16384
	ds_read_b128 v[88:91], v253
	ds_read_b128 v[92:95], v253 offset:4096
	ds_read_b128 v[96:99], v252 offset:20480
.LBB0_719:
	s_add_i32 s14, s3, s13
	s_mov_b32 s98, s14
	s_mov_b64 s[100:101], s[6:7]
	s_waitcnt lgkmcnt(0)
	v_add_u32_e32 v101, s99, v82
	v_add_u32_e32 v100, s99, v79
	s_add_i32 s14, s2, 0xc000
	s_cmp_lg_u32 s2, 0x18000
	s_cselect_b32 s2, s14, 0
	s_add_i32 s14, s13, 0xc000
	s_cmp_lg_u32 s13, 0x18000
	s_cselect_b32 s13, s14, 0
	s_add_u32 s6, s6, 0x80
	s_addc_u32 s7, s7, 0
	ds_read_b128 v[236:239], v101 offset:16384
	ds_read_b128 v[240:243], v100
	ds_read_b128 v[244:247], v100 offset:4096
	ds_read_b128 v[248:251], v101 offset:20480
	v_mfma_f32_32x32x16_bf16 v[48:63], v[84:87], v[88:91], v[48:63]
	v_mfma_f32_32x32x16_bf16 v[16:31], v[84:87], v[92:95], v[16:31]
	s_mov_b32 m0, s98
	v_lshl_add_u64 v[254:255], v[74:75], 0, s[100:101]
	global_load_lds_dwordx4 v[254:255], off
	v_mfma_f32_32x32x16_bf16 v[32:47], v[96:99], v[88:91], v[32:47]
	v_mfma_f32_32x32x16_bf16 v[0:15], v[96:99], v[92:95], v[0:15]
	s_add_i32 m0, s98, 0x2000
	v_lshl_add_u64 v[254:255], v[72:73], 0, s[100:101]
	global_load_lds_dwordx4 v[254:255], off
	v_add_u32_e32 v101, s99, v80
	v_add_u32_e32 v100, s99, v77
	s_waitcnt lgkmcnt(0)
	ds_read_b128 v[84:87], v101 offset:16384
	ds_read_b128 v[88:91], v100
	ds_read_b128 v[92:95], v100 offset:4096
	ds_read_b128 v[96:99], v101 offset:20480
	v_mfma_f32_32x32x16_bf16 v[48:63], v[236:239], v[240:243], v[48:63]
	v_mfma_f32_32x32x16_bf16 v[16:31], v[236:239], v[244:247], v[16:31]
	s_add_i32 m0, s98, 0x4000
	v_lshl_add_u64 v[254:255], v[70:71], 0, s[100:101]
	global_load_lds_dwordx4 v[254:255], off
	v_mfma_f32_32x32x16_bf16 v[32:47], v[248:251], v[240:243], v[32:47]
	v_mfma_f32_32x32x16_bf16 v[0:15], v[248:251], v[244:247], v[0:15]
	s_add_i32 m0, s98, 0x6000
	v_lshl_add_u64 v[254:255], v[68:69], 0, s[100:101]
	global_load_lds_dwordx4 v[254:255], off
	v_add_u32_e32 v101, s99, v78
	v_add_u32_e32 v100, s99, v76
	s_waitcnt lgkmcnt(0)
	ds_read_b128 v[236:239], v101 offset:16384
	ds_read_b128 v[240:243], v100
	ds_read_b128 v[244:247], v100 offset:4096
	ds_read_b128 v[248:251], v101 offset:20480
	v_mfma_f32_32x32x16_bf16 v[48:63], v[84:87], v[88:91], v[48:63]
	v_mfma_f32_32x32x16_bf16 v[16:31], v[84:87], v[92:95], v[16:31]
	s_add_i32 m0, s98, 0x8000
	v_lshl_add_u64 v[254:255], v[66:67], 0, s[100:101]
	global_load_lds_dwordx4 v[254:255], off
	v_mfma_f32_32x32x16_bf16 v[32:47], v[96:99], v[88:91], v[32:47]
	v_mfma_f32_32x32x16_bf16 v[0:15], v[96:99], v[92:95], v[0:15]
	s_add_i32 m0, s98, 0xa000
	v_lshl_add_u64 v[254:255], v[64:65], 0, s[100:101]
	global_load_lds_dwordx4 v[254:255], off
	s_waitcnt vmcnt(6) lgkmcnt(0)
	s_barrier
; DEV int stage_next(int s) { return (s == 2 * GS_STAGE) ? 0 : s + GS_STAGE; }
; template <int WAIT0>
; DEV void gk_main(f32x16 (&acc)[2][2], const GTile& t, int s0) {
;     ...
;   vm_wait_bar<WAIT0>();
;   int stc = s0, std_ = stage_next(stage_next(s0));
; #pragma nounroll
;   for (int kt = 0; kt < nk - 2; ++kt) {
;     GK_DMA(std_, kt + 2);
;     GK_COMPUTE(stc);
;     vm_wait_bar<6>();
;     stc = stage_next(stc); std_ = stage_next(std_);
;   }
;   GK_COMPUTE(stc);
;   vm_wait_bar<0>();
;   stc = stage_next(stc);
;   GK_COMPUTE(stc);
;   vm_wait_bar<0>();
	s_waitcnt lgkmcnt(0)
	s_add_i32 s99, s2, 0
	v_add_u32_e32 v253, s99, v81
	v_add_u32_e32 v252, s99, v83
	ds_read_b128 v[84:87], v252 offset:16384
	ds_read_b128 v[88:91], v253
	ds_read_b128 v[92:95], v253 offset:4096
	ds_read_b128 v[96:99], v252 offset:20480
	v_mfma_f32_32x32x16_bf16 v[48:63], v[236:239], v[240:243], v[48:63]
	v_mfma_f32_32x32x16_bf16 v[16:31], v[236:239], v[244:247], v[16:31]
	v_mfma_f32_32x32x16_bf16 v[32:47], v[248:251], v[240:243], v[32:47]
	v_mfma_f32_32x32x16_bf16 v[0:15], v[248:251], v[244:247], v[0:15]
	s_cmpk_lg_i32 s6, 0x700
	s_cbranch_scc1 .LBB0_719
	s_waitcnt lgkmcnt(0)
	s_add_i32 s3, s2, 0
	v_add_u32_e32 v84, s3, v83
	ds_read_b128 v[64:67], v84 offset:16384
	v_add_u32_e32 v72, s3, v81
	ds_read_b128 v[68:71], v72
	ds_read_b128 v[72:75], v72 offset:4096
	ds_read_b128 v[84:87], v84 offset:20480
	s_waitcnt lgkmcnt(0)
	v_mfma_f32_32x32x16_bf16 v[32:47], v[84:87], v[68:71], v[32:47]
	v_mfma_f32_32x32x16_bf16 v[0:15], v[84:87], v[72:75], v[0:15]
	v_add_u32_e32 v84, s3, v82
	v_mfma_f32_32x32x16_bf16 v[48:63], v[64:67], v[68:71], v[48:63]
	v_mfma_f32_32x32x16_bf16 v[16:31], v[64:67], v[72:75], v[16:31]
	ds_read_b128 v[64:67], v84 offset:16384
	v_add_u32_e32 v72, s3, v79
	ds_read_b128 v[68:71], v72
	ds_read_b128 v[72:75], v72 offset:4096
	ds_read_b128 v[84:87], v84 offset:20480
	s_waitcnt lgkmcnt(0)
	v_mfma_f32_32x32x16_bf16 v[32:47], v[84:87], v[68:71], v[32:47]
	v_mfma_f32_32x32x16_bf16 v[0:15], v[84:87], v[72:75], v[0:15]
	v_add_u32_e32 v84, s3, v80
	v_mfma_f32_32x32x16_bf16 v[48:63], v[64:67], v[68:71], v[48:63]
	v_mfma_f32_32x32x16_bf16 v[16:31], v[64:67], v[72:75], v[16:31]
	ds_read_b128 v[64:67], v84 offset:16384
	v_add_u32_e32 v72, s3, v77
	ds_read_b128 v[68:71], v72
	ds_read_b128 v[72:75], v72 offset:4096
	ds_read_b128 v[84:87], v84 offset:20480
	s_waitcnt lgkmcnt(0)
	v_mfma_f32_32x32x16_bf16 v[32:47], v[84:87], v[68:71], v[32:47]
	v_mfma_f32_32x32x16_bf16 v[0:15], v[84:87], v[72:75], v[0:15]
	v_add_u32_e32 v84, s3, v78
	v_mfma_f32_32x32x16_bf16 v[48:63], v[64:67], v[68:71], v[48:63]
	v_mfma_f32_32x32x16_bf16 v[16:31], v[64:67], v[72:75], v[16:31]
	ds_read_b128 v[64:67], v84 offset:16384
	v_add_u32_e32 v72, s3, v76
	s_add_i32 s3, s2, 0xc000
	ds_read_b128 v[68:71], v72
	ds_read_b128 v[72:75], v72 offset:4096
	ds_read_b128 v[84:87], v84 offset:20480
	s_cmp_lg_u32 s2, 0x18000
	s_cselect_b32 s2, s3, 0
	s_add_i32 s2, s2, 0
	s_waitcnt vmcnt(0) lgkmcnt(0)
	s_barrier
	v_add_u32_e32 v83, s2, v83
	s_waitcnt lgkmcnt(0)
	v_mfma_f32_32x32x16_bf16 v[48:63], v[64:67], v[68:71], v[48:63]
	v_mfma_f32_32x32x16_bf16 v[16:31], v[64:67], v[72:75], v[16:31]
	ds_read_b128 v[64:67], v83 offset:16384
	v_mfma_f32_32x32x16_bf16 v[32:47], v[84:87], v[68:71], v[32:47]
	v_mfma_f32_32x32x16_bf16 v[0:15], v[84:87], v[72:75], v[0:15]
	v_add_u32_e32 v72, s2, v81
	ds_read_b128 v[68:71], v72
	ds_read_b128 v[72:75], v72 offset:4096
	ds_read_b128 v[84:87], v83 offset:20480
	v_add_u32_e32 v81, s2, v82
	s_waitcnt lgkmcnt(0)
	v_mfma_f32_32x32x16_bf16 v[48:63], v[64:67], v[68:71], v[48:63]
	v_mfma_f32_32x32x16_bf16 v[16:31], v[64:67], v[72:75], v[16:31]
	ds_read_b128 v[64:67], v81 offset:16384
	v_mfma_f32_32x32x16_bf16 v[32:47], v[84:87], v[68:71], v[32:47]
	v_mfma_f32_32x32x16_bf16 v[0:15], v[84:87], v[72:75], v[0:15]
	v_add_u32_e32 v72, s2, v79
	ds_read_b128 v[68:71], v72
	ds_read_b128 v[72:75], v72 offset:4096
	ds_read_b128 v[82:85], v81 offset:20480
	v_add_u32_e32 v79, s2, v80
	s_waitcnt lgkmcnt(0)
	v_mfma_f32_32x32x16_bf16 v[48:63], v[64:67], v[68:71], v[48:63]
	v_mfma_f32_32x32x16_bf16 v[16:31], v[64:67], v[72:75], v[16:31]
	ds_read_b128 v[64:67], v79 offset:16384
	v_mfma_f32_32x32x16_bf16 v[32:47], v[82:85], v[68:71], v[32:47]
	v_mfma_f32_32x32x16_bf16 v[0:15], v[82:85], v[72:75], v[0:15]
	v_add_u32_e32 v72, s2, v77
	ds_read_b128 v[68:71], v72
	ds_read_b128 v[72:75], v72 offset:4096
	ds_read_b128 v[80:83], v79 offset:20480
	v_add_u32_e32 v77, s2, v78
	s_waitcnt lgkmcnt(0)
	v_mfma_f32_32x32x16_bf16 v[48:63], v[64:67], v[68:71], v[48:63]
	v_mfma_f32_32x32x16_bf16 v[16:31], v[64:67], v[72:75], v[16:31]
	ds_read_b128 v[64:67], v77 offset:16384
	v_mfma_f32_32x32x16_bf16 v[32:47], v[80:83], v[68:71], v[32:47]
	v_mfma_f32_32x32x16_bf16 v[0:15], v[80:83], v[72:75], v[0:15]
	v_add_u32_e32 v72, s2, v76
	ds_read_b128 v[68:71], v72
	ds_read_b128 v[72:75], v72 offset:4096
	ds_read_b128 v[76:79], v77 offset:20480
	s_waitcnt vmcnt(0) lgkmcnt(0)
	s_barrier
	s_waitcnt lgkmcnt(0)
	v_mfma_f32_32x32x16_bf16 v[48:63], v[64:67], v[68:71], v[48:63]
	v_mfma_f32_32x32x16_bf16 v[16:31], v[64:67], v[72:75], v[16:31]
	v_mfma_f32_32x32x16_bf16 v[32:47], v[76:79], v[68:71], v[32:47]
	v_mfma_f32_32x32x16_bf16 v[0:15], v[76:79], v[72:75], v[0:15]

; DEV int tid_l() { int t = threadIdx.x; asm volatile("" : "+v"(t)); return t; }
; DEV int stage_next(int s) { return (s == 2 * GS_STAGE) ? 0 : s + GS_STAGE; }
; DEV void gk_issue2(const GTile& t, int s0) {
;   const int tid = tid_l(), lane = tid & 63, wid = __builtin_amdgcn_readfirstlane(tid >> 6);
;   GK_SRC(t)
;   asm volatile("" ::: "memory");
;   GK_DMA(s0, 0);
;   GK_DMA(stage_next(s0), 1);
;   asm volatile("" ::: "memory");
; }
; template <int WAIT0>
; DEV void gk_main(f32x16 (&acc)[2][2], const GTile& t, int s0) {
;   const int tid = tid_l(), lane = tid & 63, wid = __builtin_amdgcn_readfirstlane(tid >> 6), wm = wid & 1, wn = wid >> 1, l32 = lane & 31, hi = lane >> 5;
;   GK_SRC(t)
;   const int sw = (l32 >> 1) & 7;
;   int xk[4], wk[4];
; #pragma unroll
;   for (int ks = 0; ks < 4; ++ks) { const int ko = ((2 * ks + hi) ^ sw) << 4; xk[ks] = GS_A + (64 * wm + l32) * 128 + ko; wk[ks] = GS_B + (64 * wn + l32) * 128 + ko; }
;   const int nk = t.K >> 6;
;     ...
;   vm_wait_bar<WAIT0>();
;   int stc = s0, std_ = stage_next(stage_next(s0));
; #pragma nounroll
;   for (int kt = 0; kt < nk - 2; ++kt) {
;     GK_DMA(std_, kt + 2);
;     GK_COMPUTE(stc);
;     vm_wait_bar<6>();
.LBB0_723:
.LBB0_724:
	s_nop 10
	v_mov_b32_e32 v1, v176
	s_waitcnt vmcnt(6) lgkmcnt(0)
	s_barrier
	v_readfirstlane_b32 s2, v1
	s_ashr_i32 s3, s2, 6
	v_bfe_u32 v0, v1, 3, 3
	v_and_b32_e32 v2, 31, v1
	v_lshl_or_b32 v0, s3, 3, v0
	v_lshrrev_b32_e32 v3, 1, v0
	v_and_or_b32 v6, s2, 64, v2
	s_lshr_b32 s2, s2, 1
	v_xor_b32_e32 v3, v3, v1
	s_and_b32 s2, s2, 0x1ffffc0
	v_lshlrev_b32_e32 v3, 4, v3
	v_or_b32_e32 v2, s2, v2
	s_lshl_b32 s2, s3, 10
	v_and_b32_e32 v4, 0x70, v3
	v_bfe_u32 v3, v1, 5, 1
	v_lshrrev_b32_e32 v5, 1, v1
	v_bfe_u32 v1, v1, 1, 3
	s_add_i32 s3, s2, 0
	s_add_i32 s2, s11, 0xc000
	v_bitop3_b32 v5, v3, v5, 7 bitop3:0x78
	v_bitop3_b32 v7, v3, v1, 2 bitop3:0x36
	v_bitop3_b32 v8, v3, v1, 4 bitop3:0x36
	v_bitop3_b32 v1, v3, v1, 6 bitop3:0x36
	s_cmp_lg_u32 s11, 0x18000
	v_lshlrev_b32_e32 v2, 7, v2
	v_lshlrev_b32_e32 v5, 4, v5
	v_lshlrev_b32_e32 v7, 4, v7
	v_lshlrev_b32_e32 v8, 4, v8
	v_lshlrev_b32_e32 v1, 4, v1
	s_cselect_b32 s10, s2, 0
	s_add_i32 s2, s10, 0xc000
	v_or_b32_e32 v83, v2, v5
	v_or_b32_e32 v82, v2, v7
	v_or_b32_e32 v80, v2, v8
	v_or_b32_e32 v78, v2, v1
	v_add_u32_e32 v2, 0xc0, v0
	s_cmp_lg_u32 s10, 0x18000
	v_ashrrev_i32_e32 v3, 31, v2
	s_cselect_b32 s13, s2, 0
	s_add_u32 s6, s4, 0x100
	v_lshlrev_b64 v[2:3], 11, v[2:3]
	s_addc_u32 s7, s5, 0
	v_or_b32_e32 v2, v2, v4
	v_lshl_add_u64 v[64:65], s[6:7], 0, v[2:3]
	v_add_u32_e32 v2, 0x80, v0
	v_ashrrev_i32_e32 v3, 31, v2
	v_lshlrev_b64 v[2:3], 11, v[2:3]
	v_lshlrev_b32_e32 v6, 7, v6
	v_or_b32_e32 v2, v2, v4
	v_or_b32_e32 v76, v1, v6
	v_lshl_add_u64 v[66:67], s[6:7], 0, v[2:3]
	v_add_u32_e32 v2, 64, v0
	v_ashrrev_i32_e32 v1, 31, v0
	v_ashrrev_i32_e32 v3, 31, v2
	v_lshlrev_b64 v[0:1], 11, v[0:1]
	v_lshlrev_b64 v[2:3], 11, v[2:3]
	v_or_b32_e32 v0, v0, v4
	v_or_b32_e32 v2, v2, v4
	v_lshl_add_u64 v[70:71], s[6:7], 0, v[0:1]
	v_lshl_add_u64 v[74:75], s[8:9], 0, v[0:1]
	v_mov_b32_e32 v0, 0
	v_or_b32_e32 v81, v5, v6
	v_or_b32_e32 v79, v7, v6
	v_or_b32_e32 v77, v8, v6
	v_lshl_add_u64 v[68:69], s[6:7], 0, v[2:3]
	v_lshl_add_u64 v[72:73], s[8:9], 0, v[2:3]
	s_mov_b64 s[6:7], 0
	s_mov_b32 s2, s11
	v_mov_b32_e32 v1, v0
	v_mov_b32_e32 v2, v0
	v_mov_b32_e32 v3, v0
	v_mov_b32_e32 v4, v0
	v_mov_b32_e32 v5, v0
	v_mov_b32_e32 v6, v0
	v_mov_b32_e32 v7, v0
	v_mov_b32_e32 v8, v0
	v_mov_b32_e32 v9, v0
	v_mov_b32_e32 v10, v0
	v_mov_b32_e32 v11, v0
	v_mov_b32_e32 v12, v0
	v_mov_b32_e32 v13, v0
	v_mov_b32_e32 v14, v0
	v_mov_b32_e32 v15, v0
	v_mov_b32_e32 v32, v0
	v_mov_b32_e32 v33, v0
	v_mov_b32_e32 v34, v0
	v_mov_b32_e32 v35, v0
	v_mov_b32_e32 v36, v0
	v_mov_b32_e32 v37, v0
	v_mov_b32_e32 v38, v0
	v_mov_b32_e32 v39, v0
	v_mov_b32_e32 v40, v0
	v_mov_b32_e32 v41, v0
	v_mov_b32_e32 v42, v0
	v_mov_b32_e32 v43, v0
	v_mov_b32_e32 v44, v0
	v_mov_b32_e32 v45, v0
	v_mov_b32_e32 v46, v0
	v_mov_b32_e32 v47, v0
	v_mov_b32_e32 v16, v0
	v_mov_b32_e32 v17, v0
	v_mov_b32_e32 v18, v0
	v_mov_b32_e32 v19, v0
	v_mov_b32_e32 v20, v0
	v_mov_b32_e32 v21, v0
	v_mov_b32_e32 v22, v0
	v_mov_b32_e32 v23, v0
	v_mov_b32_e32 v24, v0
	v_mov_b32_e32 v25, v0
	v_mov_b32_e32 v26, v0
	v_mov_b32_e32 v27, v0
	v_mov_b32_e32 v28, v0
	v_mov_b32_e32 v29, v0
	v_mov_b32_e32 v30, v0
	v_mov_b32_e32 v31, v0
	v_mov_b32_e32 v48, v0
	v_mov_b32_e32 v49, v0
	v_mov_b32_e32 v50, v0
	v_mov_b32_e32 v51, v0
	v_mov_b32_e32 v52, v0
	v_mov_b32_e32 v53, v0
	v_mov_b32_e32 v54, v0
	v_mov_b32_e32 v55, v0
	v_mov_b32_e32 v56, v0
	v_mov_b32_e32 v57, v0
	v_mov_b32_e32 v58, v0
	v_mov_b32_e32 v59, v0
	v_mov_b32_e32 v60, v0
	v_mov_b32_e32 v61, v0
	v_mov_b32_e32 v62, v0
	v_mov_b32_e32 v63, v0
	s_add_i32 s99, s2, 0
	v_add_u32_e32 v253, s99, v81
	v_add_u32_e32 v252, s99, v83
	ds_read_b128 v[84:87], v252 offset:16384
	ds_read_b128 v[88:91], v253
	ds_read_b128 v[92:95], v253 offset:4096
	ds_read_b128 v[96:99], v252 offset:20480
.LBB0_725:
	s_add_i32 s14, s3, s13
	s_mov_b32 s98, s14
	s_mov_b64 s[100:101], s[6:7]
	s_waitcnt lgkmcnt(0)
	v_add_u32_e32 v101, s99, v82
	v_add_u32_e32 v100, s99, v79
	s_add_i32 s14, s2, 0xc000
	s_cmp_lg_u32 s2, 0x18000
	s_cselect_b32 s2, s14, 0
	s_add_i32 s14, s13, 0xc000
	s_cmp_lg_u32 s13, 0x18000
	s_cselect_b32 s13, s14, 0
	s_add_u32 s6, s6, 0x80
	s_addc_u32 s7, s7, 0
	ds_read_b128 v[236:239], v101 offset:16384
	ds_read_b128 v[240:243], v100
	ds_read_b128 v[244:247], v100 offset:4096
	ds_read_b128 v[248:251], v101 offset:20480
	v_mfma_f32_32x32x16_bf16 v[48:63], v[84:87], v[88:91], v[48:63]
	v_mfma_f32_32x32x16_bf16 v[16:31], v[84:87], v[92:95], v[16:31]
	s_mov_b32 m0, s98
	v_lshl_add_u64 v[254:255], v[74:75], 0, s[100:101]
	global_load_lds_dwordx4 v[254:255], off
	v_mfma_f32_32x32x16_bf16 v[32:47], v[96:99], v[88:91], v[32:47]
	v_mfma_f32_32x32x16_bf16 v[0:15], v[96:99], v[92:95], v[0:15]
	s_add_i32 m0, s98, 0x2000
	v_lshl_add_u64 v[254:255], v[72:73], 0, s[100:101]
	global_load_lds_dwordx4 v[254:255], off
	v_add_u32_e32 v101, s99, v80
	v_add_u32_e32 v100, s99, v77
	s_waitcnt lgkmcnt(0)
	ds_read_b128 v[84:87], v101 offset:16384
	ds_read_b128 v[88:91], v100
	ds_read_b128 v[92:95], v100 offset:4096
	ds_read_b128 v[96:99], v101 offset:20480
	v_mfma_f32_32x32x16_bf16 v[48:63], v[236:239], v[240:243], v[48:63]
	v_mfma_f32_32x32x16_bf16 v[16:31], v[236:239], v[244:247], v[16:31]
	s_add_i32 m0, s98, 0x4000
	v_lshl_add_u64 v[254:255], v[70:71], 0, s[100:101]
	global_load_lds_dwordx4 v[254:255], off
	v_mfma_f32_32x32x16_bf16 v[32:47], v[248:251], v[240:243], v[32:47]
	v_mfma_f32_32x32x16_bf16 v[0:15], v[248:251], v[244:247], v[0:15]
	s_add_i32 m0, s98, 0x6000
	v_lshl_add_u64 v[254:255], v[68:69], 0, s[100:101]
	global_load_lds_dwordx4 v[254:255], off
	v_add_u32_e32 v101, s99, v78
	v_add_u32_e32 v100, s99, v76
	s_waitcnt lgkmcnt(0)
	ds_read_b128 v[236:239], v101 offset:16384
	ds_read_b128 v[240:243], v100
	ds_read_b128 v[244:247], v100 offset:4096
	ds_read_b128 v[248:251], v101 offset:20480
	v_mfma_f32_32x32x16_bf16 v[48:63], v[84:87], v[88:91], v[48:63]
	v_mfma_f32_32x32x16_bf16 v[16:31], v[84:87], v[92:95], v[16:31]
	s_add_i32 m0, s98, 0x8000
	v_lshl_add_u64 v[254:255], v[66:67], 0, s[100:101]
	global_load_lds_dwordx4 v[254:255], off
	v_mfma_f32_32x32x16_bf16 v[32:47], v[96:99], v[88:91], v[32:47]
	v_mfma_f32_32x32x16_bf16 v[0:15], v[96:99], v[92:95], v[0:15]
	s_add_i32 m0, s98, 0xa000
	v_lshl_add_u64 v[254:255], v[64:65], 0, s[100:101]
	global_load_lds_dwordx4 v[254:255], off
	s_waitcnt vmcnt(6) lgkmcnt(0)
	s_barrier
; DEV int stage_next(int s) { return (s == 2 * GS_STAGE) ? 0 : s + GS_STAGE; }
; template <int WAIT0>
; DEV void gk_main(f32x16 (&acc)[2][2], const GTile& t, int s0) {
;     ...
;   vm_wait_bar<WAIT0>();
;   int stc = s0, std_ = stage_next(stage_next(s0));
; #pragma nounroll
;   for (int kt = 0; kt < nk - 2; ++kt) {
;     GK_DMA(std_, kt + 2);
;     GK_COMPUTE(stc);
;     vm_wait_bar<6>();
;     stc = stage_next(stc); std_ = stage_next(std_);
;   }
;   GK_COMPUTE(stc);
;   vm_wait_bar<0>();
;   stc = stage_next(stc);
;   GK_COMPUTE(stc);
;   vm_wait_bar<0>();
	s_waitcnt lgkmcnt(0)
	s_add_i32 s99, s2, 0
	v_add_u32_e32 v253, s99, v81
	v_add_u32_e32 v252, s99, v83
	ds_read_b128 v[84:87], v252 offset:16384
	ds_read_b128 v[88:91], v253
	ds_read_b128 v[92:95], v253 offset:4096
	ds_read_b128 v[96:99], v252 offset:20480
	v_mfma_f32_32x32x16_bf16 v[48:63], v[236:239], v[240:243], v[48:63]
	v_mfma_f32_32x32x16_bf16 v[16:31], v[236:239], v[244:247], v[16:31]
	v_mfma_f32_32x32x16_bf16 v[32:47], v[248:251], v[240:243], v[32:47]
	v_mfma_f32_32x32x16_bf16 v[0:15], v[248:251], v[244:247], v[0:15]
	s_cmpk_lg_i32 s6, 0x700
	s_cbranch_scc1 .LBB0_725
	s_waitcnt lgkmcnt(0)
	s_add_i32 s3, s2, 0
	v_add_u32_e32 v84, s3, v83
	ds_read_b128 v[64:67], v84 offset:16384
	v_add_u32_e32 v72, s3, v81
	ds_read_b128 v[68:71], v72
	ds_read_b128 v[72:75], v72 offset:4096
	ds_read_b128 v[84:87], v84 offset:20480
	s_waitcnt lgkmcnt(0)
	v_mfma_f32_32x32x16_bf16 v[32:47], v[84:87], v[68:71], v[32:47]
	v_mfma_f32_32x32x16_bf16 v[0:15], v[84:87], v[72:75], v[0:15]
	v_add_u32_e32 v84, s3, v82
	v_mfma_f32_32x32x16_bf16 v[48:63], v[64:67], v[68:71], v[48:63]
	v_mfma_f32_32x32x16_bf16 v[16:31], v[64:67], v[72:75], v[16:31]
	ds_read_b128 v[64:67], v84 offset:16384
	v_add_u32_e32 v72, s3, v79
	ds_read_b128 v[68:71], v72
	ds_read_b128 v[72:75], v72 offset:4096
	ds_read_b128 v[84:87], v84 offset:20480
	s_waitcnt lgkmcnt(0)
	v_mfma_f32_32x32x16_bf16 v[32:47], v[84:87], v[68:71], v[32:47]
	v_mfma_f32_32x32x16_bf16 v[0:15], v[84:87], v[72:75], v[0:15]
	v_add_u32_e32 v84, s3, v80
	v_mfma_f32_32x32x16_bf16 v[48:63], v[64:67], v[68:71], v[48:63]
	v_mfma_f32_32x32x16_bf16 v[16:31], v[64:67], v[72:75], v[16:31]
	ds_read_b128 v[64:67], v84 offset:16384
	v_add_u32_e32 v72, s3, v77
	ds_read_b128 v[68:71], v72
	ds_read_b128 v[72:75], v72 offset:4096
	ds_read_b128 v[84:87], v84 offset:20480
	s_waitcnt lgkmcnt(0)
	v_mfma_f32_32x32x16_bf16 v[32:47], v[84:87], v[68:71], v[32:47]
	v_mfma_f32_32x32x16_bf16 v[0:15], v[84:87], v[72:75], v[0:15]
	v_add_u32_e32 v84, s3, v78
	v_mfma_f32_32x32x16_bf16 v[48:63], v[64:67], v[68:71], v[48:63]
	v_mfma_f32_32x32x16_bf16 v[16:31], v[64:67], v[72:75], v[16:31]
	ds_read_b128 v[64:67], v84 offset:16384
	v_add_u32_e32 v72, s3, v76
	s_add_i32 s3, s2, 0xc000
	ds_read_b128 v[68:71], v72
	ds_read_b128 v[72:75], v72 offset:4096
	ds_read_b128 v[84:87], v84 offset:20480
	s_cmp_lg_u32 s2, 0x18000
	s_cselect_b32 s2, s3, 0
	s_add_i32 s2, s2, 0
	s_waitcnt vmcnt(0) lgkmcnt(0)
	s_barrier
	v_add_u32_e32 v83, s2, v83
	s_waitcnt lgkmcnt(0)
	v_mfma_f32_32x32x16_bf16 v[48:63], v[64:67], v[68:71], v[48:63]
	v_mfma_f32_32x32x16_bf16 v[16:31], v[64:67], v[72:75], v[16:31]
	ds_read_b128 v[64:67], v83 offset:16384
	v_mfma_f32_32x32x16_bf16 v[32:47], v[84:87], v[68:71], v[32:47]
	v_mfma_f32_32x32x16_bf16 v[0:15], v[84:87], v[72:75], v[0:15]
	v_add_u32_e32 v72, s2, v81
	ds_read_b128 v[68:71], v72
	ds_read_b128 v[72:75], v72 offset:4096
	ds_read_b128 v[84:87], v83 offset:20480
	v_add_u32_e32 v81, s2, v82
	s_waitcnt lgkmcnt(0)
	v_mfma_f32_32x32x16_bf16 v[48:63], v[64:67], v[68:71], v[48:63]
	v_mfma_f32_32x32x16_bf16 v[16:31], v[64:67], v[72:75], v[16:31]
	ds_read_b128 v[64:67], v81 offset:16384
	v_mfma_f32_32x32x16_bf16 v[32:47], v[84:87], v[68:71], v[32:47]
	v_mfma_f32_32x32x16_bf16 v[0:15], v[84:87], v[72:75], v[0:15]
	v_add_u32_e32 v72, s2, v79
	ds_read_b128 v[68:71], v72
	ds_read_b128 v[72:75], v72 offset:4096
	ds_read_b128 v[82:85], v81 offset:20480
	v_add_u32_e32 v79, s2, v80
	s_waitcnt lgkmcnt(0)
	v_mfma_f32_32x32x16_bf16 v[48:63], v[64:67], v[68:71], v[48:63]
	v_mfma_f32_32x32x16_bf16 v[16:31], v[64:67], v[72:75], v[16:31]
	ds_read_b128 v[64:67], v79 offset:16384
	v_mfma_f32_32x32x16_bf16 v[32:47], v[82:85], v[68:71], v[32:47]
	v_mfma_f32_32x32x16_bf16 v[0:15], v[82:85], v[72:75], v[0:15]
	v_add_u32_e32 v72, s2, v77
	ds_read_b128 v[68:71], v72
	ds_read_b128 v[72:75], v72 offset:4096
	ds_read_b128 v[80:83], v79 offset:20480
	v_add_u32_e32 v77, s2, v78
	s_waitcnt lgkmcnt(0)
	v_mfma_f32_32x32x16_bf16 v[48:63], v[64:67], v[68:71], v[48:63]
	v_mfma_f32_32x32x16_bf16 v[16:31], v[64:67], v[72:75], v[16:31]
	ds_read_b128 v[64:67], v77 offset:16384
	v_mfma_f32_32x32x16_bf16 v[32:47], v[80:83], v[68:71], v[32:47]
	v_mfma_f32_32x32x16_bf16 v[0:15], v[80:83], v[72:75], v[0:15]
	v_add_u32_e32 v72, s2, v76
	ds_read_b128 v[68:71], v72
	ds_read_b128 v[72:75], v72 offset:4096
	ds_read_b128 v[76:79], v77 offset:20480
	s_waitcnt vmcnt(0) lgkmcnt(0)
	s_barrier
	s_waitcnt lgkmcnt(0)
	v_mfma_f32_32x32x16_bf16 v[48:63], v[64:67], v[68:71], v[48:63]
	v_mfma_f32_32x32x16_bf16 v[16:31], v[64:67], v[72:75], v[16:31]
	v_mfma_f32_32x32x16_bf16 v[32:47], v[76:79], v[68:71], v[32:47]
	v_mfma_f32_32x32x16_bf16 v[0:15], v[76:79], v[72:75], v[0:15]
	s_add_i32 s2, s12, 1
	s_cmp_eq_u32 s12, 3
	s_cbranch_scc1 .LBB0_711

; DEV int tid_l() { int t = threadIdx.x; asm volatile("" : "+v"(t)); return t; }
; DEV int stage_next(int s) { return (s == 2 * GS_STAGE) ? 0 : s + GS_STAGE; }
; DEV void gk_issue2(const GTile& t, int s0) {
;   const int tid = tid_l(), lane = tid & 63, wid = __builtin_amdgcn_readfirstlane(tid >> 6);
;   GK_SRC(t)
;   asm volatile("" ::: "memory");
;   GK_DMA(s0, 0);
;   GK_DMA(stage_next(s0), 1);
;   asm volatile("" ::: "memory");
; }
; template <int WAIT0>
; DEV void gk_main(f32x16 (&acc)[2][2], const GTile& t, int s0) {
;   const int tid = tid_l(), lane = tid & 63, wid = __builtin_amdgcn_readfirstlane(tid >> 6), wm = wid & 1, wn = wid >> 1, l32 = lane & 31, hi = lane >> 5;
;   GK_SRC(t)
;   const int sw = (l32 >> 1) & 7;
;   int xk[4], wk[4];
; #pragma unroll
;   for (int ks = 0; ks < 4; ++ks) { const int ko = ((2 * ks + hi) ^ sw) << 4; xk[ks] = GS_A + (64 * wm + l32) * 128 + ko; wk[ks] = GS_B + (64 * wn + l32) * 128 + ko; }
;   const int nk = t.K >> 6;
;     ...
;   vm_wait_bar<WAIT0>();
;   int stc = s0, std_ = stage_next(stage_next(s0));
; #pragma nounroll
;   for (int kt = 0; kt < nk - 2; ++kt) {
;     GK_DMA(std_, kt + 2);
;     GK_COMPUTE(stc);
;     vm_wait_bar<6>();
.LBB0_734:
	s_cmp_lg_u32 s17, 0
	s_cbranch_scc0 .LBB0_745
	s_bitcmp0_b32 s17, 0
	s_mov_b64 s[10:11], -1
	s_cbranch_scc1 .LBB0_739
	v_mov_b32_e32 v1, v176
	s_waitcnt vmcnt(63) lgkmcnt(0)
	s_barrier
	v_readfirstlane_b32 s2, v1
	s_ashr_i32 s3, s2, 6
	v_bfe_u32 v0, v1, 3, 3
	v_and_b32_e32 v2, 31, v1
	v_lshl_or_b32 v0, s3, 3, v0
	v_lshrrev_b32_e32 v3, 1, v0
	v_and_or_b32 v6, s2, 64, v2
	s_lshr_b32 s2, s2, 1
	v_xor_b32_e32 v3, v3, v1
	s_and_b32 s2, s2, 0x1ffffc0
	v_lshlrev_b32_e32 v3, 4, v3
	v_or_b32_e32 v2, s2, v2
	s_lshl_b32 s2, s3, 10
	v_and_b32_e32 v4, 0x70, v3
	v_bfe_u32 v3, v1, 5, 1
	v_lshrrev_b32_e32 v5, 1, v1
	v_bfe_u32 v1, v1, 1, 3
	s_add_i32 s3, s2, 0
	s_add_i32 s2, s16, 0xc000
	v_bitop3_b32 v5, v3, v5, 7 bitop3:0x78
	v_bitop3_b32 v7, v3, v1, 2 bitop3:0x36
	v_bitop3_b32 v8, v3, v1, 4 bitop3:0x36
	v_bitop3_b32 v1, v3, v1, 6 bitop3:0x36
	s_cmp_lg_u32 s16, 0x18000
	v_lshlrev_b32_e32 v2, 7, v2
	v_lshlrev_b32_e32 v5, 4, v5
	v_lshlrev_b32_e32 v7, 4, v7
	v_lshlrev_b32_e32 v8, 4, v8
	v_lshlrev_b32_e32 v1, 4, v1
	s_cselect_b32 s18, s2, 0
	s_add_i32 s2, s18, 0xc000
	v_or_b32_e32 v86, v2, v5
	v_or_b32_e32 v85, v2, v7
	v_or_b32_e32 v83, v2, v8
	v_or_b32_e32 v81, v2, v1
	v_add_u32_e32 v2, 0xc0, v0
	s_cmp_lg_u32 s18, 0x18000
	v_ashrrev_i32_e32 v3, 31, v2
	s_cselect_b32 s19, s2, 0
	s_add_u32 s10, s6, 0x100
	v_lshlrev_b64 v[2:3], 11, v[2:3]
	s_addc_u32 s11, s7, 0
	v_or_b32_e32 v2, v2, v4
	v_lshl_add_u64 v[66:67], s[10:11], 0, v[2:3]
	v_add_u32_e32 v2, 0x80, v0
	v_ashrrev_i32_e32 v3, 31, v2
	v_lshlrev_b64 v[2:3], 11, v[2:3]
	v_lshlrev_b32_e32 v6, 7, v6
	v_or_b32_e32 v2, v2, v4
	v_or_b32_e32 v79, v1, v6
	v_lshl_add_u64 v[68:69], s[10:11], 0, v[2:3]
	v_add_u32_e32 v2, 64, v0
	v_ashrrev_i32_e32 v1, 31, v0
	v_ashrrev_i32_e32 v3, 31, v2
	v_lshlrev_b64 v[0:1], 11, v[0:1]
	v_lshlrev_b64 v[2:3], 11, v[2:3]
	v_or_b32_e32 v0, v0, v4
	v_or_b32_e32 v2, v2, v4
	v_lshl_add_u64 v[72:73], s[10:11], 0, v[0:1]
	v_lshl_add_u64 v[76:77], s[8:9], 0, v[0:1]
	v_mov_b32_e32 v0, 0
	v_or_b32_e32 v84, v5, v6
	v_or_b32_e32 v82, v7, v6
	v_or_b32_e32 v80, v8, v6
	v_lshl_add_u64 v[70:71], s[10:11], 0, v[2:3]
	v_lshl_add_u64 v[74:75], s[8:9], 0, v[2:3]
	s_mov_b64 s[10:11], 0
	s_mov_b32 s2, s16
	v_mov_b32_e32 v1, v0
	v_mov_b32_e32 v2, v0
	v_mov_b32_e32 v3, v0
	v_mov_b32_e32 v4, v0
	v_mov_b32_e32 v5, v0
	v_mov_b32_e32 v6, v0
	v_mov_b32_e32 v7, v0
	v_mov_b32_e32 v8, v0
	v_mov_b32_e32 v9, v0
	v_mov_b32_e32 v10, v0
	v_mov_b32_e32 v11, v0
	v_mov_b32_e32 v12, v0
	v_mov_b32_e32 v13, v0
	v_mov_b32_e32 v14, v0
	v_mov_b32_e32 v15, v0
	v_mov_b32_e32 v16, v0
	v_mov_b32_e32 v17, v0
	v_mov_b32_e32 v18, v0
	v_mov_b32_e32 v19, v0
	v_mov_b32_e32 v20, v0
	v_mov_b32_e32 v21, v0
	v_mov_b32_e32 v22, v0
	v_mov_b32_e32 v23, v0
	v_mov_b32_e32 v24, v0
	v_mov_b32_e32 v25, v0
	v_mov_b32_e32 v26, v0
	v_mov_b32_e32 v27, v0
	v_mov_b32_e32 v28, v0
	v_mov_b32_e32 v29, v0
	v_mov_b32_e32 v30, v0
	v_mov_b32_e32 v31, v0
	v_mov_b32_e32 v32, v0
	v_mov_b32_e32 v33, v0
	v_mov_b32_e32 v34, v0
	v_mov_b32_e32 v35, v0
	v_mov_b32_e32 v36, v0
	v_mov_b32_e32 v37, v0
	v_mov_b32_e32 v38, v0
	v_mov_b32_e32 v39, v0
	v_mov_b32_e32 v40, v0
	v_mov_b32_e32 v41, v0
	v_mov_b32_e32 v42, v0
	v_mov_b32_e32 v43, v0
	v_mov_b32_e32 v44, v0
	v_mov_b32_e32 v45, v0
	v_mov_b32_e32 v46, v0
	v_mov_b32_e32 v47, v0
	v_mov_b32_e32 v48, v0
	v_mov_b32_e32 v49, v0
	v_mov_b32_e32 v50, v0
	v_mov_b32_e32 v51, v0
	v_mov_b32_e32 v52, v0
	v_mov_b32_e32 v53, v0
	v_mov_b32_e32 v54, v0
	v_mov_b32_e32 v55, v0
	v_mov_b32_e32 v56, v0
	v_mov_b32_e32 v57, v0
	v_mov_b32_e32 v58, v0
	v_mov_b32_e32 v59, v0
	v_mov_b32_e32 v60, v0
	v_mov_b32_e32 v61, v0
	v_mov_b32_e32 v62, v0
	v_mov_b32_e32 v63, v0
	s_add_i32 s99, s2, 0
	v_add_u32_e32 v252, s99, v86
	v_add_u32_e32 v87, s99, v84
	ds_read_b128 v[88:91], v252 offset:16384
	ds_read_b128 v[92:95], v87
	ds_read_b128 v[96:99], v87 offset:4096
	ds_read_b128 v[100:103], v252 offset:20480
.LBB0_737:
	s_add_i32 s20, s3, s19
	s_mov_b32 s98, s20
	s_mov_b64 s[100:101], s[10:11]
	s_waitcnt lgkmcnt(0)
	v_add_u32_e32 v104, s99, v85
	v_add_u32_e32 v87, s99, v82
	s_add_i32 s20, s2, 0xc000
	s_cmp_lg_u32 s2, 0x18000
	s_cselect_b32 s2, s20, 0
	s_add_i32 s20, s19, 0xc000
	s_cmp_lg_u32 s19, 0x18000
	s_cselect_b32 s19, s20, 0
	s_add_u32 s10, s10, 0x80
	s_addc_u32 s11, s11, 0
	ds_read_b128 v[236:239], v104 offset:16384
	ds_read_b128 v[240:243], v87
	ds_read_b128 v[244:247], v87 offset:4096
	ds_read_b128 v[248:251], v104 offset:20480
	v_mfma_f32_32x32x16_bf16 v[48:63], v[88:91], v[92:95], v[48:63]
	v_mfma_f32_32x32x16_bf16 v[32:47], v[88:91], v[96:99], v[32:47]
	s_mov_b32 m0, s98
	v_lshl_add_u64 v[254:255], v[76:77], 0, s[100:101]
	global_load_lds_dwordx4 v[254:255], off
	v_mfma_f32_32x32x16_bf16 v[16:31], v[100:103], v[92:95], v[16:31]
	v_mfma_f32_32x32x16_bf16 v[0:15], v[100:103], v[96:99], v[0:15]
	s_add_i32 m0, s98, 0x2000
	v_lshl_add_u64 v[254:255], v[74:75], 0, s[100:101]
	global_load_lds_dwordx4 v[254:255], off
	v_add_u32_e32 v104, s99, v83
	v_add_u32_e32 v87, s99, v80
	s_waitcnt lgkmcnt(0)
	ds_read_b128 v[88:91], v104 offset:16384
	ds_read_b128 v[92:95], v87
	ds_read_b128 v[96:99], v87 offset:4096
	ds_read_b128 v[100:103], v104 offset:20480
	v_mfma_f32_32x32x16_bf16 v[48:63], v[236:239], v[240:243], v[48:63]
	v_mfma_f32_32x32x16_bf16 v[32:47], v[236:239], v[244:247], v[32:47]
	s_add_i32 m0, s98, 0x4000
	v_lshl_add_u64 v[254:255], v[72:73], 0, s[100:101]
	global_load_lds_dwordx4 v[254:255], off
	v_mfma_f32_32x32x16_bf16 v[16:31], v[248:251], v[240:243], v[16:31]
	v_mfma_f32_32x32x16_bf16 v[0:15], v[248:251], v[244:247], v[0:15]
	s_add_i32 m0, s98, 0x6000
	v_lshl_add_u64 v[254:255], v[70:71], 0, s[100:101]
	global_load_lds_dwordx4 v[254:255], off
	v_add_u32_e32 v104, s99, v81
	v_add_u32_e32 v87, s99, v79
	s_waitcnt lgkmcnt(0)
	ds_read_b128 v[236:239], v104 offset:16384
	ds_read_b128 v[240:243], v87
	ds_read_b128 v[244:247], v87 offset:4096
	ds_read_b128 v[248:251], v104 offset:20480
	v_mfma_f32_32x32x16_bf16 v[48:63], v[88:91], v[92:95], v[48:63]
	v_mfma_f32_32x32x16_bf16 v[32:47], v[88:91], v[96:99], v[32:47]
	s_add_i32 m0, s98, 0x8000
	v_lshl_add_u64 v[254:255], v[68:69], 0, s[100:101]
	global_load_lds_dwordx4 v[254:255], off
	v_mfma_f32_32x32x16_bf16 v[16:31], v[100:103], v[92:95], v[16:31]
	v_mfma_f32_32x32x16_bf16 v[0:15], v[100:103], v[96:99], v[0:15]
	s_add_i32 m0, s98, 0xa000
	v_lshl_add_u64 v[254:255], v[66:67], 0, s[100:101]
	global_load_lds_dwordx4 v[254:255], off
	s_waitcnt vmcnt(6) lgkmcnt(0)
	s_barrier
; DEV int stage_next(int s) { return (s == 2 * GS_STAGE) ? 0 : s + GS_STAGE; }
; template <int WAIT0>
; DEV void gk_main(f32x16 (&acc)[2][2], const GTile& t, int s0) {
;     ...
;   vm_wait_bar<WAIT0>();
;   int stc = s0, std_ = stage_next(stage_next(s0));
; #pragma nounroll
;   for (int kt = 0; kt < nk - 2; ++kt) {
;     GK_DMA(std_, kt + 2);
;     GK_COMPUTE(stc);
;     vm_wait_bar<6>();
;     stc = stage_next(stc); std_ = stage_next(std_);
;   }
;   GK_COMPUTE(stc);
;   vm_wait_bar<0>();
;   stc = stage_next(stc);
;   GK_COMPUTE(stc);
;   vm_wait_bar<0>();
	s_waitcnt lgkmcnt(0)
	s_add_i32 s99, s2, 0
	v_add_u32_e32 v252, s99, v86
	v_add_u32_e32 v87, s99, v84
	ds_read_b128 v[88:91], v252 offset:16384
	ds_read_b128 v[92:95], v87
	ds_read_b128 v[96:99], v87 offset:4096
	ds_read_b128 v[100:103], v252 offset:20480
	v_mfma_f32_32x32x16_bf16 v[48:63], v[236:239], v[240:243], v[48:63]
	v_mfma_f32_32x32x16_bf16 v[32:47], v[236:239], v[244:247], v[32:47]
	v_mfma_f32_32x32x16_bf16 v[16:31], v[248:251], v[240:243], v[16:31]
	v_mfma_f32_32x32x16_bf16 v[0:15], v[248:251], v[244:247], v[0:15]
	s_cmpk_lg_i32 s10, 0x700
	s_cbranch_scc1 .LBB0_737
	s_waitcnt lgkmcnt(0)
	s_add_i32 s3, s2, 0
	v_add_u32_e32 v87, s3, v86
	ds_read_b128 v[66:69], v87 offset:16384
	v_add_u32_e32 v74, s3, v84
	ds_read_b128 v[70:73], v74
	ds_read_b128 v[74:77], v74 offset:4096
	ds_read_b128 v[88:91], v87 offset:20480
	v_add_u32_e32 v87, s3, v85
	s_mov_b64 s[10:11], 0
	s_waitcnt lgkmcnt(0)
	v_mfma_f32_32x32x16_bf16 v[0:15], v[88:91], v[74:77], v[0:15]
	v_mfma_f32_32x32x16_bf16 v[48:63], v[66:69], v[70:73], v[48:63]
	v_mfma_f32_32x32x16_bf16 v[32:47], v[66:69], v[74:77], v[32:47]
	ds_read_b128 v[66:69], v87 offset:16384
	v_add_u32_e32 v74, s3, v82
	v_mfma_f32_32x32x16_bf16 v[16:31], v[88:91], v[70:73], v[16:31]
	ds_read_b128 v[70:73], v74
	ds_read_b128 v[74:77], v74 offset:4096
	ds_read_b128 v[88:91], v87 offset:20480
	v_add_u32_e32 v87, s3, v83
	s_waitcnt lgkmcnt(0)
	v_mfma_f32_32x32x16_bf16 v[48:63], v[66:69], v[70:73], v[48:63]
	v_mfma_f32_32x32x16_bf16 v[32:47], v[66:69], v[74:77], v[32:47]
	ds_read_b128 v[66:69], v87 offset:16384
	v_mfma_f32_32x32x16_bf16 v[0:15], v[88:91], v[74:77], v[0:15]
	v_add_u32_e32 v74, s3, v80
	v_mfma_f32_32x32x16_bf16 v[16:31], v[88:91], v[70:73], v[16:31]
	ds_read_b128 v[70:73], v74
	ds_read_b128 v[74:77], v74 offset:4096
	ds_read_b128 v[88:91], v87 offset:20480
	v_add_u32_e32 v87, s3, v81
	s_waitcnt lgkmcnt(0)
	v_mfma_f32_32x32x16_bf16 v[48:63], v[66:69], v[70:73], v[48:63]
	v_mfma_f32_32x32x16_bf16 v[32:47], v[66:69], v[74:77], v[32:47]
	ds_read_b128 v[66:69], v87 offset:16384
	v_mfma_f32_32x32x16_bf16 v[0:15], v[88:91], v[74:77], v[0:15]
	v_add_u32_e32 v74, s3, v79
	s_add_i32 s3, s2, 0xc000
	s_cmp_lg_u32 s2, 0x18000
	s_cselect_b32 s2, s3, 0
	s_add_i32 s2, s2, 0
	v_add_u32_e32 v86, s2, v86
	v_mfma_f32_32x32x16_bf16 v[16:31], v[88:91], v[70:73], v[16:31]
	ds_read_b128 v[70:73], v74
	ds_read_b128 v[74:77], v74 offset:4096
	ds_read_b128 v[88:91], v87 offset:20480
	s_waitcnt vmcnt(0) lgkmcnt(0)
	s_barrier
	s_waitcnt lgkmcnt(0)
	v_mfma_f32_32x32x16_bf16 v[48:63], v[66:69], v[70:73], v[48:63]
	v_mfma_f32_32x32x16_bf16 v[32:47], v[66:69], v[74:77], v[32:47]
	ds_read_b128 v[66:69], v86 offset:16384
	v_mfma_f32_32x32x16_bf16 v[16:31], v[88:91], v[70:73], v[16:31]
	v_mfma_f32_32x32x16_bf16 v[0:15], v[88:91], v[74:77], v[0:15]
	v_add_u32_e32 v74, s2, v84
	ds_read_b128 v[70:73], v74
	ds_read_b128 v[74:77], v74 offset:4096
	ds_read_b128 v[86:89], v86 offset:20480
	v_add_u32_e32 v84, s2, v85
	s_waitcnt lgkmcnt(0)
	v_mfma_f32_32x32x16_bf16 v[48:63], v[66:69], v[70:73], v[48:63]
	v_mfma_f32_32x32x16_bf16 v[32:47], v[66:69], v[74:77], v[32:47]
	ds_read_b128 v[66:69], v84 offset:16384
	v_mfma_f32_32x32x16_bf16 v[16:31], v[86:89], v[70:73], v[16:31]
	v_mfma_f32_32x32x16_bf16 v[0:15], v[86:89], v[74:77], v[0:15]
	v_add_u32_e32 v74, s2, v82
	ds_read_b128 v[70:73], v74
	ds_read_b128 v[74:77], v74 offset:4096
	ds_read_b128 v[84:87], v84 offset:20480
	v_add_u32_e32 v82, s2, v83
	s_waitcnt lgkmcnt(0)
	v_mfma_f32_32x32x16_bf16 v[48:63], v[66:69], v[70:73], v[48:63]
	v_mfma_f32_32x32x16_bf16 v[32:47], v[66:69], v[74:77], v[32:47]
	ds_read_b128 v[66:69], v82 offset:16384
	v_mfma_f32_32x32x16_bf16 v[16:31], v[84:87], v[70:73], v[16:31]
	v_mfma_f32_32x32x16_bf16 v[0:15], v[84:87], v[74:77], v[0:15]
	v_add_u32_e32 v74, s2, v80
	ds_read_b128 v[70:73], v74
	ds_read_b128 v[74:77], v74 offset:4096
	ds_read_b128 v[82:85], v82 offset:20480
	v_add_u32_e32 v80, s2, v81
	s_waitcnt lgkmcnt(0)
	v_mfma_f32_32x32x16_bf16 v[48:63], v[66:69], v[70:73], v[48:63]
	v_mfma_f32_32x32x16_bf16 v[32:47], v[66:69], v[74:77], v[32:47]
	ds_read_b128 v[66:69], v80 offset:16384
	v_mfma_f32_32x32x16_bf16 v[16:31], v[82:85], v[70:73], v[16:31]
	v_mfma_f32_32x32x16_bf16 v[0:15], v[82:85], v[74:77], v[0:15]
	v_add_u32_e32 v74, s2, v79
	ds_read_b128 v[70:73], v74
	ds_read_b128 v[74:77], v74 offset:4096
	ds_read_b128 v[80:83], v80 offset:20480
	s_waitcnt vmcnt(0) lgkmcnt(0)
	s_barrier
	s_waitcnt lgkmcnt(0)
	v_mfma_f32_32x32x16_bf16 v[48:63], v[66:69], v[70:73], v[48:63]
	v_mfma_f32_32x32x16_bf16 v[32:47], v[66:69], v[74:77], v[32:47]
	v_mfma_f32_32x32x16_bf16 v[16:31], v[80:83], v[70:73], v[16:31]
	v_mfma_f32_32x32x16_bf16 v[0:15], v[80:83], v[74:77], v[0:15]
; DEV int tid_l() { int t = threadIdx.x; asm volatile("" : "+v"(t)); return t; }
; DEV int stage_next(int s) { return (s == 2 * GS_STAGE) ? 0 : s + GS_STAGE; }
; DEV void gk_issue2(const GTile& t, int s0) {
;   const int tid = tid_l(), lane = tid & 63, wid = __builtin_amdgcn_readfirstlane(tid >> 6);
;   GK_SRC(t)
;   asm volatile("" ::: "memory");
;   GK_DMA(s0, 0);
;   GK_DMA(stage_next(s0), 1);
;   asm volatile("" ::: "memory");
; }
; template <int WAIT0>
; DEV void gk_main(f32x16 (&acc)[2][2], const GTile& t, int s0) {
;   const int tid = tid_l(), lane = tid & 63, wid = __builtin_amdgcn_readfirstlane(tid >> 6), wm = wid & 1, wn = wid >> 1, l32 = lane & 31, hi = lane >> 5;
;   GK_SRC(t)
;   const int sw = (l32 >> 1) & 7;
;   int xk[4], wk[4];
; #pragma unroll
;   for (int ks = 0; ks < 4; ++ks) { const int ko = ((2 * ks + hi) ^ sw) << 4; xk[ks] = GS_A + (64 * wm + l32) * 128 + ko; wk[ks] = GS_B + (64 * wn + l32) * 128 + ko; }
;   const int nk = t.K >> 6;
;     ...
;   vm_wait_bar<WAIT0>();
;   int stc = s0, std_ = stage_next(stage_next(s0));
; #pragma nounroll
;   for (int kt = 0; kt < nk - 2; ++kt) {
;     GK_DMA(std_, kt + 2);
;     GK_COMPUTE(stc);
;     vm_wait_bar<6>();
.LBB0_739:
	s_and_b64 vcc, exec, s[10:11]
	s_cbranch_vccz .LBB0_743
	s_nop 9
	v_mov_b32_e32 v1, v176
	s_waitcnt vmcnt(63) lgkmcnt(0)
	s_barrier
	v_readfirstlane_b32 s2, v1
	s_ashr_i32 s3, s2, 6
	v_bfe_u32 v0, v1, 3, 3
	v_and_b32_e32 v2, 31, v1
	v_lshl_or_b32 v0, s3, 3, v0
	v_lshrrev_b32_e32 v3, 1, v0
	v_and_or_b32 v6, s2, 64, v2
	s_lshr_b32 s2, s2, 1
	v_xor_b32_e32 v3, v3, v1
	s_and_b32 s2, s2, 0x1ffffc0
	v_lshlrev_b32_e32 v3, 4, v3
	v_or_b32_e32 v2, s2, v2
	s_lshl_b32 s2, s3, 10
	v_and_b32_e32 v4, 0x70, v3
	v_bfe_u32 v3, v1, 5, 1
	v_lshrrev_b32_e32 v5, 1, v1
	v_bfe_u32 v1, v1, 1, 3
	s_add_i32 s3, s2, 0
	s_add_i32 s2, s16, 0xc000
	v_bitop3_b32 v5, v3, v5, 7 bitop3:0x78
	v_bitop3_b32 v7, v3, v1, 2 bitop3:0x36
	v_bitop3_b32 v8, v3, v1, 4 bitop3:0x36
	v_bitop3_b32 v1, v3, v1, 6 bitop3:0x36
	s_cmp_lg_u32 s16, 0x18000
	v_lshlrev_b32_e32 v2, 7, v2
	v_lshlrev_b32_e32 v5, 4, v5
	v_lshlrev_b32_e32 v7, 4, v7
	v_lshlrev_b32_e32 v8, 4, v8
	v_lshlrev_b32_e32 v1, 4, v1
	s_cselect_b32 s18, s2, 0
	s_add_i32 s2, s18, 0xc000
	v_or_b32_e32 v86, v2, v5
	v_or_b32_e32 v85, v2, v7
	v_or_b32_e32 v83, v2, v8
	v_or_b32_e32 v81, v2, v1
	v_add_u32_e32 v2, 0xc0, v0
	s_cmp_lg_u32 s18, 0x18000
	v_ashrrev_i32_e32 v3, 31, v2
	s_cselect_b32 s19, s2, 0
	s_add_u32 s10, s6, 0x100
	v_lshlrev_b64 v[2:3], 11, v[2:3]
	s_addc_u32 s11, s7, 0
	v_or_b32_e32 v2, v2, v4
	v_lshl_add_u64 v[66:67], s[10:11], 0, v[2:3]
	v_add_u32_e32 v2, 0x80, v0
	v_ashrrev_i32_e32 v3, 31, v2
	v_lshlrev_b64 v[2:3], 11, v[2:3]
	v_lshlrev_b32_e32 v6, 7, v6
	v_or_b32_e32 v2, v2, v4
	v_or_b32_e32 v79, v1, v6
	v_lshl_add_u64 v[68:69], s[10:11], 0, v[2:3]
	v_add_u32_e32 v2, 64, v0
	v_ashrrev_i32_e32 v1, 31, v0
	v_ashrrev_i32_e32 v3, 31, v2
	v_lshlrev_b64 v[0:1], 11, v[0:1]
	v_lshlrev_b64 v[2:3], 11, v[2:3]
	v_or_b32_e32 v0, v0, v4
	v_or_b32_e32 v2, v2, v4
	v_lshl_add_u64 v[72:73], s[10:11], 0, v[0:1]
	v_lshl_add_u64 v[76:77], s[8:9], 0, v[0:1]
	v_mov_b32_e32 v0, 0
	v_or_b32_e32 v84, v5, v6
	v_or_b32_e32 v82, v7, v6
	v_or_b32_e32 v80, v8, v6
	v_lshl_add_u64 v[70:71], s[10:11], 0, v[2:3]
	v_lshl_add_u64 v[74:75], s[8:9], 0, v[2:3]
	s_mov_b64 s[10:11], 0
	s_mov_b32 s2, s16
	v_mov_b32_e32 v1, v0
	v_mov_b32_e32 v2, v0
	v_mov_b32_e32 v3, v0
	v_mov_b32_e32 v4, v0
	v_mov_b32_e32 v5, v0
	v_mov_b32_e32 v6, v0
	v_mov_b32_e32 v7, v0
	v_mov_b32_e32 v8, v0
	v_mov_b32_e32 v9, v0
	v_mov_b32_e32 v10, v0
	v_mov_b32_e32 v11, v0
	v_mov_b32_e32 v12, v0
	v_mov_b32_e32 v13, v0
	v_mov_b32_e32 v14, v0
	v_mov_b32_e32 v15, v0
	v_mov_b32_e32 v16, v0
	v_mov_b32_e32 v17, v0
	v_mov_b32_e32 v18, v0
	v_mov_b32_e32 v19, v0
	v_mov_b32_e32 v20, v0
	v_mov_b32_e32 v21, v0
	v_mov_b32_e32 v22, v0
	v_mov_b32_e32 v23, v0
	v_mov_b32_e32 v24, v0
	v_mov_b32_e32 v25, v0
	v_mov_b32_e32 v26, v0
	v_mov_b32_e32 v27, v0
	v_mov_b32_e32 v28, v0
	v_mov_b32_e32 v29, v0
	v_mov_b32_e32 v30, v0
	v_mov_b32_e32 v31, v0
	v_mov_b32_e32 v32, v0
	v_mov_b32_e32 v33, v0
	v_mov_b32_e32 v34, v0
	v_mov_b32_e32 v35, v0
	v_mov_b32_e32 v36, v0
	v_mov_b32_e32 v37, v0
	v_mov_b32_e32 v38, v0
	v_mov_b32_e32 v39, v0
	v_mov_b32_e32 v40, v0
	v_mov_b32_e32 v41, v0
	v_mov_b32_e32 v42, v0
	v_mov_b32_e32 v43, v0
	v_mov_b32_e32 v44, v0
	v_mov_b32_e32 v45, v0
	v_mov_b32_e32 v46, v0
	v_mov_b32_e32 v47, v0
	v_mov_b32_e32 v48, v0
	v_mov_b32_e32 v49, v0
	v_mov_b32_e32 v50, v0
	v_mov_b32_e32 v51, v0
	v_mov_b32_e32 v52, v0
	v_mov_b32_e32 v53, v0
	v_mov_b32_e32 v54, v0
	v_mov_b32_e32 v55, v0
	v_mov_b32_e32 v56, v0
	v_mov_b32_e32 v57, v0
	v_mov_b32_e32 v58, v0
	v_mov_b32_e32 v59, v0
	v_mov_b32_e32 v60, v0
	v_mov_b32_e32 v61, v0
	v_mov_b32_e32 v62, v0
	v_mov_b32_e32 v63, v0
	s_add_i32 s99, s2, 0
	v_add_u32_e32 v252, s99, v86
	v_add_u32_e32 v87, s99, v84
	ds_read_b128 v[88:91], v252 offset:16384
	ds_read_b128 v[92:95], v87
	ds_read_b128 v[96:99], v87 offset:4096
	ds_read_b128 v[100:103], v252 offset:20480
.LBB0_741:
	s_add_i32 s20, s3, s19
	s_mov_b32 s98, s20
	s_mov_b64 s[100:101], s[10:11]
	s_waitcnt lgkmcnt(0)
	v_add_u32_e32 v104, s99, v85
	v_add_u32_e32 v87, s99, v82
	s_add_i32 s20, s2, 0xc000
	s_cmp_lg_u32 s2, 0x18000
	s_cselect_b32 s2, s20, 0
	s_add_i32 s20, s19, 0xc000
	s_cmp_lg_u32 s19, 0x18000
	s_cselect_b32 s19, s20, 0
	s_add_u32 s10, s10, 0x80
	s_addc_u32 s11, s11, 0
	ds_read_b128 v[236:239], v104 offset:16384
	ds_read_b128 v[240:243], v87
	ds_read_b128 v[244:247], v87 offset:4096
	ds_read_b128 v[248:251], v104 offset:20480
	v_mfma_f32_32x32x16_bf16 v[48:63], v[88:91], v[92:95], v[48:63]
	v_mfma_f32_32x32x16_bf16 v[32:47], v[88:91], v[96:99], v[32:47]
	s_mov_b32 m0, s98
	v_lshl_add_u64 v[254:255], v[76:77], 0, s[100:101]
	global_load_lds_dwordx4 v[254:255], off
	v_mfma_f32_32x32x16_bf16 v[16:31], v[100:103], v[92:95], v[16:31]
	v_mfma_f32_32x32x16_bf16 v[0:15], v[100:103], v[96:99], v[0:15]
	s_add_i32 m0, s98, 0x2000
	v_lshl_add_u64 v[254:255], v[74:75], 0, s[100:101]
	global_load_lds_dwordx4 v[254:255], off
	v_add_u32_e32 v104, s99, v83
	v_add_u32_e32 v87, s99, v80
	s_waitcnt lgkmcnt(0)
	ds_read_b128 v[88:91], v104 offset:16384
	ds_read_b128 v[92:95], v87
	ds_read_b128 v[96:99], v87 offset:4096
	ds_read_b128 v[100:103], v104 offset:20480
	v_mfma_f32_32x32x16_bf16 v[48:63], v[236:239], v[240:243], v[48:63]
	v_mfma_f32_32x32x16_bf16 v[32:47], v[236:239], v[244:247], v[32:47]
	s_add_i32 m0, s98, 0x4000
	v_lshl_add_u64 v[254:255], v[72:73], 0, s[100:101]
	global_load_lds_dwordx4 v[254:255], off
	v_mfma_f32_32x32x16_bf16 v[16:31], v[248:251], v[240:243], v[16:31]
	v_mfma_f32_32x32x16_bf16 v[0:15], v[248:251], v[244:247], v[0:15]
	s_add_i32 m0, s98, 0x6000
	v_lshl_add_u64 v[254:255], v[70:71], 0, s[100:101]
	global_load_lds_dwordx4 v[254:255], off
	v_add_u32_e32 v104, s99, v81
	v_add_u32_e32 v87, s99, v79
	s_waitcnt lgkmcnt(0)
	ds_read_b128 v[236:239], v104 offset:16384
	ds_read_b128 v[240:243], v87
	ds_read_b128 v[244:247], v87 offset:4096
	ds_read_b128 v[248:251], v104 offset:20480
	v_mfma_f32_32x32x16_bf16 v[48:63], v[88:91], v[92:95], v[48:63]
	v_mfma_f32_32x32x16_bf16 v[32:47], v[88:91], v[96:99], v[32:47]
	s_add_i32 m0, s98, 0x8000
	v_lshl_add_u64 v[254:255], v[68:69], 0, s[100:101]
	global_load_lds_dwordx4 v[254:255], off
	v_mfma_f32_32x32x16_bf16 v[16:31], v[100:103], v[92:95], v[16:31]
	v_mfma_f32_32x32x16_bf16 v[0:15], v[100:103], v[96:99], v[0:15]
	s_add_i32 m0, s98, 0xa000
	v_lshl_add_u64 v[254:255], v[66:67], 0, s[100:101]
	global_load_lds_dwordx4 v[254:255], off
	s_waitcnt vmcnt(6) lgkmcnt(0)
	s_barrier
; DEV int stage_next(int s) { return (s == 2 * GS_STAGE) ? 0 : s + GS_STAGE; }
; template <int WAIT0>
; DEV void gk_main(f32x16 (&acc)[2][2], const GTile& t, int s0) {
;     ...
;   vm_wait_bar<WAIT0>();
;   int stc = s0, std_ = stage_next(stage_next(s0));
; #pragma nounroll
;   for (int kt = 0; kt < nk - 2; ++kt) {
;     GK_DMA(std_, kt + 2);
;     GK_COMPUTE(stc);
;     vm_wait_bar<6>();
;     stc = stage_next(stc); std_ = stage_next(std_);
;   }
;   GK_COMPUTE(stc);
;   vm_wait_bar<0>();
;   stc = stage_next(stc);
;   GK_COMPUTE(stc);
;   vm_wait_bar<0>();
	s_waitcnt lgkmcnt(0)
	s_add_i32 s99, s2, 0
	v_add_u32_e32 v252, s99, v86
	v_add_u32_e32 v87, s99, v84
	ds_read_b128 v[88:91], v252 offset:16384
	ds_read_b128 v[92:95], v87
	ds_read_b128 v[96:99], v87 offset:4096
	ds_read_b128 v[100:103], v252 offset:20480
	v_mfma_f32_32x32x16_bf16 v[48:63], v[236:239], v[240:243], v[48:63]
	v_mfma_f32_32x32x16_bf16 v[32:47], v[236:239], v[244:247], v[32:47]
	v_mfma_f32_32x32x16_bf16 v[16:31], v[248:251], v[240:243], v[16:31]
	v_mfma_f32_32x32x16_bf16 v[0:15], v[248:251], v[244:247], v[0:15]
	s_cmpk_lg_i32 s10, 0x700
	s_cbranch_scc1 .LBB0_741
	s_waitcnt lgkmcnt(0)
	s_add_i32 s3, s2, 0
	v_add_u32_e32 v87, s3, v86
	ds_read_b128 v[66:69], v87 offset:16384
	v_add_u32_e32 v74, s3, v84
	ds_read_b128 v[70:73], v74
	ds_read_b128 v[74:77], v74 offset:4096
	ds_read_b128 v[88:91], v87 offset:20480
	v_add_u32_e32 v87, s3, v85
	s_waitcnt lgkmcnt(0)
	v_mfma_f32_32x32x16_bf16 v[0:15], v[88:91], v[74:77], v[0:15]
	v_mfma_f32_32x32x16_bf16 v[48:63], v[66:69], v[70:73], v[48:63]
	v_mfma_f32_32x32x16_bf16 v[32:47], v[66:69], v[74:77], v[32:47]
	ds_read_b128 v[66:69], v87 offset:16384
	v_add_u32_e32 v74, s3, v82
	v_mfma_f32_32x32x16_bf16 v[16:31], v[88:91], v[70:73], v[16:31]
	ds_read_b128 v[70:73], v74
	ds_read_b128 v[74:77], v74 offset:4096
	ds_read_b128 v[88:91], v87 offset:20480
	v_add_u32_e32 v87, s3, v83
	s_waitcnt lgkmcnt(0)
	v_mfma_f32_32x32x16_bf16 v[48:63], v[66:69], v[70:73], v[48:63]
	v_mfma_f32_32x32x16_bf16 v[32:47], v[66:69], v[74:77], v[32:47]
	ds_read_b128 v[66:69], v87 offset:16384
	v_mfma_f32_32x32x16_bf16 v[0:15], v[88:91], v[74:77], v[0:15]
	v_add_u32_e32 v74, s3, v80
	v_mfma_f32_32x32x16_bf16 v[16:31], v[88:91], v[70:73], v[16:31]
	ds_read_b128 v[70:73], v74
	ds_read_b128 v[74:77], v74 offset:4096
	ds_read_b128 v[88:91], v87 offset:20480
	v_add_u32_e32 v87, s3, v81
	s_waitcnt lgkmcnt(0)
	v_mfma_f32_32x32x16_bf16 v[48:63], v[66:69], v[70:73], v[48:63]
	v_mfma_f32_32x32x16_bf16 v[32:47], v[66:69], v[74:77], v[32:47]
	ds_read_b128 v[66:69], v87 offset:16384
	v_mfma_f32_32x32x16_bf16 v[0:15], v[88:91], v[74:77], v[0:15]
	v_add_u32_e32 v74, s3, v79
	s_add_i32 s3, s2, 0xc000
	s_cmp_lg_u32 s2, 0x18000
	s_cselect_b32 s2, s3, 0
	s_add_i32 s2, s2, 0
	v_add_u32_e32 v86, s2, v86
	v_mfma_f32_32x32x16_bf16 v[16:31], v[88:91], v[70:73], v[16:31]
	ds_read_b128 v[70:73], v74
	ds_read_b128 v[74:77], v74 offset:4096
	ds_read_b128 v[88:91], v87 offset:20480
	s_waitcnt vmcnt(0) lgkmcnt(0)
	s_barrier
	s_waitcnt lgkmcnt(0)
	v_mfma_f32_32x32x16_bf16 v[48:63], v[66:69], v[70:73], v[48:63]
	v_mfma_f32_32x32x16_bf16 v[32:47], v[66:69], v[74:77], v[32:47]
	ds_read_b128 v[66:69], v86 offset:16384
	v_mfma_f32_32x32x16_bf16 v[16:31], v[88:91], v[70:73], v[16:31]
	v_mfma_f32_32x32x16_bf16 v[0:15], v[88:91], v[74:77], v[0:15]
	v_add_u32_e32 v74, s2, v84
	ds_read_b128 v[70:73], v74
	ds_read_b128 v[74:77], v74 offset:4096
	ds_read_b128 v[86:89], v86 offset:20480
	v_add_u32_e32 v84, s2, v85
	s_waitcnt lgkmcnt(0)
	v_mfma_f32_32x32x16_bf16 v[48:63], v[66:69], v[70:73], v[48:63]
	v_mfma_f32_32x32x16_bf16 v[32:47], v[66:69], v[74:77], v[32:47]
	ds_read_b128 v[66:69], v84 offset:16384
	v_mfma_f32_32x32x16_bf16 v[16:31], v[86:89], v[70:73], v[16:31]
	v_mfma_f32_32x32x16_bf16 v[0:15], v[86:89], v[74:77], v[0:15]
	v_add_u32_e32 v74, s2, v82
	ds_read_b128 v[70:73], v74
	ds_read_b128 v[74:77], v74 offset:4096
	ds_read_b128 v[84:87], v84 offset:20480
	v_add_u32_e32 v82, s2, v83
	s_waitcnt lgkmcnt(0)
	v_mfma_f32_32x32x16_bf16 v[48:63], v[66:69], v[70:73], v[48:63]
	v_mfma_f32_32x32x16_bf16 v[32:47], v[66:69], v[74:77], v[32:47]
	ds_read_b128 v[66:69], v82 offset:16384
	v_mfma_f32_32x32x16_bf16 v[16:31], v[84:87], v[70:73], v[16:31]
	v_mfma_f32_32x32x16_bf16 v[0:15], v[84:87], v[74:77], v[0:15]
	v_add_u32_e32 v74, s2, v80
	ds_read_b128 v[70:73], v74
	ds_read_b128 v[74:77], v74 offset:4096
	ds_read_b128 v[82:85], v82 offset:20480
	v_add_u32_e32 v80, s2, v81
	s_waitcnt lgkmcnt(0)
	v_mfma_f32_32x32x16_bf16 v[48:63], v[66:69], v[70:73], v[48:63]
	v_mfma_f32_32x32x16_bf16 v[32:47], v[66:69], v[74:77], v[32:47]
	ds_read_b128 v[66:69], v80 offset:16384
	v_mfma_f32_32x32x16_bf16 v[16:31], v[82:85], v[70:73], v[16:31]
	v_mfma_f32_32x32x16_bf16 v[0:15], v[82:85], v[74:77], v[0:15]
	v_add_u32_e32 v74, s2, v79
	ds_read_b128 v[70:73], v74
	ds_read_b128 v[74:77], v74 offset:4096
	ds_read_b128 v[80:83], v80 offset:20480
	s_waitcnt vmcnt(0) lgkmcnt(0)
	s_barrier
	s_waitcnt lgkmcnt(0)
	v_mfma_f32_32x32x16_bf16 v[48:63], v[66:69], v[70:73], v[48:63]
	v_mfma_f32_32x32x16_bf16 v[32:47], v[66:69], v[74:77], v[32:47]
	v_mfma_f32_32x32x16_bf16 v[16:31], v[80:83], v[70:73], v[16:31]
	v_mfma_f32_32x32x16_bf16 v[0:15], v[80:83], v[74:77], v[0:15]

; DEV int tid_l() { int t = threadIdx.x; asm volatile("" : "+v"(t)); return t; }
; DEV int stage_next(int s) { return (s == 2 * GS_STAGE) ? 0 : s + GS_STAGE; }
; DEV void gk_issue2(const GTile& t, int s0) {
;   const int tid = tid_l(), lane = tid & 63, wid = __builtin_amdgcn_readfirstlane(tid >> 6);
;   GK_SRC(t)
;   asm volatile("" ::: "memory");
;   GK_DMA(s0, 0);
;   GK_DMA(stage_next(s0), 1);
;   asm volatile("" ::: "memory");
; }
; template <int WAIT0>
; DEV void gk_main(f32x16 (&acc)[2][2], const GTile& t, int s0) {
;   const int tid = tid_l(), lane = tid & 63, wid = __builtin_amdgcn_readfirstlane(tid >> 6), wm = wid & 1, wn = wid >> 1, l32 = lane & 31, hi = lane >> 5;
;   GK_SRC(t)
;   const int sw = (l32 >> 1) & 7;
;   int xk[4], wk[4];
; #pragma unroll
;   for (int ks = 0; ks < 4; ++ks) { const int ko = ((2 * ks + hi) ^ sw) << 4; xk[ks] = GS_A + (64 * wm + l32) * 128 + ko; wk[ks] = GS_B + (64 * wn + l32) * 128 + ko; }
;   const int nk = t.K >> 6;
;     ...
;   vm_wait_bar<WAIT0>();
;   int stc = s0, std_ = stage_next(stage_next(s0));
; #pragma nounroll
;   for (int kt = 0; kt < nk - 2; ++kt) {
;     GK_DMA(std_, kt + 2);
;     GK_COMPUTE(stc);
;     vm_wait_bar<6>();
.LBB0_745:
.LBB0_746:
	s_nop 10
	v_mov_b32_e32 v1, v176
	s_waitcnt vmcnt(6) lgkmcnt(0)
	s_barrier
	v_readfirstlane_b32 s2, v1
	s_ashr_i32 s3, s2, 6
	v_bfe_u32 v0, v1, 3, 3
	v_and_b32_e32 v2, 31, v1
	v_lshl_or_b32 v0, s3, 3, v0
	v_lshrrev_b32_e32 v3, 1, v0
	v_and_or_b32 v6, s2, 64, v2
	s_lshr_b32 s2, s2, 1
	v_xor_b32_e32 v3, v3, v1
	s_and_b32 s2, s2, 0x1ffffc0
	v_lshlrev_b32_e32 v3, 4, v3
	v_or_b32_e32 v2, s2, v2
	s_lshl_b32 s2, s3, 10
	v_and_b32_e32 v4, 0x70, v3
	v_bfe_u32 v3, v1, 5, 1
	v_lshrrev_b32_e32 v5, 1, v1
	v_bfe_u32 v1, v1, 1, 3
	s_add_i32 s2, s2, 0
	s_add_i32 s3, s16, 0xc000
	v_bitop3_b32 v5, v3, v5, 7 bitop3:0x78
	v_bitop3_b32 v7, v3, v1, 2 bitop3:0x36
	v_bitop3_b32 v8, v3, v1, 4 bitop3:0x36
	v_bitop3_b32 v1, v3, v1, 6 bitop3:0x36
	s_cmp_lg_u32 s16, 0x18000
	v_lshlrev_b32_e32 v2, 7, v2
	v_lshlrev_b32_e32 v5, 4, v5
	v_lshlrev_b32_e32 v7, 4, v7
	v_lshlrev_b32_e32 v8, 4, v8
	v_lshlrev_b32_e32 v1, 4, v1
	s_cselect_b32 s18, s3, 0
	s_add_i32 s3, s18, 0xc000
	v_or_b32_e32 v86, v2, v5
	v_or_b32_e32 v85, v2, v7
	v_or_b32_e32 v83, v2, v8
	v_or_b32_e32 v81, v2, v1
	v_add_u32_e32 v2, 0xc0, v0
	s_cmp_lg_u32 s18, 0x18000
	v_ashrrev_i32_e32 v3, 31, v2
	s_cselect_b32 s3, s3, 0
	s_add_u32 s10, s6, 0x100
	v_lshlrev_b64 v[2:3], 11, v[2:3]
	s_addc_u32 s11, s7, 0
	v_or_b32_e32 v2, v2, v4
	v_lshl_add_u64 v[66:67], s[10:11], 0, v[2:3]
	v_add_u32_e32 v2, 0x80, v0
	v_ashrrev_i32_e32 v3, 31, v2
	v_lshlrev_b64 v[2:3], 11, v[2:3]
	v_lshlrev_b32_e32 v6, 7, v6
	v_or_b32_e32 v2, v2, v4
	v_or_b32_e32 v79, v1, v6
	v_lshl_add_u64 v[68:69], s[10:11], 0, v[2:3]
	v_add_u32_e32 v2, 64, v0
	v_ashrrev_i32_e32 v1, 31, v0
	v_ashrrev_i32_e32 v3, 31, v2
	v_lshlrev_b64 v[0:1], 11, v[0:1]
	v_lshlrev_b64 v[2:3], 11, v[2:3]
	v_or_b32_e32 v0, v0, v4
	v_or_b32_e32 v2, v2, v4
	v_lshl_add_u64 v[72:73], s[10:11], 0, v[0:1]
	v_lshl_add_u64 v[76:77], s[8:9], 0, v[0:1]
	v_mov_b32_e32 v0, 0
	v_or_b32_e32 v84, v5, v6
	v_or_b32_e32 v82, v7, v6
	v_or_b32_e32 v80, v8, v6
	v_lshl_add_u64 v[70:71], s[10:11], 0, v[2:3]
	v_lshl_add_u64 v[74:75], s[8:9], 0, v[2:3]
	s_mov_b64 s[10:11], 0
	v_mov_b32_e32 v1, v0
	v_mov_b32_e32 v2, v0
	v_mov_b32_e32 v3, v0
	v_mov_b32_e32 v4, v0
	v_mov_b32_e32 v5, v0
	v_mov_b32_e32 v6, v0
	v_mov_b32_e32 v7, v0
	v_mov_b32_e32 v8, v0
	v_mov_b32_e32 v9, v0
	v_mov_b32_e32 v10, v0
	v_mov_b32_e32 v11, v0
	v_mov_b32_e32 v12, v0
	v_mov_b32_e32 v13, v0
	v_mov_b32_e32 v14, v0
	v_mov_b32_e32 v15, v0
	v_mov_b32_e32 v16, v0
	v_mov_b32_e32 v17, v0
	v_mov_b32_e32 v18, v0
	v_mov_b32_e32 v19, v0
	v_mov_b32_e32 v20, v0
	v_mov_b32_e32 v21, v0
	v_mov_b32_e32 v22, v0
	v_mov_b32_e32 v23, v0
	v_mov_b32_e32 v24, v0
	v_mov_b32_e32 v25, v0
	v_mov_b32_e32 v26, v0
	v_mov_b32_e32 v27, v0
	v_mov_b32_e32 v28, v0
	v_mov_b32_e32 v29, v0
	v_mov_b32_e32 v30, v0
	v_mov_b32_e32 v31, v0
	v_mov_b32_e32 v32, v0
	v_mov_b32_e32 v33, v0
	v_mov_b32_e32 v34, v0
	v_mov_b32_e32 v35, v0
	v_mov_b32_e32 v36, v0
	v_mov_b32_e32 v37, v0
	v_mov_b32_e32 v38, v0
	v_mov_b32_e32 v39, v0
	v_mov_b32_e32 v40, v0
	v_mov_b32_e32 v41, v0
	v_mov_b32_e32 v42, v0
	v_mov_b32_e32 v43, v0
	v_mov_b32_e32 v44, v0
	v_mov_b32_e32 v45, v0
	v_mov_b32_e32 v46, v0
	v_mov_b32_e32 v47, v0
	v_mov_b32_e32 v48, v0
	v_mov_b32_e32 v49, v0
	v_mov_b32_e32 v50, v0
	v_mov_b32_e32 v51, v0
	v_mov_b32_e32 v52, v0
	v_mov_b32_e32 v53, v0
	v_mov_b32_e32 v54, v0
	v_mov_b32_e32 v55, v0
	v_mov_b32_e32 v56, v0
	v_mov_b32_e32 v57, v0
	v_mov_b32_e32 v58, v0
	v_mov_b32_e32 v59, v0
	v_mov_b32_e32 v60, v0
	v_mov_b32_e32 v61, v0
	v_mov_b32_e32 v62, v0
	v_mov_b32_e32 v63, v0
	s_add_i32 s99, s16, 0
	v_add_u32_e32 v252, s99, v86
	v_add_u32_e32 v87, s99, v84
	ds_read_b128 v[88:91], v252 offset:16384
	ds_read_b128 v[92:95], v87
	ds_read_b128 v[96:99], v87 offset:4096
	ds_read_b128 v[100:103], v252 offset:20480
.LBB0_747:
	s_add_i32 s19, s2, s3
	s_mov_b32 s98, s19
	s_mov_b64 s[100:101], s[10:11]
	s_waitcnt lgkmcnt(0)
	v_add_u32_e32 v104, s99, v85
	v_add_u32_e32 v87, s99, v82
	s_add_i32 s19, s16, 0xc000
	s_cmp_lg_u32 s16, 0x18000
	s_cselect_b32 s16, s19, 0
	s_add_i32 s19, s3, 0xc000
	s_cmp_lg_u32 s3, 0x18000
	s_cselect_b32 s3, s19, 0
	s_add_u32 s10, s10, 0x80
	s_addc_u32 s11, s11, 0
	ds_read_b128 v[236:239], v104 offset:16384
	ds_read_b128 v[240:243], v87
	ds_read_b128 v[244:247], v87 offset:4096
	ds_read_b128 v[248:251], v104 offset:20480
	v_mfma_f32_32x32x16_bf16 v[48:63], v[88:91], v[92:95], v[48:63]
	v_mfma_f32_32x32x16_bf16 v[32:47], v[88:91], v[96:99], v[32:47]
	s_mov_b32 m0, s98
	v_lshl_add_u64 v[254:255], v[76:77], 0, s[100:101]
	global_load_lds_dwordx4 v[254:255], off
	v_mfma_f32_32x32x16_bf16 v[16:31], v[100:103], v[92:95], v[16:31]
	v_mfma_f32_32x32x16_bf16 v[0:15], v[100:103], v[96:99], v[0:15]
	s_add_i32 m0, s98, 0x2000
	v_lshl_add_u64 v[254:255], v[74:75], 0, s[100:101]
	global_load_lds_dwordx4 v[254:255], off
	v_add_u32_e32 v104, s99, v83
	v_add_u32_e32 v87, s99, v80
	s_waitcnt lgkmcnt(0)
	ds_read_b128 v[88:91], v104 offset:16384
	ds_read_b128 v[92:95], v87
	ds_read_b128 v[96:99], v87 offset:4096
	ds_read_b128 v[100:103], v104 offset:20480
	v_mfma_f32_32x32x16_bf16 v[48:63], v[236:239], v[240:243], v[48:63]
	v_mfma_f32_32x32x16_bf16 v[32:47], v[236:239], v[244:247], v[32:47]
	s_add_i32 m0, s98, 0x4000
	v_lshl_add_u64 v[254:255], v[72:73], 0, s[100:101]
	global_load_lds_dwordx4 v[254:255], off
	v_mfma_f32_32x32x16_bf16 v[16:31], v[248:251], v[240:243], v[16:31]
	v_mfma_f32_32x32x16_bf16 v[0:15], v[248:251], v[244:247], v[0:15]
	s_add_i32 m0, s98, 0x6000
	v_lshl_add_u64 v[254:255], v[70:71], 0, s[100:101]
	global_load_lds_dwordx4 v[254:255], off
	v_add_u32_e32 v104, s99, v81
	v_add_u32_e32 v87, s99, v79
	s_waitcnt lgkmcnt(0)
	ds_read_b128 v[236:239], v104 offset:16384
	ds_read_b128 v[240:243], v87
	ds_read_b128 v[244:247], v87 offset:4096
	ds_read_b128 v[248:251], v104 offset:20480
	v_mfma_f32_32x32x16_bf16 v[48:63], v[88:91], v[92:95], v[48:63]
	v_mfma_f32_32x32x16_bf16 v[32:47], v[88:91], v[96:99], v[32:47]
	s_add_i32 m0, s98, 0x8000
	v_lshl_add_u64 v[254:255], v[68:69], 0, s[100:101]
	global_load_lds_dwordx4 v[254:255], off
	v_mfma_f32_32x32x16_bf16 v[16:31], v[100:103], v[92:95], v[16:31]
	v_mfma_f32_32x32x16_bf16 v[0:15], v[100:103], v[96:99], v[0:15]
	s_add_i32 m0, s98, 0xa000
	v_lshl_add_u64 v[254:255], v[66:67], 0, s[100:101]
	global_load_lds_dwordx4 v[254:255], off
	s_waitcnt vmcnt(6) lgkmcnt(0)
	s_barrier
; DEV int stage_next(int s) { return (s == 2 * GS_STAGE) ? 0 : s + GS_STAGE; }
; template <int WAIT0>
; DEV void gk_main(f32x16 (&acc)[2][2], const GTile& t, int s0) {
;     ...
;   vm_wait_bar<WAIT0>();
;   int stc = s0, std_ = stage_next(stage_next(s0));
; #pragma nounroll
;   for (int kt = 0; kt < nk - 2; ++kt) {
;     GK_DMA(std_, kt + 2);
;     GK_COMPUTE(stc);
;     vm_wait_bar<6>();
;     stc = stage_next(stc); std_ = stage_next(std_);
;   }
;   GK_COMPUTE(stc);
;   vm_wait_bar<0>();
;   stc = stage_next(stc);
;   GK_COMPUTE(stc);
;   vm_wait_bar<0>();
	s_waitcnt lgkmcnt(0)
	s_add_i32 s99, s16, 0
	v_add_u32_e32 v252, s99, v86
	v_add_u32_e32 v87, s99, v84
	ds_read_b128 v[88:91], v252 offset:16384
	ds_read_b128 v[92:95], v87
	ds_read_b128 v[96:99], v87 offset:4096
	ds_read_b128 v[100:103], v252 offset:20480
	v_mfma_f32_32x32x16_bf16 v[48:63], v[236:239], v[240:243], v[48:63]
	v_mfma_f32_32x32x16_bf16 v[32:47], v[236:239], v[244:247], v[32:47]
	v_mfma_f32_32x32x16_bf16 v[16:31], v[248:251], v[240:243], v[16:31]
	v_mfma_f32_32x32x16_bf16 v[0:15], v[248:251], v[244:247], v[0:15]
	s_cmpk_lg_i32 s10, 0x700
	s_cbranch_scc1 .LBB0_747
	s_waitcnt lgkmcnt(0)
	s_add_i32 s2, s16, 0
	v_add_u32_e32 v87, s2, v86
	ds_read_b128 v[66:69], v87 offset:16384
	v_add_u32_e32 v74, s2, v84
	ds_read_b128 v[70:73], v74
	ds_read_b128 v[74:77], v74 offset:4096
	ds_read_b128 v[88:91], v87 offset:20480
	v_add_u32_e32 v87, s2, v85
	s_waitcnt lgkmcnt(0)
	v_mfma_f32_32x32x16_bf16 v[0:15], v[88:91], v[74:77], v[0:15]
	v_mfma_f32_32x32x16_bf16 v[48:63], v[66:69], v[70:73], v[48:63]
	v_mfma_f32_32x32x16_bf16 v[32:47], v[66:69], v[74:77], v[32:47]
	ds_read_b128 v[66:69], v87 offset:16384
	v_add_u32_e32 v74, s2, v82
	v_mfma_f32_32x32x16_bf16 v[16:31], v[88:91], v[70:73], v[16:31]
	ds_read_b128 v[70:73], v74
	ds_read_b128 v[74:77], v74 offset:4096
	ds_read_b128 v[88:91], v87 offset:20480
	v_add_u32_e32 v87, s2, v83
	s_waitcnt lgkmcnt(0)
	v_mfma_f32_32x32x16_bf16 v[48:63], v[66:69], v[70:73], v[48:63]
	v_mfma_f32_32x32x16_bf16 v[32:47], v[66:69], v[74:77], v[32:47]
	ds_read_b128 v[66:69], v87 offset:16384
	v_mfma_f32_32x32x16_bf16 v[0:15], v[88:91], v[74:77], v[0:15]
	v_add_u32_e32 v74, s2, v80
	v_mfma_f32_32x32x16_bf16 v[16:31], v[88:91], v[70:73], v[16:31]
	ds_read_b128 v[70:73], v74
	ds_read_b128 v[74:77], v74 offset:4096
	ds_read_b128 v[88:91], v87 offset:20480
	v_add_u32_e32 v87, s2, v81
	s_waitcnt lgkmcnt(0)
	v_mfma_f32_32x32x16_bf16 v[48:63], v[66:69], v[70:73], v[48:63]
	v_mfma_f32_32x32x16_bf16 v[32:47], v[66:69], v[74:77], v[32:47]
	ds_read_b128 v[66:69], v87 offset:16384
	v_mfma_f32_32x32x16_bf16 v[0:15], v[88:91], v[74:77], v[0:15]
	v_add_u32_e32 v74, s2, v79
	s_add_i32 s2, s16, 0xc000
	s_cmp_lg_u32 s16, 0x18000
	s_cselect_b32 s2, s2, 0
	s_add_i32 s2, s2, 0
	v_add_u32_e32 v86, s2, v86
	v_mfma_f32_32x32x16_bf16 v[16:31], v[88:91], v[70:73], v[16:31]
	ds_read_b128 v[70:73], v74
	ds_read_b128 v[74:77], v74 offset:4096
	ds_read_b128 v[88:91], v87 offset:20480
	s_waitcnt vmcnt(0) lgkmcnt(0)
	s_barrier
	s_waitcnt lgkmcnt(0)
	v_mfma_f32_32x32x16_bf16 v[48:63], v[66:69], v[70:73], v[48:63]
	v_mfma_f32_32x32x16_bf16 v[32:47], v[66:69], v[74:77], v[32:47]
	ds_read_b128 v[66:69], v86 offset:16384
	v_mfma_f32_32x32x16_bf16 v[16:31], v[88:91], v[70:73], v[16:31]
	v_mfma_f32_32x32x16_bf16 v[0:15], v[88:91], v[74:77], v[0:15]
	v_add_u32_e32 v74, s2, v84
	ds_read_b128 v[70:73], v74
	ds_read_b128 v[74:77], v74 offset:4096
	ds_read_b128 v[86:89], v86 offset:20480
	v_add_u32_e32 v84, s2, v85
	s_waitcnt lgkmcnt(0)
	v_mfma_f32_32x32x16_bf16 v[48:63], v[66:69], v[70:73], v[48:63]
	v_mfma_f32_32x32x16_bf16 v[32:47], v[66:69], v[74:77], v[32:47]
	ds_read_b128 v[66:69], v84 offset:16384
	v_mfma_f32_32x32x16_bf16 v[16:31], v[86:89], v[70:73], v[16:31]
	v_mfma_f32_32x32x16_bf16 v[0:15], v[86:89], v[74:77], v[0:15]
	v_add_u32_e32 v74, s2, v82
	ds_read_b128 v[70:73], v74
	ds_read_b128 v[74:77], v74 offset:4096
	ds_read_b128 v[84:87], v84 offset:20480
	v_add_u32_e32 v82, s2, v83
	s_waitcnt lgkmcnt(0)
	v_mfma_f32_32x32x16_bf16 v[48:63], v[66:69], v[70:73], v[48:63]
	v_mfma_f32_32x32x16_bf16 v[32:47], v[66:69], v[74:77], v[32:47]
	ds_read_b128 v[66:69], v82 offset:16384
	v_mfma_f32_32x32x16_bf16 v[16:31], v[84:87], v[70:73], v[16:31]
	v_mfma_f32_32x32x16_bf16 v[0:15], v[84:87], v[74:77], v[0:15]
	v_add_u32_e32 v74, s2, v80
	ds_read_b128 v[70:73], v74
	ds_read_b128 v[74:77], v74 offset:4096
	ds_read_b128 v[82:85], v82 offset:20480
	v_add_u32_e32 v80, s2, v81
	s_waitcnt lgkmcnt(0)
	v_mfma_f32_32x32x16_bf16 v[48:63], v[66:69], v[70:73], v[48:63]
	v_mfma_f32_32x32x16_bf16 v[32:47], v[66:69], v[74:77], v[32:47]
	ds_read_b128 v[66:69], v80 offset:16384
	v_mfma_f32_32x32x16_bf16 v[16:31], v[82:85], v[70:73], v[16:31]
	v_mfma_f32_32x32x16_bf16 v[0:15], v[82:85], v[74:77], v[0:15]
	v_add_u32_e32 v74, s2, v79
	ds_read_b128 v[70:73], v74
	ds_read_b128 v[74:77], v74 offset:4096
	ds_read_b128 v[80:83], v80 offset:20480
	s_waitcnt vmcnt(0) lgkmcnt(0)
	s_barrier
	s_waitcnt lgkmcnt(0)
	v_mfma_f32_32x32x16_bf16 v[48:63], v[66:69], v[70:73], v[48:63]
	v_mfma_f32_32x32x16_bf16 v[32:47], v[66:69], v[74:77], v[32:47]
	v_mfma_f32_32x32x16_bf16 v[16:31], v[80:83], v[70:73], v[16:31]
	v_mfma_f32_32x32x16_bf16 v[0:15], v[80:83], v[74:77], v[0:15]
	s_add_i32 s2, s17, 1
	s_mov_b32 s16, s18
	s_cmp_eq_u32 s17, 3
	s_cbranch_scc1 .LBB0_733

; DEV int tid_l() { int t = threadIdx.x; asm volatile("" : "+v"(t)); return t; }
; DEV int stage_next(int s) { return (s == 2 * GS_STAGE) ? 0 : s + GS_STAGE; }
; DEV void gk_issue2(const GTile& t, int s0) {
;   const int tid = tid_l(), lane = tid & 63, wid = __builtin_amdgcn_readfirstlane(tid >> 6);
;   GK_SRC(t)
;   asm volatile("" ::: "memory");
;   GK_DMA(s0, 0);
;   GK_DMA(stage_next(s0), 1);
;   asm volatile("" ::: "memory");
; }
; template <int WAIT0>
; DEV void gk_main(f32x16 (&acc)[2][2], const GTile& t, int s0) {
;   const int tid = tid_l(), lane = tid & 63, wid = __builtin_amdgcn_readfirstlane(tid >> 6), wm = wid & 1, wn = wid >> 1, l32 = lane & 31, hi = lane >> 5;
;   GK_SRC(t)
;   const int sw = (l32 >> 1) & 7;
;   int xk[4], wk[4];
; #pragma unroll
;   for (int ks = 0; ks < 4; ++ks) { const int ko = ((2 * ks + hi) ^ sw) << 4; xk[ks] = GS_A + (64 * wm + l32) * 128 + ko; wk[ks] = GS_B + (64 * wn + l32) * 128 + ko; }
;   const int nk = t.K >> 6;
;     ...
;   vm_wait_bar<WAIT0>();
;   int stc = s0, std_ = stage_next(stage_next(s0));
.LBB0_839:
	s_cmp_lg_u32 s19, 0
	s_cbranch_scc0 .LBB0_852
	s_bitcmp0_b32 s19, 0
	s_mov_b64 s[8:9], -1
	s_cbranch_scc1 .LBB0_844
	v_mov_b32_e32 v0, v176
	s_lshr_b32 s8, s16, 6
	v_readfirstlane_b32 s2, v0
	v_and_b32_e32 v1, 31, v0
	s_ashr_i32 s3, s2, 6
	v_and_or_b32 v7, s2, 64, v1
	s_lshr_b32 s2, s2, 1
	s_and_b32 s2, s2, 0x1ffffc0
	v_bfe_u32 v2, v0, 3, 3
	v_or_b32_e32 v1, s2, v1
	s_lshl_b32 s2, s3, 10
	v_lshl_or_b32 v4, s3, 3, v2
	s_add_i32 s3, s18, 0xc000
	s_add_i32 s2, s2, 0
	s_cmp_lg_u32 s18, 0x18000
	s_cselect_b32 s17, s3, 0
	s_add_i32 s3, s17, 0xc000
	v_lshrrev_b32_e32 v2, 1, v4
	v_bfe_u32 v3, v0, 5, 1
	v_lshrrev_b32_e32 v5, 1, v0
	v_bfe_u32 v6, v0, 1, 3
	s_cmp_lg_u32 s17, 0x18000
	v_bitop3_b32 v5, v3, v5, 7 bitop3:0x78
	v_bitop3_b32 v8, v3, v6, 2 bitop3:0x36
	v_bitop3_b32 v9, v3, v6, 4 bitop3:0x36
	v_bitop3_b32 v3, v3, v6, 6 bitop3:0x36
	s_cselect_b32 s3, s3, 0
	s_add_i32 s8, s8, -2
	v_bitop3_b32 v0, v2, 7, v0 bitop3:0x48
	v_lshlrev_b32_e32 v1, 7, v1
	v_lshlrev_b32_e32 v5, 4, v5
	v_lshlrev_b32_e32 v8, 4, v8
	v_lshlrev_b32_e32 v9, 4, v9
	v_lshlrev_b32_e32 v3, 4, v3
	v_lshlrev_b32_e32 v120, 4, v0
	s_add_u32 s10, s6, 0x100
	v_add_u32_e32 v0, 0xc0, v4
	v_lshlrev_b32_e32 v7, 7, v7
	v_or_b32_e32 v83, v1, v5
	v_or_b32_e32 v82, v1, v8
	v_or_b32_e32 v80, v1, v9
	v_or_b32_e32 v78, v1, v3
	s_addc_u32 s11, s7, 0
	v_ashrrev_i32_e32 v1, 31, v0
	v_or_b32_e32 v76, v3, v7
	v_alignbit_b32 v3, v1, v0, 31
	v_lshlrev_b32_e32 v2, 1, v0
	v_mov_b64_e32 v[0:1], s[10:11]
	v_mad_u64_u32 v[64:65], s[10:11], v2, s16, v[0:1]
	v_mov_b32_e32 v2, v65
	v_mad_u64_u32 v[2:3], s[10:11], v3, s16, v[2:3]
	v_mov_b32_e32 v65, v2
	v_add_u32_e32 v2, 0x80, v4
	v_ashrrev_i32_e32 v3, 31, v2
	v_alignbit_b32 v3, v3, v2, 31
	v_lshlrev_b32_e32 v2, 1, v2
	v_mad_u64_u32 v[66:67], s[10:11], v2, s16, v[0:1]
	v_mov_b32_e32 v2, v67
	v_mad_u64_u32 v[2:3], s[10:11], v3, s16, v[2:3]
	v_add_u32_e32 v3, 64, v4
	v_lshlrev_b32_e32 v6, 1, v3
	v_or_b32_e32 v81, v5, v7
	v_ashrrev_i32_e32 v5, 31, v3
	v_mad_u64_u32 v[68:69], s[10:11], v6, s16, v[0:1]
	v_mov_b32_e32 v67, v2
	v_mov_b32_e32 v2, v69
	v_alignbit_b32 v5, v5, v3, 31
	v_or_b32_e32 v79, v8, v7
	v_or_b32_e32 v77, v9, v7
	v_mad_u64_u32 v[2:3], s[10:11], v5, s16, v[2:3]
	v_lshlrev_b32_e32 v7, 1, v4
	v_mov_b32_e32 v69, v2
	v_ashrrev_i32_e32 v2, 31, v4
	v_mad_u64_u32 v[70:71], s[10:11], v7, s16, v[0:1]
	v_mov_b32_e32 v0, v71
	v_alignbit_b32 v4, v2, v4, 31
	v_mad_u64_u32 v[0:1], s[10:11], v4, s16, v[0:1]
	s_add_u32 s10, s4, 0x100
	s_addc_u32 s11, s5, 0
	v_mov_b32_e32 v71, v0
	v_mov_b64_e32 v[0:1], s[10:11]
	v_mad_u64_u32 v[74:75], s[10:11], v7, s16, v[0:1]
	v_mad_u64_u32 v[72:73], s[10:11], v6, s16, v[0:1]
	v_mov_b32_e32 v0, v75
	s_waitcnt vmcnt(6) lgkmcnt(0)
	s_barrier
	v_mov_b32_e32 v2, v73
	v_mad_u64_u32 v[0:1], s[10:11], v4, s16, v[0:1]
	v_mad_u64_u32 v[2:3], s[10:11], v5, s16, v[2:3]
	v_mov_b32_e32 v75, v0
	v_mov_b32_e32 v0, 0
	v_mov_b32_e32 v73, v2
	s_mov_b32 s9, s18
	v_mov_b32_e32 v1, v0
	v_mov_b32_e32 v2, v0
	v_mov_b32_e32 v3, v0
	v_mov_b32_e32 v4, v0
	v_mov_b32_e32 v5, v0
	v_mov_b32_e32 v6, v0
	v_mov_b32_e32 v7, v0
	v_mov_b32_e32 v8, v0
	v_mov_b32_e32 v9, v0
	v_mov_b32_e32 v10, v0
	v_mov_b32_e32 v11, v0
	v_mov_b32_e32 v12, v0
	v_mov_b32_e32 v13, v0
	v_mov_b32_e32 v14, v0
	v_mov_b32_e32 v15, v0
	v_mov_b32_e32 v16, v0
	v_mov_b32_e32 v17, v0
	v_mov_b32_e32 v18, v0
	v_mov_b32_e32 v19, v0
	v_mov_b32_e32 v20, v0
	v_mov_b32_e32 v21, v0
	v_mov_b32_e32 v22, v0
	v_mov_b32_e32 v23, v0
	v_mov_b32_e32 v24, v0
	v_mov_b32_e32 v25, v0
	v_mov_b32_e32 v26, v0
	v_mov_b32_e32 v27, v0
	v_mov_b32_e32 v28, v0
	v_mov_b32_e32 v29, v0
	v_mov_b32_e32 v30, v0
	v_mov_b32_e32 v31, v0
	v_mov_b32_e32 v32, v0
	v_mov_b32_e32 v33, v0
	v_mov_b32_e32 v34, v0
	v_mov_b32_e32 v35, v0
	v_mov_b32_e32 v36, v0
	v_mov_b32_e32 v37, v0
	v_mov_b32_e32 v38, v0
	v_mov_b32_e32 v39, v0
	v_mov_b32_e32 v40, v0
	v_mov_b32_e32 v41, v0
	v_mov_b32_e32 v42, v0
	v_mov_b32_e32 v43, v0
	v_mov_b32_e32 v44, v0
	v_mov_b32_e32 v45, v0
	v_mov_b32_e32 v46, v0
	v_mov_b32_e32 v47, v0
	v_mov_b32_e32 v48, v0
	v_mov_b32_e32 v49, v0
	v_mov_b32_e32 v50, v0
	v_mov_b32_e32 v51, v0
	v_mov_b32_e32 v52, v0
	v_mov_b32_e32 v53, v0
	v_mov_b32_e32 v54, v0
	v_mov_b32_e32 v55, v0
	v_mov_b32_e32 v56, v0
	v_mov_b32_e32 v57, v0
	v_mov_b32_e32 v58, v0
	v_mov_b32_e32 v59, v0
	v_mov_b32_e32 v60, v0
	v_mov_b32_e32 v61, v0
	v_mov_b32_e32 v62, v0
	v_mov_b32_e32 v63, v0
	s_add_i32 s99, s9, 0
	v_add_u32_e32 v253, s99, v81
	v_add_u32_e32 v252, s99, v83
	ds_read_b128 v[84:87], v252 offset:16384
	ds_read_b128 v[88:91], v253
	ds_read_b128 v[92:95], v253 offset:4096
	ds_read_b128 v[96:99], v252 offset:20480
; DEV int stage_next(int s) { return (s == 2 * GS_STAGE) ? 0 : s + GS_STAGE; }
; template <int WAIT0>
; DEV void gk_main(f32x16 (&acc)[2][2], const GTile& t, int s0) {
;     ...
;   vm_wait_bar<WAIT0>();
;   int stc = s0, std_ = stage_next(stage_next(s0));
; #pragma nounroll
;   for (int kt = 0; kt < nk - 2; ++kt) {
;     GK_DMA(std_, kt + 2);
;     GK_COMPUTE(stc);
;     vm_wait_bar<6>();
;     stc = stage_next(stc); std_ = stage_next(std_);
;   }
;   GK_COMPUTE(stc);
;   vm_wait_bar<0>();
;   stc = stage_next(stc);
;   GK_COMPUTE(stc);
;   vm_wait_bar<0>();
.LBB0_842:
	s_add_i32 s10, s2, s3
	s_mov_b32 s98, s10
	s_waitcnt lgkmcnt(0)
	v_add_u32_e32 v101, s99, v82
	v_add_u32_e32 v100, s99, v79
	s_add_i32 s10, s9, 0xc000
	s_cmp_lg_u32 s9, 0x18000
	s_cselect_b32 s9, s10, 0
	s_add_i32 s10, s3, 0xc000
	s_cmp_lg_u32 s3, 0x18000
	s_cselect_b32 s3, s10, 0
	s_add_i32 s8, s8, -1
	ds_read_b128 v[236:239], v101 offset:16384
	ds_read_b128 v[240:243], v100
	ds_read_b128 v[244:247], v100 offset:4096
	ds_read_b128 v[248:251], v101 offset:20480
	v_mfma_f32_32x32x16_bf16 v[48:63], v[84:87], v[88:91], v[48:63]
	v_mfma_f32_32x32x16_bf16 v[32:47], v[84:87], v[92:95], v[32:47]
	s_mov_b32 m0, s98
	v_lshl_add_u64 v[254:255], v[74:75], 0, v[120:121]
	global_load_lds_dwordx4 v[254:255], off
	v_lshl_add_u64 v[74:75], v[74:75], 0, s[94:95]
	v_mfma_f32_32x32x16_bf16 v[16:31], v[96:99], v[88:91], v[16:31]
	v_mfma_f32_32x32x16_bf16 v[0:15], v[96:99], v[92:95], v[0:15]
	s_add_i32 m0, s98, 0x2000
	v_lshl_add_u64 v[254:255], v[72:73], 0, v[120:121]
	global_load_lds_dwordx4 v[254:255], off
	v_lshl_add_u64 v[72:73], v[72:73], 0, s[94:95]
	v_add_u32_e32 v101, s99, v80
	v_add_u32_e32 v100, s99, v77
	s_waitcnt lgkmcnt(0)
	ds_read_b128 v[84:87], v101 offset:16384
	ds_read_b128 v[88:91], v100
	ds_read_b128 v[92:95], v100 offset:4096
	ds_read_b128 v[96:99], v101 offset:20480
	v_mfma_f32_32x32x16_bf16 v[48:63], v[236:239], v[240:243], v[48:63]
	v_mfma_f32_32x32x16_bf16 v[32:47], v[236:239], v[244:247], v[32:47]
	s_add_i32 m0, s98, 0x4000
	v_lshl_add_u64 v[254:255], v[70:71], 0, v[120:121]
	global_load_lds_dwordx4 v[254:255], off
	v_lshl_add_u64 v[70:71], v[70:71], 0, s[94:95]
	v_mfma_f32_32x32x16_bf16 v[16:31], v[248:251], v[240:243], v[16:31]
	v_mfma_f32_32x32x16_bf16 v[0:15], v[248:251], v[244:247], v[0:15]
	s_add_i32 m0, s98, 0x6000
	v_lshl_add_u64 v[254:255], v[68:69], 0, v[120:121]
	global_load_lds_dwordx4 v[254:255], off
	v_lshl_add_u64 v[68:69], v[68:69], 0, s[94:95]
	v_add_u32_e32 v101, s99, v78
	v_add_u32_e32 v100, s99, v76
	s_waitcnt lgkmcnt(0)
	ds_read_b128 v[236:239], v101 offset:16384
	ds_read_b128 v[240:243], v100
	ds_read_b128 v[244:247], v100 offset:4096
	ds_read_b128 v[248:251], v101 offset:20480
	v_mfma_f32_32x32x16_bf16 v[48:63], v[84:87], v[88:91], v[48:63]
	v_mfma_f32_32x32x16_bf16 v[32:47], v[84:87], v[92:95], v[32:47]
	s_add_i32 m0, s98, 0x8000
	v_lshl_add_u64 v[254:255], v[66:67], 0, v[120:121]
	global_load_lds_dwordx4 v[254:255], off
	v_lshl_add_u64 v[66:67], v[66:67], 0, s[94:95]
	v_mfma_f32_32x32x16_bf16 v[16:31], v[96:99], v[88:91], v[16:31]
	v_mfma_f32_32x32x16_bf16 v[0:15], v[96:99], v[92:95], v[0:15]
	s_add_i32 m0, s98, 0xa000
	v_lshl_add_u64 v[254:255], v[64:65], 0, v[120:121]
	global_load_lds_dwordx4 v[254:255], off
	v_lshl_add_u64 v[64:65], v[64:65], 0, s[94:95]
	s_waitcnt vmcnt(6) lgkmcnt(0)
	s_barrier
	s_waitcnt lgkmcnt(0)
	s_add_i32 s99, s9, 0
	v_add_u32_e32 v253, s99, v81
	v_add_u32_e32 v252, s99, v83
	ds_read_b128 v[84:87], v252 offset:16384
	ds_read_b128 v[88:91], v253
	ds_read_b128 v[92:95], v253 offset:4096
	ds_read_b128 v[96:99], v252 offset:20480
	v_mfma_f32_32x32x16_bf16 v[48:63], v[236:239], v[240:243], v[48:63]
	v_mfma_f32_32x32x16_bf16 v[32:47], v[236:239], v[244:247], v[32:47]
	v_mfma_f32_32x32x16_bf16 v[16:31], v[248:251], v[240:243], v[16:31]
	v_mfma_f32_32x32x16_bf16 v[0:15], v[248:251], v[244:247], v[0:15]
	s_cmp_lg_u32 s8, 0
	s_cbranch_scc1 .LBB0_842
	s_waitcnt lgkmcnt(0)
	s_add_i32 s2, s9, 0
	v_add_u32_e32 v84, s2, v83
	ds_read_b128 v[64:67], v84 offset:16384
	v_add_u32_e32 v72, s2, v81
	ds_read_b128 v[68:71], v72
	ds_read_b128 v[72:75], v72 offset:4096
	ds_read_b128 v[84:87], v84 offset:20480
	s_waitcnt lgkmcnt(0)
	v_mfma_f32_32x32x16_bf16 v[16:31], v[84:87], v[68:71], v[16:31]
	v_mfma_f32_32x32x16_bf16 v[0:15], v[84:87], v[72:75], v[0:15]
	v_add_u32_e32 v84, s2, v82
	v_mfma_f32_32x32x16_bf16 v[48:63], v[64:67], v[68:71], v[48:63]
	v_mfma_f32_32x32x16_bf16 v[32:47], v[64:67], v[72:75], v[32:47]
	ds_read_b128 v[64:67], v84 offset:16384
	v_add_u32_e32 v72, s2, v79
	ds_read_b128 v[68:71], v72
	ds_read_b128 v[72:75], v72 offset:4096
	ds_read_b128 v[84:87], v84 offset:20480
	s_waitcnt lgkmcnt(0)
	v_mfma_f32_32x32x16_bf16 v[16:31], v[84:87], v[68:71], v[16:31]
	v_mfma_f32_32x32x16_bf16 v[0:15], v[84:87], v[72:75], v[0:15]
	v_add_u32_e32 v84, s2, v80
	v_mfma_f32_32x32x16_bf16 v[48:63], v[64:67], v[68:71], v[48:63]
	v_mfma_f32_32x32x16_bf16 v[32:47], v[64:67], v[72:75], v[32:47]
	ds_read_b128 v[64:67], v84 offset:16384
	v_add_u32_e32 v72, s2, v77
	ds_read_b128 v[68:71], v72
	ds_read_b128 v[72:75], v72 offset:4096
	ds_read_b128 v[84:87], v84 offset:20480
	s_waitcnt lgkmcnt(0)
	v_mfma_f32_32x32x16_bf16 v[16:31], v[84:87], v[68:71], v[16:31]
	v_mfma_f32_32x32x16_bf16 v[0:15], v[84:87], v[72:75], v[0:15]
	v_add_u32_e32 v84, s2, v78
	v_mfma_f32_32x32x16_bf16 v[48:63], v[64:67], v[68:71], v[48:63]
	v_mfma_f32_32x32x16_bf16 v[32:47], v[64:67], v[72:75], v[32:47]
	ds_read_b128 v[64:67], v84 offset:16384
	v_add_u32_e32 v72, s2, v76
	s_add_i32 s2, s9, 0xc000
	ds_read_b128 v[68:71], v72
	ds_read_b128 v[72:75], v72 offset:4096
	ds_read_b128 v[84:87], v84 offset:20480
	s_cmp_lg_u32 s9, 0x18000
	s_cselect_b32 s2, s2, 0
	s_add_i32 s2, s2, 0
	s_waitcnt vmcnt(0) lgkmcnt(0)
	s_barrier
; DEV int tid_l() { int t = threadIdx.x; asm volatile("" : "+v"(t)); return t; }
; DEV int stage_next(int s) { return (s == 2 * GS_STAGE) ? 0 : s + GS_STAGE; }
; template <int WAIT0>
; DEV void gk_main(f32x16 (&acc)[2][2], const GTile& t, int s0) {
;   const int tid = tid_l(), lane = tid & 63, wid = __builtin_amdgcn_readfirstlane(tid >> 6), wm = wid & 1, wn = wid >> 1, l32 = lane & 31, hi = lane >> 5;
;   GK_SRC(t)
;   const int sw = (l32 >> 1) & 7;
;   int xk[4], wk[4];
; #pragma unroll
;   for (int ks = 0; ks < 4; ++ks) { const int ko = ((2 * ks + hi) ^ sw) << 4; xk[ks] = GS_A + (64 * wm + l32) * 128 + ko; wk[ks] = GS_B + (64 * wn + l32) * 128 + ko; }
;   const int nk = t.K >> 6;
;     ...
;   vm_wait_bar<WAIT0>();
;   int stc = s0, std_ = stage_next(stage_next(s0));
; #pragma nounroll
;   for (int kt = 0; kt < nk - 2; ++kt) {
;     GK_DMA(std_, kt + 2);
;     GK_COMPUTE(stc);
;     vm_wait_bar<6>();
;     stc = stage_next(stc); std_ = stage_next(std_);
;   }
;   GK_COMPUTE(stc);
;   vm_wait_bar<0>();
;   stc = stage_next(stc);
;   GK_COMPUTE(stc);
;   vm_wait_bar<0>();
	v_add_u32_e32 v83, s2, v83
	s_waitcnt lgkmcnt(0)
	v_mfma_f32_32x32x16_bf16 v[48:63], v[64:67], v[68:71], v[48:63]
	s_mov_b64 s[8:9], 0
	v_mfma_f32_32x32x16_bf16 v[32:47], v[64:67], v[72:75], v[32:47]
	ds_read_b128 v[64:67], v83 offset:16384
	v_mfma_f32_32x32x16_bf16 v[16:31], v[84:87], v[68:71], v[16:31]
	v_mfma_f32_32x32x16_bf16 v[0:15], v[84:87], v[72:75], v[0:15]
	v_add_u32_e32 v72, s2, v81
	ds_read_b128 v[68:71], v72
	ds_read_b128 v[72:75], v72 offset:4096
	ds_read_b128 v[84:87], v83 offset:20480
	v_add_u32_e32 v81, s2, v82
	s_waitcnt lgkmcnt(0)
	v_mfma_f32_32x32x16_bf16 v[48:63], v[64:67], v[68:71], v[48:63]
	v_mfma_f32_32x32x16_bf16 v[32:47], v[64:67], v[72:75], v[32:47]
	ds_read_b128 v[64:67], v81 offset:16384
	v_mfma_f32_32x32x16_bf16 v[16:31], v[84:87], v[68:71], v[16:31]
	v_mfma_f32_32x32x16_bf16 v[0:15], v[84:87], v[72:75], v[0:15]
	v_add_u32_e32 v72, s2, v79
	ds_read_b128 v[68:71], v72
	ds_read_b128 v[72:75], v72 offset:4096
	ds_read_b128 v[82:85], v81 offset:20480
	v_add_u32_e32 v79, s2, v80
	s_waitcnt lgkmcnt(0)
	v_mfma_f32_32x32x16_bf16 v[48:63], v[64:67], v[68:71], v[48:63]
	v_mfma_f32_32x32x16_bf16 v[32:47], v[64:67], v[72:75], v[32:47]
	ds_read_b128 v[64:67], v79 offset:16384
	v_mfma_f32_32x32x16_bf16 v[16:31], v[82:85], v[68:71], v[16:31]
	v_mfma_f32_32x32x16_bf16 v[0:15], v[82:85], v[72:75], v[0:15]
	v_add_u32_e32 v72, s2, v77
	ds_read_b128 v[68:71], v72
	ds_read_b128 v[72:75], v72 offset:4096
	ds_read_b128 v[80:83], v79 offset:20480
	v_add_u32_e32 v77, s2, v78
	s_waitcnt lgkmcnt(0)
	v_mfma_f32_32x32x16_bf16 v[48:63], v[64:67], v[68:71], v[48:63]
	v_mfma_f32_32x32x16_bf16 v[32:47], v[64:67], v[72:75], v[32:47]
	ds_read_b128 v[64:67], v77 offset:16384
	v_mfma_f32_32x32x16_bf16 v[16:31], v[80:83], v[68:71], v[16:31]
	v_mfma_f32_32x32x16_bf16 v[0:15], v[80:83], v[72:75], v[0:15]
	v_add_u32_e32 v72, s2, v76
	ds_read_b128 v[68:71], v72
	ds_read_b128 v[72:75], v72 offset:4096
	ds_read_b128 v[76:79], v77 offset:20480
	s_waitcnt vmcnt(0) lgkmcnt(0)
	s_barrier
	s_waitcnt lgkmcnt(0)
	v_mfma_f32_32x32x16_bf16 v[48:63], v[64:67], v[68:71], v[48:63]
	v_mfma_f32_32x32x16_bf16 v[32:47], v[64:67], v[72:75], v[32:47]
	v_mfma_f32_32x32x16_bf16 v[16:31], v[76:79], v[68:71], v[16:31]
	v_mfma_f32_32x32x16_bf16 v[0:15], v[76:79], v[72:75], v[0:15]
.LBB0_844:
	s_and_b64 vcc, exec, s[8:9]
	s_cbranch_vccz .LBB0_848
	s_nop 9
	v_mov_b32_e32 v0, v176
	s_lshr_b32 s8, s16, 6
	v_readfirstlane_b32 s2, v0
	v_and_b32_e32 v1, 31, v0
	s_ashr_i32 s3, s2, 6
	v_and_or_b32 v7, s2, 64, v1
	s_lshr_b32 s2, s2, 1
	s_and_b32 s2, s2, 0x1ffffc0
	v_bfe_u32 v2, v0, 3, 3
	v_or_b32_e32 v1, s2, v1
	s_lshl_b32 s2, s3, 10
	v_lshl_or_b32 v4, s3, 3, v2
	s_add_i32 s3, s18, 0xc000
	s_add_i32 s2, s2, 0
	s_cmp_lg_u32 s18, 0x18000
	s_cselect_b32 s17, s3, 0
	s_add_i32 s3, s17, 0xc000
	v_lshrrev_b32_e32 v2, 1, v4
	v_bfe_u32 v3, v0, 5, 1
	v_lshrrev_b32_e32 v5, 1, v0
	v_bfe_u32 v6, v0, 1, 3
	s_cmp_lg_u32 s17, 0x18000
	v_bitop3_b32 v5, v3, v5, 7 bitop3:0x78
	v_bitop3_b32 v8, v3, v6, 2 bitop3:0x36
	v_bitop3_b32 v9, v3, v6, 4 bitop3:0x36
	v_bitop3_b32 v3, v3, v6, 6 bitop3:0x36
	s_cselect_b32 s3, s3, 0
	s_add_i32 s8, s8, -2
	v_bitop3_b32 v0, v2, 7, v0 bitop3:0x48
	v_lshlrev_b32_e32 v1, 7, v1
	v_lshlrev_b32_e32 v5, 4, v5
	v_lshlrev_b32_e32 v8, 4, v8
	v_lshlrev_b32_e32 v9, 4, v9
	v_lshlrev_b32_e32 v3, 4, v3
	v_lshlrev_b32_e32 v120, 4, v0
	s_add_u32 s10, s6, 0x100
	v_add_u32_e32 v0, 0xc0, v4
	v_lshlrev_b32_e32 v7, 7, v7
	v_or_b32_e32 v83, v1, v5
	v_or_b32_e32 v82, v1, v8
	v_or_b32_e32 v80, v1, v9
	v_or_b32_e32 v78, v1, v3
	s_addc_u32 s11, s7, 0
	v_ashrrev_i32_e32 v1, 31, v0
	v_or_b32_e32 v76, v3, v7
	v_alignbit_b32 v3, v1, v0, 31
	v_lshlrev_b32_e32 v2, 1, v0
	v_mov_b64_e32 v[0:1], s[10:11]
	v_mad_u64_u32 v[64:65], s[10:11], v2, s16, v[0:1]
	v_mov_b32_e32 v2, v65
	v_mad_u64_u32 v[2:3], s[10:11], v3, s16, v[2:3]
	v_mov_b32_e32 v65, v2
	v_add_u32_e32 v2, 0x80, v4
	v_ashrrev_i32_e32 v3, 31, v2
	v_alignbit_b32 v3, v3, v2, 31
	v_lshlrev_b32_e32 v2, 1, v2
	v_mad_u64_u32 v[66:67], s[10:11], v2, s16, v[0:1]
	v_mov_b32_e32 v2, v67
	v_mad_u64_u32 v[2:3], s[10:11], v3, s16, v[2:3]
	v_add_u32_e32 v3, 64, v4
	v_lshlrev_b32_e32 v6, 1, v3
	v_or_b32_e32 v81, v5, v7
	v_ashrrev_i32_e32 v5, 31, v3
	v_mad_u64_u32 v[68:69], s[10:11], v6, s16, v[0:1]
	v_mov_b32_e32 v67, v2
	v_mov_b32_e32 v2, v69
	v_alignbit_b32 v5, v5, v3, 31
	v_or_b32_e32 v79, v8, v7
	v_or_b32_e32 v77, v9, v7
	v_mad_u64_u32 v[2:3], s[10:11], v5, s16, v[2:3]
	v_lshlrev_b32_e32 v7, 1, v4
	v_mov_b32_e32 v69, v2
	v_ashrrev_i32_e32 v2, 31, v4
	v_mad_u64_u32 v[70:71], s[10:11], v7, s16, v[0:1]
	v_mov_b32_e32 v0, v71
	v_alignbit_b32 v4, v2, v4, 31
	v_mad_u64_u32 v[0:1], s[10:11], v4, s16, v[0:1]
	s_add_u32 s10, s4, 0x100
	s_addc_u32 s11, s5, 0
	v_mov_b32_e32 v71, v0
	v_mov_b64_e32 v[0:1], s[10:11]
	v_mad_u64_u32 v[74:75], s[10:11], v7, s16, v[0:1]
	v_mad_u64_u32 v[72:73], s[10:11], v6, s16, v[0:1]
	v_mov_b32_e32 v0, v75
	s_waitcnt vmcnt(22) lgkmcnt(0)
	s_barrier
	v_mov_b32_e32 v2, v73
	v_mad_u64_u32 v[0:1], s[10:11], v4, s16, v[0:1]
	v_mad_u64_u32 v[2:3], s[10:11], v5, s16, v[2:3]
	v_mov_b32_e32 v75, v0
	v_mov_b32_e32 v0, 0
	v_mov_b32_e32 v73, v2
	s_mov_b32 s9, s18
	v_mov_b32_e32 v1, v0
	v_mov_b32_e32 v2, v0
	v_mov_b32_e32 v3, v0
	v_mov_b32_e32 v4, v0
	v_mov_b32_e32 v5, v0
	v_mov_b32_e32 v6, v0
	v_mov_b32_e32 v7, v0
	v_mov_b32_e32 v8, v0
	v_mov_b32_e32 v9, v0
	v_mov_b32_e32 v10, v0
	v_mov_b32_e32 v11, v0
	v_mov_b32_e32 v12, v0
	v_mov_b32_e32 v13, v0
	v_mov_b32_e32 v14, v0
	v_mov_b32_e32 v15, v0
	v_mov_b32_e32 v16, v0
	v_mov_b32_e32 v17, v0
	v_mov_b32_e32 v18, v0
	v_mov_b32_e32 v19, v0
	v_mov_b32_e32 v20, v0
	v_mov_b32_e32 v21, v0
	v_mov_b32_e32 v22, v0
	v_mov_b32_e32 v23, v0
	v_mov_b32_e32 v24, v0
	v_mov_b32_e32 v25, v0
	v_mov_b32_e32 v26, v0
	v_mov_b32_e32 v27, v0
	v_mov_b32_e32 v28, v0
	v_mov_b32_e32 v29, v0
	v_mov_b32_e32 v30, v0
	v_mov_b32_e32 v31, v0
	v_mov_b32_e32 v32, v0
	v_mov_b32_e32 v33, v0
	v_mov_b32_e32 v34, v0
	v_mov_b32_e32 v35, v0
	v_mov_b32_e32 v36, v0
	v_mov_b32_e32 v37, v0
	v_mov_b32_e32 v38, v0
	v_mov_b32_e32 v39, v0
	v_mov_b32_e32 v40, v0
	v_mov_b32_e32 v41, v0
	v_mov_b32_e32 v42, v0
	v_mov_b32_e32 v43, v0
	v_mov_b32_e32 v44, v0
	v_mov_b32_e32 v45, v0
	v_mov_b32_e32 v46, v0
	v_mov_b32_e32 v47, v0
	v_mov_b32_e32 v48, v0
	v_mov_b32_e32 v49, v0
	v_mov_b32_e32 v50, v0
	v_mov_b32_e32 v51, v0
	v_mov_b32_e32 v52, v0
	v_mov_b32_e32 v53, v0
	v_mov_b32_e32 v54, v0
	v_mov_b32_e32 v55, v0
	v_mov_b32_e32 v56, v0
	v_mov_b32_e32 v57, v0
	v_mov_b32_e32 v58, v0
	v_mov_b32_e32 v59, v0
	v_mov_b32_e32 v60, v0
	v_mov_b32_e32 v61, v0
	v_mov_b32_e32 v62, v0
	v_mov_b32_e32 v63, v0
	s_add_i32 s99, s9, 0
	v_add_u32_e32 v253, s99, v81
	v_add_u32_e32 v252, s99, v83
	ds_read_b128 v[84:87], v252 offset:16384
	ds_read_b128 v[88:91], v253
	ds_read_b128 v[92:95], v253 offset:4096
	ds_read_b128 v[96:99], v252 offset:20480
; DEV int stage_next(int s) { return (s == 2 * GS_STAGE) ? 0 : s + GS_STAGE; }
; template <int WAIT0>
; DEV void gk_main(f32x16 (&acc)[2][2], const GTile& t, int s0) {
;     ...
;   vm_wait_bar<WAIT0>();
;   int stc = s0, std_ = stage_next(stage_next(s0));
; #pragma nounroll
;   for (int kt = 0; kt < nk - 2; ++kt) {
;     GK_DMA(std_, kt + 2);
;     GK_COMPUTE(stc);
;     vm_wait_bar<6>();
;     stc = stage_next(stc); std_ = stage_next(std_);
;   }
.LBB0_846:
	s_add_i32 s10, s2, s3
	s_mov_b32 s98, s10
	s_waitcnt lgkmcnt(0)
	v_add_u32_e32 v101, s99, v82
	v_add_u32_e32 v100, s99, v79
	s_add_i32 s10, s9, 0xc000
	s_cmp_lg_u32 s9, 0x18000
	s_cselect_b32 s9, s10, 0
	s_add_i32 s10, s3, 0xc000
	s_cmp_lg_u32 s3, 0x18000
	s_cselect_b32 s3, s10, 0
	s_add_i32 s8, s8, -1
	ds_read_b128 v[236:239], v101 offset:16384
	ds_read_b128 v[240:243], v100
	ds_read_b128 v[244:247], v100 offset:4096
	ds_read_b128 v[248:251], v101 offset:20480
	v_mfma_f32_32x32x16_bf16 v[48:63], v[84:87], v[88:91], v[48:63]
	v_mfma_f32_32x32x16_bf16 v[32:47], v[84:87], v[92:95], v[32:47]
	s_mov_b32 m0, s98
	v_lshl_add_u64 v[254:255], v[74:75], 0, v[120:121]
	global_load_lds_dwordx4 v[254:255], off
	v_lshl_add_u64 v[74:75], v[74:75], 0, s[94:95]
	v_mfma_f32_32x32x16_bf16 v[16:31], v[96:99], v[88:91], v[16:31]
	v_mfma_f32_32x32x16_bf16 v[0:15], v[96:99], v[92:95], v[0:15]
	s_add_i32 m0, s98, 0x2000
	v_lshl_add_u64 v[254:255], v[72:73], 0, v[120:121]
	global_load_lds_dwordx4 v[254:255], off
	v_lshl_add_u64 v[72:73], v[72:73], 0, s[94:95]
	v_add_u32_e32 v101, s99, v80
	v_add_u32_e32 v100, s99, v77
	s_waitcnt lgkmcnt(0)
	ds_read_b128 v[84:87], v101 offset:16384
	ds_read_b128 v[88:91], v100
	ds_read_b128 v[92:95], v100 offset:4096
	ds_read_b128 v[96:99], v101 offset:20480
	v_mfma_f32_32x32x16_bf16 v[48:63], v[236:239], v[240:243], v[48:63]
	v_mfma_f32_32x32x16_bf16 v[32:47], v[236:239], v[244:247], v[32:47]
	s_add_i32 m0, s98, 0x4000
	v_lshl_add_u64 v[254:255], v[70:71], 0, v[120:121]
	global_load_lds_dwordx4 v[254:255], off
	v_lshl_add_u64 v[70:71], v[70:71], 0, s[94:95]
	v_mfma_f32_32x32x16_bf16 v[16:31], v[248:251], v[240:243], v[16:31]
	v_mfma_f32_32x32x16_bf16 v[0:15], v[248:251], v[244:247], v[0:15]
	s_add_i32 m0, s98, 0x6000
	v_lshl_add_u64 v[254:255], v[68:69], 0, v[120:121]
	global_load_lds_dwordx4 v[254:255], off
	v_lshl_add_u64 v[68:69], v[68:69], 0, s[94:95]
	v_add_u32_e32 v101, s99, v78
	v_add_u32_e32 v100, s99, v76
	s_waitcnt lgkmcnt(0)
	ds_read_b128 v[236:239], v101 offset:16384
	ds_read_b128 v[240:243], v100
	ds_read_b128 v[244:247], v100 offset:4096
	ds_read_b128 v[248:251], v101 offset:20480
	v_mfma_f32_32x32x16_bf16 v[48:63], v[84:87], v[88:91], v[48:63]
	v_mfma_f32_32x32x16_bf16 v[32:47], v[84:87], v[92:95], v[32:47]
	s_add_i32 m0, s98, 0x8000
	v_lshl_add_u64 v[254:255], v[66:67], 0, v[120:121]
	global_load_lds_dwordx4 v[254:255], off
	v_lshl_add_u64 v[66:67], v[66:67], 0, s[94:95]
	v_mfma_f32_32x32x16_bf16 v[16:31], v[96:99], v[88:91], v[16:31]
	v_mfma_f32_32x32x16_bf16 v[0:15], v[96:99], v[92:95], v[0:15]
	s_add_i32 m0, s98, 0xa000
	v_lshl_add_u64 v[254:255], v[64:65], 0, v[120:121]
	global_load_lds_dwordx4 v[254:255], off
	v_lshl_add_u64 v[64:65], v[64:65], 0, s[94:95]
	s_waitcnt vmcnt(6) lgkmcnt(0)
	s_barrier
	s_waitcnt lgkmcnt(0)
	s_add_i32 s99, s9, 0
	v_add_u32_e32 v253, s99, v81
	v_add_u32_e32 v252, s99, v83
	ds_read_b128 v[84:87], v252 offset:16384
	ds_read_b128 v[88:91], v253
	ds_read_b128 v[92:95], v253 offset:4096
	ds_read_b128 v[96:99], v252 offset:20480
	v_mfma_f32_32x32x16_bf16 v[48:63], v[236:239], v[240:243], v[48:63]
	v_mfma_f32_32x32x16_bf16 v[32:47], v[236:239], v[244:247], v[32:47]
	v_mfma_f32_32x32x16_bf16 v[16:31], v[248:251], v[240:243], v[16:31]
	v_mfma_f32_32x32x16_bf16 v[0:15], v[248:251], v[244:247], v[0:15]
	s_cmp_lg_u32 s8, 0
	s_cbranch_scc1 .LBB0_846
; DEV int stage_next(int s) { return (s == 2 * GS_STAGE) ? 0 : s + GS_STAGE; }
; template <int WAIT0>
; DEV void gk_main(f32x16 (&acc)[2][2], const GTile& t, int s0) {
;     ...
;   vm_wait_bar<WAIT0>();
;   int stc = s0, std_ = stage_next(stage_next(s0));
; #pragma nounroll
;   for (int kt = 0; kt < nk - 2; ++kt) {
;     GK_DMA(std_, kt + 2);
;     GK_COMPUTE(stc);
;     vm_wait_bar<6>();
;     stc = stage_next(stc); std_ = stage_next(std_);
;   }
;   GK_COMPUTE(stc);
;   vm_wait_bar<0>();
;   stc = stage_next(stc);
;   GK_COMPUTE(stc);
;   vm_wait_bar<0>();
	s_waitcnt lgkmcnt(0)
	s_add_i32 s2, s9, 0
	v_add_u32_e32 v84, s2, v83
	ds_read_b128 v[64:67], v84 offset:16384
	v_add_u32_e32 v72, s2, v81
	ds_read_b128 v[68:71], v72
	ds_read_b128 v[72:75], v72 offset:4096
	ds_read_b128 v[84:87], v84 offset:20480
	s_waitcnt lgkmcnt(0)
	v_mfma_f32_32x32x16_bf16 v[16:31], v[84:87], v[68:71], v[16:31]
	v_mfma_f32_32x32x16_bf16 v[0:15], v[84:87], v[72:75], v[0:15]
	v_add_u32_e32 v84, s2, v82
	v_mfma_f32_32x32x16_bf16 v[48:63], v[64:67], v[68:71], v[48:63]
	v_mfma_f32_32x32x16_bf16 v[32:47], v[64:67], v[72:75], v[32:47]
	ds_read_b128 v[64:67], v84 offset:16384
	v_add_u32_e32 v72, s2, v79
	ds_read_b128 v[68:71], v72
	ds_read_b128 v[72:75], v72 offset:4096
	ds_read_b128 v[84:87], v84 offset:20480
	s_waitcnt lgkmcnt(0)
	v_mfma_f32_32x32x16_bf16 v[16:31], v[84:87], v[68:71], v[16:31]
	v_mfma_f32_32x32x16_bf16 v[0:15], v[84:87], v[72:75], v[0:15]
	v_add_u32_e32 v84, s2, v80
	v_mfma_f32_32x32x16_bf16 v[48:63], v[64:67], v[68:71], v[48:63]
	v_mfma_f32_32x32x16_bf16 v[32:47], v[64:67], v[72:75], v[32:47]
	ds_read_b128 v[64:67], v84 offset:16384
	v_add_u32_e32 v72, s2, v77
	ds_read_b128 v[68:71], v72
	ds_read_b128 v[72:75], v72 offset:4096
	ds_read_b128 v[84:87], v84 offset:20480
	s_waitcnt lgkmcnt(0)
	v_mfma_f32_32x32x16_bf16 v[16:31], v[84:87], v[68:71], v[16:31]
	v_mfma_f32_32x32x16_bf16 v[0:15], v[84:87], v[72:75], v[0:15]
	v_add_u32_e32 v84, s2, v78
	v_mfma_f32_32x32x16_bf16 v[48:63], v[64:67], v[68:71], v[48:63]
	v_mfma_f32_32x32x16_bf16 v[32:47], v[64:67], v[72:75], v[32:47]
	ds_read_b128 v[64:67], v84 offset:16384
	v_add_u32_e32 v72, s2, v76
	s_add_i32 s2, s9, 0xc000
	ds_read_b128 v[68:71], v72
	ds_read_b128 v[72:75], v72 offset:4096
	ds_read_b128 v[84:87], v84 offset:20480
	s_cmp_lg_u32 s9, 0x18000
	s_cselect_b32 s2, s2, 0
	s_add_i32 s2, s2, 0
	s_waitcnt vmcnt(0) lgkmcnt(0)
	s_barrier
	v_add_u32_e32 v83, s2, v83
	s_waitcnt lgkmcnt(0)
	v_mfma_f32_32x32x16_bf16 v[48:63], v[64:67], v[68:71], v[48:63]
	v_mfma_f32_32x32x16_bf16 v[32:47], v[64:67], v[72:75], v[32:47]
	ds_read_b128 v[64:67], v83 offset:16384
	v_mfma_f32_32x32x16_bf16 v[16:31], v[84:87], v[68:71], v[16:31]
	v_mfma_f32_32x32x16_bf16 v[0:15], v[84:87], v[72:75], v[0:15]
	v_add_u32_e32 v72, s2, v81
	ds_read_b128 v[68:71], v72
	ds_read_b128 v[72:75], v72 offset:4096
	ds_read_b128 v[84:87], v83 offset:20480
	v_add_u32_e32 v81, s2, v82
	s_waitcnt lgkmcnt(0)
	v_mfma_f32_32x32x16_bf16 v[48:63], v[64:67], v[68:71], v[48:63]
	v_mfma_f32_32x32x16_bf16 v[32:47], v[64:67], v[72:75], v[32:47]
	ds_read_b128 v[64:67], v81 offset:16384
	v_mfma_f32_32x32x16_bf16 v[16:31], v[84:87], v[68:71], v[16:31]
	v_mfma_f32_32x32x16_bf16 v[0:15], v[84:87], v[72:75], v[0:15]
	v_add_u32_e32 v72, s2, v79
	ds_read_b128 v[68:71], v72
	ds_read_b128 v[72:75], v72 offset:4096
	ds_read_b128 v[82:85], v81 offset:20480
	v_add_u32_e32 v79, s2, v80
	s_waitcnt lgkmcnt(0)
	v_mfma_f32_32x32x16_bf16 v[48:63], v[64:67], v[68:71], v[48:63]
	v_mfma_f32_32x32x16_bf16 v[32:47], v[64:67], v[72:75], v[32:47]
	ds_read_b128 v[64:67], v79 offset:16384
	v_mfma_f32_32x32x16_bf16 v[16:31], v[82:85], v[68:71], v[16:31]
	v_mfma_f32_32x32x16_bf16 v[0:15], v[82:85], v[72:75], v[0:15]
	v_add_u32_e32 v72, s2, v77
	ds_read_b128 v[68:71], v72
	ds_read_b128 v[72:75], v72 offset:4096
	ds_read_b128 v[80:83], v79 offset:20480
	v_add_u32_e32 v77, s2, v78
	s_waitcnt lgkmcnt(0)
	v_mfma_f32_32x32x16_bf16 v[48:63], v[64:67], v[68:71], v[48:63]
	v_mfma_f32_32x32x16_bf16 v[32:47], v[64:67], v[72:75], v[32:47]
	ds_read_b128 v[64:67], v77 offset:16384
	v_mfma_f32_32x32x16_bf16 v[16:31], v[80:83], v[68:71], v[16:31]
	v_mfma_f32_32x32x16_bf16 v[0:15], v[80:83], v[72:75], v[0:15]
	v_add_u32_e32 v72, s2, v76
	ds_read_b128 v[68:71], v72
	ds_read_b128 v[72:75], v72 offset:4096
	ds_read_b128 v[76:79], v77 offset:20480
	s_waitcnt vmcnt(0) lgkmcnt(0)
	s_barrier
	s_waitcnt lgkmcnt(0)
	v_mfma_f32_32x32x16_bf16 v[48:63], v[64:67], v[68:71], v[48:63]
	v_mfma_f32_32x32x16_bf16 v[32:47], v[64:67], v[72:75], v[32:47]
	v_mfma_f32_32x32x16_bf16 v[16:31], v[76:79], v[68:71], v[16:31]
	v_mfma_f32_32x32x16_bf16 v[0:15], v[76:79], v[72:75], v[0:15]

; DEV int tid_l() { int t = threadIdx.x; asm volatile("" : "+v"(t)); return t; }
; DEV int stage_next(int s) { return (s == 2 * GS_STAGE) ? 0 : s + GS_STAGE; }
; template <int WAIT0>
; DEV void gk_main(f32x16 (&acc)[2][2], const GTile& t, int s0) {
;   const int tid = tid_l(), lane = tid & 63, wid = __builtin_amdgcn_readfirstlane(tid >> 6), wm = wid & 1, wn = wid >> 1, l32 = lane & 31, hi = lane >> 5;
;   GK_SRC(t)
;   const int sw = (l32 >> 1) & 7;
;   int xk[4], wk[4];
; #pragma unroll
;   for (int ks = 0; ks < 4; ++ks) { const int ko = ((2 * ks + hi) ^ sw) << 4; xk[ks] = GS_A + (64 * wm + l32) * 128 + ko; wk[ks] = GS_B + (64 * wn + l32) * 128 + ko; }
;   const int nk = t.K >> 6;
;     ...
;   vm_wait_bar<WAIT0>();
;   int stc = s0, std_ = stage_next(stage_next(s0));
; DEV void acc_zero(f32x16 (&acc)[2][2]) {
; #pragma unroll
;   for (int a = 0; a < 2; ++a)
; #pragma unroll
;     for (int b = 0; b < 2; ++b)
; #pragma unroll
;       for (int r = 0; r < 16; ++r) acc[a][b][r] = 0.f;
.LBB0_852:
.LBB0_853:
	s_nop 5
	v_mov_b32_e32 v0, v176
	s_lshr_b32 s8, s16, 6
	s_nop 2
	v_readfirstlane_b32 s2, v0
	v_and_b32_e32 v1, 31, v0
	s_ashr_i32 s3, s2, 6
	v_and_or_b32 v7, s2, 64, v1
	s_lshr_b32 s2, s2, 1
	s_and_b32 s2, s2, 0x1ffffc0
	v_bfe_u32 v2, v0, 3, 3
	v_or_b32_e32 v1, s2, v1
	s_lshl_b32 s2, s3, 10
	v_lshl_or_b32 v4, s3, 3, v2
	s_add_i32 s3, s18, 0xc000
	s_add_i32 s2, s2, 0
	s_cmp_lg_u32 s18, 0x18000
	s_cselect_b32 s17, s3, 0
	s_add_i32 s3, s17, 0xc000
	v_lshrrev_b32_e32 v2, 1, v4
	v_bfe_u32 v3, v0, 5, 1
	v_lshrrev_b32_e32 v5, 1, v0
	v_bfe_u32 v6, v0, 1, 3
	s_cmp_lg_u32 s17, 0x18000
	v_bitop3_b32 v5, v3, v5, 7 bitop3:0x78
	v_bitop3_b32 v8, v3, v6, 2 bitop3:0x36
	v_bitop3_b32 v9, v3, v6, 4 bitop3:0x36
	v_bitop3_b32 v3, v3, v6, 6 bitop3:0x36
	s_cselect_b32 s3, s3, 0
	s_add_i32 s8, s8, -2
	v_bitop3_b32 v0, v2, 7, v0 bitop3:0x48
	v_lshlrev_b32_e32 v1, 7, v1
	v_lshlrev_b32_e32 v5, 4, v5
	v_lshlrev_b32_e32 v8, 4, v8
	v_lshlrev_b32_e32 v9, 4, v9
	v_lshlrev_b32_e32 v3, 4, v3
	v_lshlrev_b32_e32 v120, 4, v0
	s_add_u32 s10, s6, 0x100
	v_add_u32_e32 v0, 0xc0, v4
	v_lshlrev_b32_e32 v7, 7, v7
	v_or_b32_e32 v83, v1, v5
	v_or_b32_e32 v82, v1, v8
	v_or_b32_e32 v80, v1, v9
	v_or_b32_e32 v78, v1, v3
	s_addc_u32 s11, s7, 0
	v_ashrrev_i32_e32 v1, 31, v0
	v_or_b32_e32 v76, v3, v7
	v_alignbit_b32 v3, v1, v0, 31
	v_lshlrev_b32_e32 v2, 1, v0
	v_mov_b64_e32 v[0:1], s[10:11]
	v_mad_u64_u32 v[64:65], s[10:11], v2, s16, v[0:1]
	v_mov_b32_e32 v2, v65
	v_mad_u64_u32 v[2:3], s[10:11], v3, s16, v[2:3]
	v_mov_b32_e32 v65, v2
	v_add_u32_e32 v2, 0x80, v4
	v_ashrrev_i32_e32 v3, 31, v2
	v_alignbit_b32 v3, v3, v2, 31
	v_lshlrev_b32_e32 v2, 1, v2
	v_mad_u64_u32 v[66:67], s[10:11], v2, s16, v[0:1]
	v_mov_b32_e32 v2, v67
	v_mad_u64_u32 v[2:3], s[10:11], v3, s16, v[2:3]
	v_add_u32_e32 v3, 64, v4
	v_lshlrev_b32_e32 v6, 1, v3
	v_or_b32_e32 v81, v5, v7
	v_ashrrev_i32_e32 v5, 31, v3
	v_mad_u64_u32 v[68:69], s[10:11], v6, s16, v[0:1]
	v_mov_b32_e32 v67, v2
	v_mov_b32_e32 v2, v69
	v_alignbit_b32 v5, v5, v3, 31
	v_or_b32_e32 v79, v8, v7
	v_or_b32_e32 v77, v9, v7
	v_mad_u64_u32 v[2:3], s[10:11], v5, s16, v[2:3]
	v_lshlrev_b32_e32 v7, 1, v4
	v_mov_b32_e32 v69, v2
	v_ashrrev_i32_e32 v2, 31, v4
	v_mad_u64_u32 v[70:71], s[10:11], v7, s16, v[0:1]
	v_mov_b32_e32 v0, v71
	v_alignbit_b32 v4, v2, v4, 31
	v_mad_u64_u32 v[0:1], s[10:11], v4, s16, v[0:1]
	s_add_u32 s10, s4, 0x100
	s_addc_u32 s11, s5, 0
	v_mov_b32_e32 v71, v0
	v_mov_b64_e32 v[0:1], s[10:11]
	v_mad_u64_u32 v[74:75], s[10:11], v7, s16, v[0:1]
	v_mad_u64_u32 v[72:73], s[10:11], v6, s16, v[0:1]
	v_mov_b32_e32 v0, v75
	s_waitcnt vmcnt(6) lgkmcnt(0)
	s_barrier
	v_mov_b32_e32 v2, v73
	v_mad_u64_u32 v[0:1], s[10:11], v4, s16, v[0:1]
	v_mad_u64_u32 v[2:3], s[10:11], v5, s16, v[2:3]
	v_mov_b32_e32 v75, v0
	v_mov_b32_e32 v0, 0
	v_mov_b32_e32 v73, v2
	s_mov_b32 s9, s18
	v_mov_b32_e32 v1, v0
	v_mov_b32_e32 v2, v0
	v_mov_b32_e32 v3, v0
	v_mov_b32_e32 v4, v0
	v_mov_b32_e32 v5, v0
	v_mov_b32_e32 v6, v0
	v_mov_b32_e32 v7, v0
	v_mov_b32_e32 v8, v0
	v_mov_b32_e32 v9, v0
	v_mov_b32_e32 v10, v0
	v_mov_b32_e32 v11, v0
	v_mov_b32_e32 v12, v0
	v_mov_b32_e32 v13, v0
	v_mov_b32_e32 v14, v0
	v_mov_b32_e32 v15, v0
	v_mov_b32_e32 v16, v0
	v_mov_b32_e32 v17, v0
	v_mov_b32_e32 v18, v0
	v_mov_b32_e32 v19, v0
	v_mov_b32_e32 v20, v0
	v_mov_b32_e32 v21, v0
	v_mov_b32_e32 v22, v0
	v_mov_b32_e32 v23, v0
	v_mov_b32_e32 v24, v0
	v_mov_b32_e32 v25, v0
	v_mov_b32_e32 v26, v0
	v_mov_b32_e32 v27, v0
	v_mov_b32_e32 v28, v0
	v_mov_b32_e32 v29, v0
	v_mov_b32_e32 v30, v0
	v_mov_b32_e32 v31, v0
	v_mov_b32_e32 v32, v0
	v_mov_b32_e32 v33, v0
	v_mov_b32_e32 v34, v0
	v_mov_b32_e32 v35, v0
	v_mov_b32_e32 v36, v0
	v_mov_b32_e32 v37, v0
	v_mov_b32_e32 v38, v0
	v_mov_b32_e32 v39, v0
	v_mov_b32_e32 v40, v0
	v_mov_b32_e32 v41, v0
	v_mov_b32_e32 v42, v0
	v_mov_b32_e32 v43, v0
	v_mov_b32_e32 v44, v0
	v_mov_b32_e32 v45, v0
	v_mov_b32_e32 v46, v0
	v_mov_b32_e32 v47, v0
	v_mov_b32_e32 v48, v0
	v_mov_b32_e32 v49, v0
	v_mov_b32_e32 v50, v0
	v_mov_b32_e32 v51, v0
	v_mov_b32_e32 v52, v0
	v_mov_b32_e32 v53, v0
	v_mov_b32_e32 v54, v0
	v_mov_b32_e32 v55, v0
	v_mov_b32_e32 v56, v0
	v_mov_b32_e32 v57, v0
	v_mov_b32_e32 v58, v0
	v_mov_b32_e32 v59, v0
	v_mov_b32_e32 v60, v0
	v_mov_b32_e32 v61, v0
	v_mov_b32_e32 v62, v0
	v_mov_b32_e32 v63, v0
	s_add_i32 s99, s9, 0
	v_add_u32_e32 v253, s99, v81
	v_add_u32_e32 v252, s99, v83
	ds_read_b128 v[84:87], v252 offset:16384
	ds_read_b128 v[88:91], v253
	ds_read_b128 v[92:95], v253 offset:4096
	ds_read_b128 v[96:99], v252 offset:20480
; DEV int stage_next(int s) { return (s == 2 * GS_STAGE) ? 0 : s + GS_STAGE; }
; template <int WAIT0>
; DEV void gk_main(f32x16 (&acc)[2][2], const GTile& t, int s0) {
;     ...
;   vm_wait_bar<WAIT0>();
;   int stc = s0, std_ = stage_next(stage_next(s0));
; #pragma nounroll
;   for (int kt = 0; kt < nk - 2; ++kt) {
;     GK_DMA(std_, kt + 2);
;     GK_COMPUTE(stc);
;     vm_wait_bar<6>();
;     stc = stage_next(stc); std_ = stage_next(std_);
;   }
.LBB0_854:
	s_add_i32 s10, s2, s3
	s_mov_b32 s98, s10
	s_waitcnt lgkmcnt(0)
	v_add_u32_e32 v101, s99, v82
	v_add_u32_e32 v100, s99, v79
	s_add_i32 s10, s9, 0xc000
	s_cmp_lg_u32 s9, 0x18000
	s_cselect_b32 s9, s10, 0
	s_add_i32 s10, s3, 0xc000
	s_cmp_lg_u32 s3, 0x18000
	s_cselect_b32 s3, s10, 0
	s_add_i32 s8, s8, -1
	ds_read_b128 v[236:239], v101 offset:16384
	ds_read_b128 v[240:243], v100
	ds_read_b128 v[244:247], v100 offset:4096
	ds_read_b128 v[248:251], v101 offset:20480
	v_mfma_f32_32x32x16_bf16 v[48:63], v[84:87], v[88:91], v[48:63]
	v_mfma_f32_32x32x16_bf16 v[32:47], v[84:87], v[92:95], v[32:47]
	s_mov_b32 m0, s98
	v_lshl_add_u64 v[254:255], v[74:75], 0, v[120:121]
	global_load_lds_dwordx4 v[254:255], off
	v_lshl_add_u64 v[74:75], v[74:75], 0, s[94:95]
	v_mfma_f32_32x32x16_bf16 v[16:31], v[96:99], v[88:91], v[16:31]
	v_mfma_f32_32x32x16_bf16 v[0:15], v[96:99], v[92:95], v[0:15]
	s_add_i32 m0, s98, 0x2000
	v_lshl_add_u64 v[254:255], v[72:73], 0, v[120:121]
	global_load_lds_dwordx4 v[254:255], off
	v_lshl_add_u64 v[72:73], v[72:73], 0, s[94:95]
	v_add_u32_e32 v101, s99, v80
	v_add_u32_e32 v100, s99, v77
	s_waitcnt lgkmcnt(0)
	ds_read_b128 v[84:87], v101 offset:16384
	ds_read_b128 v[88:91], v100
	ds_read_b128 v[92:95], v100 offset:4096
	ds_read_b128 v[96:99], v101 offset:20480
	v_mfma_f32_32x32x16_bf16 v[48:63], v[236:239], v[240:243], v[48:63]
	v_mfma_f32_32x32x16_bf16 v[32:47], v[236:239], v[244:247], v[32:47]
	s_add_i32 m0, s98, 0x4000
	v_lshl_add_u64 v[254:255], v[70:71], 0, v[120:121]
	global_load_lds_dwordx4 v[254:255], off
	v_lshl_add_u64 v[70:71], v[70:71], 0, s[94:95]
	v_mfma_f32_32x32x16_bf16 v[16:31], v[248:251], v[240:243], v[16:31]
	v_mfma_f32_32x32x16_bf16 v[0:15], v[248:251], v[244:247], v[0:15]
	s_add_i32 m0, s98, 0x6000
	v_lshl_add_u64 v[254:255], v[68:69], 0, v[120:121]
	global_load_lds_dwordx4 v[254:255], off
	v_lshl_add_u64 v[68:69], v[68:69], 0, s[94:95]
	v_add_u32_e32 v101, s99, v78
	v_add_u32_e32 v100, s99, v76
	s_waitcnt lgkmcnt(0)
	ds_read_b128 v[236:239], v101 offset:16384
	ds_read_b128 v[240:243], v100
	ds_read_b128 v[244:247], v100 offset:4096
	ds_read_b128 v[248:251], v101 offset:20480
	v_mfma_f32_32x32x16_bf16 v[48:63], v[84:87], v[88:91], v[48:63]
	v_mfma_f32_32x32x16_bf16 v[32:47], v[84:87], v[92:95], v[32:47]
	s_add_i32 m0, s98, 0x8000
	v_lshl_add_u64 v[254:255], v[66:67], 0, v[120:121]
	global_load_lds_dwordx4 v[254:255], off
	v_lshl_add_u64 v[66:67], v[66:67], 0, s[94:95]
	v_mfma_f32_32x32x16_bf16 v[16:31], v[96:99], v[88:91], v[16:31]
	v_mfma_f32_32x32x16_bf16 v[0:15], v[96:99], v[92:95], v[0:15]
	s_add_i32 m0, s98, 0xa000
	v_lshl_add_u64 v[254:255], v[64:65], 0, v[120:121]
	global_load_lds_dwordx4 v[254:255], off
	v_lshl_add_u64 v[64:65], v[64:65], 0, s[94:95]
	s_waitcnt vmcnt(6) lgkmcnt(0)
	s_barrier
	s_waitcnt lgkmcnt(0)
	s_add_i32 s99, s9, 0
	v_add_u32_e32 v253, s99, v81
	v_add_u32_e32 v252, s99, v83
	ds_read_b128 v[84:87], v252 offset:16384
	ds_read_b128 v[88:91], v253
	ds_read_b128 v[92:95], v253 offset:4096
	ds_read_b128 v[96:99], v252 offset:20480
	v_mfma_f32_32x32x16_bf16 v[48:63], v[236:239], v[240:243], v[48:63]
	v_mfma_f32_32x32x16_bf16 v[32:47], v[236:239], v[244:247], v[32:47]
	v_mfma_f32_32x32x16_bf16 v[16:31], v[248:251], v[240:243], v[16:31]
	v_mfma_f32_32x32x16_bf16 v[0:15], v[248:251], v[244:247], v[0:15]
	s_cmp_lg_u32 s8, 0
	s_cbranch_scc1 .LBB0_854
; DEV int stage_next(int s) { return (s == 2 * GS_STAGE) ? 0 : s + GS_STAGE; }
; template <int WAIT0>
; DEV void gk_main(f32x16 (&acc)[2][2], const GTile& t, int s0) {
;     ...
;   vm_wait_bar<WAIT0>();
;   int stc = s0, std_ = stage_next(stage_next(s0));
; #pragma nounroll
;   for (int kt = 0; kt < nk - 2; ++kt) {
;     GK_DMA(std_, kt + 2);
;     GK_COMPUTE(stc);
;     vm_wait_bar<6>();
;     stc = stage_next(stc); std_ = stage_next(std_);
;   }
;   GK_COMPUTE(stc);
;   vm_wait_bar<0>();
;   stc = stage_next(stc);
;   GK_COMPUTE(stc);
;   vm_wait_bar<0>();
; template <int WAIT_E, int WAIT_O, class TileFn, class EpiFn>
; DEV void gemm_seq(int ntiles, TileFn tf, EpiFn epi) {
;     ...
;   for (int i = 0; i < ntiles; ++i) {
;     f32x16 acc[2][2]; acc_zero(acc);
;     if (i == 0) gk_main<6>(acc, cur, s0);
;     else if (i & 1) gk_main<WAIT_O>(acc, cur, s0);
;     else gk_main<WAIT_E>(acc, cur, s0);
;     const int sn = stage_next(s0);
;     if (i + 1 < ntiles) { cur = tf(i + 1); gk_issue2(cur, sn); }
;     epi(i, acc, s0);
;     s0 = sn;
;   }
	s_waitcnt lgkmcnt(0)
	s_add_i32 s2, s9, 0
	v_add_u32_e32 v84, s2, v83
	ds_read_b128 v[64:67], v84 offset:16384
	v_add_u32_e32 v72, s2, v81
	ds_read_b128 v[68:71], v72
	ds_read_b128 v[72:75], v72 offset:4096
	ds_read_b128 v[84:87], v84 offset:20480
	s_waitcnt lgkmcnt(0)
	v_mfma_f32_32x32x16_bf16 v[16:31], v[84:87], v[68:71], v[16:31]
	v_mfma_f32_32x32x16_bf16 v[0:15], v[84:87], v[72:75], v[0:15]
	v_add_u32_e32 v84, s2, v82
	v_mfma_f32_32x32x16_bf16 v[48:63], v[64:67], v[68:71], v[48:63]
	v_mfma_f32_32x32x16_bf16 v[32:47], v[64:67], v[72:75], v[32:47]
	ds_read_b128 v[64:67], v84 offset:16384
	v_add_u32_e32 v72, s2, v79
	ds_read_b128 v[68:71], v72
	ds_read_b128 v[72:75], v72 offset:4096
	ds_read_b128 v[84:87], v84 offset:20480
	s_waitcnt lgkmcnt(0)
	v_mfma_f32_32x32x16_bf16 v[16:31], v[84:87], v[68:71], v[16:31]
	v_mfma_f32_32x32x16_bf16 v[0:15], v[84:87], v[72:75], v[0:15]
	v_add_u32_e32 v84, s2, v80
	v_mfma_f32_32x32x16_bf16 v[48:63], v[64:67], v[68:71], v[48:63]
	v_mfma_f32_32x32x16_bf16 v[32:47], v[64:67], v[72:75], v[32:47]
	ds_read_b128 v[64:67], v84 offset:16384
	v_add_u32_e32 v72, s2, v77
	ds_read_b128 v[68:71], v72
	ds_read_b128 v[72:75], v72 offset:4096
	ds_read_b128 v[84:87], v84 offset:20480
	s_waitcnt lgkmcnt(0)
	v_mfma_f32_32x32x16_bf16 v[16:31], v[84:87], v[68:71], v[16:31]
	v_mfma_f32_32x32x16_bf16 v[0:15], v[84:87], v[72:75], v[0:15]
	v_add_u32_e32 v84, s2, v78
	v_mfma_f32_32x32x16_bf16 v[48:63], v[64:67], v[68:71], v[48:63]
	v_mfma_f32_32x32x16_bf16 v[32:47], v[64:67], v[72:75], v[32:47]
	ds_read_b128 v[64:67], v84 offset:16384
	v_add_u32_e32 v72, s2, v76
	s_add_i32 s2, s9, 0xc000
	ds_read_b128 v[68:71], v72
	ds_read_b128 v[72:75], v72 offset:4096
	ds_read_b128 v[84:87], v84 offset:20480
	s_cmp_lg_u32 s9, 0x18000
	s_cselect_b32 s2, s2, 0
	s_add_i32 s2, s2, 0
	s_waitcnt vmcnt(0) lgkmcnt(0)
	s_barrier
	v_add_u32_e32 v83, s2, v83
	s_waitcnt lgkmcnt(0)
	v_mfma_f32_32x32x16_bf16 v[48:63], v[64:67], v[68:71], v[48:63]
	v_mfma_f32_32x32x16_bf16 v[32:47], v[64:67], v[72:75], v[32:47]
	ds_read_b128 v[64:67], v83 offset:16384
	v_mfma_f32_32x32x16_bf16 v[16:31], v[84:87], v[68:71], v[16:31]
	v_mfma_f32_32x32x16_bf16 v[0:15], v[84:87], v[72:75], v[0:15]
	v_add_u32_e32 v72, s2, v81
	ds_read_b128 v[68:71], v72
	ds_read_b128 v[72:75], v72 offset:4096
	ds_read_b128 v[84:87], v83 offset:20480
	v_add_u32_e32 v81, s2, v82
	s_waitcnt lgkmcnt(0)
	v_mfma_f32_32x32x16_bf16 v[48:63], v[64:67], v[68:71], v[48:63]
	v_mfma_f32_32x32x16_bf16 v[32:47], v[64:67], v[72:75], v[32:47]
	ds_read_b128 v[64:67], v81 offset:16384
	v_mfma_f32_32x32x16_bf16 v[16:31], v[84:87], v[68:71], v[16:31]
	v_mfma_f32_32x32x16_bf16 v[0:15], v[84:87], v[72:75], v[0:15]
	v_add_u32_e32 v72, s2, v79
	ds_read_b128 v[68:71], v72
	ds_read_b128 v[72:75], v72 offset:4096
	ds_read_b128 v[82:85], v81 offset:20480
	v_add_u32_e32 v79, s2, v80
	s_waitcnt lgkmcnt(0)
	v_mfma_f32_32x32x16_bf16 v[48:63], v[64:67], v[68:71], v[48:63]
	v_mfma_f32_32x32x16_bf16 v[32:47], v[64:67], v[72:75], v[32:47]
	ds_read_b128 v[64:67], v79 offset:16384
	v_mfma_f32_32x32x16_bf16 v[16:31], v[82:85], v[68:71], v[16:31]
	v_mfma_f32_32x32x16_bf16 v[0:15], v[82:85], v[72:75], v[0:15]
	v_add_u32_e32 v72, s2, v77
	ds_read_b128 v[68:71], v72
	ds_read_b128 v[72:75], v72 offset:4096
	ds_read_b128 v[80:83], v79 offset:20480
	v_add_u32_e32 v77, s2, v78
	s_waitcnt lgkmcnt(0)
	v_mfma_f32_32x32x16_bf16 v[48:63], v[64:67], v[68:71], v[48:63]
	v_mfma_f32_32x32x16_bf16 v[32:47], v[64:67], v[72:75], v[32:47]
	ds_read_b128 v[64:67], v77 offset:16384
	v_mfma_f32_32x32x16_bf16 v[16:31], v[80:83], v[68:71], v[16:31]
	v_mfma_f32_32x32x16_bf16 v[0:15], v[80:83], v[72:75], v[0:15]
	v_add_u32_e32 v72, s2, v76
	ds_read_b128 v[68:71], v72
	ds_read_b128 v[72:75], v72 offset:4096
	ds_read_b128 v[76:79], v77 offset:20480
	s_waitcnt vmcnt(0) lgkmcnt(0)
	s_barrier
	s_waitcnt lgkmcnt(0)
	v_mfma_f32_32x32x16_bf16 v[48:63], v[64:67], v[68:71], v[48:63]
	v_mfma_f32_32x32x16_bf16 v[32:47], v[64:67], v[72:75], v[32:47]
	v_mfma_f32_32x32x16_bf16 v[16:31], v[76:79], v[68:71], v[16:31]
	v_mfma_f32_32x32x16_bf16 v[0:15], v[76:79], v[72:75], v[0:15]
	s_add_i32 s2, s19, 1
	s_cmp_eq_u32 s19, 7
	s_mov_b64 s[8:9], 0
	s_cbranch_scc1 .LBB0_850
